# v13 + Hyena FFT: 510 v_pk_mul_f32 by the (-1,+1) sign constant folded into the op_sel/neg modifiers of their packed consumers (exact)
# speedup vs baseline: 1.0106x; 1.0076x over previous
.LBB0_414:
	s_or_b64 exec, exec, s[4:5]
	v_lshlrev_b32_e32 v41, 3, v2
	v_lshlrev_b32_e32 v157, 3, v32
	s_waitcnt vmcnt(0)
	ds_write_b64 v35, v[0:1] offset:65280
	s_waitcnt lgkmcnt(0)
	s_barrier
	s_and_saveexec_b64 s[0:1], s[40:41]
	s_xor_b64 s[0:1], exec, s[0:1]
	s_cbranch_execz .LBB0_416
	s_add_i32 s4, 0, 0x11000
	v_add3_u32 v39, s4, v41, v157
	ds_read_b64 v[0:1], v39 offset:2176
	ds_read_b64 v[2:3], v39 offset:4352
	ds_read_b64 v[4:5], v39 offset:6528
	ds_read_b64 v[6:7], v39 offset:8704
	ds_read_b64 v[8:9], v39 offset:10880
	ds_read_b64 v[10:11], v39 offset:13056
	ds_read_b64 v[12:13], v39 offset:15232
	ds_read_b64 v[14:15], v39 offset:17408
	ds_read_b64 v[16:17], v39 offset:19584
	ds_read_b64 v[18:19], v39 offset:21760
	ds_read_b64 v[20:21], v39 offset:23936
	ds_read_b64 v[22:23], v39 offset:26112
	ds_read_b64 v[24:25], v39 offset:34816
	ds_read_b64 v[26:27], v39 offset:36992
	ds_read_b64 v[28:29], v39 offset:39168
	ds_read_b64 v[30:31], v39 offset:41344
	ds_read_b64 v[78:79], v39 offset:43520
	ds_read_b64 v[80:81], v39 offset:45696
	ds_read_b64 v[82:83], v39 offset:47872
	ds_read_b64 v[84:85], v39 offset:50048
	ds_read_b64 v[86:87], v39 offset:52224
	ds_read_b64 v[88:89], v39 offset:54400
	ds_read_b64 v[90:91], v39 offset:56576
	ds_read_b64 v[92:93], v39 offset:58752
	ds_read_b64 v[94:95], v39
	ds_read_b64 v[96:97], v39 offset:60928
	ds_read_b64 v[98:99], v39 offset:63104
	ds_read_b64 v[100:101], v39 offset:65280
	s_mov_b32 s11, s14
	s_waitcnt lgkmcnt(3)
	v_pk_add_f32 v[110:111], v[94:95], v[24:25]
	v_pk_add_f32 v[24:25], v[94:95], v[24:25] neg_lo:[0,1] neg_hi:[0,1]
	v_pk_add_f32 v[94:95], v[0:1], v[26:27]
	v_pk_add_f32 v[0:1], v[0:1], v[26:27] neg_lo:[0,1] neg_hi:[0,1]
	s_mov_b32 s13, s86
	v_pk_mul_f32 v[26:27], v[0:1], s[16:17]
	s_mov_b32 s4, s21
	v_pk_fma_f32 v[0:1], v[0:1], s[6:7], v[26:27] op_sel:[0,0,1] op_sel_hi:[1,0,0]
	v_pk_add_f32 v[26:27], v[2:3], v[28:29]
	v_pk_add_f32 v[2:3], v[2:3], v[28:29] neg_lo:[0,1] neg_hi:[0,1]
	s_mov_b32 s35, s30
	v_pk_mul_f32 v[28:29], v[2:3], s[18:19]
	s_mov_b32 s8, s19
	v_pk_fma_f32 v[2:3], v[2:3], s[30:31], v[28:29] op_sel:[0,0,1] op_sel_hi:[1,0,0]
	v_pk_add_f32 v[28:29], v[4:5], v[30:31]
	v_pk_add_f32 v[4:5], v[4:5], v[30:31] neg_lo:[0,1] neg_hi:[0,1]
	s_mov_b32 s77, s6
	v_pk_mul_f32 v[30:31], v[4:5], s[20:21]
	s_mov_b32 s26, s17
	v_pk_fma_f32 v[4:5], v[4:5], s[86:87], v[30:31] op_sel:[0,0,1] op_sel_hi:[1,0,0]
	v_pk_add_f32 v[30:31], v[6:7], v[78:79]
	v_pk_add_f32 v[6:7], v[6:7], v[78:79] neg_lo:[0,1] neg_hi:[0,1]
	v_add_u32_e32 v108, 0x10780, v39
	v_pk_mul_f32 v[78:79], v[6:7], s[10:11]
	ds_read_b64 v[102:103], v39 offset:28288
	ds_read_b64 v[104:105], v39 offset:30464
	ds_read_b64 v[106:107], v39 offset:32640
	ds_read_b64 v[108:109], v108
	v_pk_fma_f32 v[6:7], v[6:7], s[14:15], v[78:79] op_sel:[0,0,1] op_sel_hi:[1,0,0]
	v_pk_add_f32 v[78:79], v[8:9], v[80:81]
	v_pk_add_f32 v[8:9], v[8:9], v[80:81] neg_lo:[0,1] neg_hi:[0,1]
	s_nop 0
	v_pk_mul_f32 v[80:81], v[8:9], s[12:13]
	s_nop 0
	v_pk_fma_f32 v[8:9], v[8:9], s[4:5], v[80:81] op_sel:[0,0,1] op_sel_hi:[1,0,0]
	v_pk_add_f32 v[80:81], v[10:11], v[82:83]
	v_pk_add_f32 v[10:11], v[10:11], v[82:83] neg_lo:[0,1] neg_hi:[0,1]
	s_nop 0
	v_pk_mul_f32 v[82:83], v[10:11], s[34:35]
	s_nop 0
	v_pk_fma_f32 v[10:11], v[10:11], s[8:9], v[82:83] op_sel:[0,0,1] op_sel_hi:[1,0,0]
	v_pk_add_f32 v[82:83], v[12:13], v[84:85]
	v_pk_add_f32 v[12:13], v[12:13], v[84:85] neg_lo:[0,1] neg_hi:[0,1]
	s_nop 0
	v_pk_mul_f32 v[84:85], v[12:13], s[76:77]
	s_nop 0
	v_pk_fma_f32 v[12:13], v[12:13], s[26:27], v[84:85] op_sel:[0,0,1] op_sel_hi:[1,0,0]
	v_pk_add_f32 v[84:85], v[14:15], v[86:87]
	v_pk_add_f32 v[14:15], v[14:15], v[86:87] neg_lo:[0,1] neg_hi:[0,1]
	v_pk_add_f32 v[86:87], v[16:17], v[88:89]
	v_pk_add_f32 v[16:17], v[16:17], v[88:89] neg_lo:[0,1] neg_hi:[0,1]
	s_nop 0
	v_pk_mul_f32 v[88:89], v[16:17], s[76:77]
	s_nop 0
	v_pk_fma_f32 v[16:17], v[16:17], s[26:27], v[88:89] op_sel:[0,0,1] op_sel_hi:[1,0,0] neg_lo:[1,0,0] neg_hi:[1,0,0]
	v_pk_add_f32 v[88:89], v[18:19], v[90:91]
	v_pk_add_f32 v[18:19], v[18:19], v[90:91] neg_lo:[0,1] neg_hi:[0,1]
	s_nop 0
	v_pk_mul_f32 v[90:91], v[18:19], s[34:35]
	s_nop 0
	v_pk_fma_f32 v[18:19], v[18:19], s[8:9], v[90:91] op_sel:[0,0,1] op_sel_hi:[1,0,0] neg_lo:[1,0,0] neg_hi:[1,0,0]
	v_pk_add_f32 v[90:91], v[20:21], v[92:93]
	v_pk_add_f32 v[20:21], v[20:21], v[92:93] neg_lo:[0,1] neg_hi:[0,1]
	s_nop 0
	v_pk_mul_f32 v[92:93], v[20:21], s[12:13]
	s_nop 0
	v_pk_fma_f32 v[20:21], v[20:21], s[4:5], v[92:93] op_sel:[0,0,1] op_sel_hi:[1,0,0] neg_lo:[1,0,0] neg_hi:[1,0,0]
	s_waitcnt lgkmcnt(6)
	v_pk_add_f32 v[92:93], v[22:23], v[96:97]
	v_pk_add_f32 v[22:23], v[22:23], v[96:97] neg_lo:[0,1] neg_hi:[0,1]
	s_nop 0
	v_pk_mul_f32 v[96:97], v[22:23], s[10:11]
	s_nop 0
	v_pk_fma_f32 v[22:23], v[22:23], s[14:15], v[96:97] op_sel:[0,0,1] op_sel_hi:[1,0,0] neg_lo:[1,0,0] neg_hi:[1,0,0]
	s_waitcnt lgkmcnt(3)
	v_pk_add_f32 v[96:97], v[102:103], v[98:99]
	v_pk_add_f32 v[98:99], v[102:103], v[98:99] neg_lo:[0,1] neg_hi:[0,1]
	s_nop 0
	v_pk_mul_f32 v[102:103], v[98:99], s[20:21]
	s_nop 0
	v_pk_fma_f32 v[98:99], v[98:99], s[86:87], v[102:103] op_sel:[0,0,1] op_sel_hi:[1,0,0] neg_lo:[1,0,0] neg_hi:[1,0,0]
	s_waitcnt lgkmcnt(2)
	v_pk_add_f32 v[102:103], v[104:105], v[100:101]
	v_pk_add_f32 v[100:101], v[104:105], v[100:101] neg_lo:[0,1] neg_hi:[0,1]
	s_nop 0
	v_pk_mul_f32 v[104:105], v[100:101], s[18:19]
	s_nop 0
	v_pk_fma_f32 v[100:101], v[100:101], s[30:31], v[104:105] op_sel:[0,0,1] op_sel_hi:[1,0,0] neg_lo:[1,0,0] neg_hi:[1,0,0]
	s_waitcnt lgkmcnt(0)
	v_pk_add_f32 v[104:105], v[106:107], v[108:109]
	v_pk_add_f32 v[106:107], v[106:107], v[108:109] neg_lo:[0,1] neg_hi:[0,1]
	s_nop 0
	v_pk_mul_f32 v[108:109], v[106:107], s[16:17]
	s_nop 0
	v_pk_fma_f32 v[106:107], v[106:107], s[6:7], v[108:109] op_sel:[0,0,1] op_sel_hi:[1,0,0] neg_lo:[1,0,0] neg_hi:[1,0,0]
	v_pk_add_f32 v[108:109], v[110:111], v[84:85]
	v_pk_add_f32 v[84:85], v[110:111], v[84:85] neg_lo:[0,1] neg_hi:[0,1]
	v_pk_add_f32 v[110:111], v[94:95], v[86:87]
	v_pk_add_f32 v[86:87], v[94:95], v[86:87] neg_lo:[0,1] neg_hi:[0,1]
	s_nop 0
	v_pk_mul_f32 v[94:95], v[86:87], s[18:19]
	s_nop 0
	v_pk_fma_f32 v[86:87], v[86:87], s[30:31], v[94:95] op_sel:[0,0,1] op_sel_hi:[1,0,0]
	v_pk_add_f32 v[94:95], v[26:27], v[88:89]
	v_pk_add_f32 v[26:27], v[26:27], v[88:89] neg_lo:[0,1] neg_hi:[0,1]
	s_nop 0
	v_pk_mul_f32 v[88:89], v[26:27], s[10:11]
	s_nop 0
	v_pk_fma_f32 v[26:27], v[26:27], s[14:15], v[88:89] op_sel:[0,0,1] op_sel_hi:[1,0,0]
	v_pk_add_f32 v[88:89], v[28:29], v[90:91]
	v_pk_add_f32 v[28:29], v[28:29], v[90:91] neg_lo:[0,1] neg_hi:[0,1]
	s_nop 0
	v_pk_mul_f32 v[90:91], v[28:29], s[34:35]
	s_nop 0
	v_pk_fma_f32 v[28:29], v[28:29], s[8:9], v[90:91] op_sel:[0,0,1] op_sel_hi:[1,0,0]
	v_pk_add_f32 v[90:91], v[30:31], v[92:93]
	v_pk_add_f32 v[30:31], v[30:31], v[92:93] neg_lo:[0,1] neg_hi:[0,1]
	v_pk_add_f32 v[92:93], v[78:79], v[96:97]
	v_pk_add_f32 v[78:79], v[78:79], v[96:97] neg_lo:[0,1] neg_hi:[0,1]
	s_nop 0
	v_pk_mul_f32 v[96:97], v[78:79], s[34:35]
	s_nop 0
	v_pk_fma_f32 v[78:79], v[78:79], s[8:9], v[96:97] op_sel:[0,0,1] op_sel_hi:[1,0,0] neg_lo:[1,0,0] neg_hi:[1,0,0]
	v_pk_add_f32 v[96:97], v[80:81], v[102:103]
	v_pk_add_f32 v[80:81], v[80:81], v[102:103] neg_lo:[0,1] neg_hi:[0,1]
	s_nop 0
	v_pk_mul_f32 v[102:103], v[80:81], s[10:11]
	s_nop 0
	v_pk_fma_f32 v[80:81], v[80:81], s[14:15], v[102:103] op_sel:[0,0,1] op_sel_hi:[1,0,0] neg_lo:[1,0,0] neg_hi:[1,0,0]
	v_pk_add_f32 v[102:103], v[82:83], v[104:105]
	v_pk_add_f32 v[82:83], v[82:83], v[104:105] neg_lo:[0,1] neg_hi:[0,1]
	s_nop 0
	v_pk_mul_f32 v[104:105], v[82:83], s[18:19]
	s_nop 0
	v_pk_fma_f32 v[82:83], v[82:83], s[30:31], v[104:105] op_sel:[0,0,1] op_sel_hi:[1,0,0] neg_lo:[1,0,0] neg_hi:[1,0,0]
	v_pk_add_f32 v[104:105], v[24:25], v[14:15] op_sel:[0,1] op_sel_hi:[1,0] neg_hi:[0,1]
	v_pk_add_f32 v[14:15], v[24:25], v[14:15] op_sel:[0,1] op_sel_hi:[1,0] neg_lo:[0,1]
	v_pk_add_f32 v[24:25], v[0:1], v[16:17]
	v_pk_add_f32 v[0:1], v[0:1], v[16:17] neg_lo:[0,1] neg_hi:[0,1]
	s_nop 0
	v_pk_mul_f32 v[16:17], v[0:1], s[18:19]
	s_nop 0
	v_pk_fma_f32 v[0:1], v[0:1], s[30:31], v[16:17] op_sel:[0,0,1] op_sel_hi:[1,0,0]
	v_pk_add_f32 v[16:17], v[2:3], v[18:19]
	v_pk_add_f32 v[2:3], v[2:3], v[18:19] neg_lo:[0,1] neg_hi:[0,1]
	s_nop 0
	v_pk_mul_f32 v[18:19], v[2:3], s[10:11]
	s_nop 0
	v_pk_fma_f32 v[2:3], v[2:3], s[14:15], v[18:19] op_sel:[0,0,1] op_sel_hi:[1,0,0]
	v_pk_add_f32 v[18:19], v[4:5], v[20:21]
	v_pk_add_f32 v[4:5], v[4:5], v[20:21] neg_lo:[0,1] neg_hi:[0,1]
	s_nop 0
	v_pk_mul_f32 v[20:21], v[4:5], s[34:35]
	s_nop 0
	v_pk_fma_f32 v[4:5], v[4:5], s[8:9], v[20:21] op_sel:[0,0,1] op_sel_hi:[1,0,0]
	v_pk_add_f32 v[20:21], v[6:7], v[22:23]
	v_pk_add_f32 v[6:7], v[6:7], v[22:23] neg_lo:[0,1] neg_hi:[0,1]
	v_pk_add_f32 v[22:23], v[8:9], v[98:99]
	v_pk_add_f32 v[8:9], v[8:9], v[98:99] neg_lo:[0,1] neg_hi:[0,1]
	s_nop 0
	v_pk_mul_f32 v[98:99], v[8:9], s[34:35]
	s_nop 0
	v_pk_fma_f32 v[8:9], v[8:9], s[8:9], v[98:99] op_sel:[0,0,1] op_sel_hi:[1,0,0] neg_lo:[1,0,0] neg_hi:[1,0,0]
	v_pk_add_f32 v[98:99], v[10:11], v[100:101]
	v_pk_add_f32 v[10:11], v[10:11], v[100:101] neg_lo:[0,1] neg_hi:[0,1]
	s_nop 0
	v_pk_mul_f32 v[100:101], v[10:11], s[10:11]
	s_nop 0
	v_pk_fma_f32 v[10:11], v[10:11], s[14:15], v[100:101] op_sel:[0,0,1] op_sel_hi:[1,0,0] neg_lo:[1,0,0] neg_hi:[1,0,0]
	v_pk_add_f32 v[100:101], v[12:13], v[106:107]
	v_pk_add_f32 v[12:13], v[12:13], v[106:107] neg_lo:[0,1] neg_hi:[0,1]
	s_nop 0
	v_pk_mul_f32 v[106:107], v[12:13], s[18:19]
	s_nop 0
	v_pk_fma_f32 v[12:13], v[12:13], s[30:31], v[106:107] op_sel:[0,0,1] op_sel_hi:[1,0,0] neg_lo:[1,0,0] neg_hi:[1,0,0]
	v_pk_add_f32 v[106:107], v[108:109], v[90:91]
	v_pk_add_f32 v[90:91], v[108:109], v[90:91] neg_lo:[0,1] neg_hi:[0,1]
	v_pk_add_f32 v[108:109], v[110:111], v[92:93]
	v_pk_add_f32 v[92:93], v[110:111], v[92:93] neg_lo:[0,1] neg_hi:[0,1]
	s_nop 0
	v_pk_mul_f32 v[110:111], v[92:93], s[10:11]
	s_nop 0
	v_pk_fma_f32 v[92:93], v[92:93], s[14:15], v[110:111] op_sel:[0,0,1] op_sel_hi:[1,0,0]
	v_pk_add_f32 v[110:111], v[94:95], v[96:97]
	v_pk_add_f32 v[94:95], v[94:95], v[96:97] neg_lo:[0,1] neg_hi:[0,1]
	v_pk_add_f32 v[96:97], v[88:89], v[102:103]
	v_pk_add_f32 v[88:89], v[88:89], v[102:103] neg_lo:[0,1] neg_hi:[0,1]
	s_nop 0
	v_pk_mul_f32 v[102:103], v[88:89], s[10:11]
	s_nop 0
	v_pk_fma_f32 v[88:89], v[88:89], s[14:15], v[102:103] op_sel:[0,0,1] op_sel_hi:[1,0,0] neg_lo:[1,0,0] neg_hi:[1,0,0]
	v_pk_add_f32 v[102:103], v[84:85], v[30:31] op_sel:[0,1] op_sel_hi:[1,0] neg_hi:[0,1]
	v_pk_add_f32 v[30:31], v[84:85], v[30:31] op_sel:[0,1] op_sel_hi:[1,0] neg_lo:[0,1]
	v_pk_add_f32 v[84:85], v[86:87], v[78:79]
	v_pk_add_f32 v[78:79], v[86:87], v[78:79] neg_lo:[0,1] neg_hi:[0,1]
	v_pk_add_f32 v[112:113], v[92:93], v[88:89]
	v_pk_mul_f32 v[86:87], v[78:79], s[10:11]
	v_pk_add_f32 v[88:89], v[92:93], v[88:89] neg_lo:[0,1] neg_hi:[0,1]
	v_pk_fma_f32 v[78:79], v[78:79], s[14:15], v[86:87] op_sel:[0,0,1] op_sel_hi:[1,0,0]
	v_pk_add_f32 v[86:87], v[26:27], v[80:81]
	v_pk_add_f32 v[26:27], v[26:27], v[80:81] neg_lo:[0,1] neg_hi:[0,1]
	v_pk_add_f32 v[80:81], v[28:29], v[82:83]
	v_pk_add_f32 v[28:29], v[28:29], v[82:83] neg_lo:[0,1] neg_hi:[0,1]
	s_nop 0
	v_pk_mul_f32 v[82:83], v[28:29], s[10:11]
	v_pk_add_f32 v[118:119], v[84:85], v[80:81]
	v_pk_fma_f32 v[28:29], v[28:29], s[14:15], v[82:83] op_sel:[0,0,1] op_sel_hi:[1,0,0] neg_lo:[1,0,0] neg_hi:[1,0,0]
	v_pk_add_f32 v[82:83], v[104:105], v[20:21]
	v_pk_add_f32 v[20:21], v[104:105], v[20:21] neg_lo:[0,1] neg_hi:[0,1]
	v_pk_add_f32 v[104:105], v[24:25], v[22:23]
	v_pk_add_f32 v[22:23], v[24:25], v[22:23] neg_lo:[0,1] neg_hi:[0,1]
	v_pk_add_f32 v[80:81], v[84:85], v[80:81] neg_lo:[0,1] neg_hi:[0,1]
	v_pk_mul_f32 v[24:25], v[22:23], s[10:11]
	v_pk_add_f32 v[120:121], v[30:31], v[26:27] op_sel:[0,1] op_sel_hi:[1,0] neg_hi:[0,1]
	v_pk_fma_f32 v[22:23], v[22:23], s[14:15], v[24:25] op_sel:[0,0,1] op_sel_hi:[1,0,0]
	v_pk_add_f32 v[24:25], v[16:17], v[98:99]
	v_pk_add_f32 v[16:17], v[16:17], v[98:99] neg_lo:[0,1] neg_hi:[0,1]
	v_pk_add_f32 v[98:99], v[18:19], v[100:101]
	v_pk_add_f32 v[18:19], v[18:19], v[100:101] neg_lo:[0,1] neg_hi:[0,1]
	s_nop 0
	v_pk_mul_f32 v[100:101], v[18:19], s[10:11]
	v_pk_add_f32 v[26:27], v[30:31], v[26:27] op_sel:[0,1] op_sel_hi:[1,0] neg_lo:[0,1]
	v_pk_fma_f32 v[18:19], v[18:19], s[14:15], v[100:101] op_sel:[0,0,1] op_sel_hi:[1,0,0] neg_lo:[1,0,0] neg_hi:[1,0,0]
	v_pk_add_f32 v[100:101], v[14:15], v[6:7] op_sel:[0,1] op_sel_hi:[1,0] neg_hi:[0,1]
	v_pk_add_f32 v[6:7], v[14:15], v[6:7] op_sel:[0,1] op_sel_hi:[1,0] neg_lo:[0,1]
	v_pk_add_f32 v[14:15], v[0:1], v[8:9]
	v_pk_add_f32 v[0:1], v[0:1], v[8:9] neg_lo:[0,1] neg_hi:[0,1]
	v_pk_add_f32 v[30:31], v[78:79], v[28:29]
	v_pk_mul_f32 v[8:9], v[0:1], s[10:11]
	v_pk_add_f32 v[28:29], v[78:79], v[28:29] neg_lo:[0,1] neg_hi:[0,1]
	v_pk_fma_f32 v[0:1], v[0:1], s[14:15], v[8:9] op_sel:[0,0,1] op_sel_hi:[1,0,0]
	v_pk_add_f32 v[8:9], v[2:3], v[10:11]
	v_pk_add_f32 v[2:3], v[2:3], v[10:11] neg_lo:[0,1] neg_hi:[0,1]
	v_pk_add_f32 v[10:11], v[4:5], v[12:13]
	v_pk_add_f32 v[4:5], v[4:5], v[12:13] neg_lo:[0,1] neg_hi:[0,1]
	s_nop 0
	v_pk_mul_f32 v[12:13], v[4:5], s[10:11]
	v_pk_add_f32 v[122:123], v[82:83], v[24:25]
	v_pk_fma_f32 v[4:5], v[4:5], s[14:15], v[12:13] op_sel:[0,0,1] op_sel_hi:[1,0,0] neg_lo:[1,0,0] neg_hi:[1,0,0]
	v_pk_add_f32 v[12:13], v[106:107], v[110:111]
	v_pk_add_f32 v[106:107], v[106:107], v[110:111] neg_lo:[0,1] neg_hi:[0,1]
	v_pk_add_f32 v[110:111], v[108:109], v[96:97]
	v_pk_add_f32 v[96:97], v[108:109], v[96:97] neg_lo:[0,1] neg_hi:[0,1]
	v_pk_add_f32 v[124:125], v[82:83], v[24:25] neg_lo:[0,1] neg_hi:[0,1]
	v_pk_add_f32 v[126:127], v[104:105], v[98:99]
	v_pk_add_f32 v[24:25], v[104:105], v[98:99] neg_lo:[0,1] neg_hi:[0,1]
	v_pk_add_f32 v[104:105], v[20:21], v[16:17] op_sel:[0,1] op_sel_hi:[1,0] neg_hi:[0,1]
	v_pk_add_f32 v[128:129], v[20:21], v[16:17] op_sel:[0,1] op_sel_hi:[1,0] neg_lo:[0,1]
	v_pk_add_f32 v[16:17], v[22:23], v[18:19] neg_lo:[0,1] neg_hi:[0,1]
	v_pk_add_f32 v[134:135], v[100:101], v[8:9]
	v_pk_add_f32 v[136:137], v[100:101], v[8:9] neg_lo:[0,1] neg_hi:[0,1]
	v_pk_add_f32 v[8:9], v[14:15], v[10:11] neg_lo:[0,1] neg_hi:[0,1]
	v_pk_add_f32 v[140:141], v[6:7], v[2:3] op_sel:[0,1] op_sel_hi:[1,0] neg_hi:[0,1]
	v_pk_add_f32 v[142:143], v[6:7], v[2:3] op_sel:[0,1] op_sel_hi:[1,0] neg_lo:[0,1]
	v_pk_add_f32 v[2:3], v[0:1], v[4:5]
	v_pk_add_f32 v[0:1], v[0:1], v[4:5] neg_lo:[0,1] neg_hi:[0,1]
	v_pk_add_f32 v[108:109], v[90:91], v[94:95] op_sel:[0,1] op_sel_hi:[1,0] neg_hi:[0,1]
	v_pk_add_f32 v[94:95], v[90:91], v[94:95] op_sel:[0,1] op_sel_hi:[1,0] neg_lo:[0,1]
	v_pk_mul_f32 v[114:115], v[88:89], s[22:23]
	v_pk_add_f32 v[116:117], v[102:103], v[86:87]
	v_pk_add_f32 v[102:103], v[102:103], v[86:87] neg_lo:[0,1] neg_hi:[0,1]
	v_pk_mul_f32 v[78:79], v[28:29], s[22:23]
	v_pk_mul_f32 v[98:99], v[24:25], s[22:23]
	v_pk_add_f32 v[130:131], v[22:23], v[18:19]
	v_pk_mul_f32 v[132:133], v[16:17], s[22:23]
	v_pk_add_f32 v[100:101], v[14:15], v[10:11]
	v_pk_mul_f32 v[138:139], v[8:9], s[22:23]
	v_pk_mul_f32 v[144:145], v[0:1], s[22:23]
	v_pk_add_f32 v[28:29], v[12:13], v[110:111]
	v_pk_add_f32 v[92:93], v[12:13], v[110:111] neg_lo:[0,1] neg_hi:[0,1]
	v_pk_add_f32 v[24:25], v[106:107], v[96:97] op_sel:[0,1] op_sel_hi:[1,0] neg_hi:[0,1]
	v_pk_add_f32 v[90:91], v[106:107], v[96:97] op_sel:[0,1] op_sel_hi:[1,0] neg_lo:[0,1]
	v_pk_add_f32 v[20:21], v[108:109], v[112:113]
	v_pk_add_f32 v[88:89], v[108:109], v[112:113] neg_lo:[0,1] neg_hi:[0,1]
	v_pk_add_f32 v[16:17], v[94:95], v[114:115] op_sel:[0,1] op_sel_hi:[1,0]
	v_pk_add_f32 v[86:87], v[94:95], v[114:115] op_sel:[0,1] op_sel_hi:[1,0] neg_lo:[0,1] neg_hi:[0,1]
	v_pk_add_f32 v[12:13], v[116:117], v[118:119]
	v_pk_add_f32 v[84:85], v[116:117], v[118:119] neg_lo:[0,1] neg_hi:[0,1]
	v_pk_add_f32 v[8:9], v[102:103], v[80:81] op_sel:[0,1] op_sel_hi:[1,0] neg_hi:[0,1]
	v_pk_add_f32 v[82:83], v[102:103], v[80:81] op_sel:[0,1] op_sel_hi:[1,0] neg_lo:[0,1]
	v_pk_add_f32 v[4:5], v[120:121], v[30:31]
	v_pk_add_f32 v[80:81], v[120:121], v[30:31] neg_lo:[0,1] neg_hi:[0,1]
	v_pk_add_f32 v[0:1], v[26:27], v[78:79] op_sel:[0,1] op_sel_hi:[1,0]
	v_pk_add_f32 v[78:79], v[26:27], v[78:79] op_sel:[0,1] op_sel_hi:[1,0] neg_lo:[0,1] neg_hi:[0,1]
	v_pk_add_f32 v[30:31], v[122:123], v[126:127]
	v_pk_add_f32 v[108:109], v[122:123], v[126:127] neg_lo:[0,1] neg_hi:[0,1]
	v_pk_add_f32 v[26:27], v[124:125], v[98:99] op_sel:[0,1] op_sel_hi:[1,0]
	v_pk_add_f32 v[106:107], v[124:125], v[98:99] op_sel:[0,1] op_sel_hi:[1,0] neg_lo:[0,1] neg_hi:[0,1]
	v_pk_add_f32 v[22:23], v[104:105], v[130:131]
	v_pk_add_f32 v[104:105], v[104:105], v[130:131] neg_lo:[0,1] neg_hi:[0,1]
	v_pk_add_f32 v[18:19], v[128:129], v[132:133] op_sel:[0,1] op_sel_hi:[1,0]
	v_pk_add_f32 v[102:103], v[128:129], v[132:133] op_sel:[0,1] op_sel_hi:[1,0] neg_lo:[0,1] neg_hi:[0,1]
	v_pk_add_f32 v[14:15], v[134:135], v[100:101]
	v_pk_add_f32 v[100:101], v[134:135], v[100:101] neg_lo:[0,1] neg_hi:[0,1]
	v_pk_add_f32 v[10:11], v[136:137], v[138:139] op_sel:[0,1] op_sel_hi:[1,0]
	v_pk_add_f32 v[98:99], v[136:137], v[138:139] op_sel:[0,1] op_sel_hi:[1,0] neg_lo:[0,1] neg_hi:[0,1]
	v_pk_add_f32 v[6:7], v[140:141], v[2:3]
	v_pk_add_f32 v[96:97], v[140:141], v[2:3] neg_lo:[0,1] neg_hi:[0,1]
	v_pk_add_f32 v[2:3], v[142:143], v[144:145] op_sel:[0,1] op_sel_hi:[1,0]
	v_pk_add_f32 v[94:95], v[142:143], v[144:145] op_sel:[0,1] op_sel_hi:[1,0] neg_lo:[0,1] neg_hi:[0,1]

.LBB0_418:
	s_or_b64 exec, exec, s[0:1]
	v_mov_b32_e32 v39, v32
	s_waitcnt lgkmcnt(0)
	s_barrier
	s_add_i32 s26, 0, 0x11000
	v_and_b32_e32 v86, 31, v39
	v_cvt_f32_ubyte0_e32 v24, v86
	v_mul_f32_e32 v80, 0x3b000000, v24
	v_sin_f32_e32 v24, v80
	v_ashrrev_i32_e32 v0, 4, v39
	v_lshlrev_b32_e32 v0, 3, v0
	v_lshlrev_b32_e32 v1, 3, v39
	v_cos_f32_e32 v80, v80
	v_add3_u32 v25, s26, v0, v1
	ds_read_b64 v[0:1], v25
	ds_read_b64 v[2:3], v25 offset:4352
	ds_read_b64 v[4:5], v25 offset:8704
	ds_read_b64 v[6:7], v25 offset:13056
	ds_read_b64 v[8:9], v25 offset:17408
	ds_read_b64 v[10:11], v25 offset:21760
	ds_read_b64 v[12:13], v25 offset:26112
	ds_read_b64 v[14:15], v25 offset:30464
	ds_read_b64 v[16:17], v25 offset:34816
	ds_read_b64 v[18:19], v25 offset:39168
	ds_read_b64 v[20:21], v25 offset:43520
	ds_read_b64 v[22:23], v25 offset:47872
	v_xor_b32_e32 v81, 0x80000000, v24
	s_waitcnt lgkmcnt(10)
	v_pk_mul_f32 v[82:83], v[2:3], v[24:25] op_sel:[1,0] op_sel_hi:[0,0] neg_hi:[0,1]
	v_pk_fma_f32 v[2:3], v[2:3], v[80:81], v[82:83] op_sel_hi:[1,0,1]
	v_pk_mul_f32 v[82:83], v[24:25], v[80:81] op_sel:[0,1] op_sel_hi:[0,0] neg_hi:[1,0]
	v_pk_fma_f32 v[82:83], v[80:81], v[80:81], v[82:83] op_sel_hi:[0,1,1]
	ds_read_b64 v[26:27], v25 offset:52224
	ds_read_b64 v[28:29], v25 offset:56576
	ds_read_b64 v[30:31], v25 offset:60928
	ds_read_b64 v[78:79], v25 offset:65280
	s_waitcnt lgkmcnt(13)
	v_pk_mul_f32 v[84:85], v[4:5], v[82:83] op_sel:[1,1] op_sel_hi:[0,1] neg_lo:[0,1]
	v_pk_fma_f32 v[4:5], v[4:5], v[82:83], v[84:85] op_sel_hi:[1,0,1]
	v_pk_mul_f32 v[84:85], v[24:25], v[82:83] op_sel:[0,1] op_sel_hi:[0,0] neg_hi:[1,0]
	v_pk_fma_f32 v[82:83], v[80:81], v[82:83], v[84:85] op_sel_hi:[0,1,1]
	s_mov_b32 s11, s14
	s_waitcnt lgkmcnt(12)
	v_pk_mul_f32 v[84:85], v[6:7], v[82:83] op_sel:[1,1] op_sel_hi:[0,1] neg_lo:[0,1]
	v_pk_fma_f32 v[6:7], v[6:7], v[82:83], v[84:85] op_sel_hi:[1,0,1]
	v_pk_mul_f32 v[84:85], v[24:25], v[82:83] op_sel:[0,1] op_sel_hi:[0,0] neg_hi:[1,0]
	v_pk_fma_f32 v[82:83], v[80:81], v[82:83], v[84:85] op_sel_hi:[0,1,1]
	s_mov_b32 s35, s30
	s_waitcnt lgkmcnt(11)
	v_pk_mul_f32 v[84:85], v[8:9], v[82:83] op_sel:[1,1] op_sel_hi:[0,1] neg_lo:[0,1]
	v_pk_fma_f32 v[8:9], v[8:9], v[82:83], v[84:85] op_sel_hi:[1,0,1]
	v_pk_mul_f32 v[84:85], v[24:25], v[82:83] op_sel:[0,1] op_sel_hi:[0,0] neg_hi:[1,0]
	v_pk_fma_f32 v[82:83], v[80:81], v[82:83], v[84:85] op_sel_hi:[0,1,1]
	s_mov_b32 s0, s19
	s_waitcnt lgkmcnt(10)
	v_pk_mul_f32 v[84:85], v[10:11], v[82:83] op_sel:[1,1] op_sel_hi:[0,1] neg_lo:[0,1]
	v_pk_fma_f32 v[10:11], v[10:11], v[82:83], v[84:85] op_sel_hi:[1,0,1]
	v_pk_mul_f32 v[84:85], v[24:25], v[82:83] op_sel:[0,1] op_sel_hi:[0,0] neg_hi:[1,0]
	v_pk_fma_f32 v[82:83], v[80:81], v[82:83], v[84:85] op_sel_hi:[0,1,1]
	s_waitcnt lgkmcnt(0)
	v_pk_mul_f32 v[84:85], v[12:13], v[82:83] op_sel:[1,1] op_sel_hi:[0,1] neg_lo:[0,1]
	v_pk_fma_f32 v[12:13], v[12:13], v[82:83], v[84:85] op_sel_hi:[1,0,1]
	v_pk_mul_f32 v[84:85], v[24:25], v[82:83] op_sel:[0,1] op_sel_hi:[0,0] neg_hi:[1,0]
	v_pk_fma_f32 v[82:83], v[80:81], v[82:83], v[84:85] op_sel_hi:[0,1,1]
	s_barrier
	v_pk_mul_f32 v[84:85], v[14:15], v[82:83] op_sel:[1,1] op_sel_hi:[0,1] neg_lo:[0,1]
	v_pk_fma_f32 v[14:15], v[14:15], v[82:83], v[84:85] op_sel_hi:[1,0,1]
	v_pk_mul_f32 v[84:85], v[24:25], v[82:83] op_sel:[0,1] op_sel_hi:[0,0] neg_hi:[1,0]
	v_pk_fma_f32 v[82:83], v[80:81], v[82:83], v[84:85] op_sel_hi:[0,1,1]
	s_nop 0
	v_pk_mul_f32 v[84:85], v[16:17], v[82:83] op_sel:[1,1] op_sel_hi:[0,1] neg_lo:[0,1]
	v_pk_fma_f32 v[16:17], v[16:17], v[82:83], v[84:85] op_sel_hi:[1,0,1]
	v_pk_mul_f32 v[84:85], v[24:25], v[82:83] op_sel:[0,1] op_sel_hi:[0,0] neg_hi:[1,0]
	v_pk_fma_f32 v[82:83], v[80:81], v[82:83], v[84:85] op_sel_hi:[0,1,1]
	s_nop 0
	v_pk_mul_f32 v[84:85], v[18:19], v[82:83] op_sel:[1,1] op_sel_hi:[0,1] neg_lo:[0,1]
	v_pk_fma_f32 v[18:19], v[18:19], v[82:83], v[84:85] op_sel_hi:[1,0,1]
	v_pk_mul_f32 v[84:85], v[24:25], v[82:83] op_sel:[0,1] op_sel_hi:[0,0] neg_hi:[1,0]
	v_pk_fma_f32 v[82:83], v[80:81], v[82:83], v[84:85] op_sel_hi:[0,1,1]
	s_nop 0
	v_pk_mul_f32 v[84:85], v[20:21], v[82:83] op_sel:[1,1] op_sel_hi:[0,1] neg_lo:[0,1]
	v_pk_fma_f32 v[20:21], v[20:21], v[82:83], v[84:85] op_sel_hi:[1,0,1]
	v_pk_mul_f32 v[84:85], v[24:25], v[82:83] op_sel:[0,1] op_sel_hi:[0,0] neg_hi:[1,0]
	v_pk_fma_f32 v[82:83], v[80:81], v[82:83], v[84:85] op_sel_hi:[0,1,1]
	s_nop 0
	v_pk_mul_f32 v[84:85], v[22:23], v[82:83] op_sel:[1,1] op_sel_hi:[0,1] neg_lo:[0,1]
	v_pk_fma_f32 v[22:23], v[22:23], v[82:83], v[84:85] op_sel_hi:[1,0,1]
	v_pk_mul_f32 v[84:85], v[24:25], v[82:83] op_sel:[0,1] op_sel_hi:[0,0] neg_hi:[1,0]
	v_pk_fma_f32 v[82:83], v[80:81], v[82:83], v[84:85] op_sel_hi:[0,1,1]
	s_nop 0
	v_pk_mul_f32 v[84:85], v[26:27], v[82:83] op_sel:[1,1] op_sel_hi:[0,1] neg_lo:[0,1]
	v_pk_fma_f32 v[26:27], v[26:27], v[82:83], v[84:85] op_sel_hi:[1,0,1]
	v_pk_mul_f32 v[84:85], v[24:25], v[82:83] op_sel:[0,1] op_sel_hi:[0,0] neg_hi:[1,0]
	v_pk_fma_f32 v[82:83], v[80:81], v[82:83], v[84:85] op_sel_hi:[0,1,1]
	s_nop 0
	v_pk_mul_f32 v[84:85], v[28:29], v[82:83] op_sel:[1,1] op_sel_hi:[0,1] neg_lo:[0,1]
	v_pk_fma_f32 v[28:29], v[28:29], v[82:83], v[84:85] op_sel_hi:[1,0,1]
	v_pk_mul_f32 v[84:85], v[24:25], v[82:83] op_sel:[0,1] op_sel_hi:[0,0] neg_hi:[1,0]
	v_pk_fma_f32 v[82:83], v[80:81], v[82:83], v[84:85] op_sel_hi:[0,1,1]
	v_pk_mul_f32 v[24:25], v[24:25], v[82:83] op_sel:[0,1] op_sel_hi:[0,0] neg_hi:[1,0]
	v_pk_fma_f32 v[24:25], v[80:81], v[82:83], v[24:25] op_sel_hi:[0,1,1]
	v_pk_mul_f32 v[80:81], v[78:79], v[24:25] op_sel:[1,1] op_sel_hi:[0,1] neg_lo:[0,1]
	v_pk_fma_f32 v[24:25], v[78:79], v[24:25], v[80:81] op_sel_hi:[1,0,1]
	v_pk_add_f32 v[78:79], v[0:1], v[16:17]
	v_pk_add_f32 v[0:1], v[0:1], v[16:17] neg_lo:[0,1] neg_hi:[0,1]
	v_pk_add_f32 v[16:17], v[2:3], v[18:19]
	v_pk_add_f32 v[2:3], v[2:3], v[18:19] neg_lo:[0,1] neg_hi:[0,1]
	v_pk_mul_f32 v[84:85], v[30:31], v[82:83] op_sel:[1,1] op_sel_hi:[0,1] neg_lo:[0,1]
	v_pk_mul_f32 v[18:19], v[2:3], s[18:19]
	v_pk_fma_f32 v[30:31], v[30:31], v[82:83], v[84:85] op_sel_hi:[1,0,1]
	v_pk_fma_f32 v[2:3], v[2:3], s[30:31], v[18:19] op_sel:[0,0,1] op_sel_hi:[1,0,0]
	v_pk_add_f32 v[18:19], v[4:5], v[20:21]
	v_pk_add_f32 v[4:5], v[4:5], v[20:21] neg_lo:[0,1] neg_hi:[0,1]
	s_nop 0
	v_pk_mul_f32 v[20:21], v[4:5], s[10:11]
	s_nop 0
	v_pk_fma_f32 v[4:5], v[4:5], s[14:15], v[20:21] op_sel:[0,0,1] op_sel_hi:[1,0,0]
	v_pk_add_f32 v[20:21], v[6:7], v[22:23]
	v_pk_add_f32 v[6:7], v[6:7], v[22:23] neg_lo:[0,1] neg_hi:[0,1]
	s_nop 0
	v_pk_mul_f32 v[22:23], v[6:7], s[34:35]
	s_nop 0
	v_pk_fma_f32 v[6:7], v[6:7], s[0:1], v[22:23] op_sel:[0,0,1] op_sel_hi:[1,0,0]
	v_pk_add_f32 v[22:23], v[8:9], v[26:27]
	v_pk_add_f32 v[8:9], v[8:9], v[26:27] neg_lo:[0,1] neg_hi:[0,1]
	v_pk_add_f32 v[26:27], v[10:11], v[28:29]
	v_pk_add_f32 v[10:11], v[10:11], v[28:29] neg_lo:[0,1] neg_hi:[0,1]
	s_nop 0
	v_pk_mul_f32 v[28:29], v[10:11], s[34:35]
	s_nop 0
	v_pk_fma_f32 v[10:11], v[10:11], s[0:1], v[28:29] op_sel:[0,0,1] op_sel_hi:[1,0,0] neg_lo:[1,0,0] neg_hi:[1,0,0]
	v_pk_add_f32 v[28:29], v[12:13], v[30:31]
	v_pk_add_f32 v[12:13], v[12:13], v[30:31] neg_lo:[0,1] neg_hi:[0,1]
	s_nop 0
	v_pk_mul_f32 v[30:31], v[12:13], s[10:11]
	s_nop 0
	v_pk_fma_f32 v[12:13], v[12:13], s[14:15], v[30:31] op_sel:[0,0,1] op_sel_hi:[1,0,0] neg_lo:[1,0,0] neg_hi:[1,0,0]
	v_pk_add_f32 v[30:31], v[14:15], v[24:25]
	v_pk_add_f32 v[14:15], v[14:15], v[24:25] neg_lo:[0,1] neg_hi:[0,1]
	s_nop 0
	v_pk_mul_f32 v[24:25], v[14:15], s[18:19]
	s_nop 0
	v_pk_fma_f32 v[14:15], v[14:15], s[30:31], v[24:25] op_sel:[0,0,1] op_sel_hi:[1,0,0] neg_lo:[1,0,0] neg_hi:[1,0,0]
	v_pk_add_f32 v[24:25], v[78:79], v[22:23]
	v_pk_add_f32 v[22:23], v[78:79], v[22:23] neg_lo:[0,1] neg_hi:[0,1]
	v_pk_add_f32 v[78:79], v[16:17], v[26:27]
	v_pk_add_f32 v[16:17], v[16:17], v[26:27] neg_lo:[0,1] neg_hi:[0,1]
	s_nop 0
	v_pk_mul_f32 v[26:27], v[16:17], s[10:11]
	s_nop 0
	v_pk_fma_f32 v[16:17], v[16:17], s[14:15], v[26:27] op_sel:[0,0,1] op_sel_hi:[1,0,0]
	v_pk_add_f32 v[26:27], v[18:19], v[28:29]
	v_pk_add_f32 v[18:19], v[18:19], v[28:29] neg_lo:[0,1] neg_hi:[0,1]
	v_pk_add_f32 v[28:29], v[20:21], v[30:31]
	v_pk_add_f32 v[20:21], v[20:21], v[30:31] neg_lo:[0,1] neg_hi:[0,1]
	s_nop 0
	v_pk_mul_f32 v[30:31], v[20:21], s[10:11]
	s_nop 0
	v_pk_fma_f32 v[20:21], v[20:21], s[14:15], v[30:31] op_sel:[0,0,1] op_sel_hi:[1,0,0] neg_lo:[1,0,0] neg_hi:[1,0,0]
	v_pk_add_f32 v[30:31], v[0:1], v[8:9] op_sel:[0,1] op_sel_hi:[1,0] neg_hi:[0,1]
	v_pk_add_f32 v[0:1], v[0:1], v[8:9] op_sel:[0,1] op_sel_hi:[1,0] neg_lo:[0,1]
	v_pk_add_f32 v[8:9], v[2:3], v[10:11]
	v_pk_add_f32 v[2:3], v[2:3], v[10:11] neg_lo:[0,1] neg_hi:[0,1]
	s_nop 0
	v_pk_mul_f32 v[10:11], v[2:3], s[10:11]
	s_nop 0
	v_pk_fma_f32 v[2:3], v[2:3], s[14:15], v[10:11] op_sel:[0,0,1] op_sel_hi:[1,0,0]
	v_pk_add_f32 v[10:11], v[4:5], v[12:13]
	v_pk_add_f32 v[4:5], v[4:5], v[12:13] neg_lo:[0,1] neg_hi:[0,1]
	v_pk_add_f32 v[12:13], v[6:7], v[14:15]
	v_pk_add_f32 v[6:7], v[6:7], v[14:15] neg_lo:[0,1] neg_hi:[0,1]
	s_nop 0
	v_pk_mul_f32 v[14:15], v[6:7], s[10:11]
	s_nop 0
	v_pk_fma_f32 v[6:7], v[6:7], s[14:15], v[14:15] op_sel:[0,0,1] op_sel_hi:[1,0,0] neg_lo:[1,0,0] neg_hi:[1,0,0]
	v_pk_add_f32 v[14:15], v[24:25], v[26:27]
	v_pk_add_f32 v[24:25], v[24:25], v[26:27] neg_lo:[0,1] neg_hi:[0,1]
	v_pk_add_f32 v[26:27], v[78:79], v[28:29]
	v_pk_add_f32 v[28:29], v[78:79], v[28:29] neg_lo:[0,1] neg_hi:[0,1]
	v_pk_add_f32 v[78:79], v[22:23], v[18:19] op_sel:[0,1] op_sel_hi:[1,0] neg_hi:[0,1]
	v_pk_add_f32 v[18:19], v[22:23], v[18:19] op_sel:[0,1] op_sel_hi:[1,0] neg_lo:[0,1]
	v_pk_add_f32 v[22:23], v[16:17], v[20:21]
	v_pk_add_f32 v[16:17], v[16:17], v[20:21] neg_lo:[0,1] neg_hi:[0,1]
	v_pk_add_f32 v[20:21], v[30:31], v[10:11]
	v_pk_add_f32 v[10:11], v[30:31], v[10:11] neg_lo:[0,1] neg_hi:[0,1]
	v_pk_add_f32 v[30:31], v[8:9], v[12:13]
	v_pk_add_f32 v[8:9], v[8:9], v[12:13] neg_lo:[0,1] neg_hi:[0,1]
	v_pk_add_f32 v[12:13], v[0:1], v[4:5] op_sel:[0,1] op_sel_hi:[1,0] neg_hi:[0,1]
	v_pk_add_f32 v[0:1], v[0:1], v[4:5] op_sel:[0,1] op_sel_hi:[1,0] neg_lo:[0,1]
	v_pk_add_f32 v[4:5], v[2:3], v[6:7]
	v_pk_add_f32 v[2:3], v[2:3], v[6:7] neg_lo:[0,1] neg_hi:[0,1]
	s_nop 0
	v_pk_mul_f32 v[2:3], v[2:3], s[22:23]
	v_pk_add_f32 v[6:7], v[14:15], v[26:27]
	v_pk_add_f32 v[14:15], v[14:15], v[26:27] neg_lo:[0,1] neg_hi:[0,1]
	v_pk_add_f32 v[26:27], v[24:25], v[28:29] op_sel:[0,1] op_sel_hi:[1,0] neg_hi:[0,1]
	v_pk_add_f32 v[24:25], v[24:25], v[28:29] op_sel:[0,1] op_sel_hi:[1,0] neg_lo:[0,1]
	v_pk_add_f32 v[28:29], v[78:79], v[22:23]
	v_pk_add_f32 v[22:23], v[78:79], v[22:23] neg_lo:[0,1] neg_hi:[0,1]
	v_pk_add_f32 v[78:79], v[18:19], v[16:17] op_sel:[0,1] op_sel_hi:[1,0] neg_hi:[0,1]
	v_pk_add_f32 v[16:17], v[18:19], v[16:17] op_sel:[0,1] op_sel_hi:[1,0] neg_lo:[0,1]
	v_pk_add_f32 v[18:19], v[20:21], v[30:31]
	v_pk_add_f32 v[20:21], v[20:21], v[30:31] neg_lo:[0,1] neg_hi:[0,1]
	v_pk_add_f32 v[30:31], v[10:11], v[8:9] op_sel:[0,1] op_sel_hi:[1,0] neg_hi:[0,1]
	v_pk_add_f32 v[8:9], v[10:11], v[8:9] op_sel:[0,1] op_sel_hi:[1,0] neg_lo:[0,1]
	v_pk_add_f32 v[10:11], v[12:13], v[4:5]
	v_pk_add_f32 v[4:5], v[12:13], v[4:5] neg_lo:[0,1] neg_hi:[0,1]
	v_pk_add_f32 v[12:13], v[0:1], v[2:3] op_sel:[0,1] op_sel_hi:[1,0]
	v_pk_add_f32 v[0:1], v[0:1], v[2:3] op_sel:[0,1] op_sel_hi:[1,0] neg_lo:[0,1] neg_hi:[0,1]
	v_lshlrev_b32_e32 v2, 4, v39
	v_and_or_b32 v2, v2, s7, v86
	v_ashrrev_i32_e32 v3, 4, v2
	v_lshlrev_b32_e32 v3, 3, v3
	v_lshlrev_b32_e32 v2, 3, v2
	v_add3_u32 v2, s26, v3, v2
	v_add_u32_e32 v3, 0x800, v2
	v_mov_b32_e32 v39, v32
	ds_write2_b64 v2, v[6:7], v[18:19] offset1:34
	ds_write2_b64 v3, v[14:15], v[20:21] offset0:16 offset1:50
	ds_write2_b64 v2, v[26:27], v[30:31] offset0:136 offset1:170
	ds_write2_b64 v3, v[24:25], v[8:9] offset0:152 offset1:186
	ds_write2_b64 v2, v[28:29], v[10:11] offset0:68 offset1:102
	ds_write2_b64 v3, v[22:23], v[4:5] offset0:84 offset1:118
	ds_write2_b64 v2, v[78:79], v[12:13] offset0:204 offset1:238
	ds_write2_b64 v3, v[16:17], v[0:1] offset0:220 offset1:254
	s_waitcnt lgkmcnt(0)
	s_barrier
	s_nop 0
	v_and_b32_e32 v86, 0x1ff, v39
	v_cvt_f32_u32_e32 v24, v86
	v_ashrrev_i32_e32 v0, 4, v39
	v_lshlrev_b32_e32 v0, 3, v0
	v_lshlrev_b32_e32 v1, 3, v39
	v_mul_f32_e32 v80, 0x39000000, v24
	v_sin_f32_e32 v24, v80
	v_cos_f32_e32 v80, v80
	v_add3_u32 v25, s26, v0, v1
	ds_read_b64 v[0:1], v25
	ds_read_b64 v[2:3], v25 offset:4352
	ds_read_b64 v[4:5], v25 offset:8704
	ds_read_b64 v[6:7], v25 offset:13056
	ds_read_b64 v[8:9], v25 offset:17408
	ds_read_b64 v[10:11], v25 offset:21760
	ds_read_b64 v[12:13], v25 offset:26112
	ds_read_b64 v[14:15], v25 offset:30464
	v_xor_b32_e32 v81, 0x80000000, v24
	s_waitcnt lgkmcnt(6)
	v_pk_mul_f32 v[82:83], v[2:3], v[24:25] op_sel:[1,0] op_sel_hi:[0,0] neg_hi:[0,1]
	v_pk_fma_f32 v[2:3], v[2:3], v[80:81], v[82:83] op_sel_hi:[1,0,1]
	v_pk_mul_f32 v[82:83], v[24:25], v[80:81] op_sel:[0,1] op_sel_hi:[0,0] neg_hi:[1,0]
	v_pk_fma_f32 v[82:83], v[80:81], v[80:81], v[82:83] op_sel_hi:[0,1,1]
	ds_read_b64 v[16:17], v25 offset:34816
	ds_read_b64 v[18:19], v25 offset:39168
	ds_read_b64 v[20:21], v25 offset:43520
	ds_read_b64 v[22:23], v25 offset:47872
	s_waitcnt lgkmcnt(9)
	v_pk_mul_f32 v[84:85], v[4:5], v[82:83] op_sel:[1,1] op_sel_hi:[0,1] neg_lo:[0,1]
	v_pk_fma_f32 v[4:5], v[4:5], v[82:83], v[84:85] op_sel_hi:[1,0,1]
	v_pk_mul_f32 v[84:85], v[24:25], v[82:83] op_sel:[0,1] op_sel_hi:[0,0] neg_hi:[1,0]
	v_pk_fma_f32 v[82:83], v[80:81], v[82:83], v[84:85] op_sel_hi:[0,1,1]
	ds_read_b64 v[26:27], v25 offset:52224
	ds_read_b64 v[28:29], v25 offset:56576
	ds_read_b64 v[30:31], v25 offset:60928
	ds_read_b64 v[78:79], v25 offset:65280
	s_waitcnt lgkmcnt(12)
	v_pk_mul_f32 v[84:85], v[6:7], v[82:83] op_sel:[1,1] op_sel_hi:[0,1] neg_lo:[0,1]
	v_pk_fma_f32 v[6:7], v[6:7], v[82:83], v[84:85] op_sel_hi:[1,0,1]
	v_pk_mul_f32 v[84:85], v[24:25], v[82:83] op_sel:[0,1] op_sel_hi:[0,0] neg_hi:[1,0]
	v_pk_fma_f32 v[82:83], v[80:81], v[82:83], v[84:85] op_sel_hi:[0,1,1]
	s_waitcnt lgkmcnt(0)
	v_pk_mul_f32 v[84:85], v[8:9], v[82:83] op_sel:[1,1] op_sel_hi:[0,1] neg_lo:[0,1]
	v_pk_fma_f32 v[8:9], v[8:9], v[82:83], v[84:85] op_sel_hi:[1,0,1]
	v_pk_mul_f32 v[84:85], v[24:25], v[82:83] op_sel:[0,1] op_sel_hi:[0,0] neg_hi:[1,0]
	v_pk_fma_f32 v[82:83], v[80:81], v[82:83], v[84:85] op_sel_hi:[0,1,1]
	s_barrier
	v_pk_mul_f32 v[84:85], v[10:11], v[82:83] op_sel:[1,1] op_sel_hi:[0,1] neg_lo:[0,1]
	v_pk_fma_f32 v[10:11], v[10:11], v[82:83], v[84:85] op_sel_hi:[1,0,1]
	v_pk_mul_f32 v[84:85], v[24:25], v[82:83] op_sel:[0,1] op_sel_hi:[0,0] neg_hi:[1,0]
	v_pk_fma_f32 v[82:83], v[80:81], v[82:83], v[84:85] op_sel_hi:[0,1,1]
	s_nop 0
	v_pk_mul_f32 v[84:85], v[12:13], v[82:83] op_sel:[1,1] op_sel_hi:[0,1] neg_lo:[0,1]
	v_pk_fma_f32 v[12:13], v[12:13], v[82:83], v[84:85] op_sel_hi:[1,0,1]
	v_pk_mul_f32 v[84:85], v[24:25], v[82:83] op_sel:[0,1] op_sel_hi:[0,0] neg_hi:[1,0]
	v_pk_fma_f32 v[82:83], v[80:81], v[82:83], v[84:85] op_sel_hi:[0,1,1]
	s_nop 0
	v_pk_mul_f32 v[84:85], v[14:15], v[82:83] op_sel:[1,1] op_sel_hi:[0,1] neg_lo:[0,1]
	v_pk_fma_f32 v[14:15], v[14:15], v[82:83], v[84:85] op_sel_hi:[1,0,1]
	v_pk_mul_f32 v[84:85], v[24:25], v[82:83] op_sel:[0,1] op_sel_hi:[0,0] neg_hi:[1,0]
	v_pk_fma_f32 v[82:83], v[80:81], v[82:83], v[84:85] op_sel_hi:[0,1,1]
	s_nop 0
	v_pk_mul_f32 v[84:85], v[16:17], v[82:83] op_sel:[1,1] op_sel_hi:[0,1] neg_lo:[0,1]
	v_pk_fma_f32 v[16:17], v[16:17], v[82:83], v[84:85] op_sel_hi:[1,0,1]
	v_pk_mul_f32 v[84:85], v[24:25], v[82:83] op_sel:[0,1] op_sel_hi:[0,0] neg_hi:[1,0]
	v_pk_fma_f32 v[82:83], v[80:81], v[82:83], v[84:85] op_sel_hi:[0,1,1]
	s_nop 0
	v_pk_mul_f32 v[84:85], v[18:19], v[82:83] op_sel:[1,1] op_sel_hi:[0,1] neg_lo:[0,1]
	v_pk_fma_f32 v[18:19], v[18:19], v[82:83], v[84:85] op_sel_hi:[1,0,1]
	v_pk_mul_f32 v[84:85], v[24:25], v[82:83] op_sel:[0,1] op_sel_hi:[0,0] neg_hi:[1,0]
	v_pk_fma_f32 v[82:83], v[80:81], v[82:83], v[84:85] op_sel_hi:[0,1,1]
	s_nop 0
	v_pk_mul_f32 v[84:85], v[20:21], v[82:83] op_sel:[1,1] op_sel_hi:[0,1] neg_lo:[0,1]
	v_pk_fma_f32 v[20:21], v[20:21], v[82:83], v[84:85] op_sel_hi:[1,0,1]
	v_pk_mul_f32 v[84:85], v[24:25], v[82:83] op_sel:[0,1] op_sel_hi:[0,0] neg_hi:[1,0]
	v_pk_fma_f32 v[82:83], v[80:81], v[82:83], v[84:85] op_sel_hi:[0,1,1]
	s_nop 0
	v_pk_mul_f32 v[84:85], v[22:23], v[82:83] op_sel:[1,1] op_sel_hi:[0,1] neg_lo:[0,1]
	v_pk_fma_f32 v[22:23], v[22:23], v[82:83], v[84:85] op_sel_hi:[1,0,1]
	v_pk_mul_f32 v[84:85], v[24:25], v[82:83] op_sel:[0,1] op_sel_hi:[0,0] neg_hi:[1,0]
	v_pk_fma_f32 v[82:83], v[80:81], v[82:83], v[84:85] op_sel_hi:[0,1,1]
	s_nop 0
	v_pk_mul_f32 v[84:85], v[26:27], v[82:83] op_sel:[1,1] op_sel_hi:[0,1] neg_lo:[0,1]
	v_pk_fma_f32 v[26:27], v[26:27], v[82:83], v[84:85] op_sel_hi:[1,0,1]
	v_pk_mul_f32 v[84:85], v[24:25], v[82:83] op_sel:[0,1] op_sel_hi:[0,0] neg_hi:[1,0]
	v_pk_fma_f32 v[82:83], v[80:81], v[82:83], v[84:85] op_sel_hi:[0,1,1]
	s_nop 0
	v_pk_mul_f32 v[84:85], v[28:29], v[82:83] op_sel:[1,1] op_sel_hi:[0,1] neg_lo:[0,1]
	v_pk_fma_f32 v[28:29], v[28:29], v[82:83], v[84:85] op_sel_hi:[1,0,1]
	v_pk_mul_f32 v[84:85], v[24:25], v[82:83] op_sel:[0,1] op_sel_hi:[0,0] neg_hi:[1,0]
	v_pk_fma_f32 v[82:83], v[80:81], v[82:83], v[84:85] op_sel_hi:[0,1,1]
	v_pk_mul_f32 v[24:25], v[24:25], v[82:83] op_sel:[0,1] op_sel_hi:[0,0] neg_hi:[1,0]
	v_pk_fma_f32 v[24:25], v[80:81], v[82:83], v[24:25] op_sel_hi:[0,1,1]
	v_pk_mul_f32 v[80:81], v[78:79], v[24:25] op_sel:[1,1] op_sel_hi:[0,1] neg_lo:[0,1]
	v_pk_fma_f32 v[24:25], v[78:79], v[24:25], v[80:81] op_sel_hi:[1,0,1]
	v_pk_add_f32 v[78:79], v[0:1], v[16:17]
	v_pk_add_f32 v[0:1], v[0:1], v[16:17] neg_lo:[0,1] neg_hi:[0,1]
	v_pk_add_f32 v[16:17], v[2:3], v[18:19]
	v_pk_add_f32 v[2:3], v[2:3], v[18:19] neg_lo:[0,1] neg_hi:[0,1]
	v_pk_mul_f32 v[84:85], v[30:31], v[82:83] op_sel:[1,1] op_sel_hi:[0,1] neg_lo:[0,1]
	v_pk_mul_f32 v[18:19], v[2:3], s[18:19]
	v_pk_fma_f32 v[30:31], v[30:31], v[82:83], v[84:85] op_sel_hi:[1,0,1]
	v_pk_fma_f32 v[2:3], v[2:3], s[30:31], v[18:19] op_sel:[0,0,1] op_sel_hi:[1,0,0]
	v_pk_add_f32 v[18:19], v[4:5], v[20:21]
	v_pk_add_f32 v[4:5], v[4:5], v[20:21] neg_lo:[0,1] neg_hi:[0,1]
	v_mov_b32_e32 v81, 0
	v_pk_mul_f32 v[20:21], v[4:5], s[10:11]
	v_mov_b32_e32 v80, 0
	v_pk_fma_f32 v[4:5], v[4:5], s[14:15], v[20:21] op_sel:[0,0,1] op_sel_hi:[1,0,0]
	v_pk_add_f32 v[20:21], v[6:7], v[22:23]
	v_pk_add_f32 v[6:7], v[6:7], v[22:23] neg_lo:[0,1] neg_hi:[0,1]
	s_nop 0
	v_pk_mul_f32 v[22:23], v[6:7], s[34:35]
	s_nop 0
	v_pk_fma_f32 v[6:7], v[6:7], s[0:1], v[22:23] op_sel:[0,0,1] op_sel_hi:[1,0,0]
	v_pk_add_f32 v[22:23], v[8:9], v[26:27]
	v_pk_add_f32 v[8:9], v[8:9], v[26:27] neg_lo:[0,1] neg_hi:[0,1]
	v_pk_add_f32 v[26:27], v[10:11], v[28:29]
	v_pk_add_f32 v[10:11], v[10:11], v[28:29] neg_lo:[0,1] neg_hi:[0,1]
	s_nop 0
	v_pk_mul_f32 v[28:29], v[10:11], s[34:35]
	s_nop 0
	v_pk_fma_f32 v[10:11], v[10:11], s[0:1], v[28:29] op_sel:[0,0,1] op_sel_hi:[1,0,0] neg_lo:[1,0,0] neg_hi:[1,0,0]
	v_pk_add_f32 v[28:29], v[12:13], v[30:31]
	v_pk_add_f32 v[12:13], v[12:13], v[30:31] neg_lo:[0,1] neg_hi:[0,1]
	s_lshl_b32 s0, s57, 9
	v_pk_mul_f32 v[30:31], v[12:13], s[10:11]
	s_add_u32 s0, s60, s0
	v_pk_fma_f32 v[12:13], v[12:13], s[14:15], v[30:31] op_sel:[0,0,1] op_sel_hi:[1,0,0] neg_lo:[1,0,0] neg_hi:[1,0,0]
	v_pk_add_f32 v[30:31], v[14:15], v[24:25]
	v_pk_add_f32 v[14:15], v[14:15], v[24:25] neg_lo:[0,1] neg_hi:[0,1]
	s_addc_u32 s1, s61, 0
	v_pk_mul_f32 v[24:25], v[14:15], s[18:19]
	s_add_u32 s0, s0, 0x81b2000
	v_pk_fma_f32 v[14:15], v[14:15], s[30:31], v[24:25] op_sel:[0,0,1] op_sel_hi:[1,0,0] neg_lo:[1,0,0] neg_hi:[1,0,0]
	v_pk_add_f32 v[24:25], v[78:79], v[22:23]
	v_pk_add_f32 v[22:23], v[78:79], v[22:23] neg_lo:[0,1] neg_hi:[0,1]
	v_pk_add_f32 v[78:79], v[16:17], v[26:27]
	v_pk_add_f32 v[16:17], v[16:17], v[26:27] neg_lo:[0,1] neg_hi:[0,1]
	s_addc_u32 s1, s1, 0
	v_pk_mul_f32 v[26:27], v[16:17], s[10:11]
	s_nop 0
	v_pk_fma_f32 v[16:17], v[16:17], s[14:15], v[26:27] op_sel:[0,0,1] op_sel_hi:[1,0,0]
	v_pk_add_f32 v[26:27], v[18:19], v[28:29]
	v_pk_add_f32 v[18:19], v[18:19], v[28:29] neg_lo:[0,1] neg_hi:[0,1]
	v_pk_add_f32 v[28:29], v[20:21], v[30:31]
	v_pk_add_f32 v[20:21], v[20:21], v[30:31] neg_lo:[0,1] neg_hi:[0,1]
	s_nop 0
	v_pk_mul_f32 v[30:31], v[20:21], s[10:11]
	s_nop 0
	v_pk_fma_f32 v[20:21], v[20:21], s[14:15], v[30:31] op_sel:[0,0,1] op_sel_hi:[1,0,0] neg_lo:[1,0,0] neg_hi:[1,0,0]
	v_pk_add_f32 v[30:31], v[0:1], v[8:9] op_sel:[0,1] op_sel_hi:[1,0] neg_hi:[0,1]
	v_pk_add_f32 v[0:1], v[0:1], v[8:9] op_sel:[0,1] op_sel_hi:[1,0] neg_lo:[0,1]
	v_pk_add_f32 v[8:9], v[2:3], v[10:11]
	v_pk_add_f32 v[2:3], v[2:3], v[10:11] neg_lo:[0,1] neg_hi:[0,1]
	s_nop 0
	v_pk_mul_f32 v[10:11], v[2:3], s[10:11]
	s_nop 0
	v_pk_fma_f32 v[2:3], v[2:3], s[14:15], v[10:11] op_sel:[0,0,1] op_sel_hi:[1,0,0]
	v_pk_add_f32 v[10:11], v[4:5], v[12:13]
	v_pk_add_f32 v[4:5], v[4:5], v[12:13] neg_lo:[0,1] neg_hi:[0,1]
	v_pk_add_f32 v[12:13], v[6:7], v[14:15]
	v_pk_add_f32 v[6:7], v[6:7], v[14:15] neg_lo:[0,1] neg_hi:[0,1]
	s_nop 0
	v_pk_mul_f32 v[14:15], v[6:7], s[10:11]
	s_nop 0
	v_pk_fma_f32 v[6:7], v[6:7], s[14:15], v[14:15] op_sel:[0,0,1] op_sel_hi:[1,0,0] neg_lo:[1,0,0] neg_hi:[1,0,0]
	v_pk_add_f32 v[14:15], v[24:25], v[26:27]
	v_pk_add_f32 v[24:25], v[24:25], v[26:27] neg_lo:[0,1] neg_hi:[0,1]
	v_pk_add_f32 v[26:27], v[78:79], v[28:29]
	v_pk_add_f32 v[28:29], v[78:79], v[28:29] neg_lo:[0,1] neg_hi:[0,1]
	v_pk_add_f32 v[78:79], v[22:23], v[18:19] op_sel:[0,1] op_sel_hi:[1,0] neg_hi:[0,1]
	v_pk_add_f32 v[18:19], v[22:23], v[18:19] op_sel:[0,1] op_sel_hi:[1,0] neg_lo:[0,1]
	v_pk_add_f32 v[22:23], v[16:17], v[20:21]
	v_pk_add_f32 v[16:17], v[16:17], v[20:21] neg_lo:[0,1] neg_hi:[0,1]
	v_pk_add_f32 v[20:21], v[30:31], v[10:11]
	v_pk_add_f32 v[10:11], v[30:31], v[10:11] neg_lo:[0,1] neg_hi:[0,1]
	v_pk_add_f32 v[30:31], v[8:9], v[12:13]
	v_pk_add_f32 v[8:9], v[8:9], v[12:13] neg_lo:[0,1] neg_hi:[0,1]
	v_pk_add_f32 v[12:13], v[0:1], v[4:5] op_sel:[0,1] op_sel_hi:[1,0] neg_hi:[0,1]
	v_pk_add_f32 v[0:1], v[0:1], v[4:5] op_sel:[0,1] op_sel_hi:[1,0] neg_lo:[0,1]
	v_pk_add_f32 v[4:5], v[2:3], v[6:7]
	v_pk_add_f32 v[2:3], v[2:3], v[6:7] neg_lo:[0,1] neg_hi:[0,1]
	s_nop 0
	v_pk_mul_f32 v[2:3], v[2:3], s[22:23]
	v_pk_add_f32 v[6:7], v[14:15], v[26:27]
	v_pk_add_f32 v[14:15], v[14:15], v[26:27] neg_lo:[0,1] neg_hi:[0,1]
	v_pk_add_f32 v[26:27], v[24:25], v[28:29] op_sel:[0,1] op_sel_hi:[1,0] neg_hi:[0,1]
	v_pk_add_f32 v[24:25], v[24:25], v[28:29] op_sel:[0,1] op_sel_hi:[1,0] neg_lo:[0,1]
	v_pk_add_f32 v[28:29], v[78:79], v[22:23]
	v_pk_add_f32 v[22:23], v[78:79], v[22:23] neg_lo:[0,1] neg_hi:[0,1]
	v_pk_add_f32 v[78:79], v[18:19], v[16:17] op_sel:[0,1] op_sel_hi:[1,0] neg_hi:[0,1]
	v_pk_add_f32 v[16:17], v[18:19], v[16:17] op_sel:[0,1] op_sel_hi:[1,0] neg_lo:[0,1]
	v_pk_add_f32 v[18:19], v[20:21], v[30:31]
	v_pk_add_f32 v[20:21], v[20:21], v[30:31] neg_lo:[0,1] neg_hi:[0,1]
	v_pk_add_f32 v[30:31], v[10:11], v[8:9] op_sel:[0,1] op_sel_hi:[1,0] neg_hi:[0,1]
	v_pk_add_f32 v[8:9], v[10:11], v[8:9] op_sel:[0,1] op_sel_hi:[1,0] neg_lo:[0,1]
	v_pk_add_f32 v[10:11], v[12:13], v[4:5]
	v_pk_add_f32 v[4:5], v[12:13], v[4:5] neg_lo:[0,1] neg_hi:[0,1]
	v_pk_add_f32 v[12:13], v[0:1], v[2:3] op_sel:[0,1] op_sel_hi:[1,0]
	v_pk_add_f32 v[0:1], v[0:1], v[2:3] op_sel:[0,1] op_sel_hi:[1,0] neg_lo:[0,1] neg_hi:[0,1]
	v_lshlrev_b32_e32 v2, 4, v39
	v_and_or_b32 v2, v2, s15, v86
	v_ashrrev_i32_e32 v3, 4, v2
	v_lshlrev_b32_e32 v3, 3, v3
	v_lshlrev_b32_e32 v2, 3, v2
	v_add3_u32 v2, s26, v3, v2
	v_and_b32_e32 v39, 31, v32
	ds_write_b64 v2, v[6:7]
	ds_write_b64 v2, v[14:15] offset:34816
	ds_write_b64 v2, v[26:27] offset:17408
	ds_write_b64 v2, v[24:25] offset:52224
	ds_write_b64 v2, v[28:29] offset:8704
	ds_write_b64 v2, v[22:23] offset:43520
	ds_write_b64 v2, v[78:79] offset:26112
	ds_write_b64 v2, v[16:17] offset:60928
	ds_write_b64 v2, v[18:19] offset:4352
	ds_write_b64 v2, v[20:21] offset:39168
	ds_write_b64 v2, v[30:31] offset:21760
	ds_write_b64 v2, v[8:9] offset:56576
	ds_write_b64 v2, v[10:11] offset:13056
	ds_write_b64 v2, v[4:5] offset:47872
	ds_write_b64 v2, v[12:13] offset:30464
	ds_write_b64 v2, v[0:1] offset:65280
	v_lshlrev_b32_e32 v2, 4, v39
	v_ashrrev_i32_e32 v3, 5, v32
	v_mov_b64_e32 v[0:1], s[0:1]
	s_mov_b32 s0, 0x180000
	v_cmp_gt_u32_e64 s[42:43], 16, v39
	v_mad_i64_i32 v[78:79], s[0:1], v3, s0, v[0:1]
	v_mov_b32_e32 v9, 0
	v_lshlrev_b32_e32 v172, 1, v2
	v_mov_b32_e32 v8, 0
	v_mov_b32_e32 v11, 0
	v_mov_b32_e32 v10, 0
	v_mov_b32_e32 v13, 0
	v_mov_b32_e32 v12, 0
	v_mov_b32_e32 v15, 0
	v_mov_b32_e32 v14, 0
	v_mov_b32_e32 v17, 0
	v_mov_b32_e32 v16, 0
	v_mov_b32_e32 v21, 0
	v_mov_b32_e32 v20, 0
	v_mov_b32_e32 v23, 0
	v_mov_b32_e32 v22, 0
	v_mov_b32_e32 v25, 0
	v_mov_b32_e32 v24, 0
	v_mov_b32_e32 v1, 0
	v_mov_b32_e32 v0, 0
	v_mov_b32_e32 v3, 0
	v_mov_b32_e32 v2, 0
	v_mov_b32_e32 v5, 0
	v_mov_b32_e32 v4, 0
	v_mov_b32_e32 v7, 0
	v_mov_b32_e32 v6, 0
	v_mov_b32_e32 v27, 0
	v_mov_b32_e32 v26, 0
	v_mov_b32_e32 v29, 0
	v_mov_b32_e32 v28, 0
	v_mov_b32_e32 v31, 0
	v_mov_b32_e32 v30, 0
	s_waitcnt lgkmcnt(0)
	s_barrier
	s_and_saveexec_b64 s[0:1], s[42:43]
	s_cbranch_execz .LBB0_428
	v_lshl_add_u64 v[0:1], v[78:79], 0, v[172:173]
	global_load_dwordx4 v[8:11], v[0:1], off offset:16
	global_load_dwordx4 v[12:15], v[0:1], off
	v_cmp_ne_u32_e64 s[44:45], 0, v39
	v_mov_b32_e32 v27, 0
	v_mov_b32_e32 v16, 0
	s_and_saveexec_b64 s[4:5], s[44:45]
	s_cbranch_execz .LBB0_421
	global_load_ushort v2, v[0:1], off offset:-2
	s_waitcnt vmcnt(0)
	v_lshlrev_b32_e32 v16, 16, v2

.LBB0_428:
	s_or_b64 exec, exec, s[0:1]
	s_movk_i32 s0, 0x88
	v_mul_lo_u32 v18, v32, s0
	v_add_u32_e32 v152, 0, v18
	v_cndmask_b32_e64 v95, 0, v80, s[42:43]
	v_cndmask_b32_e64 v94, 0, v24, s[42:43]
	v_cndmask_b32_e64 v89, 0, v81, s[42:43]
	v_cndmask_b32_e64 v88, 0, v25, s[42:43]
	v_cndmask_b32_e64 v113, 0, v30, s[42:43]
	v_cndmask_b32_e64 v112, 0, v22, s[42:43]
	v_cndmask_b32_e64 v105, 0, v31, s[42:43]
	v_cndmask_b32_e64 v104, 0, v23, s[42:43]
	v_cndmask_b32_e64 v97, 0, v28, s[42:43]
	v_cndmask_b32_e64 v96, 0, v20, s[42:43]
	v_cndmask_b32_e64 v91, 0, v29, s[42:43]
	v_cndmask_b32_e64 v90, 0, v21, s[42:43]
	v_cndmask_b32_e64 v115, 0, v26, s[42:43]
	v_cndmask_b32_e64 v114, 0, v16, s[42:43]
	v_cndmask_b32_e64 v107, 0, v27, s[42:43]
	v_cndmask_b32_e64 v106, 0, v17, s[42:43]
	v_cndmask_b32_e64 v99, 0, v6, s[42:43]
	v_cndmask_b32_e64 v98, 0, v14, s[42:43]
	v_cndmask_b32_e64 v93, 0, v7, s[42:43]
	v_cndmask_b32_e64 v92, 0, v15, s[42:43]
	v_cndmask_b32_e64 v117, 0, v4, s[42:43]
	v_cndmask_b32_e64 v116, 0, v12, s[42:43]
	v_cndmask_b32_e64 v109, 0, v5, s[42:43]
	v_cndmask_b32_e64 v108, 0, v13, s[42:43]
	v_cndmask_b32_e64 v101, 0, v2, s[42:43]
	v_cndmask_b32_e64 v100, 0, v10, s[42:43]
	v_cndmask_b32_e64 v87, 0, v3, s[42:43]
	v_cndmask_b32_e64 v86, 0, v11, s[42:43]
	v_cndmask_b32_e64 v85, 0, v0, s[42:43]
	v_cndmask_b32_e64 v84, 0, v8, s[42:43]
	v_cndmask_b32_e64 v83, 0, v1, s[42:43]
	v_cndmask_b32_e64 v82, 0, v9, s[42:43]
	v_add3_u32 v153, 0, v41, v157
	ds_write2_b64 v152, v[94:95], v[88:89] offset1:1
	ds_write2_b64 v152, v[112:113], v[104:105] offset0:2 offset1:3
	ds_write2_b64 v152, v[96:97], v[90:91] offset0:4 offset1:5
	ds_write2_b64 v152, v[114:115], v[106:107] offset0:6 offset1:7
	ds_write2_b64 v152, v[98:99], v[92:93] offset0:8 offset1:9
	ds_write2_b64 v152, v[116:117], v[108:109] offset0:10 offset1:11
	ds_write2_b64 v152, v[100:101], v[86:87] offset0:12 offset1:13
	ds_write2_b64 v152, v[84:85], v[82:83] offset0:14 offset1:15
	s_waitcnt lgkmcnt(0)
	s_barrier
	s_and_saveexec_b64 s[0:1], s[40:41]
	s_cbranch_execz .LBB0_430
	v_add_u32_e32 v142, 0x10780, v153
	ds_read_b64 v[0:1], v153
	ds_read_b64 v[2:3], v153 offset:2176
	ds_read_b64 v[4:5], v153 offset:4352
	ds_read_b64 v[6:7], v153 offset:6528
	ds_read_b64 v[8:9], v153 offset:8704
	ds_read_b64 v[10:11], v153 offset:10880
	ds_read_b64 v[12:13], v153 offset:13056
	ds_read_b64 v[14:15], v153 offset:15232
	ds_read_b64 v[16:17], v153 offset:17408
	ds_read_b64 v[18:19], v153 offset:19584
	ds_read_b64 v[20:21], v153 offset:21760
	ds_read_b64 v[22:23], v153 offset:23936
	ds_read_b64 v[24:25], v153 offset:26112
	ds_read_b64 v[26:27], v153 offset:28288
	ds_read_b64 v[28:29], v153 offset:30464
	ds_read_b64 v[30:31], v153 offset:32640
	ds_read_b64 v[80:81], v153 offset:34816
	ds_read_b64 v[102:103], v153 offset:41344
	ds_read_b64 v[110:111], v153 offset:43520
	ds_read_b64 v[118:119], v153 offset:45696
	ds_read_b64 v[120:121], v153 offset:47872
	ds_read_b64 v[122:123], v153 offset:50048
	ds_read_b64 v[124:125], v153 offset:52224
	ds_read_b64 v[126:127], v153 offset:54400
	ds_read_b64 v[128:129], v153 offset:56576
	ds_read_b64 v[130:131], v153 offset:58752
	ds_read_b64 v[132:133], v153 offset:60928
	ds_read_b64 v[134:135], v153 offset:63104
	ds_read_b64 v[136:137], v153 offset:65280
	ds_read_b64 v[138:139], v153 offset:36992
	ds_read_b64 v[140:141], v153 offset:39168
	ds_read_b64 v[142:143], v142
	s_waitcnt lgkmcnt(14)
	v_pk_add_f32 v[144:145], v[0:1], v[80:81]
	v_pk_add_f32 v[0:1], v[0:1], v[80:81] neg_lo:[0,1] neg_hi:[0,1]
	s_waitcnt lgkmcnt(2)
	v_pk_add_f32 v[80:81], v[2:3], v[138:139]
	v_pk_add_f32 v[2:3], v[2:3], v[138:139] neg_lo:[0,1] neg_hi:[0,1]
	s_mov_b32 s11, s14
	v_pk_mul_f32 v[138:139], v[2:3], s[16:17]
	s_mov_b32 s13, s86
	v_pk_fma_f32 v[2:3], v[2:3], s[6:7], v[138:139] op_sel:[0,0,1] op_sel_hi:[1,0,0]
	s_waitcnt lgkmcnt(1)
	v_pk_add_f32 v[138:139], v[4:5], v[140:141]
	v_pk_add_f32 v[4:5], v[4:5], v[140:141] neg_lo:[0,1] neg_hi:[0,1]
	s_mov_b32 s4, s21
	v_pk_mul_f32 v[140:141], v[4:5], s[18:19]
	s_mov_b32 s35, s30
	v_pk_fma_f32 v[4:5], v[4:5], s[30:31], v[140:141] op_sel:[0,0,1] op_sel_hi:[1,0,0]
	v_pk_add_f32 v[140:141], v[6:7], v[102:103]
	v_pk_add_f32 v[6:7], v[6:7], v[102:103] neg_lo:[0,1] neg_hi:[0,1]
	s_mov_b32 s8, s19
	v_pk_mul_f32 v[102:103], v[6:7], s[20:21]
	s_mov_b32 s77, s6
	v_pk_fma_f32 v[6:7], v[6:7], s[86:87], v[102:103] op_sel:[0,0,1] op_sel_hi:[1,0,0]
	v_pk_add_f32 v[102:103], v[8:9], v[110:111]
	v_pk_add_f32 v[8:9], v[8:9], v[110:111] neg_lo:[0,1] neg_hi:[0,1]
	s_mov_b32 s28, s17
	v_pk_mul_f32 v[110:111], v[8:9], s[10:11]
	s_nop 0
	v_pk_fma_f32 v[8:9], v[8:9], s[14:15], v[110:111] op_sel:[0,0,1] op_sel_hi:[1,0,0]
	v_pk_add_f32 v[110:111], v[10:11], v[118:119]
	v_pk_add_f32 v[10:11], v[10:11], v[118:119] neg_lo:[0,1] neg_hi:[0,1]
	s_nop 0
	v_pk_mul_f32 v[118:119], v[10:11], s[12:13]
	s_nop 0
	v_pk_fma_f32 v[10:11], v[10:11], s[4:5], v[118:119] op_sel:[0,0,1] op_sel_hi:[1,0,0]
	v_pk_add_f32 v[118:119], v[12:13], v[120:121]
	v_pk_add_f32 v[12:13], v[12:13], v[120:121] neg_lo:[0,1] neg_hi:[0,1]
	s_nop 0
	v_pk_mul_f32 v[120:121], v[12:13], s[34:35]
	s_nop 0
	v_pk_fma_f32 v[12:13], v[12:13], s[8:9], v[120:121] op_sel:[0,0,1] op_sel_hi:[1,0,0]
	v_pk_add_f32 v[120:121], v[14:15], v[122:123]
	v_pk_add_f32 v[14:15], v[14:15], v[122:123] neg_lo:[0,1] neg_hi:[0,1]
	s_nop 0
	v_pk_mul_f32 v[122:123], v[14:15], s[76:77]
	s_nop 0
	v_pk_fma_f32 v[14:15], v[14:15], s[28:29], v[122:123] op_sel:[0,0,1] op_sel_hi:[1,0,0]
	v_pk_add_f32 v[122:123], v[16:17], v[124:125]
	v_pk_add_f32 v[16:17], v[16:17], v[124:125] neg_lo:[0,1] neg_hi:[0,1]
	v_pk_add_f32 v[124:125], v[18:19], v[126:127]
	v_pk_add_f32 v[18:19], v[18:19], v[126:127] neg_lo:[0,1] neg_hi:[0,1]
	s_nop 0
	v_pk_mul_f32 v[126:127], v[18:19], s[76:77]
	s_nop 0
	v_pk_fma_f32 v[18:19], v[18:19], s[28:29], v[126:127] op_sel:[0,0,1] op_sel_hi:[1,0,0] neg_lo:[1,0,0] neg_hi:[1,0,0]
	v_pk_add_f32 v[126:127], v[20:21], v[128:129]
	v_pk_add_f32 v[20:21], v[20:21], v[128:129] neg_lo:[0,1] neg_hi:[0,1]
	s_nop 0
	v_pk_mul_f32 v[128:129], v[20:21], s[34:35]
	s_nop 0
	v_pk_fma_f32 v[20:21], v[20:21], s[8:9], v[128:129] op_sel:[0,0,1] op_sel_hi:[1,0,0] neg_lo:[1,0,0] neg_hi:[1,0,0]
	v_pk_add_f32 v[128:129], v[22:23], v[130:131]
	v_pk_add_f32 v[22:23], v[22:23], v[130:131] neg_lo:[0,1] neg_hi:[0,1]
	s_nop 0
	v_pk_mul_f32 v[130:131], v[22:23], s[12:13]
	s_nop 0
	v_pk_fma_f32 v[22:23], v[22:23], s[4:5], v[130:131] op_sel:[0,0,1] op_sel_hi:[1,0,0] neg_lo:[1,0,0] neg_hi:[1,0,0]
	v_pk_add_f32 v[130:131], v[24:25], v[132:133]
	v_pk_add_f32 v[24:25], v[24:25], v[132:133] neg_lo:[0,1] neg_hi:[0,1]
	s_nop 0
	v_pk_mul_f32 v[132:133], v[24:25], s[10:11]
	s_nop 0
	v_pk_fma_f32 v[24:25], v[24:25], s[14:15], v[132:133] op_sel:[0,0,1] op_sel_hi:[1,0,0] neg_lo:[1,0,0] neg_hi:[1,0,0]
	v_pk_add_f32 v[132:133], v[26:27], v[134:135]
	v_pk_add_f32 v[26:27], v[26:27], v[134:135] neg_lo:[0,1] neg_hi:[0,1]
	s_nop 0
	v_pk_mul_f32 v[134:135], v[26:27], s[20:21]
	s_nop 0
	v_pk_fma_f32 v[26:27], v[26:27], s[86:87], v[134:135] op_sel:[0,0,1] op_sel_hi:[1,0,0] neg_lo:[1,0,0] neg_hi:[1,0,0]
	v_pk_add_f32 v[134:135], v[28:29], v[136:137]
	v_pk_add_f32 v[28:29], v[28:29], v[136:137] neg_lo:[0,1] neg_hi:[0,1]
	s_nop 0
	v_pk_mul_f32 v[136:137], v[28:29], s[18:19]
	s_nop 0
	v_pk_fma_f32 v[28:29], v[28:29], s[30:31], v[136:137] op_sel:[0,0,1] op_sel_hi:[1,0,0] neg_lo:[1,0,0] neg_hi:[1,0,0]
	s_waitcnt lgkmcnt(0)
	v_pk_add_f32 v[136:137], v[30:31], v[142:143]
	v_pk_add_f32 v[30:31], v[30:31], v[142:143] neg_lo:[0,1] neg_hi:[0,1]
	s_nop 0
	v_pk_mul_f32 v[142:143], v[30:31], s[16:17]
	s_nop 0
	v_pk_fma_f32 v[30:31], v[30:31], s[6:7], v[142:143] op_sel:[0,0,1] op_sel_hi:[1,0,0] neg_lo:[1,0,0] neg_hi:[1,0,0]
	v_pk_add_f32 v[142:143], v[144:145], v[122:123]
	v_pk_add_f32 v[122:123], v[144:145], v[122:123] neg_lo:[0,1] neg_hi:[0,1]
	v_pk_add_f32 v[144:145], v[80:81], v[124:125]
	v_pk_add_f32 v[80:81], v[80:81], v[124:125] neg_lo:[0,1] neg_hi:[0,1]
	s_nop 0
	v_pk_mul_f32 v[124:125], v[80:81], s[18:19]
	s_nop 0
	v_pk_fma_f32 v[80:81], v[80:81], s[30:31], v[124:125] op_sel:[0,0,1] op_sel_hi:[1,0,0]
	v_pk_add_f32 v[124:125], v[138:139], v[126:127]
	v_pk_add_f32 v[126:127], v[138:139], v[126:127] neg_lo:[0,1] neg_hi:[0,1]
	s_nop 0
	v_pk_mul_f32 v[138:139], v[126:127], s[10:11]
	s_nop 0
	v_pk_fma_f32 v[126:127], v[126:127], s[14:15], v[138:139] op_sel:[0,0,1] op_sel_hi:[1,0,0]
	v_pk_add_f32 v[138:139], v[140:141], v[128:129]
	v_pk_add_f32 v[128:129], v[140:141], v[128:129] neg_lo:[0,1] neg_hi:[0,1]
	s_nop 0
	v_pk_mul_f32 v[140:141], v[128:129], s[34:35]
	s_nop 0
	v_pk_fma_f32 v[128:129], v[128:129], s[8:9], v[140:141] op_sel:[0,0,1] op_sel_hi:[1,0,0]
	v_pk_add_f32 v[140:141], v[102:103], v[130:131]
	v_pk_add_f32 v[102:103], v[102:103], v[130:131] neg_lo:[0,1] neg_hi:[0,1]
	v_pk_add_f32 v[130:131], v[110:111], v[132:133]
	v_pk_add_f32 v[110:111], v[110:111], v[132:133] neg_lo:[0,1] neg_hi:[0,1]
	s_nop 0
	v_pk_mul_f32 v[132:133], v[110:111], s[34:35]
	s_nop 0
	v_pk_fma_f32 v[110:111], v[110:111], s[8:9], v[132:133] op_sel:[0,0,1] op_sel_hi:[1,0,0] neg_lo:[1,0,0] neg_hi:[1,0,0]
	v_pk_add_f32 v[132:133], v[118:119], v[134:135]
	v_pk_add_f32 v[118:119], v[118:119], v[134:135] neg_lo:[0,1] neg_hi:[0,1]
	s_nop 0
	v_pk_mul_f32 v[134:135], v[118:119], s[10:11]
	s_nop 0
	v_pk_fma_f32 v[118:119], v[118:119], s[14:15], v[134:135] op_sel:[0,0,1] op_sel_hi:[1,0,0] neg_lo:[1,0,0] neg_hi:[1,0,0]
	v_pk_add_f32 v[134:135], v[120:121], v[136:137]
	v_pk_add_f32 v[120:121], v[120:121], v[136:137] neg_lo:[0,1] neg_hi:[0,1]
	s_nop 0
	v_pk_mul_f32 v[136:137], v[120:121], s[18:19]
	s_nop 0
	v_pk_fma_f32 v[120:121], v[120:121], s[30:31], v[136:137] op_sel:[0,0,1] op_sel_hi:[1,0,0] neg_lo:[1,0,0] neg_hi:[1,0,0]
	v_pk_add_f32 v[136:137], v[0:1], v[16:17] op_sel:[0,1] op_sel_hi:[1,0] neg_hi:[0,1]
	v_pk_add_f32 v[0:1], v[0:1], v[16:17] op_sel:[0,1] op_sel_hi:[1,0] neg_lo:[0,1]
	v_pk_add_f32 v[16:17], v[2:3], v[18:19]
	v_pk_add_f32 v[2:3], v[2:3], v[18:19] neg_lo:[0,1] neg_hi:[0,1]
	s_nop 0
	v_pk_mul_f32 v[18:19], v[2:3], s[18:19]
	s_nop 0
	v_pk_fma_f32 v[2:3], v[2:3], s[30:31], v[18:19] op_sel:[0,0,1] op_sel_hi:[1,0,0]
	v_pk_add_f32 v[18:19], v[4:5], v[20:21]
	v_pk_add_f32 v[4:5], v[4:5], v[20:21] neg_lo:[0,1] neg_hi:[0,1]
	s_nop 0
	v_pk_mul_f32 v[20:21], v[4:5], s[10:11]
	s_nop 0
	v_pk_fma_f32 v[4:5], v[4:5], s[14:15], v[20:21] op_sel:[0,0,1] op_sel_hi:[1,0,0]
	v_pk_add_f32 v[20:21], v[6:7], v[22:23]
	v_pk_add_f32 v[6:7], v[6:7], v[22:23] neg_lo:[0,1] neg_hi:[0,1]
	s_nop 0
	v_pk_mul_f32 v[22:23], v[6:7], s[34:35]
	s_nop 0
	v_pk_fma_f32 v[6:7], v[6:7], s[8:9], v[22:23] op_sel:[0,0,1] op_sel_hi:[1,0,0]
	v_pk_add_f32 v[22:23], v[8:9], v[24:25]
	v_pk_add_f32 v[8:9], v[8:9], v[24:25] neg_lo:[0,1] neg_hi:[0,1]
	v_pk_add_f32 v[24:25], v[10:11], v[26:27]
	v_pk_add_f32 v[10:11], v[10:11], v[26:27] neg_lo:[0,1] neg_hi:[0,1]
	s_nop 0
	v_pk_mul_f32 v[26:27], v[10:11], s[34:35]
	s_nop 0
	v_pk_fma_f32 v[10:11], v[10:11], s[8:9], v[26:27] op_sel:[0,0,1] op_sel_hi:[1,0,0] neg_lo:[1,0,0] neg_hi:[1,0,0]
	v_pk_add_f32 v[26:27], v[12:13], v[28:29]
	v_pk_add_f32 v[12:13], v[12:13], v[28:29] neg_lo:[0,1] neg_hi:[0,1]
	s_nop 0
	v_pk_mul_f32 v[28:29], v[12:13], s[10:11]
	s_nop 0
	v_pk_fma_f32 v[12:13], v[12:13], s[14:15], v[28:29] op_sel:[0,0,1] op_sel_hi:[1,0,0] neg_lo:[1,0,0] neg_hi:[1,0,0]
	v_pk_add_f32 v[28:29], v[14:15], v[30:31]
	v_pk_add_f32 v[14:15], v[14:15], v[30:31] neg_lo:[0,1] neg_hi:[0,1]
	s_nop 0
	v_pk_mul_f32 v[30:31], v[14:15], s[18:19]
	s_nop 0
	v_pk_fma_f32 v[14:15], v[14:15], s[30:31], v[30:31] op_sel:[0,0,1] op_sel_hi:[1,0,0] neg_lo:[1,0,0] neg_hi:[1,0,0]
	v_pk_add_f32 v[30:31], v[142:143], v[140:141]
	v_pk_add_f32 v[140:141], v[142:143], v[140:141] neg_lo:[0,1] neg_hi:[0,1]
	v_pk_add_f32 v[142:143], v[144:145], v[130:131]
	v_pk_add_f32 v[130:131], v[144:145], v[130:131] neg_lo:[0,1] neg_hi:[0,1]
	s_nop 0
	v_pk_mul_f32 v[144:145], v[130:131], s[10:11]
	s_nop 0
	v_pk_fma_f32 v[130:131], v[130:131], s[14:15], v[144:145] op_sel:[0,0,1] op_sel_hi:[1,0,0]
	v_pk_add_f32 v[144:145], v[124:125], v[132:133]
	v_pk_add_f32 v[124:125], v[124:125], v[132:133] neg_lo:[0,1] neg_hi:[0,1]
	v_pk_add_f32 v[132:133], v[138:139], v[134:135]
	v_pk_add_f32 v[134:135], v[138:139], v[134:135] neg_lo:[0,1] neg_hi:[0,1]
	s_nop 0
	v_pk_mul_f32 v[138:139], v[134:135], s[10:11]
	s_nop 0
	v_pk_fma_f32 v[134:135], v[134:135], s[14:15], v[138:139] op_sel:[0,0,1] op_sel_hi:[1,0,0] neg_lo:[1,0,0] neg_hi:[1,0,0]
	v_pk_add_f32 v[138:139], v[122:123], v[102:103] op_sel:[0,1] op_sel_hi:[1,0] neg_hi:[0,1]
	v_pk_add_f32 v[102:103], v[122:123], v[102:103] op_sel:[0,1] op_sel_hi:[1,0] neg_lo:[0,1]
	v_pk_add_f32 v[122:123], v[80:81], v[110:111]
	v_pk_add_f32 v[80:81], v[80:81], v[110:111] neg_lo:[0,1] neg_hi:[0,1]
	v_pk_add_f32 v[154:155], v[130:131], v[134:135]
	v_pk_mul_f32 v[110:111], v[80:81], s[10:11]
	s_nop 0
	v_pk_fma_f32 v[80:81], v[80:81], s[14:15], v[110:111] op_sel:[0,0,1] op_sel_hi:[1,0,0]
	v_pk_add_f32 v[110:111], v[126:127], v[118:119]
	v_pk_add_f32 v[118:119], v[126:127], v[118:119] neg_lo:[0,1] neg_hi:[0,1]
	v_pk_add_f32 v[126:127], v[128:129], v[120:121]
	v_pk_add_f32 v[120:121], v[128:129], v[120:121] neg_lo:[0,1] neg_hi:[0,1]
	s_nop 0
	v_pk_mul_f32 v[128:129], v[120:121], s[10:11]
	v_pk_add_f32 v[160:161], v[102:103], v[118:119] op_sel:[0,1] op_sel_hi:[1,0] neg_hi:[0,1]
	v_pk_fma_f32 v[120:121], v[120:121], s[14:15], v[128:129] op_sel:[0,0,1] op_sel_hi:[1,0,0] neg_lo:[1,0,0] neg_hi:[1,0,0]
	v_pk_add_f32 v[128:129], v[136:137], v[22:23]
	v_pk_add_f32 v[22:23], v[136:137], v[22:23] neg_lo:[0,1] neg_hi:[0,1]
	v_pk_add_f32 v[136:137], v[16:17], v[24:25]
	v_pk_add_f32 v[16:17], v[16:17], v[24:25] neg_lo:[0,1] neg_hi:[0,1]
	v_pk_add_f32 v[162:163], v[102:103], v[118:119] op_sel:[0,1] op_sel_hi:[1,0] neg_lo:[0,1]
	v_pk_mul_f32 v[24:25], v[16:17], s[10:11]
	v_pk_add_f32 v[102:103], v[80:81], v[120:121]
	v_pk_fma_f32 v[16:17], v[16:17], s[14:15], v[24:25] op_sel:[0,0,1] op_sel_hi:[1,0,0]
	v_pk_add_f32 v[24:25], v[18:19], v[26:27]
	v_pk_add_f32 v[18:19], v[18:19], v[26:27] neg_lo:[0,1] neg_hi:[0,1]
	v_pk_add_f32 v[26:27], v[20:21], v[28:29]
	v_pk_add_f32 v[20:21], v[20:21], v[28:29] neg_lo:[0,1] neg_hi:[0,1]
	s_nop 0
	v_pk_mul_f32 v[28:29], v[20:21], s[10:11]
	v_pk_add_f32 v[80:81], v[80:81], v[120:121] neg_lo:[0,1] neg_hi:[0,1]
	v_pk_fma_f32 v[20:21], v[20:21], s[14:15], v[28:29] op_sel:[0,0,1] op_sel_hi:[1,0,0] neg_lo:[1,0,0] neg_hi:[1,0,0]
	v_pk_add_f32 v[28:29], v[0:1], v[8:9] op_sel:[0,1] op_sel_hi:[1,0] neg_hi:[0,1]
	v_pk_add_f32 v[0:1], v[0:1], v[8:9] op_sel:[0,1] op_sel_hi:[1,0] neg_lo:[0,1]
	v_pk_add_f32 v[8:9], v[2:3], v[10:11]
	v_pk_add_f32 v[2:3], v[2:3], v[10:11] neg_lo:[0,1] neg_hi:[0,1]
	v_pk_add_f32 v[164:165], v[128:129], v[24:25]
	v_pk_mul_f32 v[10:11], v[2:3], s[10:11]
	v_pk_add_f32 v[128:129], v[128:129], v[24:25] neg_lo:[0,1] neg_hi:[0,1]
	v_pk_fma_f32 v[2:3], v[2:3], s[14:15], v[10:11] op_sel:[0,0,1] op_sel_hi:[1,0,0]
	v_pk_add_f32 v[10:11], v[4:5], v[12:13]
	v_pk_add_f32 v[4:5], v[4:5], v[12:13] neg_lo:[0,1] neg_hi:[0,1]
	v_pk_add_f32 v[12:13], v[6:7], v[14:15]
	v_pk_add_f32 v[6:7], v[6:7], v[14:15] neg_lo:[0,1] neg_hi:[0,1]
	s_nop 0
	v_pk_mul_f32 v[14:15], v[6:7], s[10:11]
	v_pk_add_f32 v[24:25], v[136:137], v[26:27] neg_lo:[0,1] neg_hi:[0,1]
	v_pk_fma_f32 v[6:7], v[6:7], s[14:15], v[14:15] op_sel:[0,0,1] op_sel_hi:[1,0,0] neg_lo:[1,0,0] neg_hi:[1,0,0]
	v_pk_add_f32 v[14:15], v[30:31], v[144:145]
	v_pk_add_f32 v[30:31], v[30:31], v[144:145] neg_lo:[0,1] neg_hi:[0,1]
	v_pk_add_f32 v[144:145], v[142:143], v[132:133]
	v_pk_add_f32 v[132:133], v[142:143], v[132:133] neg_lo:[0,1] neg_hi:[0,1]
	v_pk_add_f32 v[142:143], v[140:141], v[124:125] op_sel:[0,1] op_sel_hi:[1,0] neg_hi:[0,1]
	v_pk_add_f32 v[140:141], v[140:141], v[124:125] op_sel:[0,1] op_sel_hi:[1,0] neg_lo:[0,1]
	v_pk_add_f32 v[124:125], v[130:131], v[134:135] neg_lo:[0,1] neg_hi:[0,1]
	v_pk_add_f32 v[134:135], v[138:139], v[110:111]
	v_pk_add_f32 v[110:111], v[138:139], v[110:111] neg_lo:[0,1] neg_hi:[0,1]
	v_pk_add_f32 v[138:139], v[122:123], v[126:127]
	v_pk_add_f32 v[122:123], v[122:123], v[126:127] neg_lo:[0,1] neg_hi:[0,1]
	v_pk_add_f32 v[168:169], v[22:23], v[18:19] op_sel:[0,1] op_sel_hi:[1,0] neg_hi:[0,1]
	v_pk_add_f32 v[170:171], v[22:23], v[18:19] op_sel:[0,1] op_sel_hi:[1,0] neg_lo:[0,1]
	v_pk_add_f32 v[18:19], v[16:17], v[20:21]
	v_pk_add_f32 v[16:17], v[16:17], v[20:21] neg_lo:[0,1] neg_hi:[0,1]
	v_pk_add_f32 v[184:185], v[28:29], v[10:11]
	v_pk_add_f32 v[186:187], v[28:29], v[10:11] neg_lo:[0,1] neg_hi:[0,1]
	v_pk_add_f32 v[10:11], v[8:9], v[12:13]
	v_pk_add_f32 v[8:9], v[8:9], v[12:13] neg_lo:[0,1] neg_hi:[0,1]
	v_pk_add_f32 v[190:191], v[0:1], v[4:5] op_sel:[0,1] op_sel_hi:[1,0] neg_hi:[0,1]
	v_pk_add_f32 v[192:193], v[0:1], v[4:5] op_sel:[0,1] op_sel_hi:[1,0] neg_lo:[0,1]
	v_pk_add_f32 v[0:1], v[2:3], v[6:7] neg_lo:[0,1] neg_hi:[0,1]
	v_pk_mul_f32 v[130:131], v[124:125], s[22:23]
	v_pk_mul_f32 v[158:159], v[122:123], s[22:23]
	v_pk_add_f32 v[166:167], v[136:137], v[26:27]
	v_pk_mul_f32 v[136:137], v[24:25], s[22:23]
	v_pk_mul_f32 v[182:183], v[16:17], s[22:23]
	v_pk_mul_f32 v[188:189], v[8:9], s[22:23]
	v_pk_add_f32 v[194:195], v[2:3], v[6:7]
	v_pk_mul_f32 v[196:197], v[0:1], s[22:23]
	v_pk_add_f32 v[28:29], v[14:15], v[144:145]
	v_pk_add_f32 v[126:127], v[14:15], v[144:145] neg_lo:[0,1] neg_hi:[0,1]
	v_pk_add_f32 v[24:25], v[30:31], v[132:133] op_sel:[0,1] op_sel_hi:[1,0] neg_hi:[0,1]
	v_pk_add_f32 v[124:125], v[30:31], v[132:133] op_sel:[0,1] op_sel_hi:[1,0] neg_lo:[0,1]
	v_pk_add_f32 v[20:21], v[142:143], v[154:155]
	v_pk_add_f32 v[122:123], v[142:143], v[154:155] neg_lo:[0,1] neg_hi:[0,1]
	v_pk_add_f32 v[16:17], v[140:141], v[130:131] op_sel:[0,1] op_sel_hi:[1,0]
	v_pk_add_f32 v[120:121], v[140:141], v[130:131] op_sel:[0,1] op_sel_hi:[1,0] neg_lo:[0,1] neg_hi:[0,1]
	v_pk_add_f32 v[12:13], v[134:135], v[138:139]
	v_pk_add_f32 v[118:119], v[134:135], v[138:139] neg_lo:[0,1] neg_hi:[0,1]
	v_pk_add_f32 v[8:9], v[110:111], v[158:159] op_sel:[0,1] op_sel_hi:[1,0]
	v_pk_add_f32 v[110:111], v[110:111], v[158:159] op_sel:[0,1] op_sel_hi:[1,0] neg_lo:[0,1] neg_hi:[0,1]
	v_pk_add_f32 v[4:5], v[160:161], v[102:103]
	v_pk_add_f32 v[102:103], v[160:161], v[102:103] neg_lo:[0,1] neg_hi:[0,1]
	v_pk_add_f32 v[0:1], v[162:163], v[80:81] op_sel:[0,1] op_sel_hi:[1,0] neg_hi:[0,1]
	v_pk_add_f32 v[80:81], v[162:163], v[80:81] op_sel:[0,1] op_sel_hi:[1,0] neg_lo:[0,1]
	v_pk_add_f32 v[30:31], v[164:165], v[166:167]
	v_pk_add_f32 v[142:143], v[164:165], v[166:167] neg_lo:[0,1] neg_hi:[0,1]
	v_pk_add_f32 v[26:27], v[128:129], v[136:137] op_sel:[0,1] op_sel_hi:[1,0]
	v_pk_add_f32 v[140:141], v[128:129], v[136:137] op_sel:[0,1] op_sel_hi:[1,0] neg_lo:[0,1] neg_hi:[0,1]
	v_pk_add_f32 v[22:23], v[168:169], v[18:19]
	v_pk_add_f32 v[138:139], v[168:169], v[18:19] neg_lo:[0,1] neg_hi:[0,1]
	v_pk_add_f32 v[18:19], v[170:171], v[182:183] op_sel:[0,1] op_sel_hi:[1,0]
	v_pk_add_f32 v[136:137], v[170:171], v[182:183] op_sel:[0,1] op_sel_hi:[1,0] neg_lo:[0,1] neg_hi:[0,1]
	v_pk_add_f32 v[14:15], v[184:185], v[10:11]
	v_pk_add_f32 v[134:135], v[184:185], v[10:11] neg_lo:[0,1] neg_hi:[0,1]
	v_pk_add_f32 v[10:11], v[186:187], v[188:189] op_sel:[0,1] op_sel_hi:[1,0]
	v_pk_add_f32 v[132:133], v[186:187], v[188:189] op_sel:[0,1] op_sel_hi:[1,0] neg_lo:[0,1] neg_hi:[0,1]
	v_pk_add_f32 v[6:7], v[190:191], v[194:195]
	v_pk_add_f32 v[130:131], v[190:191], v[194:195] neg_lo:[0,1] neg_hi:[0,1]
	v_pk_add_f32 v[2:3], v[192:193], v[196:197] op_sel:[0,1] op_sel_hi:[1,0]
	v_pk_add_f32 v[128:129], v[192:193], v[196:197] op_sel:[0,1] op_sel_hi:[1,0] neg_lo:[0,1] neg_hi:[0,1]

.LBB0_432:
	s_or_b64 exec, exec, s[0:1]
	v_mov_b32_e32 v120, v32
	s_waitcnt lgkmcnt(0)
	s_barrier
	s_mov_b32 s11, s14
	v_and_b32_e32 v121, 31, v120
	v_cvt_f32_ubyte0_e32 v24, v121
	v_mul_f32_e32 v102, 0x3b000000, v24
	v_sin_f32_e32 v24, v102
	v_ashrrev_i32_e32 v0, 4, v120
	v_lshlrev_b32_e32 v0, 3, v0
	v_lshlrev_b32_e32 v1, 3, v120
	v_cos_f32_e32 v102, v102
	v_add3_u32 v25, 0, v0, v1
	ds_read_b64 v[0:1], v25
	ds_read_b64 v[2:3], v25 offset:4352
	ds_read_b64 v[4:5], v25 offset:8704
	ds_read_b64 v[6:7], v25 offset:13056
	ds_read_b64 v[8:9], v25 offset:17408
	ds_read_b64 v[10:11], v25 offset:21760
	ds_read_b64 v[12:13], v25 offset:26112
	ds_read_b64 v[14:15], v25 offset:30464
	ds_read_b64 v[16:17], v25 offset:34816
	ds_read_b64 v[18:19], v25 offset:39168
	ds_read_b64 v[20:21], v25 offset:43520
	ds_read_b64 v[22:23], v25 offset:47872
	v_xor_b32_e32 v103, 0x80000000, v24
	s_waitcnt lgkmcnt(10)
	v_pk_mul_f32 v[110:111], v[2:3], v[24:25] op_sel:[1,0] op_sel_hi:[0,0] neg_hi:[0,1]
	v_pk_fma_f32 v[2:3], v[2:3], v[102:103], v[110:111] op_sel_hi:[1,0,1]
	v_pk_mul_f32 v[110:111], v[24:25], v[102:103] op_sel:[0,1] op_sel_hi:[0,0] neg_hi:[1,0]
	v_pk_fma_f32 v[110:111], v[102:103], v[102:103], v[110:111] op_sel_hi:[0,1,1]
	ds_read_b64 v[26:27], v25 offset:52224
	ds_read_b64 v[28:29], v25 offset:56576
	ds_read_b64 v[30:31], v25 offset:60928
	ds_read_b64 v[80:81], v25 offset:65280
	s_waitcnt lgkmcnt(13)
	v_pk_mul_f32 v[118:119], v[4:5], v[110:111] op_sel:[1,1] op_sel_hi:[0,1] neg_lo:[0,1]
	v_pk_fma_f32 v[4:5], v[4:5], v[110:111], v[118:119] op_sel_hi:[1,0,1]
	v_pk_mul_f32 v[118:119], v[24:25], v[110:111] op_sel:[0,1] op_sel_hi:[0,0] neg_hi:[1,0]
	v_pk_fma_f32 v[110:111], v[102:103], v[110:111], v[118:119] op_sel_hi:[0,1,1]
	s_mov_b32 s35, s30
	s_waitcnt lgkmcnt(12)
	v_pk_mul_f32 v[118:119], v[6:7], v[110:111] op_sel:[1,1] op_sel_hi:[0,1] neg_lo:[0,1]
	v_pk_fma_f32 v[6:7], v[6:7], v[110:111], v[118:119] op_sel_hi:[1,0,1]
	v_pk_mul_f32 v[118:119], v[24:25], v[110:111] op_sel:[0,1] op_sel_hi:[0,0] neg_hi:[1,0]
	v_pk_fma_f32 v[110:111], v[102:103], v[110:111], v[118:119] op_sel_hi:[0,1,1]
	s_mov_b32 s0, s19
	s_waitcnt lgkmcnt(11)
	v_pk_mul_f32 v[118:119], v[8:9], v[110:111] op_sel:[1,1] op_sel_hi:[0,1] neg_lo:[0,1]
	v_pk_fma_f32 v[8:9], v[8:9], v[110:111], v[118:119] op_sel_hi:[1,0,1]
	v_pk_mul_f32 v[118:119], v[24:25], v[110:111] op_sel:[0,1] op_sel_hi:[0,0] neg_hi:[1,0]
	v_pk_fma_f32 v[110:111], v[102:103], v[110:111], v[118:119] op_sel_hi:[0,1,1]
	s_waitcnt lgkmcnt(0)
	v_pk_mul_f32 v[118:119], v[10:11], v[110:111] op_sel:[1,1] op_sel_hi:[0,1] neg_lo:[0,1]
	v_pk_fma_f32 v[10:11], v[10:11], v[110:111], v[118:119] op_sel_hi:[1,0,1]
	v_pk_mul_f32 v[118:119], v[24:25], v[110:111] op_sel:[0,1] op_sel_hi:[0,0] neg_hi:[1,0]
	v_pk_fma_f32 v[110:111], v[102:103], v[110:111], v[118:119] op_sel_hi:[0,1,1]
	s_barrier
	v_pk_mul_f32 v[118:119], v[12:13], v[110:111] op_sel:[1,1] op_sel_hi:[0,1] neg_lo:[0,1]
	v_pk_fma_f32 v[12:13], v[12:13], v[110:111], v[118:119] op_sel_hi:[1,0,1]
	v_pk_mul_f32 v[118:119], v[24:25], v[110:111] op_sel:[0,1] op_sel_hi:[0,0] neg_hi:[1,0]
	v_pk_fma_f32 v[110:111], v[102:103], v[110:111], v[118:119] op_sel_hi:[0,1,1]
	s_nop 0
	v_pk_mul_f32 v[118:119], v[14:15], v[110:111] op_sel:[1,1] op_sel_hi:[0,1] neg_lo:[0,1]
	v_pk_fma_f32 v[14:15], v[14:15], v[110:111], v[118:119] op_sel_hi:[1,0,1]
	v_pk_mul_f32 v[118:119], v[24:25], v[110:111] op_sel:[0,1] op_sel_hi:[0,0] neg_hi:[1,0]
	v_pk_fma_f32 v[110:111], v[102:103], v[110:111], v[118:119] op_sel_hi:[0,1,1]
	v_lshlrev_b32_e32 v155, 3, v47
	v_pk_mul_f32 v[118:119], v[16:17], v[110:111] op_sel:[1,1] op_sel_hi:[0,1] neg_lo:[0,1]
	v_pk_fma_f32 v[16:17], v[16:17], v[110:111], v[118:119] op_sel_hi:[1,0,1]
	v_pk_mul_f32 v[118:119], v[24:25], v[110:111] op_sel:[0,1] op_sel_hi:[0,0] neg_hi:[1,0]
	v_pk_fma_f32 v[110:111], v[102:103], v[110:111], v[118:119] op_sel_hi:[0,1,1]
	s_nop 0
	v_pk_mul_f32 v[118:119], v[18:19], v[110:111] op_sel:[1,1] op_sel_hi:[0,1] neg_lo:[0,1]
	v_pk_fma_f32 v[18:19], v[18:19], v[110:111], v[118:119] op_sel_hi:[1,0,1]
	v_pk_mul_f32 v[118:119], v[24:25], v[110:111] op_sel:[0,1] op_sel_hi:[0,0] neg_hi:[1,0]
	v_pk_fma_f32 v[110:111], v[102:103], v[110:111], v[118:119] op_sel_hi:[0,1,1]
	s_nop 0
	v_pk_mul_f32 v[118:119], v[20:21], v[110:111] op_sel:[1,1] op_sel_hi:[0,1] neg_lo:[0,1]
	v_pk_fma_f32 v[20:21], v[20:21], v[110:111], v[118:119] op_sel_hi:[1,0,1]
	v_pk_mul_f32 v[118:119], v[24:25], v[110:111] op_sel:[0,1] op_sel_hi:[0,0] neg_hi:[1,0]
	v_pk_fma_f32 v[110:111], v[102:103], v[110:111], v[118:119] op_sel_hi:[0,1,1]
	s_nop 0
	v_pk_mul_f32 v[118:119], v[22:23], v[110:111] op_sel:[1,1] op_sel_hi:[0,1] neg_lo:[0,1]
	v_pk_fma_f32 v[22:23], v[22:23], v[110:111], v[118:119] op_sel_hi:[1,0,1]
	v_pk_mul_f32 v[118:119], v[24:25], v[110:111] op_sel:[0,1] op_sel_hi:[0,0] neg_hi:[1,0]
	v_pk_fma_f32 v[110:111], v[102:103], v[110:111], v[118:119] op_sel_hi:[0,1,1]
	s_nop 0
	v_pk_mul_f32 v[118:119], v[26:27], v[110:111] op_sel:[1,1] op_sel_hi:[0,1] neg_lo:[0,1]
	v_pk_fma_f32 v[26:27], v[26:27], v[110:111], v[118:119] op_sel_hi:[1,0,1]
	v_pk_mul_f32 v[118:119], v[24:25], v[110:111] op_sel:[0,1] op_sel_hi:[0,0] neg_hi:[1,0]
	v_pk_fma_f32 v[110:111], v[102:103], v[110:111], v[118:119] op_sel_hi:[0,1,1]
	s_nop 0
	v_pk_mul_f32 v[118:119], v[28:29], v[110:111] op_sel:[1,1] op_sel_hi:[0,1] neg_lo:[0,1]
	v_pk_fma_f32 v[28:29], v[28:29], v[110:111], v[118:119] op_sel_hi:[1,0,1]
	v_pk_mul_f32 v[118:119], v[24:25], v[110:111] op_sel:[0,1] op_sel_hi:[0,0] neg_hi:[1,0]
	v_pk_fma_f32 v[110:111], v[102:103], v[110:111], v[118:119] op_sel_hi:[0,1,1]
	v_pk_mul_f32 v[24:25], v[24:25], v[110:111] op_sel:[0,1] op_sel_hi:[0,0] neg_hi:[1,0]
	v_pk_fma_f32 v[24:25], v[102:103], v[110:111], v[24:25] op_sel_hi:[0,1,1]
	v_pk_mul_f32 v[102:103], v[80:81], v[24:25] op_sel:[1,1] op_sel_hi:[0,1] neg_lo:[0,1]
	v_pk_fma_f32 v[24:25], v[80:81], v[24:25], v[102:103] op_sel_hi:[1,0,1]
	v_pk_add_f32 v[80:81], v[0:1], v[16:17]
	v_pk_add_f32 v[0:1], v[0:1], v[16:17] neg_lo:[0,1] neg_hi:[0,1]
	v_pk_add_f32 v[16:17], v[2:3], v[18:19]
	v_pk_add_f32 v[2:3], v[2:3], v[18:19] neg_lo:[0,1] neg_hi:[0,1]
	v_pk_mul_f32 v[118:119], v[30:31], v[110:111] op_sel:[1,1] op_sel_hi:[0,1] neg_lo:[0,1]
	v_pk_mul_f32 v[18:19], v[2:3], s[18:19]
	v_pk_fma_f32 v[30:31], v[30:31], v[110:111], v[118:119] op_sel_hi:[1,0,1]
	v_pk_fma_f32 v[2:3], v[2:3], s[30:31], v[18:19] op_sel:[0,0,1] op_sel_hi:[1,0,0]
	v_pk_add_f32 v[18:19], v[4:5], v[20:21]
	v_pk_add_f32 v[4:5], v[4:5], v[20:21] neg_lo:[0,1] neg_hi:[0,1]
	s_nop 0
	v_pk_mul_f32 v[20:21], v[4:5], s[10:11]
	s_nop 0
	v_pk_fma_f32 v[4:5], v[4:5], s[14:15], v[20:21] op_sel:[0,0,1] op_sel_hi:[1,0,0]
	v_pk_add_f32 v[20:21], v[6:7], v[22:23]
	v_pk_add_f32 v[6:7], v[6:7], v[22:23] neg_lo:[0,1] neg_hi:[0,1]
	s_nop 0
	v_pk_mul_f32 v[22:23], v[6:7], s[34:35]
	s_nop 0
	v_pk_fma_f32 v[6:7], v[6:7], s[0:1], v[22:23] op_sel:[0,0,1] op_sel_hi:[1,0,0]
	v_pk_add_f32 v[22:23], v[8:9], v[26:27]
	v_pk_add_f32 v[8:9], v[8:9], v[26:27] neg_lo:[0,1] neg_hi:[0,1]
	v_pk_add_f32 v[26:27], v[10:11], v[28:29]
	v_pk_add_f32 v[10:11], v[10:11], v[28:29] neg_lo:[0,1] neg_hi:[0,1]
	s_nop 0
	v_pk_mul_f32 v[28:29], v[10:11], s[34:35]
	s_nop 0
	v_pk_fma_f32 v[10:11], v[10:11], s[0:1], v[28:29] op_sel:[0,0,1] op_sel_hi:[1,0,0] neg_lo:[1,0,0] neg_hi:[1,0,0]
	v_pk_add_f32 v[28:29], v[12:13], v[30:31]
	v_pk_add_f32 v[12:13], v[12:13], v[30:31] neg_lo:[0,1] neg_hi:[0,1]
	s_nop 0
	v_pk_mul_f32 v[30:31], v[12:13], s[10:11]
	s_nop 0
	v_pk_fma_f32 v[12:13], v[12:13], s[14:15], v[30:31] op_sel:[0,0,1] op_sel_hi:[1,0,0] neg_lo:[1,0,0] neg_hi:[1,0,0]
	v_pk_add_f32 v[30:31], v[14:15], v[24:25]
	v_pk_add_f32 v[14:15], v[14:15], v[24:25] neg_lo:[0,1] neg_hi:[0,1]
	s_nop 0
	v_pk_mul_f32 v[24:25], v[14:15], s[18:19]
	s_nop 0
	v_pk_fma_f32 v[14:15], v[14:15], s[30:31], v[24:25] op_sel:[0,0,1] op_sel_hi:[1,0,0] neg_lo:[1,0,0] neg_hi:[1,0,0]
	v_pk_add_f32 v[24:25], v[80:81], v[22:23]
	v_pk_add_f32 v[22:23], v[80:81], v[22:23] neg_lo:[0,1] neg_hi:[0,1]
	v_pk_add_f32 v[80:81], v[16:17], v[26:27]
	v_pk_add_f32 v[16:17], v[16:17], v[26:27] neg_lo:[0,1] neg_hi:[0,1]
	s_nop 0
	v_pk_mul_f32 v[26:27], v[16:17], s[10:11]
	s_nop 0
	v_pk_fma_f32 v[16:17], v[16:17], s[14:15], v[26:27] op_sel:[0,0,1] op_sel_hi:[1,0,0]
	v_pk_add_f32 v[26:27], v[18:19], v[28:29]
	v_pk_add_f32 v[18:19], v[18:19], v[28:29] neg_lo:[0,1] neg_hi:[0,1]
	v_pk_add_f32 v[28:29], v[20:21], v[30:31]
	v_pk_add_f32 v[20:21], v[20:21], v[30:31] neg_lo:[0,1] neg_hi:[0,1]
	s_nop 0
	v_pk_mul_f32 v[30:31], v[20:21], s[10:11]
	s_nop 0
	v_pk_fma_f32 v[20:21], v[20:21], s[14:15], v[30:31] op_sel:[0,0,1] op_sel_hi:[1,0,0] neg_lo:[1,0,0] neg_hi:[1,0,0]
	v_pk_add_f32 v[30:31], v[0:1], v[8:9] op_sel:[0,1] op_sel_hi:[1,0] neg_hi:[0,1]
	v_pk_add_f32 v[0:1], v[0:1], v[8:9] op_sel:[0,1] op_sel_hi:[1,0] neg_lo:[0,1]
	v_pk_add_f32 v[8:9], v[2:3], v[10:11]
	v_pk_add_f32 v[2:3], v[2:3], v[10:11] neg_lo:[0,1] neg_hi:[0,1]
	s_nop 0
	v_pk_mul_f32 v[10:11], v[2:3], s[10:11]
	s_nop 0
	v_pk_fma_f32 v[2:3], v[2:3], s[14:15], v[10:11] op_sel:[0,0,1] op_sel_hi:[1,0,0]
	v_pk_add_f32 v[10:11], v[4:5], v[12:13]
	v_pk_add_f32 v[4:5], v[4:5], v[12:13] neg_lo:[0,1] neg_hi:[0,1]
	v_pk_add_f32 v[12:13], v[6:7], v[14:15]
	v_pk_add_f32 v[6:7], v[6:7], v[14:15] neg_lo:[0,1] neg_hi:[0,1]
	s_nop 0
	v_pk_mul_f32 v[14:15], v[6:7], s[10:11]
	s_nop 0
	v_pk_fma_f32 v[6:7], v[6:7], s[14:15], v[14:15] op_sel:[0,0,1] op_sel_hi:[1,0,0] neg_lo:[1,0,0] neg_hi:[1,0,0]
	v_pk_add_f32 v[14:15], v[24:25], v[26:27]
	v_pk_add_f32 v[24:25], v[24:25], v[26:27] neg_lo:[0,1] neg_hi:[0,1]
	v_pk_add_f32 v[26:27], v[80:81], v[28:29]
	v_pk_add_f32 v[28:29], v[80:81], v[28:29] neg_lo:[0,1] neg_hi:[0,1]
	v_pk_add_f32 v[80:81], v[22:23], v[18:19] op_sel:[0,1] op_sel_hi:[1,0] neg_hi:[0,1]
	v_pk_add_f32 v[18:19], v[22:23], v[18:19] op_sel:[0,1] op_sel_hi:[1,0] neg_lo:[0,1]
	v_pk_add_f32 v[22:23], v[16:17], v[20:21]
	v_pk_add_f32 v[16:17], v[16:17], v[20:21] neg_lo:[0,1] neg_hi:[0,1]
	v_pk_add_f32 v[20:21], v[30:31], v[10:11]
	v_pk_add_f32 v[10:11], v[30:31], v[10:11] neg_lo:[0,1] neg_hi:[0,1]
	v_pk_add_f32 v[30:31], v[8:9], v[12:13]
	v_pk_add_f32 v[8:9], v[8:9], v[12:13] neg_lo:[0,1] neg_hi:[0,1]
	v_pk_add_f32 v[12:13], v[0:1], v[4:5] op_sel:[0,1] op_sel_hi:[1,0] neg_hi:[0,1]
	v_pk_add_f32 v[0:1], v[0:1], v[4:5] op_sel:[0,1] op_sel_hi:[1,0] neg_lo:[0,1]
	v_pk_add_f32 v[4:5], v[2:3], v[6:7]
	v_pk_add_f32 v[2:3], v[2:3], v[6:7] neg_lo:[0,1] neg_hi:[0,1]
	s_nop 0
	v_pk_mul_f32 v[2:3], v[2:3], s[22:23]
	v_pk_add_f32 v[6:7], v[14:15], v[26:27]
	v_pk_add_f32 v[14:15], v[14:15], v[26:27] neg_lo:[0,1] neg_hi:[0,1]
	v_pk_add_f32 v[26:27], v[24:25], v[28:29] op_sel:[0,1] op_sel_hi:[1,0] neg_hi:[0,1]
	v_pk_add_f32 v[24:25], v[24:25], v[28:29] op_sel:[0,1] op_sel_hi:[1,0] neg_lo:[0,1]
	v_pk_add_f32 v[28:29], v[80:81], v[22:23]
	v_pk_add_f32 v[22:23], v[80:81], v[22:23] neg_lo:[0,1] neg_hi:[0,1]
	v_pk_add_f32 v[80:81], v[18:19], v[16:17] op_sel:[0,1] op_sel_hi:[1,0] neg_hi:[0,1]
	v_pk_add_f32 v[16:17], v[18:19], v[16:17] op_sel:[0,1] op_sel_hi:[1,0] neg_lo:[0,1]
	v_pk_add_f32 v[18:19], v[20:21], v[30:31]
	v_pk_add_f32 v[20:21], v[20:21], v[30:31] neg_lo:[0,1] neg_hi:[0,1]
	v_pk_add_f32 v[30:31], v[10:11], v[8:9] op_sel:[0,1] op_sel_hi:[1,0] neg_hi:[0,1]
	v_pk_add_f32 v[8:9], v[10:11], v[8:9] op_sel:[0,1] op_sel_hi:[1,0] neg_lo:[0,1]
	v_pk_add_f32 v[10:11], v[12:13], v[4:5]
	v_pk_add_f32 v[4:5], v[12:13], v[4:5] neg_lo:[0,1] neg_hi:[0,1]
	v_pk_add_f32 v[12:13], v[0:1], v[2:3] op_sel:[0,1] op_sel_hi:[1,0]
	v_pk_add_f32 v[0:1], v[0:1], v[2:3] op_sel:[0,1] op_sel_hi:[1,0] neg_lo:[0,1] neg_hi:[0,1]
	v_lshlrev_b32_e32 v2, 4, v120
	v_and_or_b32 v2, v2, s7, v121
	v_ashrrev_i32_e32 v3, 4, v2
	v_lshlrev_b32_e32 v3, 3, v3
	v_lshlrev_b32_e32 v2, 3, v2
	v_add3_u32 v2, 0, v3, v2
	v_add_u32_e32 v3, 0x800, v2
	v_mov_b32_e32 v120, v32
	ds_write2_b64 v2, v[6:7], v[18:19] offset1:34
	ds_write2_b64 v3, v[14:15], v[20:21] offset0:16 offset1:50
	ds_write2_b64 v2, v[26:27], v[30:31] offset0:136 offset1:170
	ds_write2_b64 v3, v[24:25], v[8:9] offset0:152 offset1:186
	ds_write2_b64 v2, v[28:29], v[10:11] offset0:68 offset1:102
	ds_write2_b64 v3, v[22:23], v[4:5] offset0:84 offset1:118
	ds_write2_b64 v2, v[80:81], v[12:13] offset0:204 offset1:238
	ds_write2_b64 v3, v[16:17], v[0:1] offset0:220 offset1:254
	s_waitcnt lgkmcnt(0)
	s_barrier
	s_nop 0
	v_and_b32_e32 v121, 0x1ff, v120
	v_cvt_f32_u32_e32 v24, v121
	v_ashrrev_i32_e32 v0, 4, v120
	v_lshlrev_b32_e32 v0, 3, v0
	v_lshlrev_b32_e32 v1, 3, v120
	v_mul_f32_e32 v102, 0x39000000, v24
	v_sin_f32_e32 v24, v102
	v_cos_f32_e32 v102, v102
	v_add3_u32 v25, 0, v0, v1
	ds_read_b64 v[0:1], v25
	ds_read_b64 v[2:3], v25 offset:4352
	ds_read_b64 v[4:5], v25 offset:8704
	ds_read_b64 v[6:7], v25 offset:13056
	ds_read_b64 v[8:9], v25 offset:17408
	ds_read_b64 v[10:11], v25 offset:21760
	ds_read_b64 v[12:13], v25 offset:26112
	ds_read_b64 v[14:15], v25 offset:30464
	v_xor_b32_e32 v103, 0x80000000, v24
	s_waitcnt lgkmcnt(6)
	v_pk_mul_f32 v[110:111], v[2:3], v[24:25] op_sel:[1,0] op_sel_hi:[0,0] neg_hi:[0,1]
	v_pk_fma_f32 v[2:3], v[2:3], v[102:103], v[110:111] op_sel_hi:[1,0,1]
	v_pk_mul_f32 v[110:111], v[24:25], v[102:103] op_sel:[0,1] op_sel_hi:[0,0] neg_hi:[1,0]
	v_pk_fma_f32 v[110:111], v[102:103], v[102:103], v[110:111] op_sel_hi:[0,1,1]
	ds_read_b64 v[16:17], v25 offset:34816
	ds_read_b64 v[18:19], v25 offset:39168
	ds_read_b64 v[20:21], v25 offset:43520
	ds_read_b64 v[22:23], v25 offset:47872
	s_waitcnt lgkmcnt(9)
	v_pk_mul_f32 v[118:119], v[4:5], v[110:111] op_sel:[1,1] op_sel_hi:[0,1] neg_lo:[0,1]
	v_pk_fma_f32 v[4:5], v[4:5], v[110:111], v[118:119] op_sel_hi:[1,0,1]
	v_pk_mul_f32 v[118:119], v[24:25], v[110:111] op_sel:[0,1] op_sel_hi:[0,0] neg_hi:[1,0]
	v_pk_fma_f32 v[110:111], v[102:103], v[110:111], v[118:119] op_sel_hi:[0,1,1]
	ds_read_b64 v[26:27], v25 offset:52224
	ds_read_b64 v[28:29], v25 offset:56576
	ds_read_b64 v[30:31], v25 offset:60928
	ds_read_b64 v[80:81], v25 offset:65280
	s_waitcnt lgkmcnt(12)
	v_pk_mul_f32 v[118:119], v[6:7], v[110:111] op_sel:[1,1] op_sel_hi:[0,1] neg_lo:[0,1]
	v_pk_fma_f32 v[6:7], v[6:7], v[110:111], v[118:119] op_sel_hi:[1,0,1]
	v_pk_mul_f32 v[118:119], v[24:25], v[110:111] op_sel:[0,1] op_sel_hi:[0,0] neg_hi:[1,0]
	v_pk_fma_f32 v[110:111], v[102:103], v[110:111], v[118:119] op_sel_hi:[0,1,1]
	s_waitcnt lgkmcnt(0)
	v_pk_mul_f32 v[118:119], v[8:9], v[110:111] op_sel:[1,1] op_sel_hi:[0,1] neg_lo:[0,1]
	v_pk_fma_f32 v[8:9], v[8:9], v[110:111], v[118:119] op_sel_hi:[1,0,1]
	v_pk_mul_f32 v[118:119], v[24:25], v[110:111] op_sel:[0,1] op_sel_hi:[0,0] neg_hi:[1,0]
	v_pk_fma_f32 v[110:111], v[102:103], v[110:111], v[118:119] op_sel_hi:[0,1,1]
	s_barrier
	v_pk_mul_f32 v[118:119], v[10:11], v[110:111] op_sel:[1,1] op_sel_hi:[0,1] neg_lo:[0,1]
	v_pk_fma_f32 v[10:11], v[10:11], v[110:111], v[118:119] op_sel_hi:[1,0,1]
	v_pk_mul_f32 v[118:119], v[24:25], v[110:111] op_sel:[0,1] op_sel_hi:[0,0] neg_hi:[1,0]
	v_pk_fma_f32 v[110:111], v[102:103], v[110:111], v[118:119] op_sel_hi:[0,1,1]
	s_nop 0
	v_pk_mul_f32 v[118:119], v[12:13], v[110:111] op_sel:[1,1] op_sel_hi:[0,1] neg_lo:[0,1]
	v_pk_fma_f32 v[12:13], v[12:13], v[110:111], v[118:119] op_sel_hi:[1,0,1]
	v_pk_mul_f32 v[118:119], v[24:25], v[110:111] op_sel:[0,1] op_sel_hi:[0,0] neg_hi:[1,0]
	v_pk_fma_f32 v[110:111], v[102:103], v[110:111], v[118:119] op_sel_hi:[0,1,1]
	s_nop 0
	v_pk_mul_f32 v[118:119], v[14:15], v[110:111] op_sel:[1,1] op_sel_hi:[0,1] neg_lo:[0,1]
	v_pk_fma_f32 v[14:15], v[14:15], v[110:111], v[118:119] op_sel_hi:[1,0,1]
	v_pk_mul_f32 v[118:119], v[24:25], v[110:111] op_sel:[0,1] op_sel_hi:[0,0] neg_hi:[1,0]
	v_pk_fma_f32 v[110:111], v[102:103], v[110:111], v[118:119] op_sel_hi:[0,1,1]
	s_nop 0
	v_pk_mul_f32 v[118:119], v[16:17], v[110:111] op_sel:[1,1] op_sel_hi:[0,1] neg_lo:[0,1]
	v_pk_fma_f32 v[16:17], v[16:17], v[110:111], v[118:119] op_sel_hi:[1,0,1]
	v_pk_mul_f32 v[118:119], v[24:25], v[110:111] op_sel:[0,1] op_sel_hi:[0,0] neg_hi:[1,0]
	v_pk_fma_f32 v[110:111], v[102:103], v[110:111], v[118:119] op_sel_hi:[0,1,1]
	s_nop 0
	v_pk_mul_f32 v[118:119], v[18:19], v[110:111] op_sel:[1,1] op_sel_hi:[0,1] neg_lo:[0,1]
	v_pk_fma_f32 v[18:19], v[18:19], v[110:111], v[118:119] op_sel_hi:[1,0,1]
	v_pk_mul_f32 v[118:119], v[24:25], v[110:111] op_sel:[0,1] op_sel_hi:[0,0] neg_hi:[1,0]
	v_pk_fma_f32 v[110:111], v[102:103], v[110:111], v[118:119] op_sel_hi:[0,1,1]
	s_nop 0
	v_pk_mul_f32 v[118:119], v[20:21], v[110:111] op_sel:[1,1] op_sel_hi:[0,1] neg_lo:[0,1]
	v_pk_fma_f32 v[20:21], v[20:21], v[110:111], v[118:119] op_sel_hi:[1,0,1]
	v_pk_mul_f32 v[118:119], v[24:25], v[110:111] op_sel:[0,1] op_sel_hi:[0,0] neg_hi:[1,0]
	v_pk_fma_f32 v[110:111], v[102:103], v[110:111], v[118:119] op_sel_hi:[0,1,1]
	s_nop 0
	v_pk_mul_f32 v[118:119], v[22:23], v[110:111] op_sel:[1,1] op_sel_hi:[0,1] neg_lo:[0,1]
	v_pk_fma_f32 v[22:23], v[22:23], v[110:111], v[118:119] op_sel_hi:[1,0,1]
	v_pk_mul_f32 v[118:119], v[24:25], v[110:111] op_sel:[0,1] op_sel_hi:[0,0] neg_hi:[1,0]
	v_pk_fma_f32 v[110:111], v[102:103], v[110:111], v[118:119] op_sel_hi:[0,1,1]
	s_nop 0
	v_pk_mul_f32 v[118:119], v[26:27], v[110:111] op_sel:[1,1] op_sel_hi:[0,1] neg_lo:[0,1]
	v_pk_fma_f32 v[26:27], v[26:27], v[110:111], v[118:119] op_sel_hi:[1,0,1]
	v_pk_mul_f32 v[118:119], v[24:25], v[110:111] op_sel:[0,1] op_sel_hi:[0,0] neg_hi:[1,0]
	v_pk_fma_f32 v[110:111], v[102:103], v[110:111], v[118:119] op_sel_hi:[0,1,1]
	s_nop 0
	v_pk_mul_f32 v[118:119], v[28:29], v[110:111] op_sel:[1,1] op_sel_hi:[0,1] neg_lo:[0,1]
	v_pk_fma_f32 v[28:29], v[28:29], v[110:111], v[118:119] op_sel_hi:[1,0,1]
	v_pk_mul_f32 v[118:119], v[24:25], v[110:111] op_sel:[0,1] op_sel_hi:[0,0] neg_hi:[1,0]
	v_pk_fma_f32 v[110:111], v[102:103], v[110:111], v[118:119] op_sel_hi:[0,1,1]
	v_pk_mul_f32 v[24:25], v[24:25], v[110:111] op_sel:[0,1] op_sel_hi:[0,0] neg_hi:[1,0]
	v_pk_fma_f32 v[24:25], v[102:103], v[110:111], v[24:25] op_sel_hi:[0,1,1]
	v_pk_mul_f32 v[102:103], v[80:81], v[24:25] op_sel:[1,1] op_sel_hi:[0,1] neg_lo:[0,1]
	v_pk_fma_f32 v[24:25], v[80:81], v[24:25], v[102:103] op_sel_hi:[1,0,1]
	v_pk_add_f32 v[80:81], v[0:1], v[16:17]
	v_pk_add_f32 v[0:1], v[0:1], v[16:17] neg_lo:[0,1] neg_hi:[0,1]
	v_pk_add_f32 v[16:17], v[2:3], v[18:19]
	v_pk_add_f32 v[2:3], v[2:3], v[18:19] neg_lo:[0,1] neg_hi:[0,1]
	v_pk_mul_f32 v[118:119], v[30:31], v[110:111] op_sel:[1,1] op_sel_hi:[0,1] neg_lo:[0,1]
	v_pk_mul_f32 v[18:19], v[2:3], s[18:19]
	v_pk_fma_f32 v[30:31], v[30:31], v[110:111], v[118:119] op_sel_hi:[1,0,1]
	v_pk_fma_f32 v[2:3], v[2:3], s[30:31], v[18:19] op_sel:[0,0,1] op_sel_hi:[1,0,0]
	v_pk_add_f32 v[18:19], v[4:5], v[20:21]
	v_pk_add_f32 v[4:5], v[4:5], v[20:21] neg_lo:[0,1] neg_hi:[0,1]
	s_nop 0
	v_pk_mul_f32 v[20:21], v[4:5], s[10:11]
	s_nop 0
	v_pk_fma_f32 v[4:5], v[4:5], s[14:15], v[20:21] op_sel:[0,0,1] op_sel_hi:[1,0,0]
	v_pk_add_f32 v[20:21], v[6:7], v[22:23]
	v_pk_add_f32 v[6:7], v[6:7], v[22:23] neg_lo:[0,1] neg_hi:[0,1]
	s_nop 0
	v_pk_mul_f32 v[22:23], v[6:7], s[34:35]
	s_nop 0
	v_pk_fma_f32 v[6:7], v[6:7], s[0:1], v[22:23] op_sel:[0,0,1] op_sel_hi:[1,0,0]
	v_pk_add_f32 v[22:23], v[8:9], v[26:27]
	v_pk_add_f32 v[8:9], v[8:9], v[26:27] neg_lo:[0,1] neg_hi:[0,1]
	v_pk_add_f32 v[26:27], v[10:11], v[28:29]
	v_pk_add_f32 v[10:11], v[10:11], v[28:29] neg_lo:[0,1] neg_hi:[0,1]
	s_nop 0
	v_pk_mul_f32 v[28:29], v[10:11], s[34:35]
	s_nop 0
	v_pk_fma_f32 v[10:11], v[10:11], s[0:1], v[28:29] op_sel:[0,0,1] op_sel_hi:[1,0,0] neg_lo:[1,0,0] neg_hi:[1,0,0]
	v_pk_add_f32 v[28:29], v[12:13], v[30:31]
	v_pk_add_f32 v[12:13], v[12:13], v[30:31] neg_lo:[0,1] neg_hi:[0,1]
	s_mov_b32 s0, 0
	v_pk_mul_f32 v[30:31], v[12:13], s[10:11]
	s_nop 0
	v_pk_fma_f32 v[12:13], v[12:13], s[14:15], v[30:31] op_sel:[0,0,1] op_sel_hi:[1,0,0] neg_lo:[1,0,0] neg_hi:[1,0,0]
	v_pk_add_f32 v[30:31], v[14:15], v[24:25]
	v_pk_add_f32 v[14:15], v[14:15], v[24:25] neg_lo:[0,1] neg_hi:[0,1]
	s_nop 0
	v_pk_mul_f32 v[24:25], v[14:15], s[18:19]
	s_nop 0
	v_pk_fma_f32 v[14:15], v[14:15], s[30:31], v[24:25] op_sel:[0,0,1] op_sel_hi:[1,0,0] neg_lo:[1,0,0] neg_hi:[1,0,0]
	v_pk_add_f32 v[24:25], v[80:81], v[22:23]
	v_pk_add_f32 v[22:23], v[80:81], v[22:23] neg_lo:[0,1] neg_hi:[0,1]
	v_pk_add_f32 v[80:81], v[16:17], v[26:27]
	v_pk_add_f32 v[16:17], v[16:17], v[26:27] neg_lo:[0,1] neg_hi:[0,1]
	s_nop 0
	v_pk_mul_f32 v[26:27], v[16:17], s[10:11]
	s_nop 0
	v_pk_fma_f32 v[16:17], v[16:17], s[14:15], v[26:27] op_sel:[0,0,1] op_sel_hi:[1,0,0]
	v_pk_add_f32 v[26:27], v[18:19], v[28:29]
	v_pk_add_f32 v[18:19], v[18:19], v[28:29] neg_lo:[0,1] neg_hi:[0,1]
	v_pk_add_f32 v[28:29], v[20:21], v[30:31]
	v_pk_add_f32 v[20:21], v[20:21], v[30:31] neg_lo:[0,1] neg_hi:[0,1]
	s_nop 0
	v_pk_mul_f32 v[30:31], v[20:21], s[10:11]
	s_nop 0
	v_pk_fma_f32 v[20:21], v[20:21], s[14:15], v[30:31] op_sel:[0,0,1] op_sel_hi:[1,0,0] neg_lo:[1,0,0] neg_hi:[1,0,0]
	v_pk_add_f32 v[30:31], v[0:1], v[8:9] op_sel:[0,1] op_sel_hi:[1,0] neg_hi:[0,1]
	v_pk_add_f32 v[0:1], v[0:1], v[8:9] op_sel:[0,1] op_sel_hi:[1,0] neg_lo:[0,1]
	v_pk_add_f32 v[8:9], v[2:3], v[10:11]
	v_pk_add_f32 v[2:3], v[2:3], v[10:11] neg_lo:[0,1] neg_hi:[0,1]
	s_nop 0
	v_pk_mul_f32 v[10:11], v[2:3], s[10:11]
	s_nop 0
	v_pk_fma_f32 v[2:3], v[2:3], s[14:15], v[10:11] op_sel:[0,0,1] op_sel_hi:[1,0,0]
	v_pk_add_f32 v[10:11], v[4:5], v[12:13]
	v_pk_add_f32 v[4:5], v[4:5], v[12:13] neg_lo:[0,1] neg_hi:[0,1]
	v_pk_add_f32 v[12:13], v[6:7], v[14:15]
	v_pk_add_f32 v[6:7], v[6:7], v[14:15] neg_lo:[0,1] neg_hi:[0,1]
	s_nop 0
	v_pk_mul_f32 v[14:15], v[6:7], s[10:11]
	s_nop 0
	v_pk_fma_f32 v[6:7], v[6:7], s[14:15], v[14:15] op_sel:[0,0,1] op_sel_hi:[1,0,0] neg_lo:[1,0,0] neg_hi:[1,0,0]
	v_pk_add_f32 v[14:15], v[24:25], v[26:27]
	v_pk_add_f32 v[24:25], v[24:25], v[26:27] neg_lo:[0,1] neg_hi:[0,1]
	v_pk_add_f32 v[26:27], v[80:81], v[28:29]
	v_pk_add_f32 v[28:29], v[80:81], v[28:29] neg_lo:[0,1] neg_hi:[0,1]
	v_pk_add_f32 v[80:81], v[22:23], v[18:19] op_sel:[0,1] op_sel_hi:[1,0] neg_hi:[0,1]
	v_pk_add_f32 v[18:19], v[22:23], v[18:19] op_sel:[0,1] op_sel_hi:[1,0] neg_lo:[0,1]
	v_pk_add_f32 v[22:23], v[16:17], v[20:21]
	v_pk_add_f32 v[16:17], v[16:17], v[20:21] neg_lo:[0,1] neg_hi:[0,1]
	v_pk_add_f32 v[20:21], v[30:31], v[10:11]
	v_pk_add_f32 v[10:11], v[30:31], v[10:11] neg_lo:[0,1] neg_hi:[0,1]
	v_pk_add_f32 v[30:31], v[8:9], v[12:13]
	v_pk_add_f32 v[8:9], v[8:9], v[12:13] neg_lo:[0,1] neg_hi:[0,1]
	v_pk_add_f32 v[12:13], v[0:1], v[4:5] op_sel:[0,1] op_sel_hi:[1,0] neg_hi:[0,1]
	v_pk_add_f32 v[0:1], v[0:1], v[4:5] op_sel:[0,1] op_sel_hi:[1,0] neg_lo:[0,1]
	v_pk_add_f32 v[4:5], v[2:3], v[6:7]
	v_pk_add_f32 v[2:3], v[2:3], v[6:7] neg_lo:[0,1] neg_hi:[0,1]
	s_nop 0
	v_pk_mul_f32 v[2:3], v[2:3], s[22:23]
	v_pk_add_f32 v[6:7], v[14:15], v[26:27]
	v_pk_add_f32 v[14:15], v[14:15], v[26:27] neg_lo:[0,1] neg_hi:[0,1]
	v_pk_add_f32 v[26:27], v[24:25], v[28:29] op_sel:[0,1] op_sel_hi:[1,0] neg_hi:[0,1]
	v_pk_add_f32 v[24:25], v[24:25], v[28:29] op_sel:[0,1] op_sel_hi:[1,0] neg_lo:[0,1]
	v_pk_add_f32 v[28:29], v[80:81], v[22:23]
	v_pk_add_f32 v[22:23], v[80:81], v[22:23] neg_lo:[0,1] neg_hi:[0,1]
	v_pk_add_f32 v[80:81], v[18:19], v[16:17] op_sel:[0,1] op_sel_hi:[1,0] neg_hi:[0,1]
	v_pk_add_f32 v[16:17], v[18:19], v[16:17] op_sel:[0,1] op_sel_hi:[1,0] neg_lo:[0,1]
	v_pk_add_f32 v[18:19], v[20:21], v[30:31]
	v_pk_add_f32 v[20:21], v[20:21], v[30:31] neg_lo:[0,1] neg_hi:[0,1]
	v_pk_add_f32 v[30:31], v[10:11], v[8:9] op_sel:[0,1] op_sel_hi:[1,0] neg_hi:[0,1]
	v_pk_add_f32 v[8:9], v[10:11], v[8:9] op_sel:[0,1] op_sel_hi:[1,0] neg_lo:[0,1]
	v_pk_add_f32 v[10:11], v[12:13], v[4:5]
	v_pk_add_f32 v[4:5], v[12:13], v[4:5] neg_lo:[0,1] neg_hi:[0,1]
	v_pk_add_f32 v[12:13], v[0:1], v[2:3] op_sel:[0,1] op_sel_hi:[1,0]
	v_pk_add_f32 v[0:1], v[0:1], v[2:3] op_sel:[0,1] op_sel_hi:[1,0] neg_lo:[0,1] neg_hi:[0,1]
	v_lshlrev_b32_e32 v2, 4, v120
	v_and_or_b32 v2, v2, s15, v121
	v_ashrrev_i32_e32 v3, 4, v2
	v_lshlrev_b32_e32 v3, 3, v3
	v_lshlrev_b32_e32 v2, 3, v2
	v_add3_u32 v2, 0, v3, v2
	ds_write_b64 v2, v[6:7]
	ds_write_b64 v2, v[14:15] offset:34816
	ds_write_b64 v2, v[26:27] offset:17408
	ds_write_b64 v2, v[24:25] offset:52224
	ds_write_b64 v2, v[28:29] offset:8704
	ds_write_b64 v2, v[22:23] offset:43520
	ds_write_b64 v2, v[80:81] offset:26112
	ds_write_b64 v2, v[16:17] offset:60928
	ds_write_b64 v2, v[18:19] offset:4352
	ds_write_b64 v2, v[20:21] offset:39168
	ds_write_b64 v2, v[30:31] offset:21760
	ds_write_b64 v2, v[8:9] offset:56576
	ds_write_b64 v2, v[10:11] offset:13056
	ds_write_b64 v2, v[4:5] offset:47872
	ds_write_b64 v2, v[12:13] offset:30464
	ds_write_b64 v2, v[0:1] offset:65280
	v_sub_u32_e32 v80, 0x2000, v32
	v_ashrrev_i32_e32 v0, 4, v80
	v_add_u32_e32 v154, v0, v80
	v_lshlrev_b32_e32 v0, 3, v0
	v_sub_u32_e32 v156, v0, v157
	v_mov_b32_e32 v0, v154
	v_mov_b32_e32 v1, v156
	v_mov_b32_e32 v2, v155
	s_waitcnt lgkmcnt(0)
	s_barrier
.LBB0_433:
	v_or_b32_e32 v3, s0, v32
	v_cmp_ne_u32_e32 vcc, 0, v3
	v_add_u32_e32 v12, 0, v2
	v_add_u32_e32 v4, 0x11000, v12
	v_cndmask_b32_e32 v3, 0, v0, vcc
	v_lshl_add_u32 v3, v3, 3, 0
	v_add_u32_e32 v3, 0x11000, v3
	ds_read_b64 v[4:5], v4
	ds_read_b64 v[8:9], v12
	ds_read_b64 v[6:7], v3
	s_add_i32 s0, s0, 2
	v_add_u32_e32 v2, 0x2200, v2
	v_add_u32_e32 v0, 0xfffffbc0, v0
	s_cmp_lg_u32 s0, 16
	s_waitcnt lgkmcnt(0)
	v_add_f32_e32 v3, v4, v6
	v_mul_f32_e32 v4, 0.5, v3
	v_sub_f32_e32 v3, v5, v7
	v_mul_f32_e32 v6, 0.5, v3
	v_pk_mul_f32 v[6:7], v[8:9], v[6:7] op_sel:[1,0] op_sel_hi:[0,0]
	v_pk_fma_f32 v[10:11], v[8:9], v[4:5], v[6:7] neg_lo:[0,0,1] neg_hi:[0,0,1]
	v_pk_fma_f32 v[4:5], v[8:9], v[4:5], v[6:7] op_sel_hi:[1,0,1]
	v_add_u32_e32 v3, 0x12100, v12
	v_mov_b32_e32 v11, v5
	v_pk_mul_f32 v[4:5], v[10:11], s[24:25]
	ds_write_b64 v12, v[4:5]
	ds_read_b64 v[4:5], v3
	ds_read_b64 v[8:9], v12 offset:4352
	v_add_u32_e32 v3, 0, v1
	v_add_u32_e32 v3, 0x1ff00, v3
	ds_read_b64 v[6:7], v3
	v_add_u32_e32 v1, 0xffffde00, v1
	s_waitcnt lgkmcnt(0)
	v_add_f32_e32 v3, v4, v6
	v_mul_f32_e32 v4, 0.5, v3
	v_sub_f32_e32 v3, v5, v7
	v_mul_f32_e32 v6, 0.5, v3
	v_pk_mul_f32 v[6:7], v[8:9], v[6:7] op_sel:[1,0] op_sel_hi:[0,0]
	v_pk_fma_f32 v[10:11], v[8:9], v[4:5], v[6:7] neg_lo:[0,0,1] neg_hi:[0,0,1]
	v_pk_fma_f32 v[4:5], v[8:9], v[4:5], v[6:7] op_sel_hi:[1,0,1]
	s_nop 0
	v_mov_b32_e32 v11, v5
	v_pk_mul_f32 v[4:5], v[10:11], s[24:25]
	ds_write_b64 v12, v[4:5] offset:4352
	s_cbranch_scc1 .LBB0_433
	s_waitcnt lgkmcnt(0)
	s_barrier
	s_and_saveexec_b64 s[0:1], s[40:41]
	s_cbranch_execz .LBB0_436
	ds_read_b64 v[0:1], v37 offset:2176
	ds_read_b64 v[2:3], v37 offset:4352
	ds_read_b64 v[4:5], v37 offset:6528
	ds_read_b64 v[6:7], v37 offset:8704
	ds_read_b64 v[8:9], v37 offset:10880
	ds_read_b64 v[10:11], v37 offset:13056
	ds_read_b64 v[12:13], v37 offset:15232
	ds_read_b64 v[14:15], v37 offset:17408
	ds_read_b64 v[16:17], v37 offset:19584
	ds_read_b64 v[18:19], v37 offset:21760
	ds_read_b64 v[20:21], v37 offset:23936
	ds_read_b64 v[22:23], v37 offset:26112
	ds_read_b64 v[24:25], v37 offset:34816
	ds_read_b64 v[26:27], v37 offset:36992
	ds_read_b64 v[28:29], v37 offset:39168
	ds_read_b64 v[30:31], v37 offset:41344
	ds_read_b64 v[102:103], v37 offset:43520
	ds_read_b64 v[110:111], v37 offset:45696
	ds_read_b64 v[118:119], v37 offset:47872
	ds_read_b64 v[120:121], v37 offset:50048
	ds_read_b64 v[122:123], v37 offset:52224
	ds_read_b64 v[124:125], v37 offset:54400
	ds_read_b64 v[126:127], v37 offset:56576
	ds_read_b64 v[128:129], v37 offset:58752
	ds_read_b64 v[130:131], v37
	ds_read_b64 v[132:133], v37 offset:60928
	ds_read_b64 v[134:135], v37 offset:63104
	ds_read_b64 v[136:137], v37 offset:65280
	s_mov_b32 s11, s14
	s_waitcnt lgkmcnt(3)
	v_pk_add_f32 v[158:159], v[130:131], v[24:25]
	v_pk_add_f32 v[24:25], v[130:131], v[24:25] neg_lo:[0,1] neg_hi:[0,1]
	v_pk_add_f32 v[130:131], v[0:1], v[26:27]
	v_pk_add_f32 v[0:1], v[0:1], v[26:27] neg_lo:[0,1] neg_hi:[0,1]
	s_mov_b32 s13, s86
	v_pk_mul_f32 v[26:27], v[0:1], s[16:17]
	s_mov_b32 s4, s21
	v_pk_fma_f32 v[0:1], v[0:1], s[6:7], v[26:27] op_sel:[0,0,1] op_sel_hi:[1,0,0]
	v_pk_add_f32 v[26:27], v[2:3], v[28:29]
	v_pk_add_f32 v[2:3], v[2:3], v[28:29] neg_lo:[0,1] neg_hi:[0,1]
	s_mov_b32 s35, s30
	v_pk_mul_f32 v[28:29], v[2:3], s[18:19]
	s_mov_b32 s8, s19
	v_pk_fma_f32 v[2:3], v[2:3], s[30:31], v[28:29] op_sel:[0,0,1] op_sel_hi:[1,0,0]
	v_pk_add_f32 v[28:29], v[4:5], v[30:31]
	v_pk_add_f32 v[4:5], v[4:5], v[30:31] neg_lo:[0,1] neg_hi:[0,1]
	s_mov_b32 s77, s6
	v_pk_mul_f32 v[30:31], v[4:5], s[20:21]
	s_mov_b32 s28, s17
	v_pk_fma_f32 v[4:5], v[4:5], s[86:87], v[30:31] op_sel:[0,0,1] op_sel_hi:[1,0,0]
	v_pk_add_f32 v[30:31], v[6:7], v[102:103]
	v_pk_add_f32 v[6:7], v[6:7], v[102:103] neg_lo:[0,1] neg_hi:[0,1]
	v_add_u32_e32 v47, 0x10780, v37
	v_pk_mul_f32 v[102:103], v[6:7], s[10:11]
	ds_read_b64 v[138:139], v37 offset:28288
	ds_read_b64 v[140:141], v37 offset:30464
	ds_read_b64 v[142:143], v37 offset:32640
	ds_read_b64 v[144:145], v47
	v_pk_fma_f32 v[6:7], v[6:7], s[14:15], v[102:103] op_sel:[0,0,1] op_sel_hi:[1,0,0]
	v_pk_add_f32 v[102:103], v[8:9], v[110:111]
	v_pk_add_f32 v[8:9], v[8:9], v[110:111] neg_lo:[0,1] neg_hi:[0,1]
	s_nop 0
	v_pk_mul_f32 v[110:111], v[8:9], s[12:13]
	s_nop 0
	v_pk_fma_f32 v[8:9], v[8:9], s[4:5], v[110:111] op_sel:[0,0,1] op_sel_hi:[1,0,0]
	v_pk_add_f32 v[110:111], v[10:11], v[118:119]
	v_pk_add_f32 v[10:11], v[10:11], v[118:119] neg_lo:[0,1] neg_hi:[0,1]
	s_nop 0
	v_pk_mul_f32 v[118:119], v[10:11], s[34:35]
	s_nop 0
	v_pk_fma_f32 v[10:11], v[10:11], s[8:9], v[118:119] op_sel:[0,0,1] op_sel_hi:[1,0,0]
	v_pk_add_f32 v[118:119], v[12:13], v[120:121]
	v_pk_add_f32 v[12:13], v[12:13], v[120:121] neg_lo:[0,1] neg_hi:[0,1]
	s_nop 0
	v_pk_mul_f32 v[120:121], v[12:13], s[76:77]
	s_nop 0
	v_pk_fma_f32 v[12:13], v[12:13], s[28:29], v[120:121] op_sel:[0,0,1] op_sel_hi:[1,0,0]
	v_pk_add_f32 v[120:121], v[14:15], v[122:123]
	v_pk_add_f32 v[14:15], v[14:15], v[122:123] neg_lo:[0,1] neg_hi:[0,1]
	v_pk_add_f32 v[122:123], v[16:17], v[124:125]
	v_pk_add_f32 v[16:17], v[16:17], v[124:125] neg_lo:[0,1] neg_hi:[0,1]
	s_nop 0
	v_pk_mul_f32 v[124:125], v[16:17], s[76:77]
	s_nop 0
	v_pk_fma_f32 v[16:17], v[16:17], s[28:29], v[124:125] op_sel:[0,0,1] op_sel_hi:[1,0,0] neg_lo:[1,0,0] neg_hi:[1,0,0]
	v_pk_add_f32 v[124:125], v[18:19], v[126:127]
	v_pk_add_f32 v[18:19], v[18:19], v[126:127] neg_lo:[0,1] neg_hi:[0,1]
	s_nop 0
	v_pk_mul_f32 v[126:127], v[18:19], s[34:35]
	s_nop 0
	v_pk_fma_f32 v[18:19], v[18:19], s[8:9], v[126:127] op_sel:[0,0,1] op_sel_hi:[1,0,0] neg_lo:[1,0,0] neg_hi:[1,0,0]
	v_pk_add_f32 v[126:127], v[20:21], v[128:129]
	v_pk_add_f32 v[20:21], v[20:21], v[128:129] neg_lo:[0,1] neg_hi:[0,1]
	s_nop 0
	v_pk_mul_f32 v[128:129], v[20:21], s[12:13]
	s_nop 0
	v_pk_fma_f32 v[20:21], v[20:21], s[4:5], v[128:129] op_sel:[0,0,1] op_sel_hi:[1,0,0] neg_lo:[1,0,0] neg_hi:[1,0,0]
	s_waitcnt lgkmcnt(6)
	v_pk_add_f32 v[128:129], v[22:23], v[132:133]
	v_pk_add_f32 v[22:23], v[22:23], v[132:133] neg_lo:[0,1] neg_hi:[0,1]
	s_nop 0
	v_pk_mul_f32 v[132:133], v[22:23], s[10:11]
	s_nop 0
	v_pk_fma_f32 v[22:23], v[22:23], s[14:15], v[132:133] op_sel:[0,0,1] op_sel_hi:[1,0,0] neg_lo:[1,0,0] neg_hi:[1,0,0]
	s_waitcnt lgkmcnt(3)
	v_pk_add_f32 v[132:133], v[138:139], v[134:135]
	v_pk_add_f32 v[134:135], v[138:139], v[134:135] neg_lo:[0,1] neg_hi:[0,1]
	s_nop 0
	v_pk_mul_f32 v[138:139], v[134:135], s[20:21]
	s_nop 0
	v_pk_fma_f32 v[134:135], v[134:135], s[86:87], v[138:139] op_sel:[0,0,1] op_sel_hi:[1,0,0] neg_lo:[1,0,0] neg_hi:[1,0,0]
	s_waitcnt lgkmcnt(2)
	v_pk_add_f32 v[138:139], v[140:141], v[136:137]
	v_pk_add_f32 v[136:137], v[140:141], v[136:137] neg_lo:[0,1] neg_hi:[0,1]
	s_nop 0
	v_pk_mul_f32 v[140:141], v[136:137], s[18:19]
	s_nop 0
	v_pk_fma_f32 v[136:137], v[136:137], s[30:31], v[140:141] op_sel:[0,0,1] op_sel_hi:[1,0,0] neg_lo:[1,0,0] neg_hi:[1,0,0]
	s_waitcnt lgkmcnt(0)
	v_pk_add_f32 v[140:141], v[142:143], v[144:145]
	v_pk_add_f32 v[142:143], v[142:143], v[144:145] neg_lo:[0,1] neg_hi:[0,1]
	s_nop 0
	v_pk_mul_f32 v[144:145], v[142:143], s[16:17]
	s_nop 0
	v_pk_fma_f32 v[142:143], v[142:143], s[6:7], v[144:145] op_sel:[0,0,1] op_sel_hi:[1,0,0] neg_lo:[1,0,0] neg_hi:[1,0,0]
	v_pk_add_f32 v[144:145], v[158:159], v[120:121]
	v_pk_add_f32 v[120:121], v[158:159], v[120:121] neg_lo:[0,1] neg_hi:[0,1]
	v_pk_add_f32 v[158:159], v[130:131], v[122:123]
	v_pk_add_f32 v[122:123], v[130:131], v[122:123] neg_lo:[0,1] neg_hi:[0,1]
	s_nop 0
	v_pk_mul_f32 v[130:131], v[122:123], s[18:19]
	s_nop 0
	v_pk_fma_f32 v[122:123], v[122:123], s[30:31], v[130:131] op_sel:[0,0,1] op_sel_hi:[1,0,0]
	v_pk_add_f32 v[130:131], v[26:27], v[124:125]
	v_pk_add_f32 v[26:27], v[26:27], v[124:125] neg_lo:[0,1] neg_hi:[0,1]
	s_nop 0
	v_pk_mul_f32 v[124:125], v[26:27], s[10:11]
	s_nop 0
	v_pk_fma_f32 v[26:27], v[26:27], s[14:15], v[124:125] op_sel:[0,0,1] op_sel_hi:[1,0,0]
	v_pk_add_f32 v[124:125], v[28:29], v[126:127]
	v_pk_add_f32 v[28:29], v[28:29], v[126:127] neg_lo:[0,1] neg_hi:[0,1]
	s_nop 0
	v_pk_mul_f32 v[126:127], v[28:29], s[34:35]
	s_nop 0
	v_pk_fma_f32 v[28:29], v[28:29], s[8:9], v[126:127] op_sel:[0,0,1] op_sel_hi:[1,0,0]
	v_pk_add_f32 v[126:127], v[30:31], v[128:129]
	v_pk_add_f32 v[30:31], v[30:31], v[128:129] neg_lo:[0,1] neg_hi:[0,1]
	v_pk_add_f32 v[128:129], v[102:103], v[132:133]
	v_pk_add_f32 v[102:103], v[102:103], v[132:133] neg_lo:[0,1] neg_hi:[0,1]
	s_nop 0
	v_pk_mul_f32 v[132:133], v[102:103], s[34:35]
	s_nop 0
	v_pk_fma_f32 v[102:103], v[102:103], s[8:9], v[132:133] op_sel:[0,0,1] op_sel_hi:[1,0,0] neg_lo:[1,0,0] neg_hi:[1,0,0]
	v_pk_add_f32 v[132:133], v[110:111], v[138:139]
	v_pk_add_f32 v[110:111], v[110:111], v[138:139] neg_lo:[0,1] neg_hi:[0,1]
	s_nop 0
	v_pk_mul_f32 v[138:139], v[110:111], s[10:11]
	s_nop 0
	v_pk_fma_f32 v[110:111], v[110:111], s[14:15], v[138:139] op_sel:[0,0,1] op_sel_hi:[1,0,0] neg_lo:[1,0,0] neg_hi:[1,0,0]
	v_pk_add_f32 v[138:139], v[118:119], v[140:141]
	v_pk_add_f32 v[118:119], v[118:119], v[140:141] neg_lo:[0,1] neg_hi:[0,1]
	s_nop 0
	v_pk_mul_f32 v[140:141], v[118:119], s[18:19]
	s_nop 0
	v_pk_fma_f32 v[118:119], v[118:119], s[30:31], v[140:141] op_sel:[0,0,1] op_sel_hi:[1,0,0] neg_lo:[1,0,0] neg_hi:[1,0,0]
	v_pk_add_f32 v[140:141], v[24:25], v[14:15] op_sel:[0,1] op_sel_hi:[1,0] neg_hi:[0,1]
	v_pk_add_f32 v[14:15], v[24:25], v[14:15] op_sel:[0,1] op_sel_hi:[1,0] neg_lo:[0,1]
	v_pk_add_f32 v[24:25], v[0:1], v[16:17]
	v_pk_add_f32 v[0:1], v[0:1], v[16:17] neg_lo:[0,1] neg_hi:[0,1]
	s_nop 0
	v_pk_mul_f32 v[16:17], v[0:1], s[18:19]
	s_nop 0
	v_pk_fma_f32 v[0:1], v[0:1], s[30:31], v[16:17] op_sel:[0,0,1] op_sel_hi:[1,0,0]
	v_pk_add_f32 v[16:17], v[2:3], v[18:19]
	v_pk_add_f32 v[2:3], v[2:3], v[18:19] neg_lo:[0,1] neg_hi:[0,1]
	s_nop 0
	v_pk_mul_f32 v[18:19], v[2:3], s[10:11]
	s_nop 0
	v_pk_fma_f32 v[2:3], v[2:3], s[14:15], v[18:19] op_sel:[0,0,1] op_sel_hi:[1,0,0]
	v_pk_add_f32 v[18:19], v[4:5], v[20:21]
	v_pk_add_f32 v[4:5], v[4:5], v[20:21] neg_lo:[0,1] neg_hi:[0,1]
	s_nop 0
	v_pk_mul_f32 v[20:21], v[4:5], s[34:35]
	s_nop 0
	v_pk_fma_f32 v[4:5], v[4:5], s[8:9], v[20:21] op_sel:[0,0,1] op_sel_hi:[1,0,0]
	v_pk_add_f32 v[20:21], v[6:7], v[22:23]
	v_pk_add_f32 v[6:7], v[6:7], v[22:23] neg_lo:[0,1] neg_hi:[0,1]
	v_pk_add_f32 v[22:23], v[8:9], v[134:135]
	v_pk_add_f32 v[8:9], v[8:9], v[134:135] neg_lo:[0,1] neg_hi:[0,1]
	s_nop 0
	v_pk_mul_f32 v[134:135], v[8:9], s[34:35]
	s_nop 0
	v_pk_fma_f32 v[8:9], v[8:9], s[8:9], v[134:135] op_sel:[0,0,1] op_sel_hi:[1,0,0] neg_lo:[1,0,0] neg_hi:[1,0,0]
	v_pk_add_f32 v[134:135], v[10:11], v[136:137]
	v_pk_add_f32 v[10:11], v[10:11], v[136:137] neg_lo:[0,1] neg_hi:[0,1]
	s_nop 0
	v_pk_mul_f32 v[136:137], v[10:11], s[10:11]
	s_nop 0
	v_pk_fma_f32 v[10:11], v[10:11], s[14:15], v[136:137] op_sel:[0,0,1] op_sel_hi:[1,0,0] neg_lo:[1,0,0] neg_hi:[1,0,0]
	v_pk_add_f32 v[136:137], v[12:13], v[142:143]
	v_pk_add_f32 v[12:13], v[12:13], v[142:143] neg_lo:[0,1] neg_hi:[0,1]
	s_nop 0
	v_pk_mul_f32 v[142:143], v[12:13], s[18:19]
	s_nop 0
	v_pk_fma_f32 v[12:13], v[12:13], s[30:31], v[142:143] op_sel:[0,0,1] op_sel_hi:[1,0,0] neg_lo:[1,0,0] neg_hi:[1,0,0]
	v_pk_add_f32 v[142:143], v[144:145], v[126:127]
	v_pk_add_f32 v[126:127], v[144:145], v[126:127] neg_lo:[0,1] neg_hi:[0,1]
	v_pk_add_f32 v[144:145], v[158:159], v[128:129]
	v_pk_add_f32 v[128:129], v[158:159], v[128:129] neg_lo:[0,1] neg_hi:[0,1]
	s_nop 0
	v_pk_mul_f32 v[158:159], v[128:129], s[10:11]
	s_nop 0
	v_pk_fma_f32 v[128:129], v[128:129], s[14:15], v[158:159] op_sel:[0,0,1] op_sel_hi:[1,0,0]
	v_pk_add_f32 v[158:159], v[130:131], v[132:133]
	v_pk_add_f32 v[130:131], v[130:131], v[132:133] neg_lo:[0,1] neg_hi:[0,1]
	v_pk_add_f32 v[132:133], v[124:125], v[138:139]
	v_pk_add_f32 v[124:125], v[124:125], v[138:139] neg_lo:[0,1] neg_hi:[0,1]
	s_nop 0
	v_pk_mul_f32 v[138:139], v[124:125], s[10:11]
	s_nop 0
	v_pk_fma_f32 v[124:125], v[124:125], s[14:15], v[138:139] op_sel:[0,0,1] op_sel_hi:[1,0,0] neg_lo:[1,0,0] neg_hi:[1,0,0]
	v_pk_add_f32 v[138:139], v[120:121], v[30:31] op_sel:[0,1] op_sel_hi:[1,0] neg_hi:[0,1]
	v_pk_add_f32 v[30:31], v[120:121], v[30:31] op_sel:[0,1] op_sel_hi:[1,0] neg_lo:[0,1]
	v_pk_add_f32 v[120:121], v[122:123], v[102:103]
	v_pk_add_f32 v[102:103], v[122:123], v[102:103] neg_lo:[0,1] neg_hi:[0,1]
	v_pk_add_f32 v[160:161], v[128:129], v[124:125]
	v_pk_mul_f32 v[122:123], v[102:103], s[10:11]
	v_pk_add_f32 v[124:125], v[128:129], v[124:125] neg_lo:[0,1] neg_hi:[0,1]
	v_pk_fma_f32 v[102:103], v[102:103], s[14:15], v[122:123] op_sel:[0,0,1] op_sel_hi:[1,0,0]
	v_pk_add_f32 v[122:123], v[26:27], v[110:111]
	v_pk_add_f32 v[26:27], v[26:27], v[110:111] neg_lo:[0,1] neg_hi:[0,1]
	v_pk_add_f32 v[110:111], v[28:29], v[118:119]
	v_pk_add_f32 v[28:29], v[28:29], v[118:119] neg_lo:[0,1] neg_hi:[0,1]
	s_nop 0
	v_pk_mul_f32 v[118:119], v[28:29], s[10:11]
	v_pk_add_f32 v[166:167], v[120:121], v[110:111]
	v_pk_fma_f32 v[28:29], v[28:29], s[14:15], v[118:119] op_sel:[0,0,1] op_sel_hi:[1,0,0] neg_lo:[1,0,0] neg_hi:[1,0,0]
	v_pk_add_f32 v[118:119], v[140:141], v[20:21]
	v_pk_add_f32 v[20:21], v[140:141], v[20:21] neg_lo:[0,1] neg_hi:[0,1]
	v_pk_add_f32 v[140:141], v[24:25], v[22:23]
	v_pk_add_f32 v[22:23], v[24:25], v[22:23] neg_lo:[0,1] neg_hi:[0,1]
	v_pk_add_f32 v[110:111], v[120:121], v[110:111] neg_lo:[0,1] neg_hi:[0,1]
	v_pk_mul_f32 v[24:25], v[22:23], s[10:11]
	v_pk_add_f32 v[168:169], v[30:31], v[26:27] op_sel:[0,1] op_sel_hi:[1,0] neg_hi:[0,1]
	v_pk_fma_f32 v[22:23], v[22:23], s[14:15], v[24:25] op_sel:[0,0,1] op_sel_hi:[1,0,0]
	v_pk_add_f32 v[24:25], v[16:17], v[134:135]
	v_pk_add_f32 v[16:17], v[16:17], v[134:135] neg_lo:[0,1] neg_hi:[0,1]
	v_pk_add_f32 v[134:135], v[18:19], v[136:137]
	v_pk_add_f32 v[18:19], v[18:19], v[136:137] neg_lo:[0,1] neg_hi:[0,1]
	s_nop 0
	v_pk_mul_f32 v[136:137], v[18:19], s[10:11]
	v_pk_add_f32 v[26:27], v[30:31], v[26:27] op_sel:[0,1] op_sel_hi:[1,0] neg_lo:[0,1]
	v_pk_fma_f32 v[18:19], v[18:19], s[14:15], v[136:137] op_sel:[0,0,1] op_sel_hi:[1,0,0] neg_lo:[1,0,0] neg_hi:[1,0,0]
	v_pk_add_f32 v[136:137], v[14:15], v[6:7] op_sel:[0,1] op_sel_hi:[1,0] neg_hi:[0,1]
	v_pk_add_f32 v[6:7], v[14:15], v[6:7] op_sel:[0,1] op_sel_hi:[1,0] neg_lo:[0,1]
	v_pk_add_f32 v[14:15], v[0:1], v[8:9]
	v_pk_add_f32 v[0:1], v[0:1], v[8:9] neg_lo:[0,1] neg_hi:[0,1]
	v_pk_add_f32 v[30:31], v[102:103], v[28:29]
	v_pk_mul_f32 v[8:9], v[0:1], s[10:11]
	v_pk_add_f32 v[28:29], v[102:103], v[28:29] neg_lo:[0,1] neg_hi:[0,1]
	v_pk_fma_f32 v[0:1], v[0:1], s[14:15], v[8:9] op_sel:[0,0,1] op_sel_hi:[1,0,0]
	v_pk_add_f32 v[8:9], v[2:3], v[10:11]
	v_pk_add_f32 v[2:3], v[2:3], v[10:11] neg_lo:[0,1] neg_hi:[0,1]
	v_pk_add_f32 v[10:11], v[4:5], v[12:13]
	v_pk_add_f32 v[4:5], v[4:5], v[12:13] neg_lo:[0,1] neg_hi:[0,1]
	s_nop 0
	v_pk_mul_f32 v[12:13], v[4:5], s[10:11]
	v_pk_add_f32 v[170:171], v[118:119], v[24:25]
	v_pk_fma_f32 v[4:5], v[4:5], s[14:15], v[12:13] op_sel:[0,0,1] op_sel_hi:[1,0,0] neg_lo:[1,0,0] neg_hi:[1,0,0]
	v_pk_add_f32 v[12:13], v[142:143], v[158:159]
	v_pk_add_f32 v[142:143], v[142:143], v[158:159] neg_lo:[0,1] neg_hi:[0,1]
	v_pk_add_f32 v[158:159], v[144:145], v[132:133]
	v_pk_add_f32 v[132:133], v[144:145], v[132:133] neg_lo:[0,1] neg_hi:[0,1]
	v_pk_add_f32 v[182:183], v[118:119], v[24:25] neg_lo:[0,1] neg_hi:[0,1]
	v_pk_add_f32 v[184:185], v[140:141], v[134:135]
	v_pk_add_f32 v[24:25], v[140:141], v[134:135] neg_lo:[0,1] neg_hi:[0,1]
	v_pk_add_f32 v[140:141], v[20:21], v[16:17] op_sel:[0,1] op_sel_hi:[1,0] neg_hi:[0,1]
	v_pk_add_f32 v[186:187], v[20:21], v[16:17] op_sel:[0,1] op_sel_hi:[1,0] neg_lo:[0,1]
	v_pk_add_f32 v[16:17], v[22:23], v[18:19] neg_lo:[0,1] neg_hi:[0,1]
	v_pk_add_f32 v[192:193], v[136:137], v[8:9]
	v_pk_add_f32 v[194:195], v[136:137], v[8:9] neg_lo:[0,1] neg_hi:[0,1]
	v_pk_add_f32 v[8:9], v[14:15], v[10:11] neg_lo:[0,1] neg_hi:[0,1]
	v_pk_add_f32 v[198:199], v[6:7], v[2:3] op_sel:[0,1] op_sel_hi:[1,0] neg_hi:[0,1]
	v_pk_add_f32 v[200:201], v[6:7], v[2:3] op_sel:[0,1] op_sel_hi:[1,0] neg_lo:[0,1]
	v_pk_add_f32 v[2:3], v[0:1], v[4:5]
	v_pk_add_f32 v[0:1], v[0:1], v[4:5] neg_lo:[0,1] neg_hi:[0,1]
	v_pk_add_f32 v[144:145], v[126:127], v[130:131] op_sel:[0,1] op_sel_hi:[1,0] neg_hi:[0,1]
	v_pk_add_f32 v[130:131], v[126:127], v[130:131] op_sel:[0,1] op_sel_hi:[1,0] neg_lo:[0,1]
	v_pk_mul_f32 v[162:163], v[124:125], s[22:23]
	v_pk_add_f32 v[164:165], v[138:139], v[122:123]
	v_pk_add_f32 v[138:139], v[138:139], v[122:123] neg_lo:[0,1] neg_hi:[0,1]
	v_pk_mul_f32 v[102:103], v[28:29], s[22:23]
	v_pk_mul_f32 v[134:135], v[24:25], s[22:23]
	v_pk_add_f32 v[188:189], v[22:23], v[18:19]
	v_pk_mul_f32 v[190:191], v[16:17], s[22:23]
	v_pk_add_f32 v[136:137], v[14:15], v[10:11]
	v_pk_mul_f32 v[196:197], v[8:9], s[22:23]
	v_pk_mul_f32 v[202:203], v[0:1], s[22:23]
	v_pk_add_f32 v[28:29], v[12:13], v[158:159]
	v_pk_add_f32 v[128:129], v[12:13], v[158:159] neg_lo:[0,1] neg_hi:[0,1]
	v_pk_add_f32 v[24:25], v[142:143], v[132:133] op_sel:[0,1] op_sel_hi:[1,0] neg_hi:[0,1]
	v_pk_add_f32 v[126:127], v[142:143], v[132:133] op_sel:[0,1] op_sel_hi:[1,0] neg_lo:[0,1]
	v_pk_add_f32 v[20:21], v[144:145], v[160:161]
	v_pk_add_f32 v[124:125], v[144:145], v[160:161] neg_lo:[0,1] neg_hi:[0,1]
	v_pk_add_f32 v[16:17], v[130:131], v[162:163] op_sel:[0,1] op_sel_hi:[1,0]
	v_pk_add_f32 v[122:123], v[130:131], v[162:163] op_sel:[0,1] op_sel_hi:[1,0] neg_lo:[0,1] neg_hi:[0,1]
	v_pk_add_f32 v[12:13], v[164:165], v[166:167]
	v_pk_add_f32 v[120:121], v[164:165], v[166:167] neg_lo:[0,1] neg_hi:[0,1]
	v_pk_add_f32 v[8:9], v[138:139], v[110:111] op_sel:[0,1] op_sel_hi:[1,0] neg_hi:[0,1]
	v_pk_add_f32 v[118:119], v[138:139], v[110:111] op_sel:[0,1] op_sel_hi:[1,0] neg_lo:[0,1]
	v_pk_add_f32 v[4:5], v[168:169], v[30:31]
	v_pk_add_f32 v[110:111], v[168:169], v[30:31] neg_lo:[0,1] neg_hi:[0,1]
	v_pk_add_f32 v[0:1], v[26:27], v[102:103] op_sel:[0,1] op_sel_hi:[1,0]
	v_pk_add_f32 v[102:103], v[26:27], v[102:103] op_sel:[0,1] op_sel_hi:[1,0] neg_lo:[0,1] neg_hi:[0,1]
	v_pk_add_f32 v[30:31], v[170:171], v[184:185]
	v_pk_add_f32 v[144:145], v[170:171], v[184:185] neg_lo:[0,1] neg_hi:[0,1]
	v_pk_add_f32 v[26:27], v[182:183], v[134:135] op_sel:[0,1] op_sel_hi:[1,0]
	v_pk_add_f32 v[142:143], v[182:183], v[134:135] op_sel:[0,1] op_sel_hi:[1,0] neg_lo:[0,1] neg_hi:[0,1]
	v_pk_add_f32 v[22:23], v[140:141], v[188:189]
	v_pk_add_f32 v[140:141], v[140:141], v[188:189] neg_lo:[0,1] neg_hi:[0,1]
	v_pk_add_f32 v[18:19], v[186:187], v[190:191] op_sel:[0,1] op_sel_hi:[1,0]
	v_pk_add_f32 v[138:139], v[186:187], v[190:191] op_sel:[0,1] op_sel_hi:[1,0] neg_lo:[0,1] neg_hi:[0,1]
	v_pk_add_f32 v[14:15], v[192:193], v[136:137]
	v_pk_add_f32 v[136:137], v[192:193], v[136:137] neg_lo:[0,1] neg_hi:[0,1]
	v_pk_add_f32 v[10:11], v[194:195], v[196:197] op_sel:[0,1] op_sel_hi:[1,0]
	v_pk_add_f32 v[134:135], v[194:195], v[196:197] op_sel:[0,1] op_sel_hi:[1,0] neg_lo:[0,1] neg_hi:[0,1]
	v_pk_add_f32 v[6:7], v[198:199], v[2:3]
	v_pk_add_f32 v[132:133], v[198:199], v[2:3] neg_lo:[0,1] neg_hi:[0,1]
	v_pk_add_f32 v[2:3], v[200:201], v[202:203] op_sel:[0,1] op_sel_hi:[1,0]
	v_pk_add_f32 v[130:131], v[200:201], v[202:203] op_sel:[0,1] op_sel_hi:[1,0] neg_lo:[0,1] neg_hi:[0,1]

.LBB0_438:
	s_or_b64 exec, exec, s[0:1]
	v_mov_b32_e32 v47, v32
	s_waitcnt lgkmcnt(0)
	s_barrier
	s_mov_b32 s11, s14
	v_and_b32_e32 v81, 31, v47
	v_cvt_f32_ubyte0_e32 v24, v81
	v_mul_f32_e32 v110, 0x3b000000, v24
	v_sin_f32_e32 v24, v110
	v_ashrrev_i32_e32 v0, 4, v47
	v_lshlrev_b32_e32 v0, 3, v0
	v_lshlrev_b32_e32 v1, 3, v47
	v_cos_f32_e32 v110, v110
	v_add3_u32 v25, 0, v0, v1
	ds_read_b64 v[0:1], v25
	ds_read_b64 v[2:3], v25 offset:4352
	ds_read_b64 v[4:5], v25 offset:8704
	ds_read_b64 v[6:7], v25 offset:13056
	ds_read_b64 v[8:9], v25 offset:17408
	ds_read_b64 v[10:11], v25 offset:21760
	ds_read_b64 v[12:13], v25 offset:26112
	ds_read_b64 v[14:15], v25 offset:30464
	ds_read_b64 v[16:17], v25 offset:34816
	ds_read_b64 v[18:19], v25 offset:39168
	ds_read_b64 v[20:21], v25 offset:43520
	ds_read_b64 v[22:23], v25 offset:47872
	v_xor_b32_e32 v111, 0x80000000, v24
	s_waitcnt lgkmcnt(10)
	v_pk_mul_f32 v[118:119], v[2:3], v[24:25] op_sel:[1,0] op_sel_hi:[0,0] neg_hi:[0,1]
	v_pk_fma_f32 v[2:3], v[2:3], v[110:111], v[118:119] op_sel_hi:[1,0,1]
	v_pk_mul_f32 v[118:119], v[24:25], v[110:111] op_sel:[0,1] op_sel_hi:[0,0] neg_hi:[1,0]
	v_pk_fma_f32 v[118:119], v[110:111], v[110:111], v[118:119] op_sel_hi:[0,1,1]
	ds_read_b64 v[26:27], v25 offset:52224
	ds_read_b64 v[28:29], v25 offset:56576
	ds_read_b64 v[30:31], v25 offset:60928
	ds_read_b64 v[102:103], v25 offset:65280
	s_waitcnt lgkmcnt(13)
	v_pk_mul_f32 v[120:121], v[4:5], v[118:119] op_sel:[1,1] op_sel_hi:[0,1] neg_lo:[0,1]
	v_pk_fma_f32 v[4:5], v[4:5], v[118:119], v[120:121] op_sel_hi:[1,0,1]
	v_pk_mul_f32 v[120:121], v[24:25], v[118:119] op_sel:[0,1] op_sel_hi:[0,0] neg_hi:[1,0]
	v_pk_fma_f32 v[118:119], v[110:111], v[118:119], v[120:121] op_sel_hi:[0,1,1]
	s_mov_b32 s35, s30
	s_waitcnt lgkmcnt(12)
	v_pk_mul_f32 v[120:121], v[6:7], v[118:119] op_sel:[1,1] op_sel_hi:[0,1] neg_lo:[0,1]
	v_pk_fma_f32 v[6:7], v[6:7], v[118:119], v[120:121] op_sel_hi:[1,0,1]
	v_pk_mul_f32 v[120:121], v[24:25], v[118:119] op_sel:[0,1] op_sel_hi:[0,0] neg_hi:[1,0]
	v_pk_fma_f32 v[118:119], v[110:111], v[118:119], v[120:121] op_sel_hi:[0,1,1]
	s_mov_b32 s0, s19
	s_waitcnt lgkmcnt(11)
	v_pk_mul_f32 v[120:121], v[8:9], v[118:119] op_sel:[1,1] op_sel_hi:[0,1] neg_lo:[0,1]
	v_pk_fma_f32 v[8:9], v[8:9], v[118:119], v[120:121] op_sel_hi:[1,0,1]
	v_pk_mul_f32 v[120:121], v[24:25], v[118:119] op_sel:[0,1] op_sel_hi:[0,0] neg_hi:[1,0]
	v_pk_fma_f32 v[118:119], v[110:111], v[118:119], v[120:121] op_sel_hi:[0,1,1]
	s_waitcnt lgkmcnt(0)
	v_pk_mul_f32 v[120:121], v[10:11], v[118:119] op_sel:[1,1] op_sel_hi:[0,1] neg_lo:[0,1]
	v_pk_fma_f32 v[10:11], v[10:11], v[118:119], v[120:121] op_sel_hi:[1,0,1]
	v_pk_mul_f32 v[120:121], v[24:25], v[118:119] op_sel:[0,1] op_sel_hi:[0,0] neg_hi:[1,0]
	v_pk_fma_f32 v[118:119], v[110:111], v[118:119], v[120:121] op_sel_hi:[0,1,1]
	s_barrier
	v_pk_mul_f32 v[120:121], v[12:13], v[118:119] op_sel:[1,1] op_sel_hi:[0,1] neg_lo:[0,1]
	v_pk_fma_f32 v[12:13], v[12:13], v[118:119], v[120:121] op_sel_hi:[1,0,1]
	v_pk_mul_f32 v[120:121], v[24:25], v[118:119] op_sel:[0,1] op_sel_hi:[0,0] neg_hi:[1,0]
	v_pk_fma_f32 v[118:119], v[110:111], v[118:119], v[120:121] op_sel_hi:[0,1,1]
	s_nop 0
	v_pk_mul_f32 v[120:121], v[14:15], v[118:119] op_sel:[1,1] op_sel_hi:[0,1] neg_lo:[0,1]
	v_pk_fma_f32 v[14:15], v[14:15], v[118:119], v[120:121] op_sel_hi:[1,0,1]
	v_pk_mul_f32 v[120:121], v[24:25], v[118:119] op_sel:[0,1] op_sel_hi:[0,0] neg_hi:[1,0]
	v_pk_fma_f32 v[118:119], v[110:111], v[118:119], v[120:121] op_sel_hi:[0,1,1]
	s_nop 0
	v_pk_mul_f32 v[120:121], v[16:17], v[118:119] op_sel:[1,1] op_sel_hi:[0,1] neg_lo:[0,1]
	v_pk_fma_f32 v[16:17], v[16:17], v[118:119], v[120:121] op_sel_hi:[1,0,1]
	v_pk_mul_f32 v[120:121], v[24:25], v[118:119] op_sel:[0,1] op_sel_hi:[0,0] neg_hi:[1,0]
	v_pk_fma_f32 v[118:119], v[110:111], v[118:119], v[120:121] op_sel_hi:[0,1,1]
	s_nop 0
	v_pk_mul_f32 v[120:121], v[18:19], v[118:119] op_sel:[1,1] op_sel_hi:[0,1] neg_lo:[0,1]
	v_pk_fma_f32 v[18:19], v[18:19], v[118:119], v[120:121] op_sel_hi:[1,0,1]
	v_pk_mul_f32 v[120:121], v[24:25], v[118:119] op_sel:[0,1] op_sel_hi:[0,0] neg_hi:[1,0]
	v_pk_fma_f32 v[118:119], v[110:111], v[118:119], v[120:121] op_sel_hi:[0,1,1]
	s_nop 0
	v_pk_mul_f32 v[120:121], v[20:21], v[118:119] op_sel:[1,1] op_sel_hi:[0,1] neg_lo:[0,1]
	v_pk_fma_f32 v[20:21], v[20:21], v[118:119], v[120:121] op_sel_hi:[1,0,1]
	v_pk_mul_f32 v[120:121], v[24:25], v[118:119] op_sel:[0,1] op_sel_hi:[0,0] neg_hi:[1,0]
	v_pk_fma_f32 v[118:119], v[110:111], v[118:119], v[120:121] op_sel_hi:[0,1,1]
	s_nop 0
	v_pk_mul_f32 v[120:121], v[22:23], v[118:119] op_sel:[1,1] op_sel_hi:[0,1] neg_lo:[0,1]
	v_pk_fma_f32 v[22:23], v[22:23], v[118:119], v[120:121] op_sel_hi:[1,0,1]
	v_pk_mul_f32 v[120:121], v[24:25], v[118:119] op_sel:[0,1] op_sel_hi:[0,0] neg_hi:[1,0]
	v_pk_fma_f32 v[118:119], v[110:111], v[118:119], v[120:121] op_sel_hi:[0,1,1]
	s_nop 0
	v_pk_mul_f32 v[120:121], v[26:27], v[118:119] op_sel:[1,1] op_sel_hi:[0,1] neg_lo:[0,1]
	v_pk_fma_f32 v[26:27], v[26:27], v[118:119], v[120:121] op_sel_hi:[1,0,1]
	v_pk_mul_f32 v[120:121], v[24:25], v[118:119] op_sel:[0,1] op_sel_hi:[0,0] neg_hi:[1,0]
	v_pk_fma_f32 v[118:119], v[110:111], v[118:119], v[120:121] op_sel_hi:[0,1,1]
	s_nop 0
	v_pk_mul_f32 v[120:121], v[28:29], v[118:119] op_sel:[1,1] op_sel_hi:[0,1] neg_lo:[0,1]
	v_pk_fma_f32 v[28:29], v[28:29], v[118:119], v[120:121] op_sel_hi:[1,0,1]
	v_pk_mul_f32 v[120:121], v[24:25], v[118:119] op_sel:[0,1] op_sel_hi:[0,0] neg_hi:[1,0]
	v_pk_fma_f32 v[118:119], v[110:111], v[118:119], v[120:121] op_sel_hi:[0,1,1]
	v_pk_mul_f32 v[24:25], v[24:25], v[118:119] op_sel:[0,1] op_sel_hi:[0,0] neg_hi:[1,0]
	v_pk_fma_f32 v[24:25], v[110:111], v[118:119], v[24:25] op_sel_hi:[0,1,1]
	v_pk_mul_f32 v[110:111], v[102:103], v[24:25] op_sel:[1,1] op_sel_hi:[0,1] neg_lo:[0,1]
	v_pk_fma_f32 v[24:25], v[102:103], v[24:25], v[110:111] op_sel_hi:[1,0,1]
	v_pk_add_f32 v[102:103], v[0:1], v[16:17]
	v_pk_add_f32 v[0:1], v[0:1], v[16:17] neg_lo:[0,1] neg_hi:[0,1]
	v_pk_add_f32 v[16:17], v[2:3], v[18:19]
	v_pk_add_f32 v[2:3], v[2:3], v[18:19] neg_lo:[0,1] neg_hi:[0,1]
	v_pk_mul_f32 v[120:121], v[30:31], v[118:119] op_sel:[1,1] op_sel_hi:[0,1] neg_lo:[0,1]
	v_pk_mul_f32 v[18:19], v[2:3], s[18:19]
	v_pk_fma_f32 v[30:31], v[30:31], v[118:119], v[120:121] op_sel_hi:[1,0,1]
	v_pk_fma_f32 v[2:3], v[2:3], s[30:31], v[18:19] op_sel:[0,0,1] op_sel_hi:[1,0,0]
	v_pk_add_f32 v[18:19], v[4:5], v[20:21]
	v_pk_add_f32 v[4:5], v[4:5], v[20:21] neg_lo:[0,1] neg_hi:[0,1]
	s_nop 0
	v_pk_mul_f32 v[20:21], v[4:5], s[10:11]
	s_nop 0
	v_pk_fma_f32 v[4:5], v[4:5], s[14:15], v[20:21] op_sel:[0,0,1] op_sel_hi:[1,0,0]
	v_pk_add_f32 v[20:21], v[6:7], v[22:23]
	v_pk_add_f32 v[6:7], v[6:7], v[22:23] neg_lo:[0,1] neg_hi:[0,1]
	s_nop 0
	v_pk_mul_f32 v[22:23], v[6:7], s[34:35]
	s_nop 0
	v_pk_fma_f32 v[6:7], v[6:7], s[0:1], v[22:23] op_sel:[0,0,1] op_sel_hi:[1,0,0]
	v_pk_add_f32 v[22:23], v[8:9], v[26:27]
	v_pk_add_f32 v[8:9], v[8:9], v[26:27] neg_lo:[0,1] neg_hi:[0,1]
	v_pk_add_f32 v[26:27], v[10:11], v[28:29]
	v_pk_add_f32 v[10:11], v[10:11], v[28:29] neg_lo:[0,1] neg_hi:[0,1]
	s_nop 0
	v_pk_mul_f32 v[28:29], v[10:11], s[34:35]
	s_nop 0
	v_pk_fma_f32 v[10:11], v[10:11], s[0:1], v[28:29] op_sel:[0,0,1] op_sel_hi:[1,0,0] neg_lo:[1,0,0] neg_hi:[1,0,0]
	v_pk_add_f32 v[28:29], v[12:13], v[30:31]
	v_pk_add_f32 v[12:13], v[12:13], v[30:31] neg_lo:[0,1] neg_hi:[0,1]
	s_nop 0
	v_pk_mul_f32 v[30:31], v[12:13], s[10:11]
	s_nop 0
	v_pk_fma_f32 v[12:13], v[12:13], s[14:15], v[30:31] op_sel:[0,0,1] op_sel_hi:[1,0,0] neg_lo:[1,0,0] neg_hi:[1,0,0]
	v_pk_add_f32 v[30:31], v[14:15], v[24:25]
	v_pk_add_f32 v[14:15], v[14:15], v[24:25] neg_lo:[0,1] neg_hi:[0,1]
	s_nop 0
	v_pk_mul_f32 v[24:25], v[14:15], s[18:19]
	s_nop 0
	v_pk_fma_f32 v[14:15], v[14:15], s[30:31], v[24:25] op_sel:[0,0,1] op_sel_hi:[1,0,0] neg_lo:[1,0,0] neg_hi:[1,0,0]
	v_pk_add_f32 v[24:25], v[102:103], v[22:23]
	v_pk_add_f32 v[22:23], v[102:103], v[22:23] neg_lo:[0,1] neg_hi:[0,1]
	v_pk_add_f32 v[102:103], v[16:17], v[26:27]
	v_pk_add_f32 v[16:17], v[16:17], v[26:27] neg_lo:[0,1] neg_hi:[0,1]
	s_nop 0
	v_pk_mul_f32 v[26:27], v[16:17], s[10:11]
	s_nop 0
	v_pk_fma_f32 v[16:17], v[16:17], s[14:15], v[26:27] op_sel:[0,0,1] op_sel_hi:[1,0,0]
	v_pk_add_f32 v[26:27], v[18:19], v[28:29]
	v_pk_add_f32 v[18:19], v[18:19], v[28:29] neg_lo:[0,1] neg_hi:[0,1]
	v_pk_add_f32 v[28:29], v[20:21], v[30:31]
	v_pk_add_f32 v[20:21], v[20:21], v[30:31] neg_lo:[0,1] neg_hi:[0,1]
	s_nop 0
	v_pk_mul_f32 v[30:31], v[20:21], s[10:11]
	s_nop 0
	v_pk_fma_f32 v[20:21], v[20:21], s[14:15], v[30:31] op_sel:[0,0,1] op_sel_hi:[1,0,0] neg_lo:[1,0,0] neg_hi:[1,0,0]
	v_pk_add_f32 v[30:31], v[0:1], v[8:9] op_sel:[0,1] op_sel_hi:[1,0] neg_hi:[0,1]
	v_pk_add_f32 v[0:1], v[0:1], v[8:9] op_sel:[0,1] op_sel_hi:[1,0] neg_lo:[0,1]
	v_pk_add_f32 v[8:9], v[2:3], v[10:11]
	v_pk_add_f32 v[2:3], v[2:3], v[10:11] neg_lo:[0,1] neg_hi:[0,1]
	s_nop 0
	v_pk_mul_f32 v[10:11], v[2:3], s[10:11]
	s_nop 0
	v_pk_fma_f32 v[2:3], v[2:3], s[14:15], v[10:11] op_sel:[0,0,1] op_sel_hi:[1,0,0]
	v_pk_add_f32 v[10:11], v[4:5], v[12:13]
	v_pk_add_f32 v[4:5], v[4:5], v[12:13] neg_lo:[0,1] neg_hi:[0,1]
	v_pk_add_f32 v[12:13], v[6:7], v[14:15]
	v_pk_add_f32 v[6:7], v[6:7], v[14:15] neg_lo:[0,1] neg_hi:[0,1]
	s_nop 0
	v_pk_mul_f32 v[14:15], v[6:7], s[10:11]
	s_nop 0
	v_pk_fma_f32 v[6:7], v[6:7], s[14:15], v[14:15] op_sel:[0,0,1] op_sel_hi:[1,0,0] neg_lo:[1,0,0] neg_hi:[1,0,0]
	v_pk_add_f32 v[14:15], v[24:25], v[26:27]
	v_pk_add_f32 v[24:25], v[24:25], v[26:27] neg_lo:[0,1] neg_hi:[0,1]
	v_pk_add_f32 v[26:27], v[102:103], v[28:29]
	v_pk_add_f32 v[28:29], v[102:103], v[28:29] neg_lo:[0,1] neg_hi:[0,1]
	v_pk_add_f32 v[102:103], v[22:23], v[18:19] op_sel:[0,1] op_sel_hi:[1,0] neg_hi:[0,1]
	v_pk_add_f32 v[18:19], v[22:23], v[18:19] op_sel:[0,1] op_sel_hi:[1,0] neg_lo:[0,1]
	v_pk_add_f32 v[22:23], v[16:17], v[20:21]
	v_pk_add_f32 v[16:17], v[16:17], v[20:21] neg_lo:[0,1] neg_hi:[0,1]
	v_pk_add_f32 v[20:21], v[30:31], v[10:11]
	v_pk_add_f32 v[10:11], v[30:31], v[10:11] neg_lo:[0,1] neg_hi:[0,1]
	v_pk_add_f32 v[30:31], v[8:9], v[12:13]
	v_pk_add_f32 v[8:9], v[8:9], v[12:13] neg_lo:[0,1] neg_hi:[0,1]
	v_pk_add_f32 v[12:13], v[0:1], v[4:5] op_sel:[0,1] op_sel_hi:[1,0] neg_hi:[0,1]
	v_pk_add_f32 v[0:1], v[0:1], v[4:5] op_sel:[0,1] op_sel_hi:[1,0] neg_lo:[0,1]
	v_pk_add_f32 v[4:5], v[2:3], v[6:7]
	v_pk_add_f32 v[2:3], v[2:3], v[6:7] neg_lo:[0,1] neg_hi:[0,1]
	s_nop 0
	v_pk_mul_f32 v[2:3], v[2:3], s[22:23]
	v_pk_add_f32 v[6:7], v[14:15], v[26:27]
	v_pk_add_f32 v[14:15], v[14:15], v[26:27] neg_lo:[0,1] neg_hi:[0,1]
	v_pk_add_f32 v[26:27], v[24:25], v[28:29] op_sel:[0,1] op_sel_hi:[1,0] neg_hi:[0,1]
	v_pk_add_f32 v[24:25], v[24:25], v[28:29] op_sel:[0,1] op_sel_hi:[1,0] neg_lo:[0,1]
	v_pk_add_f32 v[28:29], v[102:103], v[22:23]
	v_pk_add_f32 v[22:23], v[102:103], v[22:23] neg_lo:[0,1] neg_hi:[0,1]
	v_pk_add_f32 v[102:103], v[18:19], v[16:17] op_sel:[0,1] op_sel_hi:[1,0] neg_hi:[0,1]
	v_pk_add_f32 v[16:17], v[18:19], v[16:17] op_sel:[0,1] op_sel_hi:[1,0] neg_lo:[0,1]
	v_pk_add_f32 v[18:19], v[20:21], v[30:31]
	v_pk_add_f32 v[20:21], v[20:21], v[30:31] neg_lo:[0,1] neg_hi:[0,1]
	v_pk_add_f32 v[30:31], v[10:11], v[8:9] op_sel:[0,1] op_sel_hi:[1,0] neg_hi:[0,1]
	v_pk_add_f32 v[8:9], v[10:11], v[8:9] op_sel:[0,1] op_sel_hi:[1,0] neg_lo:[0,1]
	v_pk_add_f32 v[10:11], v[12:13], v[4:5]
	v_pk_add_f32 v[4:5], v[12:13], v[4:5] neg_lo:[0,1] neg_hi:[0,1]
	v_pk_add_f32 v[12:13], v[0:1], v[2:3] op_sel:[0,1] op_sel_hi:[1,0]
	v_pk_add_f32 v[0:1], v[0:1], v[2:3] op_sel:[0,1] op_sel_hi:[1,0] neg_lo:[0,1] neg_hi:[0,1]
	v_lshlrev_b32_e32 v2, 4, v47
	v_and_or_b32 v2, v2, s7, v81
	v_ashrrev_i32_e32 v3, 4, v2
	v_lshlrev_b32_e32 v3, 3, v3
	v_lshlrev_b32_e32 v2, 3, v2
	v_add3_u32 v2, 0, v3, v2
	v_add_u32_e32 v3, 0x800, v2
	v_mov_b32_e32 v47, v32
	ds_write2_b64 v2, v[6:7], v[18:19] offset1:34
	ds_write2_b64 v3, v[14:15], v[20:21] offset0:16 offset1:50
	ds_write2_b64 v2, v[26:27], v[30:31] offset0:136 offset1:170
	ds_write2_b64 v3, v[24:25], v[8:9] offset0:152 offset1:186
	ds_write2_b64 v2, v[28:29], v[10:11] offset0:68 offset1:102
	ds_write2_b64 v3, v[22:23], v[4:5] offset0:84 offset1:118
	ds_write2_b64 v2, v[102:103], v[12:13] offset0:204 offset1:238
	ds_write2_b64 v3, v[16:17], v[0:1] offset0:220 offset1:254
	s_waitcnt lgkmcnt(0)
	s_barrier
	s_nop 0
	v_and_b32_e32 v81, 0x1ff, v47
	v_cvt_f32_u32_e32 v24, v81
	v_ashrrev_i32_e32 v0, 4, v47
	v_lshlrev_b32_e32 v0, 3, v0
	v_lshlrev_b32_e32 v1, 3, v47
	v_mul_f32_e32 v110, 0x39000000, v24
	v_sin_f32_e32 v24, v110
	v_cos_f32_e32 v110, v110
	v_add3_u32 v25, 0, v0, v1
	ds_read_b64 v[0:1], v25
	ds_read_b64 v[2:3], v25 offset:4352
	ds_read_b64 v[4:5], v25 offset:8704
	ds_read_b64 v[6:7], v25 offset:13056
	ds_read_b64 v[8:9], v25 offset:17408
	ds_read_b64 v[10:11], v25 offset:21760
	ds_read_b64 v[12:13], v25 offset:26112
	ds_read_b64 v[14:15], v25 offset:30464
	v_xor_b32_e32 v111, 0x80000000, v24
	s_waitcnt lgkmcnt(6)
	v_pk_mul_f32 v[118:119], v[2:3], v[24:25] op_sel:[1,0] op_sel_hi:[0,0] neg_hi:[0,1]
	v_pk_fma_f32 v[2:3], v[2:3], v[110:111], v[118:119] op_sel_hi:[1,0,1]
	v_pk_mul_f32 v[118:119], v[24:25], v[110:111] op_sel:[0,1] op_sel_hi:[0,0] neg_hi:[1,0]
	v_pk_fma_f32 v[118:119], v[110:111], v[110:111], v[118:119] op_sel_hi:[0,1,1]
	ds_read_b64 v[16:17], v25 offset:34816
	ds_read_b64 v[18:19], v25 offset:39168
	ds_read_b64 v[20:21], v25 offset:43520
	ds_read_b64 v[22:23], v25 offset:47872
	s_waitcnt lgkmcnt(9)
	v_pk_mul_f32 v[120:121], v[4:5], v[118:119] op_sel:[1,1] op_sel_hi:[0,1] neg_lo:[0,1]
	v_pk_fma_f32 v[4:5], v[4:5], v[118:119], v[120:121] op_sel_hi:[1,0,1]
	v_pk_mul_f32 v[120:121], v[24:25], v[118:119] op_sel:[0,1] op_sel_hi:[0,0] neg_hi:[1,0]
	v_pk_fma_f32 v[118:119], v[110:111], v[118:119], v[120:121] op_sel_hi:[0,1,1]
	ds_read_b64 v[26:27], v25 offset:52224
	ds_read_b64 v[28:29], v25 offset:56576
	ds_read_b64 v[30:31], v25 offset:60928
	ds_read_b64 v[102:103], v25 offset:65280
	s_waitcnt lgkmcnt(12)
	v_pk_mul_f32 v[120:121], v[6:7], v[118:119] op_sel:[1,1] op_sel_hi:[0,1] neg_lo:[0,1]
	v_pk_fma_f32 v[6:7], v[6:7], v[118:119], v[120:121] op_sel_hi:[1,0,1]
	v_pk_mul_f32 v[120:121], v[24:25], v[118:119] op_sel:[0,1] op_sel_hi:[0,0] neg_hi:[1,0]
	v_pk_fma_f32 v[118:119], v[110:111], v[118:119], v[120:121] op_sel_hi:[0,1,1]
	s_waitcnt lgkmcnt(0)
	v_pk_mul_f32 v[120:121], v[8:9], v[118:119] op_sel:[1,1] op_sel_hi:[0,1] neg_lo:[0,1]
	v_pk_fma_f32 v[8:9], v[8:9], v[118:119], v[120:121] op_sel_hi:[1,0,1]
	v_pk_mul_f32 v[120:121], v[24:25], v[118:119] op_sel:[0,1] op_sel_hi:[0,0] neg_hi:[1,0]
	v_pk_fma_f32 v[118:119], v[110:111], v[118:119], v[120:121] op_sel_hi:[0,1,1]
	s_barrier
	v_pk_mul_f32 v[120:121], v[10:11], v[118:119] op_sel:[1,1] op_sel_hi:[0,1] neg_lo:[0,1]
	v_pk_fma_f32 v[10:11], v[10:11], v[118:119], v[120:121] op_sel_hi:[1,0,1]
	v_pk_mul_f32 v[120:121], v[24:25], v[118:119] op_sel:[0,1] op_sel_hi:[0,0] neg_hi:[1,0]
	v_pk_fma_f32 v[118:119], v[110:111], v[118:119], v[120:121] op_sel_hi:[0,1,1]
	s_nop 0
	v_pk_mul_f32 v[120:121], v[12:13], v[118:119] op_sel:[1,1] op_sel_hi:[0,1] neg_lo:[0,1]
	v_pk_fma_f32 v[12:13], v[12:13], v[118:119], v[120:121] op_sel_hi:[1,0,1]
	v_pk_mul_f32 v[120:121], v[24:25], v[118:119] op_sel:[0,1] op_sel_hi:[0,0] neg_hi:[1,0]
	v_pk_fma_f32 v[118:119], v[110:111], v[118:119], v[120:121] op_sel_hi:[0,1,1]
	s_nop 0
	v_pk_mul_f32 v[120:121], v[14:15], v[118:119] op_sel:[1,1] op_sel_hi:[0,1] neg_lo:[0,1]
	v_pk_fma_f32 v[14:15], v[14:15], v[118:119], v[120:121] op_sel_hi:[1,0,1]
	v_pk_mul_f32 v[120:121], v[24:25], v[118:119] op_sel:[0,1] op_sel_hi:[0,0] neg_hi:[1,0]
	v_pk_fma_f32 v[118:119], v[110:111], v[118:119], v[120:121] op_sel_hi:[0,1,1]
	s_nop 0
	v_pk_mul_f32 v[120:121], v[16:17], v[118:119] op_sel:[1,1] op_sel_hi:[0,1] neg_lo:[0,1]
	v_pk_fma_f32 v[16:17], v[16:17], v[118:119], v[120:121] op_sel_hi:[1,0,1]
	v_pk_mul_f32 v[120:121], v[24:25], v[118:119] op_sel:[0,1] op_sel_hi:[0,0] neg_hi:[1,0]
	v_pk_fma_f32 v[118:119], v[110:111], v[118:119], v[120:121] op_sel_hi:[0,1,1]
	s_nop 0
	v_pk_mul_f32 v[120:121], v[18:19], v[118:119] op_sel:[1,1] op_sel_hi:[0,1] neg_lo:[0,1]
	v_pk_fma_f32 v[18:19], v[18:19], v[118:119], v[120:121] op_sel_hi:[1,0,1]
	v_pk_mul_f32 v[120:121], v[24:25], v[118:119] op_sel:[0,1] op_sel_hi:[0,0] neg_hi:[1,0]
	v_pk_fma_f32 v[118:119], v[110:111], v[118:119], v[120:121] op_sel_hi:[0,1,1]
	s_nop 0
	v_pk_mul_f32 v[120:121], v[20:21], v[118:119] op_sel:[1,1] op_sel_hi:[0,1] neg_lo:[0,1]
	v_pk_fma_f32 v[20:21], v[20:21], v[118:119], v[120:121] op_sel_hi:[1,0,1]
	v_pk_mul_f32 v[120:121], v[24:25], v[118:119] op_sel:[0,1] op_sel_hi:[0,0] neg_hi:[1,0]
	v_pk_fma_f32 v[118:119], v[110:111], v[118:119], v[120:121] op_sel_hi:[0,1,1]
	s_nop 0
	v_pk_mul_f32 v[120:121], v[22:23], v[118:119] op_sel:[1,1] op_sel_hi:[0,1] neg_lo:[0,1]
	v_pk_fma_f32 v[22:23], v[22:23], v[118:119], v[120:121] op_sel_hi:[1,0,1]
	v_pk_mul_f32 v[120:121], v[24:25], v[118:119] op_sel:[0,1] op_sel_hi:[0,0] neg_hi:[1,0]
	v_pk_fma_f32 v[118:119], v[110:111], v[118:119], v[120:121] op_sel_hi:[0,1,1]
	s_nop 0
	v_pk_mul_f32 v[120:121], v[26:27], v[118:119] op_sel:[1,1] op_sel_hi:[0,1] neg_lo:[0,1]
	v_pk_fma_f32 v[26:27], v[26:27], v[118:119], v[120:121] op_sel_hi:[1,0,1]
	v_pk_mul_f32 v[120:121], v[24:25], v[118:119] op_sel:[0,1] op_sel_hi:[0,0] neg_hi:[1,0]
	v_pk_fma_f32 v[118:119], v[110:111], v[118:119], v[120:121] op_sel_hi:[0,1,1]
	s_nop 0
	v_pk_mul_f32 v[120:121], v[28:29], v[118:119] op_sel:[1,1] op_sel_hi:[0,1] neg_lo:[0,1]
	v_pk_fma_f32 v[28:29], v[28:29], v[118:119], v[120:121] op_sel_hi:[1,0,1]
	v_pk_mul_f32 v[120:121], v[24:25], v[118:119] op_sel:[0,1] op_sel_hi:[0,0] neg_hi:[1,0]
	v_pk_fma_f32 v[118:119], v[110:111], v[118:119], v[120:121] op_sel_hi:[0,1,1]
	v_pk_mul_f32 v[24:25], v[24:25], v[118:119] op_sel:[0,1] op_sel_hi:[0,0] neg_hi:[1,0]
	v_pk_fma_f32 v[24:25], v[110:111], v[118:119], v[24:25] op_sel_hi:[0,1,1]
	v_pk_mul_f32 v[110:111], v[102:103], v[24:25] op_sel:[1,1] op_sel_hi:[0,1] neg_lo:[0,1]
	v_pk_fma_f32 v[24:25], v[102:103], v[24:25], v[110:111] op_sel_hi:[1,0,1]
	v_pk_add_f32 v[102:103], v[0:1], v[16:17]
	v_pk_add_f32 v[0:1], v[0:1], v[16:17] neg_lo:[0,1] neg_hi:[0,1]
	v_pk_add_f32 v[16:17], v[2:3], v[18:19]
	v_pk_add_f32 v[2:3], v[2:3], v[18:19] neg_lo:[0,1] neg_hi:[0,1]
	v_pk_mul_f32 v[120:121], v[30:31], v[118:119] op_sel:[1,1] op_sel_hi:[0,1] neg_lo:[0,1]
	v_pk_mul_f32 v[18:19], v[2:3], s[18:19]
	v_pk_fma_f32 v[30:31], v[30:31], v[118:119], v[120:121] op_sel_hi:[1,0,1]
	v_pk_fma_f32 v[2:3], v[2:3], s[30:31], v[18:19] op_sel:[0,0,1] op_sel_hi:[1,0,0]
	v_pk_add_f32 v[18:19], v[4:5], v[20:21]
	v_pk_add_f32 v[4:5], v[4:5], v[20:21] neg_lo:[0,1] neg_hi:[0,1]
	s_nop 0
	v_pk_mul_f32 v[20:21], v[4:5], s[10:11]
	s_nop 0
	v_pk_fma_f32 v[4:5], v[4:5], s[14:15], v[20:21] op_sel:[0,0,1] op_sel_hi:[1,0,0]
	v_pk_add_f32 v[20:21], v[6:7], v[22:23]
	v_pk_add_f32 v[6:7], v[6:7], v[22:23] neg_lo:[0,1] neg_hi:[0,1]
	s_nop 0
	v_pk_mul_f32 v[22:23], v[6:7], s[34:35]
	s_nop 0
	v_pk_fma_f32 v[6:7], v[6:7], s[0:1], v[22:23] op_sel:[0,0,1] op_sel_hi:[1,0,0]
	v_pk_add_f32 v[22:23], v[8:9], v[26:27]
	v_pk_add_f32 v[8:9], v[8:9], v[26:27] neg_lo:[0,1] neg_hi:[0,1]
	v_pk_add_f32 v[26:27], v[10:11], v[28:29]
	v_pk_add_f32 v[10:11], v[10:11], v[28:29] neg_lo:[0,1] neg_hi:[0,1]
	s_nop 0
	v_pk_mul_f32 v[28:29], v[10:11], s[34:35]
	s_nop 0
	v_pk_fma_f32 v[10:11], v[10:11], s[0:1], v[28:29] op_sel:[0,0,1] op_sel_hi:[1,0,0] neg_lo:[1,0,0] neg_hi:[1,0,0]
	v_pk_add_f32 v[28:29], v[12:13], v[30:31]
	v_pk_add_f32 v[12:13], v[12:13], v[30:31] neg_lo:[0,1] neg_hi:[0,1]
	s_nop 0
	v_pk_mul_f32 v[30:31], v[12:13], s[10:11]
	s_nop 0
	v_pk_fma_f32 v[12:13], v[12:13], s[14:15], v[30:31] op_sel:[0,0,1] op_sel_hi:[1,0,0] neg_lo:[1,0,0] neg_hi:[1,0,0]
	v_pk_add_f32 v[30:31], v[14:15], v[24:25]
	v_pk_add_f32 v[14:15], v[14:15], v[24:25] neg_lo:[0,1] neg_hi:[0,1]
	s_nop 0
	v_pk_mul_f32 v[24:25], v[14:15], s[18:19]
	s_nop 0
	v_pk_fma_f32 v[14:15], v[14:15], s[30:31], v[24:25] op_sel:[0,0,1] op_sel_hi:[1,0,0] neg_lo:[1,0,0] neg_hi:[1,0,0]
	v_pk_add_f32 v[24:25], v[102:103], v[22:23]
	v_pk_add_f32 v[22:23], v[102:103], v[22:23] neg_lo:[0,1] neg_hi:[0,1]
	v_pk_add_f32 v[102:103], v[16:17], v[26:27]
	v_pk_add_f32 v[16:17], v[16:17], v[26:27] neg_lo:[0,1] neg_hi:[0,1]
	s_nop 0
	v_pk_mul_f32 v[26:27], v[16:17], s[10:11]
	s_nop 0
	v_pk_fma_f32 v[16:17], v[16:17], s[14:15], v[26:27] op_sel:[0,0,1] op_sel_hi:[1,0,0]
	v_pk_add_f32 v[26:27], v[18:19], v[28:29]
	v_pk_add_f32 v[18:19], v[18:19], v[28:29] neg_lo:[0,1] neg_hi:[0,1]
	v_pk_add_f32 v[28:29], v[20:21], v[30:31]
	v_pk_add_f32 v[20:21], v[20:21], v[30:31] neg_lo:[0,1] neg_hi:[0,1]
	s_nop 0
	v_pk_mul_f32 v[30:31], v[20:21], s[10:11]
	s_nop 0
	v_pk_fma_f32 v[20:21], v[20:21], s[14:15], v[30:31] op_sel:[0,0,1] op_sel_hi:[1,0,0] neg_lo:[1,0,0] neg_hi:[1,0,0]
	v_pk_add_f32 v[30:31], v[0:1], v[8:9] op_sel:[0,1] op_sel_hi:[1,0] neg_hi:[0,1]
	v_pk_add_f32 v[0:1], v[0:1], v[8:9] op_sel:[0,1] op_sel_hi:[1,0] neg_lo:[0,1]
	v_pk_add_f32 v[8:9], v[2:3], v[10:11]
	v_pk_add_f32 v[2:3], v[2:3], v[10:11] neg_lo:[0,1] neg_hi:[0,1]
	s_nop 0
	v_pk_mul_f32 v[10:11], v[2:3], s[10:11]
	s_nop 0
	v_pk_fma_f32 v[2:3], v[2:3], s[14:15], v[10:11] op_sel:[0,0,1] op_sel_hi:[1,0,0]
	v_pk_add_f32 v[10:11], v[4:5], v[12:13]
	v_pk_add_f32 v[4:5], v[4:5], v[12:13] neg_lo:[0,1] neg_hi:[0,1]
	v_pk_add_f32 v[12:13], v[6:7], v[14:15]
	v_pk_add_f32 v[6:7], v[6:7], v[14:15] neg_lo:[0,1] neg_hi:[0,1]
	s_nop 0
	v_pk_mul_f32 v[14:15], v[6:7], s[10:11]
	s_nop 0
	v_pk_fma_f32 v[6:7], v[6:7], s[14:15], v[14:15] op_sel:[0,0,1] op_sel_hi:[1,0,0] neg_lo:[1,0,0] neg_hi:[1,0,0]
	v_pk_add_f32 v[14:15], v[24:25], v[26:27]
	v_pk_add_f32 v[24:25], v[24:25], v[26:27] neg_lo:[0,1] neg_hi:[0,1]
	v_pk_add_f32 v[26:27], v[102:103], v[28:29]
	v_pk_add_f32 v[28:29], v[102:103], v[28:29] neg_lo:[0,1] neg_hi:[0,1]
	v_pk_add_f32 v[102:103], v[22:23], v[18:19] op_sel:[0,1] op_sel_hi:[1,0] neg_hi:[0,1]
	v_pk_add_f32 v[18:19], v[22:23], v[18:19] op_sel:[0,1] op_sel_hi:[1,0] neg_lo:[0,1]
	v_pk_add_f32 v[22:23], v[16:17], v[20:21]
	v_pk_add_f32 v[16:17], v[16:17], v[20:21] neg_lo:[0,1] neg_hi:[0,1]
	v_pk_add_f32 v[20:21], v[30:31], v[10:11]
	v_pk_add_f32 v[10:11], v[30:31], v[10:11] neg_lo:[0,1] neg_hi:[0,1]
	v_pk_add_f32 v[30:31], v[8:9], v[12:13]
	v_pk_add_f32 v[8:9], v[8:9], v[12:13] neg_lo:[0,1] neg_hi:[0,1]
	v_pk_add_f32 v[12:13], v[0:1], v[4:5] op_sel:[0,1] op_sel_hi:[1,0] neg_hi:[0,1]
	v_pk_add_f32 v[0:1], v[0:1], v[4:5] op_sel:[0,1] op_sel_hi:[1,0] neg_lo:[0,1]
	v_pk_add_f32 v[4:5], v[2:3], v[6:7]
	v_pk_add_f32 v[2:3], v[2:3], v[6:7] neg_lo:[0,1] neg_hi:[0,1]
	s_nop 0
	v_pk_mul_f32 v[2:3], v[2:3], s[22:23]
	v_pk_add_f32 v[6:7], v[14:15], v[26:27]
	v_pk_add_f32 v[14:15], v[14:15], v[26:27] neg_lo:[0,1] neg_hi:[0,1]
	v_pk_add_f32 v[26:27], v[24:25], v[28:29] op_sel:[0,1] op_sel_hi:[1,0] neg_hi:[0,1]
	v_pk_add_f32 v[24:25], v[24:25], v[28:29] op_sel:[0,1] op_sel_hi:[1,0] neg_lo:[0,1]
	v_pk_add_f32 v[28:29], v[102:103], v[22:23]
	v_pk_add_f32 v[22:23], v[102:103], v[22:23] neg_lo:[0,1] neg_hi:[0,1]
	v_pk_add_f32 v[102:103], v[18:19], v[16:17] op_sel:[0,1] op_sel_hi:[1,0] neg_hi:[0,1]
	v_pk_add_f32 v[16:17], v[18:19], v[16:17] op_sel:[0,1] op_sel_hi:[1,0] neg_lo:[0,1]
	v_pk_add_f32 v[18:19], v[20:21], v[30:31]
	v_pk_add_f32 v[20:21], v[20:21], v[30:31] neg_lo:[0,1] neg_hi:[0,1]
	v_pk_add_f32 v[30:31], v[10:11], v[8:9] op_sel:[0,1] op_sel_hi:[1,0] neg_hi:[0,1]
	v_pk_add_f32 v[8:9], v[10:11], v[8:9] op_sel:[0,1] op_sel_hi:[1,0] neg_lo:[0,1]
	v_pk_add_f32 v[10:11], v[12:13], v[4:5]
	v_pk_add_f32 v[4:5], v[12:13], v[4:5] neg_lo:[0,1] neg_hi:[0,1]
	v_pk_add_f32 v[12:13], v[0:1], v[2:3] op_sel:[0,1] op_sel_hi:[1,0]
	v_pk_add_f32 v[0:1], v[0:1], v[2:3] op_sel:[0,1] op_sel_hi:[1,0] neg_lo:[0,1] neg_hi:[0,1]
	v_lshlrev_b32_e32 v2, 4, v47
	v_and_or_b32 v2, v2, s15, v81
	v_ashrrev_i32_e32 v3, 4, v2
	v_lshlrev_b32_e32 v3, 3, v3
	v_lshlrev_b32_e32 v2, 3, v2
	v_add3_u32 v2, 0, v3, v2
	ds_write_b64 v2, v[6:7]
	ds_write_b64 v2, v[14:15] offset:34816
	ds_write_b64 v2, v[26:27] offset:17408
	ds_write_b64 v2, v[24:25] offset:52224
	ds_write_b64 v2, v[28:29] offset:8704
	ds_write_b64 v2, v[22:23] offset:43520
	ds_write_b64 v2, v[102:103] offset:26112
	ds_write_b64 v2, v[16:17] offset:60928
	ds_write_b64 v2, v[18:19] offset:4352
	ds_write_b64 v2, v[20:21] offset:39168
	ds_write_b64 v2, v[30:31] offset:21760
	ds_write_b64 v2, v[8:9] offset:56576
	ds_write_b64 v2, v[10:11] offset:13056
	ds_write_b64 v2, v[4:5] offset:47872
	ds_write_b64 v2, v[12:13] offset:30464
	ds_write_b64 v2, v[0:1] offset:65280
	s_waitcnt lgkmcnt(0)
	s_barrier
	s_and_saveexec_b64 s[0:1], s[42:43]
	s_cbranch_execz .LBB0_448
	v_lshl_add_u64 v[2:3], v[78:79], 0, v[172:173]
	s_mov_b64 s[4:5], 0x40000
	v_lshl_add_u64 v[0:1], v[2:3], 0, s[4:5]
	v_add_co_u32_e32 v2, vcc, 0x40000, v2
	v_cmp_ne_u32_e64 s[44:45], 0, v39
	s_nop 0
	v_addc_co_u32_e32 v3, vcc, 0, v3, vcc
	global_load_dwordx4 v[12:15], v[2:3], off
	global_load_dwordx4 v[8:11], v[0:1], off offset:16
	v_mov_b32_e32 v19, 0
	v_mov_b32_e32 v18, 0
	s_and_saveexec_b64 s[4:5], s[44:45]
	s_cbranch_execz .LBB0_441
	global_load_ushort v2, v[0:1], off offset:-2
	s_waitcnt vmcnt(0)
	v_lshlrev_b32_e32 v18, 16, v2

.LBB0_480:
	s_or_b64 exec, exec, s[0:1]
	s_barrier
	ds_write2_b64 v152, v[110:111], v[102:103] offset1:1
	ds_write2_b64 v152, v[94:95], v[88:89] offset0:2 offset1:3
	ds_write2_b64 v152, v[112:113], v[104:105] offset0:4 offset1:5
	ds_write2_b64 v152, v[96:97], v[90:91] offset0:6 offset1:7
	ds_write2_b64 v152, v[114:115], v[106:107] offset0:8 offset1:9
	ds_write2_b64 v152, v[98:99], v[92:93] offset0:10 offset1:11
	ds_write2_b64 v152, v[116:117], v[108:109] offset0:12 offset1:13
	ds_write2_b64 v152, v[100:101], v[86:87] offset0:14 offset1:15
	s_waitcnt lgkmcnt(0)
	s_barrier
	s_and_saveexec_b64 s[0:1], s[40:41]
	s_cbranch_execz .LBB0_482
	ds_read_b64 v[0:1], v37 offset:2176
	ds_read_b64 v[2:3], v37 offset:4352
	ds_read_b64 v[4:5], v37 offset:6528
	ds_read_b64 v[6:7], v37 offset:8704
	ds_read_b64 v[8:9], v37 offset:10880
	ds_read_b64 v[10:11], v37 offset:13056
	ds_read_b64 v[12:13], v37 offset:15232
	ds_read_b64 v[14:15], v37 offset:17408
	ds_read_b64 v[16:17], v37 offset:19584
	ds_read_b64 v[18:19], v37 offset:21760
	ds_read_b64 v[20:21], v37 offset:23936
	ds_read_b64 v[22:23], v37 offset:26112
	ds_read_b64 v[24:25], v37 offset:34816
	ds_read_b64 v[26:27], v37 offset:36992
	ds_read_b64 v[28:29], v37 offset:39168
	ds_read_b64 v[30:31], v37 offset:41344
	ds_read_b64 v[82:83], v37 offset:43520
	ds_read_b64 v[84:85], v37 offset:45696
	ds_read_b64 v[118:119], v37 offset:47872
	ds_read_b64 v[120:121], v37 offset:50048
	ds_read_b64 v[122:123], v37 offset:52224
	ds_read_b64 v[124:125], v37 offset:54400
	ds_read_b64 v[126:127], v37 offset:56576
	ds_read_b64 v[128:129], v37 offset:58752
	ds_read_b64 v[130:131], v37
	ds_read_b64 v[132:133], v37 offset:60928
	ds_read_b64 v[134:135], v37 offset:63104
	ds_read_b64 v[136:137], v37 offset:65280
	s_mov_b32 s11, s14
	s_waitcnt lgkmcnt(3)
	v_pk_add_f32 v[158:159], v[130:131], v[24:25]
	v_pk_add_f32 v[24:25], v[130:131], v[24:25] neg_lo:[0,1] neg_hi:[0,1]
	v_pk_add_f32 v[130:131], v[0:1], v[26:27]
	v_pk_add_f32 v[0:1], v[0:1], v[26:27] neg_lo:[0,1] neg_hi:[0,1]
	s_mov_b32 s13, s86
	v_pk_mul_f32 v[26:27], v[0:1], s[16:17]
	s_mov_b32 s4, s21
	v_pk_fma_f32 v[0:1], v[0:1], s[6:7], v[26:27] op_sel:[0,0,1] op_sel_hi:[1,0,0]
	v_pk_add_f32 v[26:27], v[2:3], v[28:29]
	v_pk_add_f32 v[2:3], v[2:3], v[28:29] neg_lo:[0,1] neg_hi:[0,1]
	s_mov_b32 s35, s30
	v_pk_mul_f32 v[28:29], v[2:3], s[18:19]
	s_mov_b32 s8, s19
	v_pk_fma_f32 v[2:3], v[2:3], s[30:31], v[28:29] op_sel:[0,0,1] op_sel_hi:[1,0,0]
	v_pk_add_f32 v[28:29], v[4:5], v[30:31]
	v_pk_add_f32 v[4:5], v[4:5], v[30:31] neg_lo:[0,1] neg_hi:[0,1]
	s_mov_b32 s77, s6
	v_pk_mul_f32 v[30:31], v[4:5], s[20:21]
	s_mov_b32 s28, s17
	v_pk_fma_f32 v[4:5], v[4:5], s[86:87], v[30:31] op_sel:[0,0,1] op_sel_hi:[1,0,0]
	v_pk_add_f32 v[30:31], v[6:7], v[82:83]
	v_pk_add_f32 v[6:7], v[6:7], v[82:83] neg_lo:[0,1] neg_hi:[0,1]
	v_add_u32_e32 v47, 0x10780, v37
	v_pk_mul_f32 v[82:83], v[6:7], s[10:11]
	ds_read_b64 v[138:139], v37 offset:28288
	ds_read_b64 v[140:141], v37 offset:30464
	ds_read_b64 v[142:143], v37 offset:32640
	ds_read_b64 v[144:145], v47
	v_pk_fma_f32 v[6:7], v[6:7], s[14:15], v[82:83] op_sel:[0,0,1] op_sel_hi:[1,0,0]
	v_pk_add_f32 v[82:83], v[8:9], v[84:85]
	v_pk_add_f32 v[8:9], v[8:9], v[84:85] neg_lo:[0,1] neg_hi:[0,1]
	s_nop 0
	v_pk_mul_f32 v[84:85], v[8:9], s[12:13]
	s_nop 0
	v_pk_fma_f32 v[8:9], v[8:9], s[4:5], v[84:85] op_sel:[0,0,1] op_sel_hi:[1,0,0]
	v_pk_add_f32 v[84:85], v[10:11], v[118:119]
	v_pk_add_f32 v[10:11], v[10:11], v[118:119] neg_lo:[0,1] neg_hi:[0,1]
	s_nop 0
	v_pk_mul_f32 v[118:119], v[10:11], s[34:35]
	s_nop 0
	v_pk_fma_f32 v[10:11], v[10:11], s[8:9], v[118:119] op_sel:[0,0,1] op_sel_hi:[1,0,0]
	v_pk_add_f32 v[118:119], v[12:13], v[120:121]
	v_pk_add_f32 v[12:13], v[12:13], v[120:121] neg_lo:[0,1] neg_hi:[0,1]
	s_nop 0
	v_pk_mul_f32 v[120:121], v[12:13], s[76:77]
	s_nop 0
	v_pk_fma_f32 v[12:13], v[12:13], s[28:29], v[120:121] op_sel:[0,0,1] op_sel_hi:[1,0,0]
	v_pk_add_f32 v[120:121], v[14:15], v[122:123]
	v_pk_add_f32 v[14:15], v[14:15], v[122:123] neg_lo:[0,1] neg_hi:[0,1]
	v_pk_add_f32 v[122:123], v[16:17], v[124:125]
	v_pk_add_f32 v[16:17], v[16:17], v[124:125] neg_lo:[0,1] neg_hi:[0,1]
	s_nop 0
	v_pk_mul_f32 v[124:125], v[16:17], s[76:77]
	s_nop 0
	v_pk_fma_f32 v[16:17], v[16:17], s[28:29], v[124:125] op_sel:[0,0,1] op_sel_hi:[1,0,0] neg_lo:[1,0,0] neg_hi:[1,0,0]
	v_pk_add_f32 v[124:125], v[18:19], v[126:127]
	v_pk_add_f32 v[18:19], v[18:19], v[126:127] neg_lo:[0,1] neg_hi:[0,1]
	s_nop 0
	v_pk_mul_f32 v[126:127], v[18:19], s[34:35]
	s_nop 0
	v_pk_fma_f32 v[18:19], v[18:19], s[8:9], v[126:127] op_sel:[0,0,1] op_sel_hi:[1,0,0] neg_lo:[1,0,0] neg_hi:[1,0,0]
	v_pk_add_f32 v[126:127], v[20:21], v[128:129]
	v_pk_add_f32 v[20:21], v[20:21], v[128:129] neg_lo:[0,1] neg_hi:[0,1]
	s_nop 0
	v_pk_mul_f32 v[128:129], v[20:21], s[12:13]
	s_nop 0
	v_pk_fma_f32 v[20:21], v[20:21], s[4:5], v[128:129] op_sel:[0,0,1] op_sel_hi:[1,0,0] neg_lo:[1,0,0] neg_hi:[1,0,0]
	s_waitcnt lgkmcnt(6)
	v_pk_add_f32 v[128:129], v[22:23], v[132:133]
	v_pk_add_f32 v[22:23], v[22:23], v[132:133] neg_lo:[0,1] neg_hi:[0,1]
	s_nop 0
	v_pk_mul_f32 v[132:133], v[22:23], s[10:11]
	s_nop 0
	v_pk_fma_f32 v[22:23], v[22:23], s[14:15], v[132:133] op_sel:[0,0,1] op_sel_hi:[1,0,0] neg_lo:[1,0,0] neg_hi:[1,0,0]
	s_waitcnt lgkmcnt(3)
	v_pk_add_f32 v[132:133], v[138:139], v[134:135]
	v_pk_add_f32 v[134:135], v[138:139], v[134:135] neg_lo:[0,1] neg_hi:[0,1]
	s_nop 0
	v_pk_mul_f32 v[138:139], v[134:135], s[20:21]
	s_nop 0
	v_pk_fma_f32 v[134:135], v[134:135], s[86:87], v[138:139] op_sel:[0,0,1] op_sel_hi:[1,0,0] neg_lo:[1,0,0] neg_hi:[1,0,0]
	s_waitcnt lgkmcnt(2)
	v_pk_add_f32 v[138:139], v[140:141], v[136:137]
	v_pk_add_f32 v[136:137], v[140:141], v[136:137] neg_lo:[0,1] neg_hi:[0,1]
	s_nop 0
	v_pk_mul_f32 v[140:141], v[136:137], s[18:19]
	s_nop 0
	v_pk_fma_f32 v[136:137], v[136:137], s[30:31], v[140:141] op_sel:[0,0,1] op_sel_hi:[1,0,0] neg_lo:[1,0,0] neg_hi:[1,0,0]
	s_waitcnt lgkmcnt(0)
	v_pk_add_f32 v[140:141], v[142:143], v[144:145]
	v_pk_add_f32 v[142:143], v[142:143], v[144:145] neg_lo:[0,1] neg_hi:[0,1]
	s_nop 0
	v_pk_mul_f32 v[144:145], v[142:143], s[16:17]
	s_nop 0
	v_pk_fma_f32 v[142:143], v[142:143], s[6:7], v[144:145] op_sel:[0,0,1] op_sel_hi:[1,0,0] neg_lo:[1,0,0] neg_hi:[1,0,0]
	v_pk_add_f32 v[144:145], v[158:159], v[120:121]
	v_pk_add_f32 v[120:121], v[158:159], v[120:121] neg_lo:[0,1] neg_hi:[0,1]
	v_pk_add_f32 v[158:159], v[130:131], v[122:123]
	v_pk_add_f32 v[122:123], v[130:131], v[122:123] neg_lo:[0,1] neg_hi:[0,1]
	s_nop 0
	v_pk_mul_f32 v[130:131], v[122:123], s[18:19]
	s_nop 0
	v_pk_fma_f32 v[122:123], v[122:123], s[30:31], v[130:131] op_sel:[0,0,1] op_sel_hi:[1,0,0]
	v_pk_add_f32 v[130:131], v[26:27], v[124:125]
	v_pk_add_f32 v[26:27], v[26:27], v[124:125] neg_lo:[0,1] neg_hi:[0,1]
	s_nop 0
	v_pk_mul_f32 v[124:125], v[26:27], s[10:11]
	s_nop 0
	v_pk_fma_f32 v[26:27], v[26:27], s[14:15], v[124:125] op_sel:[0,0,1] op_sel_hi:[1,0,0]
	v_pk_add_f32 v[124:125], v[28:29], v[126:127]
	v_pk_add_f32 v[28:29], v[28:29], v[126:127] neg_lo:[0,1] neg_hi:[0,1]
	s_nop 0
	v_pk_mul_f32 v[126:127], v[28:29], s[34:35]
	s_nop 0
	v_pk_fma_f32 v[28:29], v[28:29], s[8:9], v[126:127] op_sel:[0,0,1] op_sel_hi:[1,0,0]
	v_pk_add_f32 v[126:127], v[30:31], v[128:129]
	v_pk_add_f32 v[30:31], v[30:31], v[128:129] neg_lo:[0,1] neg_hi:[0,1]
	v_pk_add_f32 v[128:129], v[82:83], v[132:133]
	v_pk_add_f32 v[82:83], v[82:83], v[132:133] neg_lo:[0,1] neg_hi:[0,1]
	s_nop 0
	v_pk_mul_f32 v[132:133], v[82:83], s[34:35]
	s_nop 0
	v_pk_fma_f32 v[82:83], v[82:83], s[8:9], v[132:133] op_sel:[0,0,1] op_sel_hi:[1,0,0] neg_lo:[1,0,0] neg_hi:[1,0,0]
	v_pk_add_f32 v[132:133], v[84:85], v[138:139]
	v_pk_add_f32 v[84:85], v[84:85], v[138:139] neg_lo:[0,1] neg_hi:[0,1]
	s_nop 0
	v_pk_mul_f32 v[138:139], v[84:85], s[10:11]
	s_nop 0
	v_pk_fma_f32 v[84:85], v[84:85], s[14:15], v[138:139] op_sel:[0,0,1] op_sel_hi:[1,0,0] neg_lo:[1,0,0] neg_hi:[1,0,0]
	v_pk_add_f32 v[138:139], v[118:119], v[140:141]
	v_pk_add_f32 v[118:119], v[118:119], v[140:141] neg_lo:[0,1] neg_hi:[0,1]
	s_nop 0
	v_pk_mul_f32 v[140:141], v[118:119], s[18:19]
	s_nop 0
	v_pk_fma_f32 v[118:119], v[118:119], s[30:31], v[140:141] op_sel:[0,0,1] op_sel_hi:[1,0,0] neg_lo:[1,0,0] neg_hi:[1,0,0]
	v_pk_add_f32 v[140:141], v[24:25], v[14:15] op_sel:[0,1] op_sel_hi:[1,0] neg_hi:[0,1]
	v_pk_add_f32 v[14:15], v[24:25], v[14:15] op_sel:[0,1] op_sel_hi:[1,0] neg_lo:[0,1]
	v_pk_add_f32 v[24:25], v[0:1], v[16:17]
	v_pk_add_f32 v[0:1], v[0:1], v[16:17] neg_lo:[0,1] neg_hi:[0,1]
	s_nop 0
	v_pk_mul_f32 v[16:17], v[0:1], s[18:19]
	s_nop 0
	v_pk_fma_f32 v[0:1], v[0:1], s[30:31], v[16:17] op_sel:[0,0,1] op_sel_hi:[1,0,0]
	v_pk_add_f32 v[16:17], v[2:3], v[18:19]
	v_pk_add_f32 v[2:3], v[2:3], v[18:19] neg_lo:[0,1] neg_hi:[0,1]
	s_nop 0
	v_pk_mul_f32 v[18:19], v[2:3], s[10:11]
	s_nop 0
	v_pk_fma_f32 v[2:3], v[2:3], s[14:15], v[18:19] op_sel:[0,0,1] op_sel_hi:[1,0,0]
	v_pk_add_f32 v[18:19], v[4:5], v[20:21]
	v_pk_add_f32 v[4:5], v[4:5], v[20:21] neg_lo:[0,1] neg_hi:[0,1]
	s_nop 0
	v_pk_mul_f32 v[20:21], v[4:5], s[34:35]
	s_nop 0
	v_pk_fma_f32 v[4:5], v[4:5], s[8:9], v[20:21] op_sel:[0,0,1] op_sel_hi:[1,0,0]
	v_pk_add_f32 v[20:21], v[6:7], v[22:23]
	v_pk_add_f32 v[6:7], v[6:7], v[22:23] neg_lo:[0,1] neg_hi:[0,1]
	v_pk_add_f32 v[22:23], v[8:9], v[134:135]
	v_pk_add_f32 v[8:9], v[8:9], v[134:135] neg_lo:[0,1] neg_hi:[0,1]
	s_nop 0
	v_pk_mul_f32 v[134:135], v[8:9], s[34:35]
	s_nop 0
	v_pk_fma_f32 v[8:9], v[8:9], s[8:9], v[134:135] op_sel:[0,0,1] op_sel_hi:[1,0,0] neg_lo:[1,0,0] neg_hi:[1,0,0]
	v_pk_add_f32 v[134:135], v[10:11], v[136:137]
	v_pk_add_f32 v[10:11], v[10:11], v[136:137] neg_lo:[0,1] neg_hi:[0,1]
	s_nop 0
	v_pk_mul_f32 v[136:137], v[10:11], s[10:11]
	s_nop 0
	v_pk_fma_f32 v[10:11], v[10:11], s[14:15], v[136:137] op_sel:[0,0,1] op_sel_hi:[1,0,0] neg_lo:[1,0,0] neg_hi:[1,0,0]
	v_pk_add_f32 v[136:137], v[12:13], v[142:143]
	v_pk_add_f32 v[12:13], v[12:13], v[142:143] neg_lo:[0,1] neg_hi:[0,1]
	s_nop 0
	v_pk_mul_f32 v[142:143], v[12:13], s[18:19]
	s_nop 0
	v_pk_fma_f32 v[12:13], v[12:13], s[30:31], v[142:143] op_sel:[0,0,1] op_sel_hi:[1,0,0] neg_lo:[1,0,0] neg_hi:[1,0,0]
	v_pk_add_f32 v[142:143], v[144:145], v[126:127]
	v_pk_add_f32 v[126:127], v[144:145], v[126:127] neg_lo:[0,1] neg_hi:[0,1]
	v_pk_add_f32 v[144:145], v[158:159], v[128:129]
	v_pk_add_f32 v[128:129], v[158:159], v[128:129] neg_lo:[0,1] neg_hi:[0,1]
	s_nop 0
	v_pk_mul_f32 v[158:159], v[128:129], s[10:11]
	s_nop 0
	v_pk_fma_f32 v[128:129], v[128:129], s[14:15], v[158:159] op_sel:[0,0,1] op_sel_hi:[1,0,0]
	v_pk_add_f32 v[158:159], v[130:131], v[132:133]
	v_pk_add_f32 v[130:131], v[130:131], v[132:133] neg_lo:[0,1] neg_hi:[0,1]
	v_pk_add_f32 v[132:133], v[124:125], v[138:139]
	v_pk_add_f32 v[124:125], v[124:125], v[138:139] neg_lo:[0,1] neg_hi:[0,1]
	s_nop 0
	v_pk_mul_f32 v[138:139], v[124:125], s[10:11]
	s_nop 0
	v_pk_fma_f32 v[124:125], v[124:125], s[14:15], v[138:139] op_sel:[0,0,1] op_sel_hi:[1,0,0] neg_lo:[1,0,0] neg_hi:[1,0,0]
	v_pk_add_f32 v[138:139], v[120:121], v[30:31] op_sel:[0,1] op_sel_hi:[1,0] neg_hi:[0,1]
	v_pk_add_f32 v[30:31], v[120:121], v[30:31] op_sel:[0,1] op_sel_hi:[1,0] neg_lo:[0,1]
	v_pk_add_f32 v[120:121], v[122:123], v[82:83]
	v_pk_add_f32 v[82:83], v[122:123], v[82:83] neg_lo:[0,1] neg_hi:[0,1]
	v_pk_add_f32 v[160:161], v[128:129], v[124:125]
	v_pk_mul_f32 v[122:123], v[82:83], s[10:11]
	v_pk_add_f32 v[124:125], v[128:129], v[124:125] neg_lo:[0,1] neg_hi:[0,1]
	v_pk_fma_f32 v[82:83], v[82:83], s[14:15], v[122:123] op_sel:[0,0,1] op_sel_hi:[1,0,0]
	v_pk_add_f32 v[122:123], v[26:27], v[84:85]
	v_pk_add_f32 v[26:27], v[26:27], v[84:85] neg_lo:[0,1] neg_hi:[0,1]
	v_pk_add_f32 v[84:85], v[28:29], v[118:119]
	v_pk_add_f32 v[28:29], v[28:29], v[118:119] neg_lo:[0,1] neg_hi:[0,1]
	s_nop 0
	v_pk_mul_f32 v[118:119], v[28:29], s[10:11]
	v_pk_add_f32 v[166:167], v[120:121], v[84:85]
	v_pk_fma_f32 v[28:29], v[28:29], s[14:15], v[118:119] op_sel:[0,0,1] op_sel_hi:[1,0,0] neg_lo:[1,0,0] neg_hi:[1,0,0]
	v_pk_add_f32 v[118:119], v[140:141], v[20:21]
	v_pk_add_f32 v[20:21], v[140:141], v[20:21] neg_lo:[0,1] neg_hi:[0,1]
	v_pk_add_f32 v[140:141], v[24:25], v[22:23]
	v_pk_add_f32 v[22:23], v[24:25], v[22:23] neg_lo:[0,1] neg_hi:[0,1]
	v_pk_add_f32 v[84:85], v[120:121], v[84:85] neg_lo:[0,1] neg_hi:[0,1]
	v_pk_mul_f32 v[24:25], v[22:23], s[10:11]
	v_pk_add_f32 v[168:169], v[30:31], v[26:27] op_sel:[0,1] op_sel_hi:[1,0] neg_hi:[0,1]
	v_pk_fma_f32 v[22:23], v[22:23], s[14:15], v[24:25] op_sel:[0,0,1] op_sel_hi:[1,0,0]
	v_pk_add_f32 v[24:25], v[16:17], v[134:135]
	v_pk_add_f32 v[16:17], v[16:17], v[134:135] neg_lo:[0,1] neg_hi:[0,1]
	v_pk_add_f32 v[134:135], v[18:19], v[136:137]
	v_pk_add_f32 v[18:19], v[18:19], v[136:137] neg_lo:[0,1] neg_hi:[0,1]
	s_nop 0
	v_pk_mul_f32 v[136:137], v[18:19], s[10:11]
	v_pk_add_f32 v[26:27], v[30:31], v[26:27] op_sel:[0,1] op_sel_hi:[1,0] neg_lo:[0,1]
	v_pk_fma_f32 v[18:19], v[18:19], s[14:15], v[136:137] op_sel:[0,0,1] op_sel_hi:[1,0,0] neg_lo:[1,0,0] neg_hi:[1,0,0]
	v_pk_add_f32 v[136:137], v[14:15], v[6:7] op_sel:[0,1] op_sel_hi:[1,0] neg_hi:[0,1]
	v_pk_add_f32 v[6:7], v[14:15], v[6:7] op_sel:[0,1] op_sel_hi:[1,0] neg_lo:[0,1]
	v_pk_add_f32 v[14:15], v[0:1], v[8:9]
	v_pk_add_f32 v[0:1], v[0:1], v[8:9] neg_lo:[0,1] neg_hi:[0,1]
	v_pk_add_f32 v[30:31], v[82:83], v[28:29]
	v_pk_mul_f32 v[8:9], v[0:1], s[10:11]
	v_pk_add_f32 v[28:29], v[82:83], v[28:29] neg_lo:[0,1] neg_hi:[0,1]
	v_pk_fma_f32 v[0:1], v[0:1], s[14:15], v[8:9] op_sel:[0,0,1] op_sel_hi:[1,0,0]
	v_pk_add_f32 v[8:9], v[2:3], v[10:11]
	v_pk_add_f32 v[2:3], v[2:3], v[10:11] neg_lo:[0,1] neg_hi:[0,1]
	v_pk_add_f32 v[10:11], v[4:5], v[12:13]
	v_pk_add_f32 v[4:5], v[4:5], v[12:13] neg_lo:[0,1] neg_hi:[0,1]
	s_nop 0
	v_pk_mul_f32 v[12:13], v[4:5], s[10:11]
	v_pk_add_f32 v[170:171], v[118:119], v[24:25]
	v_pk_fma_f32 v[4:5], v[4:5], s[14:15], v[12:13] op_sel:[0,0,1] op_sel_hi:[1,0,0] neg_lo:[1,0,0] neg_hi:[1,0,0]
	v_pk_add_f32 v[12:13], v[142:143], v[158:159]
	v_pk_add_f32 v[142:143], v[142:143], v[158:159] neg_lo:[0,1] neg_hi:[0,1]
	v_pk_add_f32 v[158:159], v[144:145], v[132:133]
	v_pk_add_f32 v[132:133], v[144:145], v[132:133] neg_lo:[0,1] neg_hi:[0,1]
	v_pk_add_f32 v[182:183], v[118:119], v[24:25] neg_lo:[0,1] neg_hi:[0,1]
	v_pk_add_f32 v[184:185], v[140:141], v[134:135]
	v_pk_add_f32 v[24:25], v[140:141], v[134:135] neg_lo:[0,1] neg_hi:[0,1]
	v_pk_add_f32 v[140:141], v[20:21], v[16:17] op_sel:[0,1] op_sel_hi:[1,0] neg_hi:[0,1]
	v_pk_add_f32 v[186:187], v[20:21], v[16:17] op_sel:[0,1] op_sel_hi:[1,0] neg_lo:[0,1]
	v_pk_add_f32 v[16:17], v[22:23], v[18:19] neg_lo:[0,1] neg_hi:[0,1]
	v_pk_add_f32 v[192:193], v[136:137], v[8:9]
	v_pk_add_f32 v[194:195], v[136:137], v[8:9] neg_lo:[0,1] neg_hi:[0,1]
	v_pk_add_f32 v[8:9], v[14:15], v[10:11] neg_lo:[0,1] neg_hi:[0,1]
	v_pk_add_f32 v[198:199], v[6:7], v[2:3] op_sel:[0,1] op_sel_hi:[1,0] neg_hi:[0,1]
	v_pk_add_f32 v[200:201], v[6:7], v[2:3] op_sel:[0,1] op_sel_hi:[1,0] neg_lo:[0,1]
	v_pk_add_f32 v[2:3], v[0:1], v[4:5]
	v_pk_add_f32 v[0:1], v[0:1], v[4:5] neg_lo:[0,1] neg_hi:[0,1]
	v_pk_add_f32 v[144:145], v[126:127], v[130:131] op_sel:[0,1] op_sel_hi:[1,0] neg_hi:[0,1]
	v_pk_add_f32 v[130:131], v[126:127], v[130:131] op_sel:[0,1] op_sel_hi:[1,0] neg_lo:[0,1]
	v_pk_mul_f32 v[162:163], v[124:125], s[22:23]
	v_pk_add_f32 v[164:165], v[138:139], v[122:123]
	v_pk_add_f32 v[138:139], v[138:139], v[122:123] neg_lo:[0,1] neg_hi:[0,1]
	v_pk_mul_f32 v[82:83], v[28:29], s[22:23]
	v_pk_mul_f32 v[134:135], v[24:25], s[22:23]
	v_pk_add_f32 v[188:189], v[22:23], v[18:19]
	v_pk_mul_f32 v[190:191], v[16:17], s[22:23]
	v_pk_add_f32 v[136:137], v[14:15], v[10:11]
	v_pk_mul_f32 v[196:197], v[8:9], s[22:23]
	v_pk_mul_f32 v[202:203], v[0:1], s[22:23]
	v_pk_add_f32 v[28:29], v[12:13], v[158:159]
	v_pk_add_f32 v[128:129], v[12:13], v[158:159] neg_lo:[0,1] neg_hi:[0,1]
	v_pk_add_f32 v[24:25], v[142:143], v[132:133] op_sel:[0,1] op_sel_hi:[1,0] neg_hi:[0,1]
	v_pk_add_f32 v[126:127], v[142:143], v[132:133] op_sel:[0,1] op_sel_hi:[1,0] neg_lo:[0,1]
	v_pk_add_f32 v[20:21], v[144:145], v[160:161]
	v_pk_add_f32 v[124:125], v[144:145], v[160:161] neg_lo:[0,1] neg_hi:[0,1]
	v_pk_add_f32 v[16:17], v[130:131], v[162:163] op_sel:[0,1] op_sel_hi:[1,0]
	v_pk_add_f32 v[122:123], v[130:131], v[162:163] op_sel:[0,1] op_sel_hi:[1,0] neg_lo:[0,1] neg_hi:[0,1]
	v_pk_add_f32 v[12:13], v[164:165], v[166:167]
	v_pk_add_f32 v[120:121], v[164:165], v[166:167] neg_lo:[0,1] neg_hi:[0,1]
	v_pk_add_f32 v[8:9], v[138:139], v[84:85] op_sel:[0,1] op_sel_hi:[1,0] neg_hi:[0,1]
	v_pk_add_f32 v[118:119], v[138:139], v[84:85] op_sel:[0,1] op_sel_hi:[1,0] neg_lo:[0,1]
	v_pk_add_f32 v[4:5], v[168:169], v[30:31]
	v_pk_add_f32 v[84:85], v[168:169], v[30:31] neg_lo:[0,1] neg_hi:[0,1]
	v_pk_add_f32 v[0:1], v[26:27], v[82:83] op_sel:[0,1] op_sel_hi:[1,0]
	v_pk_add_f32 v[82:83], v[26:27], v[82:83] op_sel:[0,1] op_sel_hi:[1,0] neg_lo:[0,1] neg_hi:[0,1]
	v_pk_add_f32 v[30:31], v[170:171], v[184:185]
	v_pk_add_f32 v[144:145], v[170:171], v[184:185] neg_lo:[0,1] neg_hi:[0,1]
	v_pk_add_f32 v[26:27], v[182:183], v[134:135] op_sel:[0,1] op_sel_hi:[1,0]
	v_pk_add_f32 v[142:143], v[182:183], v[134:135] op_sel:[0,1] op_sel_hi:[1,0] neg_lo:[0,1] neg_hi:[0,1]
	v_pk_add_f32 v[22:23], v[140:141], v[188:189]
	v_pk_add_f32 v[140:141], v[140:141], v[188:189] neg_lo:[0,1] neg_hi:[0,1]
	v_pk_add_f32 v[18:19], v[186:187], v[190:191] op_sel:[0,1] op_sel_hi:[1,0]
	v_pk_add_f32 v[138:139], v[186:187], v[190:191] op_sel:[0,1] op_sel_hi:[1,0] neg_lo:[0,1] neg_hi:[0,1]
	v_pk_add_f32 v[14:15], v[192:193], v[136:137]
	v_pk_add_f32 v[136:137], v[192:193], v[136:137] neg_lo:[0,1] neg_hi:[0,1]
	v_pk_add_f32 v[10:11], v[194:195], v[196:197] op_sel:[0,1] op_sel_hi:[1,0]
	v_pk_add_f32 v[134:135], v[194:195], v[196:197] op_sel:[0,1] op_sel_hi:[1,0] neg_lo:[0,1] neg_hi:[0,1]
	v_pk_add_f32 v[6:7], v[198:199], v[2:3]
	v_pk_add_f32 v[132:133], v[198:199], v[2:3] neg_lo:[0,1] neg_hi:[0,1]
	v_pk_add_f32 v[2:3], v[200:201], v[202:203] op_sel:[0,1] op_sel_hi:[1,0]
	v_pk_add_f32 v[130:131], v[200:201], v[202:203] op_sel:[0,1] op_sel_hi:[1,0] neg_lo:[0,1] neg_hi:[0,1]

.LBB0_484:
	s_or_b64 exec, exec, s[0:1]
	v_mov_b32_e32 v47, v32
	s_waitcnt lgkmcnt(0)
	s_barrier
	s_mov_b32 s11, s14
	v_and_b32_e32 v81, 31, v47
	v_cvt_f32_ubyte0_e32 v24, v81
	v_mul_f32_e32 v84, 0x3b000000, v24
	v_sin_f32_e32 v24, v84
	v_ashrrev_i32_e32 v0, 4, v47
	v_lshlrev_b32_e32 v0, 3, v0
	v_lshlrev_b32_e32 v1, 3, v47
	v_cos_f32_e32 v84, v84
	v_add3_u32 v25, 0, v0, v1
	ds_read_b64 v[0:1], v25
	ds_read_b64 v[2:3], v25 offset:4352
	ds_read_b64 v[4:5], v25 offset:8704
	ds_read_b64 v[6:7], v25 offset:13056
	ds_read_b64 v[8:9], v25 offset:17408
	ds_read_b64 v[10:11], v25 offset:21760
	ds_read_b64 v[12:13], v25 offset:26112
	ds_read_b64 v[14:15], v25 offset:30464
	ds_read_b64 v[16:17], v25 offset:34816
	ds_read_b64 v[18:19], v25 offset:39168
	ds_read_b64 v[20:21], v25 offset:43520
	ds_read_b64 v[22:23], v25 offset:47872
	v_xor_b32_e32 v85, 0x80000000, v24
	s_waitcnt lgkmcnt(10)
	v_pk_mul_f32 v[118:119], v[2:3], v[24:25] op_sel:[1,0] op_sel_hi:[0,0] neg_hi:[0,1]
	v_pk_fma_f32 v[2:3], v[2:3], v[84:85], v[118:119] op_sel_hi:[1,0,1]
	v_pk_mul_f32 v[118:119], v[24:25], v[84:85] op_sel:[0,1] op_sel_hi:[0,0] neg_hi:[1,0]
	v_pk_fma_f32 v[118:119], v[84:85], v[84:85], v[118:119] op_sel_hi:[0,1,1]
	ds_read_b64 v[26:27], v25 offset:52224
	ds_read_b64 v[28:29], v25 offset:56576
	ds_read_b64 v[30:31], v25 offset:60928
	ds_read_b64 v[82:83], v25 offset:65280
	s_waitcnt lgkmcnt(13)
	v_pk_mul_f32 v[120:121], v[4:5], v[118:119] op_sel:[1,1] op_sel_hi:[0,1] neg_lo:[0,1]
	v_pk_fma_f32 v[4:5], v[4:5], v[118:119], v[120:121] op_sel_hi:[1,0,1]
	v_pk_mul_f32 v[120:121], v[24:25], v[118:119] op_sel:[0,1] op_sel_hi:[0,0] neg_hi:[1,0]
	v_pk_fma_f32 v[118:119], v[84:85], v[118:119], v[120:121] op_sel_hi:[0,1,1]
	s_mov_b32 s35, s30
	s_waitcnt lgkmcnt(12)
	v_pk_mul_f32 v[120:121], v[6:7], v[118:119] op_sel:[1,1] op_sel_hi:[0,1] neg_lo:[0,1]
	v_pk_fma_f32 v[6:7], v[6:7], v[118:119], v[120:121] op_sel_hi:[1,0,1]
	v_pk_mul_f32 v[120:121], v[24:25], v[118:119] op_sel:[0,1] op_sel_hi:[0,0] neg_hi:[1,0]
	v_pk_fma_f32 v[118:119], v[84:85], v[118:119], v[120:121] op_sel_hi:[0,1,1]
	s_mov_b32 s0, s19
	s_waitcnt lgkmcnt(11)
	v_pk_mul_f32 v[120:121], v[8:9], v[118:119] op_sel:[1,1] op_sel_hi:[0,1] neg_lo:[0,1]
	v_pk_fma_f32 v[8:9], v[8:9], v[118:119], v[120:121] op_sel_hi:[1,0,1]
	v_pk_mul_f32 v[120:121], v[24:25], v[118:119] op_sel:[0,1] op_sel_hi:[0,0] neg_hi:[1,0]
	v_pk_fma_f32 v[118:119], v[84:85], v[118:119], v[120:121] op_sel_hi:[0,1,1]
	s_waitcnt lgkmcnt(0)
	v_pk_mul_f32 v[120:121], v[10:11], v[118:119] op_sel:[1,1] op_sel_hi:[0,1] neg_lo:[0,1]
	v_pk_fma_f32 v[10:11], v[10:11], v[118:119], v[120:121] op_sel_hi:[1,0,1]
	v_pk_mul_f32 v[120:121], v[24:25], v[118:119] op_sel:[0,1] op_sel_hi:[0,0] neg_hi:[1,0]
	v_pk_fma_f32 v[118:119], v[84:85], v[118:119], v[120:121] op_sel_hi:[0,1,1]
	s_barrier
	v_pk_mul_f32 v[120:121], v[12:13], v[118:119] op_sel:[1,1] op_sel_hi:[0,1] neg_lo:[0,1]
	v_pk_fma_f32 v[12:13], v[12:13], v[118:119], v[120:121] op_sel_hi:[1,0,1]
	v_pk_mul_f32 v[120:121], v[24:25], v[118:119] op_sel:[0,1] op_sel_hi:[0,0] neg_hi:[1,0]
	v_pk_fma_f32 v[118:119], v[84:85], v[118:119], v[120:121] op_sel_hi:[0,1,1]
	s_nop 0
	v_pk_mul_f32 v[120:121], v[14:15], v[118:119] op_sel:[1,1] op_sel_hi:[0,1] neg_lo:[0,1]
	v_pk_fma_f32 v[14:15], v[14:15], v[118:119], v[120:121] op_sel_hi:[1,0,1]
	v_pk_mul_f32 v[120:121], v[24:25], v[118:119] op_sel:[0,1] op_sel_hi:[0,0] neg_hi:[1,0]
	v_pk_fma_f32 v[118:119], v[84:85], v[118:119], v[120:121] op_sel_hi:[0,1,1]
	s_nop 0
	v_pk_mul_f32 v[120:121], v[16:17], v[118:119] op_sel:[1,1] op_sel_hi:[0,1] neg_lo:[0,1]
	v_pk_fma_f32 v[16:17], v[16:17], v[118:119], v[120:121] op_sel_hi:[1,0,1]
	v_pk_mul_f32 v[120:121], v[24:25], v[118:119] op_sel:[0,1] op_sel_hi:[0,0] neg_hi:[1,0]
	v_pk_fma_f32 v[118:119], v[84:85], v[118:119], v[120:121] op_sel_hi:[0,1,1]
	s_nop 0
	v_pk_mul_f32 v[120:121], v[18:19], v[118:119] op_sel:[1,1] op_sel_hi:[0,1] neg_lo:[0,1]
	v_pk_fma_f32 v[18:19], v[18:19], v[118:119], v[120:121] op_sel_hi:[1,0,1]
	v_pk_mul_f32 v[120:121], v[24:25], v[118:119] op_sel:[0,1] op_sel_hi:[0,0] neg_hi:[1,0]
	v_pk_fma_f32 v[118:119], v[84:85], v[118:119], v[120:121] op_sel_hi:[0,1,1]
	s_nop 0
	v_pk_mul_f32 v[120:121], v[20:21], v[118:119] op_sel:[1,1] op_sel_hi:[0,1] neg_lo:[0,1]
	v_pk_fma_f32 v[20:21], v[20:21], v[118:119], v[120:121] op_sel_hi:[1,0,1]
	v_pk_mul_f32 v[120:121], v[24:25], v[118:119] op_sel:[0,1] op_sel_hi:[0,0] neg_hi:[1,0]
	v_pk_fma_f32 v[118:119], v[84:85], v[118:119], v[120:121] op_sel_hi:[0,1,1]
	s_nop 0
	v_pk_mul_f32 v[120:121], v[22:23], v[118:119] op_sel:[1,1] op_sel_hi:[0,1] neg_lo:[0,1]
	v_pk_fma_f32 v[22:23], v[22:23], v[118:119], v[120:121] op_sel_hi:[1,0,1]
	v_pk_mul_f32 v[120:121], v[24:25], v[118:119] op_sel:[0,1] op_sel_hi:[0,0] neg_hi:[1,0]
	v_pk_fma_f32 v[118:119], v[84:85], v[118:119], v[120:121] op_sel_hi:[0,1,1]
	s_nop 0
	v_pk_mul_f32 v[120:121], v[26:27], v[118:119] op_sel:[1,1] op_sel_hi:[0,1] neg_lo:[0,1]
	v_pk_fma_f32 v[26:27], v[26:27], v[118:119], v[120:121] op_sel_hi:[1,0,1]
	v_pk_mul_f32 v[120:121], v[24:25], v[118:119] op_sel:[0,1] op_sel_hi:[0,0] neg_hi:[1,0]
	v_pk_fma_f32 v[118:119], v[84:85], v[118:119], v[120:121] op_sel_hi:[0,1,1]
	s_nop 0
	v_pk_mul_f32 v[120:121], v[28:29], v[118:119] op_sel:[1,1] op_sel_hi:[0,1] neg_lo:[0,1]
	v_pk_fma_f32 v[28:29], v[28:29], v[118:119], v[120:121] op_sel_hi:[1,0,1]
	v_pk_mul_f32 v[120:121], v[24:25], v[118:119] op_sel:[0,1] op_sel_hi:[0,0] neg_hi:[1,0]
	v_pk_fma_f32 v[118:119], v[84:85], v[118:119], v[120:121] op_sel_hi:[0,1,1]
	v_pk_mul_f32 v[24:25], v[24:25], v[118:119] op_sel:[0,1] op_sel_hi:[0,0] neg_hi:[1,0]
	v_pk_fma_f32 v[24:25], v[84:85], v[118:119], v[24:25] op_sel_hi:[0,1,1]
	v_pk_mul_f32 v[84:85], v[82:83], v[24:25] op_sel:[1,1] op_sel_hi:[0,1] neg_lo:[0,1]
	v_pk_fma_f32 v[24:25], v[82:83], v[24:25], v[84:85] op_sel_hi:[1,0,1]
	v_pk_add_f32 v[82:83], v[0:1], v[16:17]
	v_pk_add_f32 v[0:1], v[0:1], v[16:17] neg_lo:[0,1] neg_hi:[0,1]
	v_pk_add_f32 v[16:17], v[2:3], v[18:19]
	v_pk_add_f32 v[2:3], v[2:3], v[18:19] neg_lo:[0,1] neg_hi:[0,1]
	v_pk_mul_f32 v[120:121], v[30:31], v[118:119] op_sel:[1,1] op_sel_hi:[0,1] neg_lo:[0,1]
	v_pk_mul_f32 v[18:19], v[2:3], s[18:19]
	v_pk_fma_f32 v[30:31], v[30:31], v[118:119], v[120:121] op_sel_hi:[1,0,1]
	v_pk_fma_f32 v[2:3], v[2:3], s[30:31], v[18:19] op_sel:[0,0,1] op_sel_hi:[1,0,0]
	v_pk_add_f32 v[18:19], v[4:5], v[20:21]
	v_pk_add_f32 v[4:5], v[4:5], v[20:21] neg_lo:[0,1] neg_hi:[0,1]
	s_nop 0
	v_pk_mul_f32 v[20:21], v[4:5], s[10:11]
	s_nop 0
	v_pk_fma_f32 v[4:5], v[4:5], s[14:15], v[20:21] op_sel:[0,0,1] op_sel_hi:[1,0,0]
	v_pk_add_f32 v[20:21], v[6:7], v[22:23]
	v_pk_add_f32 v[6:7], v[6:7], v[22:23] neg_lo:[0,1] neg_hi:[0,1]
	s_nop 0
	v_pk_mul_f32 v[22:23], v[6:7], s[34:35]
	s_nop 0
	v_pk_fma_f32 v[6:7], v[6:7], s[0:1], v[22:23] op_sel:[0,0,1] op_sel_hi:[1,0,0]
	v_pk_add_f32 v[22:23], v[8:9], v[26:27]
	v_pk_add_f32 v[8:9], v[8:9], v[26:27] neg_lo:[0,1] neg_hi:[0,1]
	v_pk_add_f32 v[26:27], v[10:11], v[28:29]
	v_pk_add_f32 v[10:11], v[10:11], v[28:29] neg_lo:[0,1] neg_hi:[0,1]
	s_nop 0
	v_pk_mul_f32 v[28:29], v[10:11], s[34:35]
	s_nop 0
	v_pk_fma_f32 v[10:11], v[10:11], s[0:1], v[28:29] op_sel:[0,0,1] op_sel_hi:[1,0,0] neg_lo:[1,0,0] neg_hi:[1,0,0]
	v_pk_add_f32 v[28:29], v[12:13], v[30:31]
	v_pk_add_f32 v[12:13], v[12:13], v[30:31] neg_lo:[0,1] neg_hi:[0,1]
	s_nop 0
	v_pk_mul_f32 v[30:31], v[12:13], s[10:11]
	s_nop 0
	v_pk_fma_f32 v[12:13], v[12:13], s[14:15], v[30:31] op_sel:[0,0,1] op_sel_hi:[1,0,0] neg_lo:[1,0,0] neg_hi:[1,0,0]
	v_pk_add_f32 v[30:31], v[14:15], v[24:25]
	v_pk_add_f32 v[14:15], v[14:15], v[24:25] neg_lo:[0,1] neg_hi:[0,1]
	s_nop 0
	v_pk_mul_f32 v[24:25], v[14:15], s[18:19]
	s_nop 0
	v_pk_fma_f32 v[14:15], v[14:15], s[30:31], v[24:25] op_sel:[0,0,1] op_sel_hi:[1,0,0] neg_lo:[1,0,0] neg_hi:[1,0,0]
	v_pk_add_f32 v[24:25], v[82:83], v[22:23]
	v_pk_add_f32 v[22:23], v[82:83], v[22:23] neg_lo:[0,1] neg_hi:[0,1]
	v_pk_add_f32 v[82:83], v[16:17], v[26:27]
	v_pk_add_f32 v[16:17], v[16:17], v[26:27] neg_lo:[0,1] neg_hi:[0,1]
	s_nop 0
	v_pk_mul_f32 v[26:27], v[16:17], s[10:11]
	s_nop 0
	v_pk_fma_f32 v[16:17], v[16:17], s[14:15], v[26:27] op_sel:[0,0,1] op_sel_hi:[1,0,0]
	v_pk_add_f32 v[26:27], v[18:19], v[28:29]
	v_pk_add_f32 v[18:19], v[18:19], v[28:29] neg_lo:[0,1] neg_hi:[0,1]
	v_pk_add_f32 v[28:29], v[20:21], v[30:31]
	v_pk_add_f32 v[20:21], v[20:21], v[30:31] neg_lo:[0,1] neg_hi:[0,1]
	s_nop 0
	v_pk_mul_f32 v[30:31], v[20:21], s[10:11]
	s_nop 0
	v_pk_fma_f32 v[20:21], v[20:21], s[14:15], v[30:31] op_sel:[0,0,1] op_sel_hi:[1,0,0] neg_lo:[1,0,0] neg_hi:[1,0,0]
	v_pk_add_f32 v[30:31], v[0:1], v[8:9] op_sel:[0,1] op_sel_hi:[1,0] neg_hi:[0,1]
	v_pk_add_f32 v[0:1], v[0:1], v[8:9] op_sel:[0,1] op_sel_hi:[1,0] neg_lo:[0,1]
	v_pk_add_f32 v[8:9], v[2:3], v[10:11]
	v_pk_add_f32 v[2:3], v[2:3], v[10:11] neg_lo:[0,1] neg_hi:[0,1]
	s_nop 0
	v_pk_mul_f32 v[10:11], v[2:3], s[10:11]
	s_nop 0
	v_pk_fma_f32 v[2:3], v[2:3], s[14:15], v[10:11] op_sel:[0,0,1] op_sel_hi:[1,0,0]
	v_pk_add_f32 v[10:11], v[4:5], v[12:13]
	v_pk_add_f32 v[4:5], v[4:5], v[12:13] neg_lo:[0,1] neg_hi:[0,1]
	v_pk_add_f32 v[12:13], v[6:7], v[14:15]
	v_pk_add_f32 v[6:7], v[6:7], v[14:15] neg_lo:[0,1] neg_hi:[0,1]
	s_nop 0
	v_pk_mul_f32 v[14:15], v[6:7], s[10:11]
	s_nop 0
	v_pk_fma_f32 v[6:7], v[6:7], s[14:15], v[14:15] op_sel:[0,0,1] op_sel_hi:[1,0,0] neg_lo:[1,0,0] neg_hi:[1,0,0]
	v_pk_add_f32 v[14:15], v[24:25], v[26:27]
	v_pk_add_f32 v[24:25], v[24:25], v[26:27] neg_lo:[0,1] neg_hi:[0,1]
	v_pk_add_f32 v[26:27], v[82:83], v[28:29]
	v_pk_add_f32 v[28:29], v[82:83], v[28:29] neg_lo:[0,1] neg_hi:[0,1]
	v_pk_add_f32 v[82:83], v[22:23], v[18:19] op_sel:[0,1] op_sel_hi:[1,0] neg_hi:[0,1]
	v_pk_add_f32 v[18:19], v[22:23], v[18:19] op_sel:[0,1] op_sel_hi:[1,0] neg_lo:[0,1]
	v_pk_add_f32 v[22:23], v[16:17], v[20:21]
	v_pk_add_f32 v[16:17], v[16:17], v[20:21] neg_lo:[0,1] neg_hi:[0,1]
	v_pk_add_f32 v[20:21], v[30:31], v[10:11]
	v_pk_add_f32 v[10:11], v[30:31], v[10:11] neg_lo:[0,1] neg_hi:[0,1]
	v_pk_add_f32 v[30:31], v[8:9], v[12:13]
	v_pk_add_f32 v[8:9], v[8:9], v[12:13] neg_lo:[0,1] neg_hi:[0,1]
	v_pk_add_f32 v[12:13], v[0:1], v[4:5] op_sel:[0,1] op_sel_hi:[1,0] neg_hi:[0,1]
	v_pk_add_f32 v[0:1], v[0:1], v[4:5] op_sel:[0,1] op_sel_hi:[1,0] neg_lo:[0,1]
	v_pk_add_f32 v[4:5], v[2:3], v[6:7]
	v_pk_add_f32 v[2:3], v[2:3], v[6:7] neg_lo:[0,1] neg_hi:[0,1]
	s_nop 0
	v_pk_mul_f32 v[2:3], v[2:3], s[22:23]
	v_pk_add_f32 v[6:7], v[14:15], v[26:27]
	v_pk_add_f32 v[14:15], v[14:15], v[26:27] neg_lo:[0,1] neg_hi:[0,1]
	v_pk_add_f32 v[26:27], v[24:25], v[28:29] op_sel:[0,1] op_sel_hi:[1,0] neg_hi:[0,1]
	v_pk_add_f32 v[24:25], v[24:25], v[28:29] op_sel:[0,1] op_sel_hi:[1,0] neg_lo:[0,1]
	v_pk_add_f32 v[28:29], v[82:83], v[22:23]
	v_pk_add_f32 v[22:23], v[82:83], v[22:23] neg_lo:[0,1] neg_hi:[0,1]
	v_pk_add_f32 v[82:83], v[18:19], v[16:17] op_sel:[0,1] op_sel_hi:[1,0] neg_hi:[0,1]
	v_pk_add_f32 v[16:17], v[18:19], v[16:17] op_sel:[0,1] op_sel_hi:[1,0] neg_lo:[0,1]
	v_pk_add_f32 v[18:19], v[20:21], v[30:31]
	v_pk_add_f32 v[20:21], v[20:21], v[30:31] neg_lo:[0,1] neg_hi:[0,1]
	v_pk_add_f32 v[30:31], v[10:11], v[8:9] op_sel:[0,1] op_sel_hi:[1,0] neg_hi:[0,1]
	v_pk_add_f32 v[8:9], v[10:11], v[8:9] op_sel:[0,1] op_sel_hi:[1,0] neg_lo:[0,1]
	v_pk_add_f32 v[10:11], v[12:13], v[4:5]
	v_pk_add_f32 v[4:5], v[12:13], v[4:5] neg_lo:[0,1] neg_hi:[0,1]
	v_pk_add_f32 v[12:13], v[0:1], v[2:3] op_sel:[0,1] op_sel_hi:[1,0]
	v_pk_add_f32 v[0:1], v[0:1], v[2:3] op_sel:[0,1] op_sel_hi:[1,0] neg_lo:[0,1] neg_hi:[0,1]
	v_lshlrev_b32_e32 v2, 4, v47
	v_and_or_b32 v2, v2, s7, v81
	v_ashrrev_i32_e32 v3, 4, v2
	v_lshlrev_b32_e32 v3, 3, v3
	v_lshlrev_b32_e32 v2, 3, v2
	v_add3_u32 v2, 0, v3, v2
	v_add_u32_e32 v3, 0x800, v2
	v_mov_b32_e32 v47, v32
	ds_write2_b64 v2, v[6:7], v[18:19] offset1:34
	ds_write2_b64 v3, v[14:15], v[20:21] offset0:16 offset1:50
	ds_write2_b64 v2, v[26:27], v[30:31] offset0:136 offset1:170
	ds_write2_b64 v3, v[24:25], v[8:9] offset0:152 offset1:186
	ds_write2_b64 v2, v[28:29], v[10:11] offset0:68 offset1:102
	ds_write2_b64 v3, v[22:23], v[4:5] offset0:84 offset1:118
	ds_write2_b64 v2, v[82:83], v[12:13] offset0:204 offset1:238
	ds_write2_b64 v3, v[16:17], v[0:1] offset0:220 offset1:254
	s_waitcnt lgkmcnt(0)
	s_barrier
	s_nop 0
	v_and_b32_e32 v81, 0x1ff, v47
	v_cvt_f32_u32_e32 v24, v81
	v_ashrrev_i32_e32 v0, 4, v47
	v_lshlrev_b32_e32 v0, 3, v0
	v_lshlrev_b32_e32 v1, 3, v47
	v_mul_f32_e32 v84, 0x39000000, v24
	v_sin_f32_e32 v24, v84
	v_cos_f32_e32 v84, v84
	v_add3_u32 v25, 0, v0, v1
	ds_read_b64 v[0:1], v25
	ds_read_b64 v[2:3], v25 offset:4352
	ds_read_b64 v[4:5], v25 offset:8704
	ds_read_b64 v[6:7], v25 offset:13056
	ds_read_b64 v[8:9], v25 offset:17408
	ds_read_b64 v[10:11], v25 offset:21760
	ds_read_b64 v[12:13], v25 offset:26112
	ds_read_b64 v[14:15], v25 offset:30464
	v_xor_b32_e32 v85, 0x80000000, v24
	s_waitcnt lgkmcnt(6)
	v_pk_mul_f32 v[118:119], v[2:3], v[24:25] op_sel:[1,0] op_sel_hi:[0,0] neg_hi:[0,1]
	v_pk_fma_f32 v[2:3], v[2:3], v[84:85], v[118:119] op_sel_hi:[1,0,1]
	v_pk_mul_f32 v[118:119], v[24:25], v[84:85] op_sel:[0,1] op_sel_hi:[0,0] neg_hi:[1,0]
	v_pk_fma_f32 v[118:119], v[84:85], v[84:85], v[118:119] op_sel_hi:[0,1,1]
	ds_read_b64 v[16:17], v25 offset:34816
	ds_read_b64 v[18:19], v25 offset:39168
	ds_read_b64 v[20:21], v25 offset:43520
	ds_read_b64 v[22:23], v25 offset:47872
	s_waitcnt lgkmcnt(9)
	v_pk_mul_f32 v[120:121], v[4:5], v[118:119] op_sel:[1,1] op_sel_hi:[0,1] neg_lo:[0,1]
	v_pk_fma_f32 v[4:5], v[4:5], v[118:119], v[120:121] op_sel_hi:[1,0,1]
	v_pk_mul_f32 v[120:121], v[24:25], v[118:119] op_sel:[0,1] op_sel_hi:[0,0] neg_hi:[1,0]
	v_pk_fma_f32 v[118:119], v[84:85], v[118:119], v[120:121] op_sel_hi:[0,1,1]
	ds_read_b64 v[26:27], v25 offset:52224
	ds_read_b64 v[28:29], v25 offset:56576
	ds_read_b64 v[30:31], v25 offset:60928
	ds_read_b64 v[82:83], v25 offset:65280
	s_waitcnt lgkmcnt(12)
	v_pk_mul_f32 v[120:121], v[6:7], v[118:119] op_sel:[1,1] op_sel_hi:[0,1] neg_lo:[0,1]
	v_pk_fma_f32 v[6:7], v[6:7], v[118:119], v[120:121] op_sel_hi:[1,0,1]
	v_pk_mul_f32 v[120:121], v[24:25], v[118:119] op_sel:[0,1] op_sel_hi:[0,0] neg_hi:[1,0]
	v_pk_fma_f32 v[118:119], v[84:85], v[118:119], v[120:121] op_sel_hi:[0,1,1]
	s_waitcnt lgkmcnt(0)
	v_pk_mul_f32 v[120:121], v[8:9], v[118:119] op_sel:[1,1] op_sel_hi:[0,1] neg_lo:[0,1]
	v_pk_fma_f32 v[8:9], v[8:9], v[118:119], v[120:121] op_sel_hi:[1,0,1]
	v_pk_mul_f32 v[120:121], v[24:25], v[118:119] op_sel:[0,1] op_sel_hi:[0,0] neg_hi:[1,0]
	v_pk_fma_f32 v[118:119], v[84:85], v[118:119], v[120:121] op_sel_hi:[0,1,1]
	s_barrier
	v_pk_mul_f32 v[120:121], v[10:11], v[118:119] op_sel:[1,1] op_sel_hi:[0,1] neg_lo:[0,1]
	v_pk_fma_f32 v[10:11], v[10:11], v[118:119], v[120:121] op_sel_hi:[1,0,1]
	v_pk_mul_f32 v[120:121], v[24:25], v[118:119] op_sel:[0,1] op_sel_hi:[0,0] neg_hi:[1,0]
	v_pk_fma_f32 v[118:119], v[84:85], v[118:119], v[120:121] op_sel_hi:[0,1,1]
	s_nop 0
	v_pk_mul_f32 v[120:121], v[12:13], v[118:119] op_sel:[1,1] op_sel_hi:[0,1] neg_lo:[0,1]
	v_pk_fma_f32 v[12:13], v[12:13], v[118:119], v[120:121] op_sel_hi:[1,0,1]
	v_pk_mul_f32 v[120:121], v[24:25], v[118:119] op_sel:[0,1] op_sel_hi:[0,0] neg_hi:[1,0]
	v_pk_fma_f32 v[118:119], v[84:85], v[118:119], v[120:121] op_sel_hi:[0,1,1]
	s_nop 0
	v_pk_mul_f32 v[120:121], v[14:15], v[118:119] op_sel:[1,1] op_sel_hi:[0,1] neg_lo:[0,1]
	v_pk_fma_f32 v[14:15], v[14:15], v[118:119], v[120:121] op_sel_hi:[1,0,1]
	v_pk_mul_f32 v[120:121], v[24:25], v[118:119] op_sel:[0,1] op_sel_hi:[0,0] neg_hi:[1,0]
	v_pk_fma_f32 v[118:119], v[84:85], v[118:119], v[120:121] op_sel_hi:[0,1,1]
	s_nop 0
	v_pk_mul_f32 v[120:121], v[16:17], v[118:119] op_sel:[1,1] op_sel_hi:[0,1] neg_lo:[0,1]
	v_pk_fma_f32 v[16:17], v[16:17], v[118:119], v[120:121] op_sel_hi:[1,0,1]
	v_pk_mul_f32 v[120:121], v[24:25], v[118:119] op_sel:[0,1] op_sel_hi:[0,0] neg_hi:[1,0]
	v_pk_fma_f32 v[118:119], v[84:85], v[118:119], v[120:121] op_sel_hi:[0,1,1]
	s_nop 0
	v_pk_mul_f32 v[120:121], v[18:19], v[118:119] op_sel:[1,1] op_sel_hi:[0,1] neg_lo:[0,1]
	v_pk_fma_f32 v[18:19], v[18:19], v[118:119], v[120:121] op_sel_hi:[1,0,1]
	v_pk_mul_f32 v[120:121], v[24:25], v[118:119] op_sel:[0,1] op_sel_hi:[0,0] neg_hi:[1,0]
	v_pk_fma_f32 v[118:119], v[84:85], v[118:119], v[120:121] op_sel_hi:[0,1,1]
	s_nop 0
	v_pk_mul_f32 v[120:121], v[20:21], v[118:119] op_sel:[1,1] op_sel_hi:[0,1] neg_lo:[0,1]
	v_pk_fma_f32 v[20:21], v[20:21], v[118:119], v[120:121] op_sel_hi:[1,0,1]
	v_pk_mul_f32 v[120:121], v[24:25], v[118:119] op_sel:[0,1] op_sel_hi:[0,0] neg_hi:[1,0]
	v_pk_fma_f32 v[118:119], v[84:85], v[118:119], v[120:121] op_sel_hi:[0,1,1]
	s_nop 0
	v_pk_mul_f32 v[120:121], v[22:23], v[118:119] op_sel:[1,1] op_sel_hi:[0,1] neg_lo:[0,1]
	v_pk_fma_f32 v[22:23], v[22:23], v[118:119], v[120:121] op_sel_hi:[1,0,1]
	v_pk_mul_f32 v[120:121], v[24:25], v[118:119] op_sel:[0,1] op_sel_hi:[0,0] neg_hi:[1,0]
	v_pk_fma_f32 v[118:119], v[84:85], v[118:119], v[120:121] op_sel_hi:[0,1,1]
	s_nop 0
	v_pk_mul_f32 v[120:121], v[26:27], v[118:119] op_sel:[1,1] op_sel_hi:[0,1] neg_lo:[0,1]
	v_pk_fma_f32 v[26:27], v[26:27], v[118:119], v[120:121] op_sel_hi:[1,0,1]
	v_pk_mul_f32 v[120:121], v[24:25], v[118:119] op_sel:[0,1] op_sel_hi:[0,0] neg_hi:[1,0]
	v_pk_fma_f32 v[118:119], v[84:85], v[118:119], v[120:121] op_sel_hi:[0,1,1]
	s_nop 0
	v_pk_mul_f32 v[120:121], v[28:29], v[118:119] op_sel:[1,1] op_sel_hi:[0,1] neg_lo:[0,1]
	v_pk_fma_f32 v[28:29], v[28:29], v[118:119], v[120:121] op_sel_hi:[1,0,1]
	v_pk_mul_f32 v[120:121], v[24:25], v[118:119] op_sel:[0,1] op_sel_hi:[0,0] neg_hi:[1,0]
	v_pk_fma_f32 v[118:119], v[84:85], v[118:119], v[120:121] op_sel_hi:[0,1,1]
	v_pk_mul_f32 v[24:25], v[24:25], v[118:119] op_sel:[0,1] op_sel_hi:[0,0] neg_hi:[1,0]
	v_pk_fma_f32 v[24:25], v[84:85], v[118:119], v[24:25] op_sel_hi:[0,1,1]
	v_pk_mul_f32 v[84:85], v[82:83], v[24:25] op_sel:[1,1] op_sel_hi:[0,1] neg_lo:[0,1]
	v_pk_fma_f32 v[24:25], v[82:83], v[24:25], v[84:85] op_sel_hi:[1,0,1]
	v_pk_add_f32 v[82:83], v[0:1], v[16:17]
	v_pk_add_f32 v[0:1], v[0:1], v[16:17] neg_lo:[0,1] neg_hi:[0,1]
	v_pk_add_f32 v[16:17], v[2:3], v[18:19]
	v_pk_add_f32 v[2:3], v[2:3], v[18:19] neg_lo:[0,1] neg_hi:[0,1]
	v_pk_mul_f32 v[120:121], v[30:31], v[118:119] op_sel:[1,1] op_sel_hi:[0,1] neg_lo:[0,1]
	v_pk_mul_f32 v[18:19], v[2:3], s[18:19]
	v_pk_fma_f32 v[30:31], v[30:31], v[118:119], v[120:121] op_sel_hi:[1,0,1]
	v_pk_fma_f32 v[2:3], v[2:3], s[30:31], v[18:19] op_sel:[0,0,1] op_sel_hi:[1,0,0]
	v_pk_add_f32 v[18:19], v[4:5], v[20:21]
	v_pk_add_f32 v[4:5], v[4:5], v[20:21] neg_lo:[0,1] neg_hi:[0,1]
	s_nop 0
	v_pk_mul_f32 v[20:21], v[4:5], s[10:11]
	s_nop 0
	v_pk_fma_f32 v[4:5], v[4:5], s[14:15], v[20:21] op_sel:[0,0,1] op_sel_hi:[1,0,0]
	v_pk_add_f32 v[20:21], v[6:7], v[22:23]
	v_pk_add_f32 v[6:7], v[6:7], v[22:23] neg_lo:[0,1] neg_hi:[0,1]
	s_nop 0
	v_pk_mul_f32 v[22:23], v[6:7], s[34:35]
	s_nop 0
	v_pk_fma_f32 v[6:7], v[6:7], s[0:1], v[22:23] op_sel:[0,0,1] op_sel_hi:[1,0,0]
	v_pk_add_f32 v[22:23], v[8:9], v[26:27]
	v_pk_add_f32 v[8:9], v[8:9], v[26:27] neg_lo:[0,1] neg_hi:[0,1]
	v_pk_add_f32 v[26:27], v[10:11], v[28:29]
	v_pk_add_f32 v[10:11], v[10:11], v[28:29] neg_lo:[0,1] neg_hi:[0,1]
	s_nop 0
	v_pk_mul_f32 v[28:29], v[10:11], s[34:35]
	s_nop 0
	v_pk_fma_f32 v[10:11], v[10:11], s[0:1], v[28:29] op_sel:[0,0,1] op_sel_hi:[1,0,0] neg_lo:[1,0,0] neg_hi:[1,0,0]
	v_pk_add_f32 v[28:29], v[12:13], v[30:31]
	v_pk_add_f32 v[12:13], v[12:13], v[30:31] neg_lo:[0,1] neg_hi:[0,1]
	s_mov_b32 s0, 0
	v_pk_mul_f32 v[30:31], v[12:13], s[10:11]
	s_nop 0
	v_pk_fma_f32 v[12:13], v[12:13], s[14:15], v[30:31] op_sel:[0,0,1] op_sel_hi:[1,0,0] neg_lo:[1,0,0] neg_hi:[1,0,0]
	v_pk_add_f32 v[30:31], v[14:15], v[24:25]
	v_pk_add_f32 v[14:15], v[14:15], v[24:25] neg_lo:[0,1] neg_hi:[0,1]
	s_nop 0
	v_pk_mul_f32 v[24:25], v[14:15], s[18:19]
	s_nop 0
	v_pk_fma_f32 v[14:15], v[14:15], s[30:31], v[24:25] op_sel:[0,0,1] op_sel_hi:[1,0,0] neg_lo:[1,0,0] neg_hi:[1,0,0]
	v_pk_add_f32 v[24:25], v[82:83], v[22:23]
	v_pk_add_f32 v[22:23], v[82:83], v[22:23] neg_lo:[0,1] neg_hi:[0,1]
	v_pk_add_f32 v[82:83], v[16:17], v[26:27]
	v_pk_add_f32 v[16:17], v[16:17], v[26:27] neg_lo:[0,1] neg_hi:[0,1]
	s_nop 0
	v_pk_mul_f32 v[26:27], v[16:17], s[10:11]
	s_nop 0
	v_pk_fma_f32 v[16:17], v[16:17], s[14:15], v[26:27] op_sel:[0,0,1] op_sel_hi:[1,0,0]
	v_pk_add_f32 v[26:27], v[18:19], v[28:29]
	v_pk_add_f32 v[18:19], v[18:19], v[28:29] neg_lo:[0,1] neg_hi:[0,1]
	v_pk_add_f32 v[28:29], v[20:21], v[30:31]
	v_pk_add_f32 v[20:21], v[20:21], v[30:31] neg_lo:[0,1] neg_hi:[0,1]
	s_nop 0
	v_pk_mul_f32 v[30:31], v[20:21], s[10:11]
	s_nop 0
	v_pk_fma_f32 v[20:21], v[20:21], s[14:15], v[30:31] op_sel:[0,0,1] op_sel_hi:[1,0,0] neg_lo:[1,0,0] neg_hi:[1,0,0]
	v_pk_add_f32 v[30:31], v[0:1], v[8:9] op_sel:[0,1] op_sel_hi:[1,0] neg_hi:[0,1]
	v_pk_add_f32 v[0:1], v[0:1], v[8:9] op_sel:[0,1] op_sel_hi:[1,0] neg_lo:[0,1]
	v_pk_add_f32 v[8:9], v[2:3], v[10:11]
	v_pk_add_f32 v[2:3], v[2:3], v[10:11] neg_lo:[0,1] neg_hi:[0,1]
	s_nop 0
	v_pk_mul_f32 v[10:11], v[2:3], s[10:11]
	s_nop 0
	v_pk_fma_f32 v[2:3], v[2:3], s[14:15], v[10:11] op_sel:[0,0,1] op_sel_hi:[1,0,0]
	v_pk_add_f32 v[10:11], v[4:5], v[12:13]
	v_pk_add_f32 v[4:5], v[4:5], v[12:13] neg_lo:[0,1] neg_hi:[0,1]
	v_pk_add_f32 v[12:13], v[6:7], v[14:15]
	v_pk_add_f32 v[6:7], v[6:7], v[14:15] neg_lo:[0,1] neg_hi:[0,1]
	s_nop 0
	v_pk_mul_f32 v[14:15], v[6:7], s[10:11]
	s_nop 0
	v_pk_fma_f32 v[6:7], v[6:7], s[14:15], v[14:15] op_sel:[0,0,1] op_sel_hi:[1,0,0] neg_lo:[1,0,0] neg_hi:[1,0,0]
	v_pk_add_f32 v[14:15], v[24:25], v[26:27]
	v_pk_add_f32 v[24:25], v[24:25], v[26:27] neg_lo:[0,1] neg_hi:[0,1]
	v_pk_add_f32 v[26:27], v[82:83], v[28:29]
	v_pk_add_f32 v[28:29], v[82:83], v[28:29] neg_lo:[0,1] neg_hi:[0,1]
	v_pk_add_f32 v[82:83], v[22:23], v[18:19] op_sel:[0,1] op_sel_hi:[1,0] neg_hi:[0,1]
	v_pk_add_f32 v[18:19], v[22:23], v[18:19] op_sel:[0,1] op_sel_hi:[1,0] neg_lo:[0,1]
	v_pk_add_f32 v[22:23], v[16:17], v[20:21]
	v_pk_add_f32 v[16:17], v[16:17], v[20:21] neg_lo:[0,1] neg_hi:[0,1]
	v_pk_add_f32 v[20:21], v[30:31], v[10:11]
	v_pk_add_f32 v[10:11], v[30:31], v[10:11] neg_lo:[0,1] neg_hi:[0,1]
	v_pk_add_f32 v[30:31], v[8:9], v[12:13]
	v_pk_add_f32 v[8:9], v[8:9], v[12:13] neg_lo:[0,1] neg_hi:[0,1]
	v_pk_add_f32 v[12:13], v[0:1], v[4:5] op_sel:[0,1] op_sel_hi:[1,0] neg_hi:[0,1]
	v_pk_add_f32 v[0:1], v[0:1], v[4:5] op_sel:[0,1] op_sel_hi:[1,0] neg_lo:[0,1]
	v_pk_add_f32 v[4:5], v[2:3], v[6:7]
	v_pk_add_f32 v[2:3], v[2:3], v[6:7] neg_lo:[0,1] neg_hi:[0,1]
	s_nop 0
	v_pk_mul_f32 v[2:3], v[2:3], s[22:23]
	v_pk_add_f32 v[6:7], v[14:15], v[26:27]
	v_pk_add_f32 v[14:15], v[14:15], v[26:27] neg_lo:[0,1] neg_hi:[0,1]
	v_pk_add_f32 v[26:27], v[24:25], v[28:29] op_sel:[0,1] op_sel_hi:[1,0] neg_hi:[0,1]
	v_pk_add_f32 v[24:25], v[24:25], v[28:29] op_sel:[0,1] op_sel_hi:[1,0] neg_lo:[0,1]
	v_pk_add_f32 v[28:29], v[82:83], v[22:23]
	v_pk_add_f32 v[22:23], v[82:83], v[22:23] neg_lo:[0,1] neg_hi:[0,1]
	v_pk_add_f32 v[82:83], v[18:19], v[16:17] op_sel:[0,1] op_sel_hi:[1,0] neg_hi:[0,1]
	v_pk_add_f32 v[16:17], v[18:19], v[16:17] op_sel:[0,1] op_sel_hi:[1,0] neg_lo:[0,1]
	v_pk_add_f32 v[18:19], v[20:21], v[30:31]
	v_pk_add_f32 v[20:21], v[20:21], v[30:31] neg_lo:[0,1] neg_hi:[0,1]
	v_pk_add_f32 v[30:31], v[10:11], v[8:9] op_sel:[0,1] op_sel_hi:[1,0] neg_hi:[0,1]
	v_pk_add_f32 v[8:9], v[10:11], v[8:9] op_sel:[0,1] op_sel_hi:[1,0] neg_lo:[0,1]
	v_pk_add_f32 v[10:11], v[12:13], v[4:5]
	v_pk_add_f32 v[4:5], v[12:13], v[4:5] neg_lo:[0,1] neg_hi:[0,1]
	v_pk_add_f32 v[12:13], v[0:1], v[2:3] op_sel:[0,1] op_sel_hi:[1,0]
	v_pk_add_f32 v[0:1], v[0:1], v[2:3] op_sel:[0,1] op_sel_hi:[1,0] neg_lo:[0,1] neg_hi:[0,1]
	v_lshlrev_b32_e32 v2, 4, v47
	v_and_or_b32 v2, v2, s15, v81
	v_ashrrev_i32_e32 v3, 4, v2
	v_lshlrev_b32_e32 v3, 3, v3
	v_lshlrev_b32_e32 v2, 3, v2
	v_add3_u32 v2, 0, v3, v2
	ds_write_b64 v2, v[6:7]
	ds_write_b64 v2, v[14:15] offset:34816
	ds_write_b64 v2, v[26:27] offset:17408
	ds_write_b64 v2, v[24:25] offset:52224
	ds_write_b64 v2, v[28:29] offset:8704
	ds_write_b64 v2, v[22:23] offset:43520
	ds_write_b64 v2, v[82:83] offset:26112
	ds_write_b64 v2, v[16:17] offset:60928
	ds_write_b64 v2, v[18:19] offset:4352
	ds_write_b64 v2, v[20:21] offset:39168
	ds_write_b64 v2, v[30:31] offset:21760
	ds_write_b64 v2, v[8:9] offset:56576
	ds_write_b64 v2, v[10:11] offset:13056
	ds_write_b64 v2, v[4:5] offset:47872
	ds_write_b64 v2, v[12:13] offset:30464
	ds_write_b64 v2, v[0:1] offset:65280
	v_mov_b32_e32 v0, v154
	v_mov_b32_e32 v1, v156
	v_mov_b32_e32 v2, v155
	s_waitcnt lgkmcnt(0)
	s_barrier
.LBB0_485:
	v_or_b32_e32 v3, s0, v32
	v_cmp_ne_u32_e32 vcc, 0, v3
	v_add_u32_e32 v9, 0, v2
	v_add_u32_e32 v4, 0x11000, v9
	v_cndmask_b32_e32 v3, 0, v0, vcc
	v_lshl_add_u32 v3, v3, 3, 0
	v_add_u32_e32 v3, 0x11000, v3
	ds_read_b64 v[4:5], v4
	ds_read_b64 v[6:7], v3
	s_add_i32 s0, s0, 2
	v_add_u32_e32 v2, 0x2200, v2
	v_add_u32_e32 v0, 0xfffffbc0, v0
	s_cmp_lg_u32 s0, 16
	s_waitcnt lgkmcnt(0)
	v_add_f32_e32 v3, v5, v7
	v_mul_f32_e32 v8, 0.5, v3
	v_sub_f32_e32 v3, v4, v6
	ds_read_b64 v[6:7], v9
	v_mul_f32_e32 v4, -0.5, v3
	v_add_u32_e32 v3, 0x12100, v9
	s_waitcnt lgkmcnt(0)
	v_pk_mul_f32 v[4:5], v[6:7], v[4:5] op_sel:[1,0] op_sel_hi:[0,0]
	v_pk_fma_f32 v[10:11], v[6:7], v[8:9], v[4:5] neg_lo:[0,0,1] neg_hi:[0,0,1]
	v_pk_fma_f32 v[4:5], v[6:7], v[8:9], v[4:5] op_sel_hi:[1,0,1]
	s_nop 0
	v_mov_b32_e32 v11, v5
	v_pk_mul_f32 v[4:5], v[10:11], s[24:25]
	ds_write_b64 v9, v[4:5]
	ds_read_b64 v[4:5], v3
	v_add_u32_e32 v3, 0, v1
	v_add_u32_e32 v3, 0x1ff00, v3
	ds_read_b64 v[6:7], v3
	v_add_u32_e32 v1, 0xffffde00, v1
	s_waitcnt lgkmcnt(0)
	v_add_f32_e32 v3, v5, v7
	v_mul_f32_e32 v8, 0.5, v3
	v_sub_f32_e32 v3, v4, v6
	ds_read_b64 v[6:7], v9 offset:4352
	v_mul_f32_e32 v4, -0.5, v3
	s_waitcnt lgkmcnt(0)
	v_pk_mul_f32 v[4:5], v[6:7], v[4:5] op_sel:[1,0] op_sel_hi:[0,0]
	v_pk_fma_f32 v[10:11], v[6:7], v[8:9], v[4:5] neg_lo:[0,0,1] neg_hi:[0,0,1]
	v_pk_fma_f32 v[4:5], v[6:7], v[8:9], v[4:5] op_sel_hi:[1,0,1]
	s_nop 0
	v_mov_b32_e32 v11, v5
	v_pk_mul_f32 v[4:5], v[10:11], s[24:25]
	ds_write_b64 v9, v[4:5] offset:4352
	s_cbranch_scc1 .LBB0_485
	s_waitcnt lgkmcnt(0)
	s_barrier
	s_and_saveexec_b64 s[0:1], s[40:41]
	s_cbranch_execz .LBB0_488
	ds_read_b64 v[0:1], v37 offset:2176
	ds_read_b64 v[2:3], v37 offset:4352
	ds_read_b64 v[4:5], v37 offset:6528
	ds_read_b64 v[6:7], v37 offset:8704
	ds_read_b64 v[8:9], v37 offset:10880
	ds_read_b64 v[10:11], v37 offset:13056
	ds_read_b64 v[12:13], v37 offset:15232
	ds_read_b64 v[14:15], v37 offset:17408
	ds_read_b64 v[16:17], v37 offset:19584
	ds_read_b64 v[18:19], v37 offset:21760
	ds_read_b64 v[20:21], v37 offset:23936
	ds_read_b64 v[22:23], v37 offset:26112
	ds_read_b64 v[24:25], v37 offset:34816
	ds_read_b64 v[26:27], v37 offset:36992
	ds_read_b64 v[28:29], v37 offset:39168
	ds_read_b64 v[30:31], v37 offset:41344
	ds_read_b64 v[82:83], v37 offset:43520
	ds_read_b64 v[84:85], v37 offset:45696
	ds_read_b64 v[118:119], v37 offset:47872
	ds_read_b64 v[120:121], v37 offset:50048
	ds_read_b64 v[122:123], v37 offset:52224
	ds_read_b64 v[124:125], v37 offset:54400
	ds_read_b64 v[126:127], v37 offset:56576
	ds_read_b64 v[128:129], v37 offset:58752
	ds_read_b64 v[130:131], v37
	ds_read_b64 v[132:133], v37 offset:60928
	ds_read_b64 v[134:135], v37 offset:63104
	ds_read_b64 v[136:137], v37 offset:65280
	s_mov_b32 s11, s14
	s_waitcnt lgkmcnt(3)
	v_pk_add_f32 v[158:159], v[130:131], v[24:25]
	v_pk_add_f32 v[24:25], v[130:131], v[24:25] neg_lo:[0,1] neg_hi:[0,1]
	v_pk_add_f32 v[130:131], v[0:1], v[26:27]
	v_pk_add_f32 v[0:1], v[0:1], v[26:27] neg_lo:[0,1] neg_hi:[0,1]
	s_mov_b32 s13, s86
	v_pk_mul_f32 v[26:27], v[0:1], s[16:17]
	s_mov_b32 s4, s21
	v_pk_fma_f32 v[0:1], v[0:1], s[6:7], v[26:27] op_sel:[0,0,1] op_sel_hi:[1,0,0]
	v_pk_add_f32 v[26:27], v[2:3], v[28:29]
	v_pk_add_f32 v[2:3], v[2:3], v[28:29] neg_lo:[0,1] neg_hi:[0,1]
	s_mov_b32 s35, s30
	v_pk_mul_f32 v[28:29], v[2:3], s[18:19]
	s_mov_b32 s8, s19
	v_pk_fma_f32 v[2:3], v[2:3], s[30:31], v[28:29] op_sel:[0,0,1] op_sel_hi:[1,0,0]
	v_pk_add_f32 v[28:29], v[4:5], v[30:31]
	v_pk_add_f32 v[4:5], v[4:5], v[30:31] neg_lo:[0,1] neg_hi:[0,1]
	s_mov_b32 s77, s6
	v_pk_mul_f32 v[30:31], v[4:5], s[20:21]
	s_mov_b32 s28, s17
	v_pk_fma_f32 v[4:5], v[4:5], s[86:87], v[30:31] op_sel:[0,0,1] op_sel_hi:[1,0,0]
	v_pk_add_f32 v[30:31], v[6:7], v[82:83]
	v_pk_add_f32 v[6:7], v[6:7], v[82:83] neg_lo:[0,1] neg_hi:[0,1]
	v_add_u32_e32 v47, 0x10780, v37
	v_pk_mul_f32 v[82:83], v[6:7], s[10:11]
	ds_read_b64 v[138:139], v37 offset:28288
	ds_read_b64 v[140:141], v37 offset:30464
	ds_read_b64 v[142:143], v37 offset:32640
	ds_read_b64 v[144:145], v47
	v_pk_fma_f32 v[6:7], v[6:7], s[14:15], v[82:83] op_sel:[0,0,1] op_sel_hi:[1,0,0]
	v_pk_add_f32 v[82:83], v[8:9], v[84:85]
	v_pk_add_f32 v[8:9], v[8:9], v[84:85] neg_lo:[0,1] neg_hi:[0,1]
	s_nop 0
	v_pk_mul_f32 v[84:85], v[8:9], s[12:13]
	s_nop 0
	v_pk_fma_f32 v[8:9], v[8:9], s[4:5], v[84:85] op_sel:[0,0,1] op_sel_hi:[1,0,0]
	v_pk_add_f32 v[84:85], v[10:11], v[118:119]
	v_pk_add_f32 v[10:11], v[10:11], v[118:119] neg_lo:[0,1] neg_hi:[0,1]
	s_nop 0
	v_pk_mul_f32 v[118:119], v[10:11], s[34:35]
	s_nop 0
	v_pk_fma_f32 v[10:11], v[10:11], s[8:9], v[118:119] op_sel:[0,0,1] op_sel_hi:[1,0,0]
	v_pk_add_f32 v[118:119], v[12:13], v[120:121]
	v_pk_add_f32 v[12:13], v[12:13], v[120:121] neg_lo:[0,1] neg_hi:[0,1]
	s_nop 0
	v_pk_mul_f32 v[120:121], v[12:13], s[76:77]
	s_nop 0
	v_pk_fma_f32 v[12:13], v[12:13], s[28:29], v[120:121] op_sel:[0,0,1] op_sel_hi:[1,0,0]
	v_pk_add_f32 v[120:121], v[14:15], v[122:123]
	v_pk_add_f32 v[14:15], v[14:15], v[122:123] neg_lo:[0,1] neg_hi:[0,1]
	v_pk_add_f32 v[122:123], v[16:17], v[124:125]
	v_pk_add_f32 v[16:17], v[16:17], v[124:125] neg_lo:[0,1] neg_hi:[0,1]
	s_nop 0
	v_pk_mul_f32 v[124:125], v[16:17], s[76:77]
	s_nop 0
	v_pk_fma_f32 v[16:17], v[16:17], s[28:29], v[124:125] op_sel:[0,0,1] op_sel_hi:[1,0,0] neg_lo:[1,0,0] neg_hi:[1,0,0]
	v_pk_add_f32 v[124:125], v[18:19], v[126:127]
	v_pk_add_f32 v[18:19], v[18:19], v[126:127] neg_lo:[0,1] neg_hi:[0,1]
	s_nop 0
	v_pk_mul_f32 v[126:127], v[18:19], s[34:35]
	s_nop 0
	v_pk_fma_f32 v[18:19], v[18:19], s[8:9], v[126:127] op_sel:[0,0,1] op_sel_hi:[1,0,0] neg_lo:[1,0,0] neg_hi:[1,0,0]
	v_pk_add_f32 v[126:127], v[20:21], v[128:129]
	v_pk_add_f32 v[20:21], v[20:21], v[128:129] neg_lo:[0,1] neg_hi:[0,1]
	s_nop 0
	v_pk_mul_f32 v[128:129], v[20:21], s[12:13]
	s_nop 0
	v_pk_fma_f32 v[20:21], v[20:21], s[4:5], v[128:129] op_sel:[0,0,1] op_sel_hi:[1,0,0] neg_lo:[1,0,0] neg_hi:[1,0,0]
	s_waitcnt lgkmcnt(6)
	v_pk_add_f32 v[128:129], v[22:23], v[132:133]
	v_pk_add_f32 v[22:23], v[22:23], v[132:133] neg_lo:[0,1] neg_hi:[0,1]
	s_nop 0
	v_pk_mul_f32 v[132:133], v[22:23], s[10:11]
	s_nop 0
	v_pk_fma_f32 v[22:23], v[22:23], s[14:15], v[132:133] op_sel:[0,0,1] op_sel_hi:[1,0,0] neg_lo:[1,0,0] neg_hi:[1,0,0]
	s_waitcnt lgkmcnt(3)
	v_pk_add_f32 v[132:133], v[138:139], v[134:135]
	v_pk_add_f32 v[134:135], v[138:139], v[134:135] neg_lo:[0,1] neg_hi:[0,1]
	s_nop 0
	v_pk_mul_f32 v[138:139], v[134:135], s[20:21]
	s_nop 0
	v_pk_fma_f32 v[134:135], v[134:135], s[86:87], v[138:139] op_sel:[0,0,1] op_sel_hi:[1,0,0] neg_lo:[1,0,0] neg_hi:[1,0,0]
	s_waitcnt lgkmcnt(2)
	v_pk_add_f32 v[138:139], v[140:141], v[136:137]
	v_pk_add_f32 v[136:137], v[140:141], v[136:137] neg_lo:[0,1] neg_hi:[0,1]
	s_nop 0
	v_pk_mul_f32 v[140:141], v[136:137], s[18:19]
	s_nop 0
	v_pk_fma_f32 v[136:137], v[136:137], s[30:31], v[140:141] op_sel:[0,0,1] op_sel_hi:[1,0,0] neg_lo:[1,0,0] neg_hi:[1,0,0]
	s_waitcnt lgkmcnt(0)
	v_pk_add_f32 v[140:141], v[142:143], v[144:145]
	v_pk_add_f32 v[142:143], v[142:143], v[144:145] neg_lo:[0,1] neg_hi:[0,1]
	s_nop 0
	v_pk_mul_f32 v[144:145], v[142:143], s[16:17]
	s_nop 0
	v_pk_fma_f32 v[142:143], v[142:143], s[6:7], v[144:145] op_sel:[0,0,1] op_sel_hi:[1,0,0] neg_lo:[1,0,0] neg_hi:[1,0,0]
	v_pk_add_f32 v[144:145], v[158:159], v[120:121]
	v_pk_add_f32 v[120:121], v[158:159], v[120:121] neg_lo:[0,1] neg_hi:[0,1]
	v_pk_add_f32 v[158:159], v[130:131], v[122:123]
	v_pk_add_f32 v[122:123], v[130:131], v[122:123] neg_lo:[0,1] neg_hi:[0,1]
	s_nop 0
	v_pk_mul_f32 v[130:131], v[122:123], s[18:19]
	s_nop 0
	v_pk_fma_f32 v[122:123], v[122:123], s[30:31], v[130:131] op_sel:[0,0,1] op_sel_hi:[1,0,0]
	v_pk_add_f32 v[130:131], v[26:27], v[124:125]
	v_pk_add_f32 v[26:27], v[26:27], v[124:125] neg_lo:[0,1] neg_hi:[0,1]
	s_nop 0
	v_pk_mul_f32 v[124:125], v[26:27], s[10:11]
	s_nop 0
	v_pk_fma_f32 v[26:27], v[26:27], s[14:15], v[124:125] op_sel:[0,0,1] op_sel_hi:[1,0,0]
	v_pk_add_f32 v[124:125], v[28:29], v[126:127]
	v_pk_add_f32 v[28:29], v[28:29], v[126:127] neg_lo:[0,1] neg_hi:[0,1]
	s_nop 0
	v_pk_mul_f32 v[126:127], v[28:29], s[34:35]
	s_nop 0
	v_pk_fma_f32 v[28:29], v[28:29], s[8:9], v[126:127] op_sel:[0,0,1] op_sel_hi:[1,0,0]
	v_pk_add_f32 v[126:127], v[30:31], v[128:129]
	v_pk_add_f32 v[30:31], v[30:31], v[128:129] neg_lo:[0,1] neg_hi:[0,1]
	v_pk_add_f32 v[128:129], v[82:83], v[132:133]
	v_pk_add_f32 v[82:83], v[82:83], v[132:133] neg_lo:[0,1] neg_hi:[0,1]
	s_nop 0
	v_pk_mul_f32 v[132:133], v[82:83], s[34:35]
	s_nop 0
	v_pk_fma_f32 v[82:83], v[82:83], s[8:9], v[132:133] op_sel:[0,0,1] op_sel_hi:[1,0,0] neg_lo:[1,0,0] neg_hi:[1,0,0]
	v_pk_add_f32 v[132:133], v[84:85], v[138:139]
	v_pk_add_f32 v[84:85], v[84:85], v[138:139] neg_lo:[0,1] neg_hi:[0,1]
	s_nop 0
	v_pk_mul_f32 v[138:139], v[84:85], s[10:11]
	s_nop 0
	v_pk_fma_f32 v[84:85], v[84:85], s[14:15], v[138:139] op_sel:[0,0,1] op_sel_hi:[1,0,0] neg_lo:[1,0,0] neg_hi:[1,0,0]
	v_pk_add_f32 v[138:139], v[118:119], v[140:141]
	v_pk_add_f32 v[118:119], v[118:119], v[140:141] neg_lo:[0,1] neg_hi:[0,1]
	s_nop 0
	v_pk_mul_f32 v[140:141], v[118:119], s[18:19]
	s_nop 0
	v_pk_fma_f32 v[118:119], v[118:119], s[30:31], v[140:141] op_sel:[0,0,1] op_sel_hi:[1,0,0] neg_lo:[1,0,0] neg_hi:[1,0,0]
	v_pk_add_f32 v[140:141], v[24:25], v[14:15] op_sel:[0,1] op_sel_hi:[1,0] neg_hi:[0,1]
	v_pk_add_f32 v[14:15], v[24:25], v[14:15] op_sel:[0,1] op_sel_hi:[1,0] neg_lo:[0,1]
	v_pk_add_f32 v[24:25], v[0:1], v[16:17]
	v_pk_add_f32 v[0:1], v[0:1], v[16:17] neg_lo:[0,1] neg_hi:[0,1]
	s_nop 0
	v_pk_mul_f32 v[16:17], v[0:1], s[18:19]
	s_nop 0
	v_pk_fma_f32 v[0:1], v[0:1], s[30:31], v[16:17] op_sel:[0,0,1] op_sel_hi:[1,0,0]
	v_pk_add_f32 v[16:17], v[2:3], v[18:19]
	v_pk_add_f32 v[2:3], v[2:3], v[18:19] neg_lo:[0,1] neg_hi:[0,1]
	s_nop 0
	v_pk_mul_f32 v[18:19], v[2:3], s[10:11]
	s_nop 0
	v_pk_fma_f32 v[2:3], v[2:3], s[14:15], v[18:19] op_sel:[0,0,1] op_sel_hi:[1,0,0]
	v_pk_add_f32 v[18:19], v[4:5], v[20:21]
	v_pk_add_f32 v[4:5], v[4:5], v[20:21] neg_lo:[0,1] neg_hi:[0,1]
	s_nop 0
	v_pk_mul_f32 v[20:21], v[4:5], s[34:35]
	s_nop 0
	v_pk_fma_f32 v[4:5], v[4:5], s[8:9], v[20:21] op_sel:[0,0,1] op_sel_hi:[1,0,0]
	v_pk_add_f32 v[20:21], v[6:7], v[22:23]
	v_pk_add_f32 v[6:7], v[6:7], v[22:23] neg_lo:[0,1] neg_hi:[0,1]
	v_pk_add_f32 v[22:23], v[8:9], v[134:135]
	v_pk_add_f32 v[8:9], v[8:9], v[134:135] neg_lo:[0,1] neg_hi:[0,1]
	s_nop 0
	v_pk_mul_f32 v[134:135], v[8:9], s[34:35]
	s_nop 0
	v_pk_fma_f32 v[8:9], v[8:9], s[8:9], v[134:135] op_sel:[0,0,1] op_sel_hi:[1,0,0] neg_lo:[1,0,0] neg_hi:[1,0,0]
	v_pk_add_f32 v[134:135], v[10:11], v[136:137]
	v_pk_add_f32 v[10:11], v[10:11], v[136:137] neg_lo:[0,1] neg_hi:[0,1]
	s_nop 0
	v_pk_mul_f32 v[136:137], v[10:11], s[10:11]
	s_nop 0
	v_pk_fma_f32 v[10:11], v[10:11], s[14:15], v[136:137] op_sel:[0,0,1] op_sel_hi:[1,0,0] neg_lo:[1,0,0] neg_hi:[1,0,0]
	v_pk_add_f32 v[136:137], v[12:13], v[142:143]
	v_pk_add_f32 v[12:13], v[12:13], v[142:143] neg_lo:[0,1] neg_hi:[0,1]
	s_nop 0
	v_pk_mul_f32 v[142:143], v[12:13], s[18:19]
	s_nop 0
	v_pk_fma_f32 v[12:13], v[12:13], s[30:31], v[142:143] op_sel:[0,0,1] op_sel_hi:[1,0,0] neg_lo:[1,0,0] neg_hi:[1,0,0]
	v_pk_add_f32 v[142:143], v[144:145], v[126:127]
	v_pk_add_f32 v[126:127], v[144:145], v[126:127] neg_lo:[0,1] neg_hi:[0,1]
	v_pk_add_f32 v[144:145], v[158:159], v[128:129]
	v_pk_add_f32 v[128:129], v[158:159], v[128:129] neg_lo:[0,1] neg_hi:[0,1]
	s_nop 0
	v_pk_mul_f32 v[158:159], v[128:129], s[10:11]
	s_nop 0
	v_pk_fma_f32 v[128:129], v[128:129], s[14:15], v[158:159] op_sel:[0,0,1] op_sel_hi:[1,0,0]
	v_pk_add_f32 v[158:159], v[130:131], v[132:133]
	v_pk_add_f32 v[130:131], v[130:131], v[132:133] neg_lo:[0,1] neg_hi:[0,1]
	v_pk_add_f32 v[132:133], v[124:125], v[138:139]
	v_pk_add_f32 v[124:125], v[124:125], v[138:139] neg_lo:[0,1] neg_hi:[0,1]
	s_nop 0
	v_pk_mul_f32 v[138:139], v[124:125], s[10:11]
	s_nop 0
	v_pk_fma_f32 v[124:125], v[124:125], s[14:15], v[138:139] op_sel:[0,0,1] op_sel_hi:[1,0,0] neg_lo:[1,0,0] neg_hi:[1,0,0]
	v_pk_add_f32 v[138:139], v[120:121], v[30:31] op_sel:[0,1] op_sel_hi:[1,0] neg_hi:[0,1]
	v_pk_add_f32 v[30:31], v[120:121], v[30:31] op_sel:[0,1] op_sel_hi:[1,0] neg_lo:[0,1]
	v_pk_add_f32 v[120:121], v[122:123], v[82:83]
	v_pk_add_f32 v[82:83], v[122:123], v[82:83] neg_lo:[0,1] neg_hi:[0,1]
	v_pk_add_f32 v[160:161], v[128:129], v[124:125]
	v_pk_mul_f32 v[122:123], v[82:83], s[10:11]
	v_pk_add_f32 v[124:125], v[128:129], v[124:125] neg_lo:[0,1] neg_hi:[0,1]
	v_pk_fma_f32 v[82:83], v[82:83], s[14:15], v[122:123] op_sel:[0,0,1] op_sel_hi:[1,0,0]
	v_pk_add_f32 v[122:123], v[26:27], v[84:85]
	v_pk_add_f32 v[26:27], v[26:27], v[84:85] neg_lo:[0,1] neg_hi:[0,1]
	v_pk_add_f32 v[84:85], v[28:29], v[118:119]
	v_pk_add_f32 v[28:29], v[28:29], v[118:119] neg_lo:[0,1] neg_hi:[0,1]
	s_nop 0
	v_pk_mul_f32 v[118:119], v[28:29], s[10:11]
	v_pk_add_f32 v[166:167], v[120:121], v[84:85]
	v_pk_fma_f32 v[28:29], v[28:29], s[14:15], v[118:119] op_sel:[0,0,1] op_sel_hi:[1,0,0] neg_lo:[1,0,0] neg_hi:[1,0,0]
	v_pk_add_f32 v[118:119], v[140:141], v[20:21]
	v_pk_add_f32 v[20:21], v[140:141], v[20:21] neg_lo:[0,1] neg_hi:[0,1]
	v_pk_add_f32 v[140:141], v[24:25], v[22:23]
	v_pk_add_f32 v[22:23], v[24:25], v[22:23] neg_lo:[0,1] neg_hi:[0,1]
	v_pk_add_f32 v[84:85], v[120:121], v[84:85] neg_lo:[0,1] neg_hi:[0,1]
	v_pk_mul_f32 v[24:25], v[22:23], s[10:11]
	v_pk_add_f32 v[168:169], v[30:31], v[26:27] op_sel:[0,1] op_sel_hi:[1,0] neg_hi:[0,1]
	v_pk_fma_f32 v[22:23], v[22:23], s[14:15], v[24:25] op_sel:[0,0,1] op_sel_hi:[1,0,0]
	v_pk_add_f32 v[24:25], v[16:17], v[134:135]
	v_pk_add_f32 v[16:17], v[16:17], v[134:135] neg_lo:[0,1] neg_hi:[0,1]
	v_pk_add_f32 v[134:135], v[18:19], v[136:137]
	v_pk_add_f32 v[18:19], v[18:19], v[136:137] neg_lo:[0,1] neg_hi:[0,1]
	s_nop 0
	v_pk_mul_f32 v[136:137], v[18:19], s[10:11]
	v_pk_add_f32 v[26:27], v[30:31], v[26:27] op_sel:[0,1] op_sel_hi:[1,0] neg_lo:[0,1]
	v_pk_fma_f32 v[18:19], v[18:19], s[14:15], v[136:137] op_sel:[0,0,1] op_sel_hi:[1,0,0] neg_lo:[1,0,0] neg_hi:[1,0,0]
	v_pk_add_f32 v[136:137], v[14:15], v[6:7] op_sel:[0,1] op_sel_hi:[1,0] neg_hi:[0,1]
	v_pk_add_f32 v[6:7], v[14:15], v[6:7] op_sel:[0,1] op_sel_hi:[1,0] neg_lo:[0,1]
	v_pk_add_f32 v[14:15], v[0:1], v[8:9]
	v_pk_add_f32 v[0:1], v[0:1], v[8:9] neg_lo:[0,1] neg_hi:[0,1]
	v_pk_add_f32 v[30:31], v[82:83], v[28:29]
	v_pk_mul_f32 v[8:9], v[0:1], s[10:11]
	v_pk_add_f32 v[28:29], v[82:83], v[28:29] neg_lo:[0,1] neg_hi:[0,1]
	v_pk_fma_f32 v[0:1], v[0:1], s[14:15], v[8:9] op_sel:[0,0,1] op_sel_hi:[1,0,0]
	v_pk_add_f32 v[8:9], v[2:3], v[10:11]
	v_pk_add_f32 v[2:3], v[2:3], v[10:11] neg_lo:[0,1] neg_hi:[0,1]
	v_pk_add_f32 v[10:11], v[4:5], v[12:13]
	v_pk_add_f32 v[4:5], v[4:5], v[12:13] neg_lo:[0,1] neg_hi:[0,1]
	s_nop 0
	v_pk_mul_f32 v[12:13], v[4:5], s[10:11]
	v_pk_add_f32 v[170:171], v[118:119], v[24:25]
	v_pk_fma_f32 v[4:5], v[4:5], s[14:15], v[12:13] op_sel:[0,0,1] op_sel_hi:[1,0,0] neg_lo:[1,0,0] neg_hi:[1,0,0]
	v_pk_add_f32 v[12:13], v[142:143], v[158:159]
	v_pk_add_f32 v[142:143], v[142:143], v[158:159] neg_lo:[0,1] neg_hi:[0,1]
	v_pk_add_f32 v[158:159], v[144:145], v[132:133]
	v_pk_add_f32 v[132:133], v[144:145], v[132:133] neg_lo:[0,1] neg_hi:[0,1]
	v_pk_add_f32 v[182:183], v[118:119], v[24:25] neg_lo:[0,1] neg_hi:[0,1]
	v_pk_add_f32 v[184:185], v[140:141], v[134:135]
	v_pk_add_f32 v[24:25], v[140:141], v[134:135] neg_lo:[0,1] neg_hi:[0,1]
	v_pk_add_f32 v[140:141], v[20:21], v[16:17] op_sel:[0,1] op_sel_hi:[1,0] neg_hi:[0,1]
	v_pk_add_f32 v[186:187], v[20:21], v[16:17] op_sel:[0,1] op_sel_hi:[1,0] neg_lo:[0,1]
	v_pk_add_f32 v[16:17], v[22:23], v[18:19] neg_lo:[0,1] neg_hi:[0,1]
	v_pk_add_f32 v[192:193], v[136:137], v[8:9]
	v_pk_add_f32 v[194:195], v[136:137], v[8:9] neg_lo:[0,1] neg_hi:[0,1]
	v_pk_add_f32 v[8:9], v[14:15], v[10:11] neg_lo:[0,1] neg_hi:[0,1]
	v_pk_add_f32 v[198:199], v[6:7], v[2:3] op_sel:[0,1] op_sel_hi:[1,0] neg_hi:[0,1]
	v_pk_add_f32 v[200:201], v[6:7], v[2:3] op_sel:[0,1] op_sel_hi:[1,0] neg_lo:[0,1]
	v_pk_add_f32 v[2:3], v[0:1], v[4:5]
	v_pk_add_f32 v[0:1], v[0:1], v[4:5] neg_lo:[0,1] neg_hi:[0,1]
	v_pk_add_f32 v[144:145], v[126:127], v[130:131] op_sel:[0,1] op_sel_hi:[1,0] neg_hi:[0,1]
	v_pk_add_f32 v[130:131], v[126:127], v[130:131] op_sel:[0,1] op_sel_hi:[1,0] neg_lo:[0,1]
	v_pk_mul_f32 v[162:163], v[124:125], s[22:23]
	v_pk_add_f32 v[164:165], v[138:139], v[122:123]
	v_pk_add_f32 v[138:139], v[138:139], v[122:123] neg_lo:[0,1] neg_hi:[0,1]
	v_pk_mul_f32 v[82:83], v[28:29], s[22:23]
	v_pk_mul_f32 v[134:135], v[24:25], s[22:23]
	v_pk_add_f32 v[188:189], v[22:23], v[18:19]
	v_pk_mul_f32 v[190:191], v[16:17], s[22:23]
	v_pk_add_f32 v[136:137], v[14:15], v[10:11]
	v_pk_mul_f32 v[196:197], v[8:9], s[22:23]
	v_pk_mul_f32 v[202:203], v[0:1], s[22:23]
	v_pk_add_f32 v[28:29], v[12:13], v[158:159]
	v_pk_add_f32 v[128:129], v[12:13], v[158:159] neg_lo:[0,1] neg_hi:[0,1]
	v_pk_add_f32 v[24:25], v[142:143], v[132:133] op_sel:[0,1] op_sel_hi:[1,0] neg_hi:[0,1]
	v_pk_add_f32 v[126:127], v[142:143], v[132:133] op_sel:[0,1] op_sel_hi:[1,0] neg_lo:[0,1]
	v_pk_add_f32 v[20:21], v[144:145], v[160:161]
	v_pk_add_f32 v[124:125], v[144:145], v[160:161] neg_lo:[0,1] neg_hi:[0,1]
	v_pk_add_f32 v[16:17], v[130:131], v[162:163] op_sel:[0,1] op_sel_hi:[1,0]
	v_pk_add_f32 v[122:123], v[130:131], v[162:163] op_sel:[0,1] op_sel_hi:[1,0] neg_lo:[0,1] neg_hi:[0,1]
	v_pk_add_f32 v[12:13], v[164:165], v[166:167]
	v_pk_add_f32 v[120:121], v[164:165], v[166:167] neg_lo:[0,1] neg_hi:[0,1]
	v_pk_add_f32 v[8:9], v[138:139], v[84:85] op_sel:[0,1] op_sel_hi:[1,0] neg_hi:[0,1]
	v_pk_add_f32 v[118:119], v[138:139], v[84:85] op_sel:[0,1] op_sel_hi:[1,0] neg_lo:[0,1]
	v_pk_add_f32 v[4:5], v[168:169], v[30:31]
	v_pk_add_f32 v[84:85], v[168:169], v[30:31] neg_lo:[0,1] neg_hi:[0,1]
	v_pk_add_f32 v[0:1], v[26:27], v[82:83] op_sel:[0,1] op_sel_hi:[1,0]
	v_pk_add_f32 v[82:83], v[26:27], v[82:83] op_sel:[0,1] op_sel_hi:[1,0] neg_lo:[0,1] neg_hi:[0,1]
	v_pk_add_f32 v[30:31], v[170:171], v[184:185]
	v_pk_add_f32 v[144:145], v[170:171], v[184:185] neg_lo:[0,1] neg_hi:[0,1]
	v_pk_add_f32 v[26:27], v[182:183], v[134:135] op_sel:[0,1] op_sel_hi:[1,0]
	v_pk_add_f32 v[142:143], v[182:183], v[134:135] op_sel:[0,1] op_sel_hi:[1,0] neg_lo:[0,1] neg_hi:[0,1]
	v_pk_add_f32 v[22:23], v[140:141], v[188:189]
	v_pk_add_f32 v[140:141], v[140:141], v[188:189] neg_lo:[0,1] neg_hi:[0,1]
	v_pk_add_f32 v[18:19], v[186:187], v[190:191] op_sel:[0,1] op_sel_hi:[1,0]
	v_pk_add_f32 v[138:139], v[186:187], v[190:191] op_sel:[0,1] op_sel_hi:[1,0] neg_lo:[0,1] neg_hi:[0,1]
	v_pk_add_f32 v[14:15], v[192:193], v[136:137]
	v_pk_add_f32 v[136:137], v[192:193], v[136:137] neg_lo:[0,1] neg_hi:[0,1]
	v_pk_add_f32 v[10:11], v[194:195], v[196:197] op_sel:[0,1] op_sel_hi:[1,0]
	v_pk_add_f32 v[134:135], v[194:195], v[196:197] op_sel:[0,1] op_sel_hi:[1,0] neg_lo:[0,1] neg_hi:[0,1]
	v_pk_add_f32 v[6:7], v[198:199], v[2:3]
	v_pk_add_f32 v[132:133], v[198:199], v[2:3] neg_lo:[0,1] neg_hi:[0,1]
	v_pk_add_f32 v[2:3], v[200:201], v[202:203] op_sel:[0,1] op_sel_hi:[1,0]
	v_pk_add_f32 v[130:131], v[200:201], v[202:203] op_sel:[0,1] op_sel_hi:[1,0] neg_lo:[0,1] neg_hi:[0,1]

.LBB0_490:
	s_or_b64 exec, exec, s[0:1]
	v_mov_b32_e32 v37, v32
	s_waitcnt lgkmcnt(0)
	s_barrier
	s_mov_b32 s11, s14
	v_and_b32_e32 v47, 31, v37
	v_cvt_f32_ubyte0_e32 v24, v47
	v_mul_f32_e32 v81, 0x3b000000, v24
	v_sin_f32_e32 v24, v81
	v_ashrrev_i32_e32 v0, 4, v37
	v_lshlrev_b32_e32 v0, 3, v0
	v_lshlrev_b32_e32 v1, 3, v37
	v_cos_f32_e32 v84, v81
	v_add3_u32 v25, 0, v0, v1
	ds_read_b64 v[0:1], v25
	ds_read_b64 v[2:3], v25 offset:4352
	ds_read_b64 v[4:5], v25 offset:8704
	ds_read_b64 v[6:7], v25 offset:13056
	ds_read_b64 v[8:9], v25 offset:17408
	ds_read_b64 v[10:11], v25 offset:21760
	ds_read_b64 v[12:13], v25 offset:26112
	ds_read_b64 v[14:15], v25 offset:30464
	ds_read_b64 v[16:17], v25 offset:34816
	ds_read_b64 v[18:19], v25 offset:39168
	ds_read_b64 v[20:21], v25 offset:43520
	ds_read_b64 v[22:23], v25 offset:47872
	v_xor_b32_e32 v85, 0x80000000, v24
	s_waitcnt lgkmcnt(10)
	v_pk_mul_f32 v[118:119], v[2:3], v[24:25] op_sel:[1,0] op_sel_hi:[0,0] neg_hi:[0,1]
	v_pk_fma_f32 v[2:3], v[2:3], v[84:85], v[118:119] op_sel_hi:[1,0,1]
	v_pk_mul_f32 v[118:119], v[24:25], v[84:85] op_sel:[0,1] op_sel_hi:[0,0] neg_hi:[1,0]
	v_pk_fma_f32 v[118:119], v[84:85], v[84:85], v[118:119] op_sel_hi:[0,1,1]
	ds_read_b64 v[26:27], v25 offset:52224
	ds_read_b64 v[28:29], v25 offset:56576
	ds_read_b64 v[30:31], v25 offset:60928
	ds_read_b64 v[82:83], v25 offset:65280
	s_waitcnt lgkmcnt(13)
	v_pk_mul_f32 v[120:121], v[4:5], v[118:119] op_sel:[1,1] op_sel_hi:[0,1] neg_lo:[0,1]
	v_pk_fma_f32 v[4:5], v[4:5], v[118:119], v[120:121] op_sel_hi:[1,0,1]
	v_pk_mul_f32 v[120:121], v[24:25], v[118:119] op_sel:[0,1] op_sel_hi:[0,0] neg_hi:[1,0]
	v_pk_fma_f32 v[118:119], v[84:85], v[118:119], v[120:121] op_sel_hi:[0,1,1]
	s_mov_b32 s35, s30
	s_waitcnt lgkmcnt(12)
	v_pk_mul_f32 v[120:121], v[6:7], v[118:119] op_sel:[1,1] op_sel_hi:[0,1] neg_lo:[0,1]
	v_pk_fma_f32 v[6:7], v[6:7], v[118:119], v[120:121] op_sel_hi:[1,0,1]
	v_pk_mul_f32 v[120:121], v[24:25], v[118:119] op_sel:[0,1] op_sel_hi:[0,0] neg_hi:[1,0]
	v_pk_fma_f32 v[118:119], v[84:85], v[118:119], v[120:121] op_sel_hi:[0,1,1]
	s_mov_b32 s0, s19
	s_waitcnt lgkmcnt(11)
	v_pk_mul_f32 v[120:121], v[8:9], v[118:119] op_sel:[1,1] op_sel_hi:[0,1] neg_lo:[0,1]
	v_pk_fma_f32 v[8:9], v[8:9], v[118:119], v[120:121] op_sel_hi:[1,0,1]
	v_pk_mul_f32 v[120:121], v[24:25], v[118:119] op_sel:[0,1] op_sel_hi:[0,0] neg_hi:[1,0]
	v_pk_fma_f32 v[118:119], v[84:85], v[118:119], v[120:121] op_sel_hi:[0,1,1]
	s_waitcnt lgkmcnt(0)
	v_pk_mul_f32 v[120:121], v[10:11], v[118:119] op_sel:[1,1] op_sel_hi:[0,1] neg_lo:[0,1]
	v_pk_fma_f32 v[10:11], v[10:11], v[118:119], v[120:121] op_sel_hi:[1,0,1]
	v_pk_mul_f32 v[120:121], v[24:25], v[118:119] op_sel:[0,1] op_sel_hi:[0,0] neg_hi:[1,0]
	v_pk_fma_f32 v[118:119], v[84:85], v[118:119], v[120:121] op_sel_hi:[0,1,1]
	s_barrier
	v_pk_mul_f32 v[120:121], v[12:13], v[118:119] op_sel:[1,1] op_sel_hi:[0,1] neg_lo:[0,1]
	v_pk_fma_f32 v[12:13], v[12:13], v[118:119], v[120:121] op_sel_hi:[1,0,1]
	v_pk_mul_f32 v[120:121], v[24:25], v[118:119] op_sel:[0,1] op_sel_hi:[0,0] neg_hi:[1,0]
	v_pk_fma_f32 v[118:119], v[84:85], v[118:119], v[120:121] op_sel_hi:[0,1,1]
	s_nop 0
	v_pk_mul_f32 v[120:121], v[14:15], v[118:119] op_sel:[1,1] op_sel_hi:[0,1] neg_lo:[0,1]
	v_pk_fma_f32 v[14:15], v[14:15], v[118:119], v[120:121] op_sel_hi:[1,0,1]
	v_pk_mul_f32 v[120:121], v[24:25], v[118:119] op_sel:[0,1] op_sel_hi:[0,0] neg_hi:[1,0]
	v_pk_fma_f32 v[118:119], v[84:85], v[118:119], v[120:121] op_sel_hi:[0,1,1]
	s_nop 0
	v_pk_mul_f32 v[120:121], v[16:17], v[118:119] op_sel:[1,1] op_sel_hi:[0,1] neg_lo:[0,1]
	v_pk_fma_f32 v[16:17], v[16:17], v[118:119], v[120:121] op_sel_hi:[1,0,1]
	v_pk_mul_f32 v[120:121], v[24:25], v[118:119] op_sel:[0,1] op_sel_hi:[0,0] neg_hi:[1,0]
	v_pk_fma_f32 v[118:119], v[84:85], v[118:119], v[120:121] op_sel_hi:[0,1,1]
	s_nop 0
	v_pk_mul_f32 v[120:121], v[18:19], v[118:119] op_sel:[1,1] op_sel_hi:[0,1] neg_lo:[0,1]
	v_pk_fma_f32 v[18:19], v[18:19], v[118:119], v[120:121] op_sel_hi:[1,0,1]
	v_pk_mul_f32 v[120:121], v[24:25], v[118:119] op_sel:[0,1] op_sel_hi:[0,0] neg_hi:[1,0]
	v_pk_fma_f32 v[118:119], v[84:85], v[118:119], v[120:121] op_sel_hi:[0,1,1]
	s_nop 0
	v_pk_mul_f32 v[120:121], v[20:21], v[118:119] op_sel:[1,1] op_sel_hi:[0,1] neg_lo:[0,1]
	v_pk_fma_f32 v[20:21], v[20:21], v[118:119], v[120:121] op_sel_hi:[1,0,1]
	v_pk_mul_f32 v[120:121], v[24:25], v[118:119] op_sel:[0,1] op_sel_hi:[0,0] neg_hi:[1,0]
	v_pk_fma_f32 v[118:119], v[84:85], v[118:119], v[120:121] op_sel_hi:[0,1,1]
	s_nop 0
	v_pk_mul_f32 v[120:121], v[22:23], v[118:119] op_sel:[1,1] op_sel_hi:[0,1] neg_lo:[0,1]
	v_pk_fma_f32 v[22:23], v[22:23], v[118:119], v[120:121] op_sel_hi:[1,0,1]
	v_pk_mul_f32 v[120:121], v[24:25], v[118:119] op_sel:[0,1] op_sel_hi:[0,0] neg_hi:[1,0]
	v_pk_fma_f32 v[118:119], v[84:85], v[118:119], v[120:121] op_sel_hi:[0,1,1]
	s_nop 0
	v_pk_mul_f32 v[120:121], v[26:27], v[118:119] op_sel:[1,1] op_sel_hi:[0,1] neg_lo:[0,1]
	v_pk_fma_f32 v[26:27], v[26:27], v[118:119], v[120:121] op_sel_hi:[1,0,1]
	v_pk_mul_f32 v[120:121], v[24:25], v[118:119] op_sel:[0,1] op_sel_hi:[0,0] neg_hi:[1,0]
	v_pk_fma_f32 v[118:119], v[84:85], v[118:119], v[120:121] op_sel_hi:[0,1,1]
	s_nop 0
	v_pk_mul_f32 v[120:121], v[28:29], v[118:119] op_sel:[1,1] op_sel_hi:[0,1] neg_lo:[0,1]
	v_pk_fma_f32 v[28:29], v[28:29], v[118:119], v[120:121] op_sel_hi:[1,0,1]
	v_pk_mul_f32 v[120:121], v[24:25], v[118:119] op_sel:[0,1] op_sel_hi:[0,0] neg_hi:[1,0]
	v_pk_fma_f32 v[118:119], v[84:85], v[118:119], v[120:121] op_sel_hi:[0,1,1]
	v_pk_mul_f32 v[24:25], v[24:25], v[118:119] op_sel:[0,1] op_sel_hi:[0,0] neg_hi:[1,0]
	v_pk_fma_f32 v[24:25], v[84:85], v[118:119], v[24:25] op_sel_hi:[0,1,1]
	v_pk_mul_f32 v[84:85], v[82:83], v[24:25] op_sel:[1,1] op_sel_hi:[0,1] neg_lo:[0,1]
	v_pk_fma_f32 v[24:25], v[82:83], v[24:25], v[84:85] op_sel_hi:[1,0,1]
	v_pk_add_f32 v[82:83], v[0:1], v[16:17]
	v_pk_add_f32 v[0:1], v[0:1], v[16:17] neg_lo:[0,1] neg_hi:[0,1]
	v_pk_add_f32 v[16:17], v[2:3], v[18:19]
	v_pk_add_f32 v[2:3], v[2:3], v[18:19] neg_lo:[0,1] neg_hi:[0,1]
	v_pk_mul_f32 v[120:121], v[30:31], v[118:119] op_sel:[1,1] op_sel_hi:[0,1] neg_lo:[0,1]
	v_pk_mul_f32 v[18:19], v[2:3], s[18:19]
	v_pk_fma_f32 v[30:31], v[30:31], v[118:119], v[120:121] op_sel_hi:[1,0,1]
	v_pk_fma_f32 v[2:3], v[2:3], s[30:31], v[18:19] op_sel:[0,0,1] op_sel_hi:[1,0,0]
	v_pk_add_f32 v[18:19], v[4:5], v[20:21]
	v_pk_add_f32 v[4:5], v[4:5], v[20:21] neg_lo:[0,1] neg_hi:[0,1]
	s_nop 0
	v_pk_mul_f32 v[20:21], v[4:5], s[10:11]
	s_nop 0
	v_pk_fma_f32 v[4:5], v[4:5], s[14:15], v[20:21] op_sel:[0,0,1] op_sel_hi:[1,0,0]
	v_pk_add_f32 v[20:21], v[6:7], v[22:23]
	v_pk_add_f32 v[6:7], v[6:7], v[22:23] neg_lo:[0,1] neg_hi:[0,1]
	s_nop 0
	v_pk_mul_f32 v[22:23], v[6:7], s[34:35]
	s_nop 0
	v_pk_fma_f32 v[6:7], v[6:7], s[0:1], v[22:23] op_sel:[0,0,1] op_sel_hi:[1,0,0]
	v_pk_add_f32 v[22:23], v[8:9], v[26:27]
	v_pk_add_f32 v[8:9], v[8:9], v[26:27] neg_lo:[0,1] neg_hi:[0,1]
	v_pk_add_f32 v[26:27], v[10:11], v[28:29]
	v_pk_add_f32 v[10:11], v[10:11], v[28:29] neg_lo:[0,1] neg_hi:[0,1]
	s_nop 0
	v_pk_mul_f32 v[28:29], v[10:11], s[34:35]
	s_nop 0
	v_pk_fma_f32 v[10:11], v[10:11], s[0:1], v[28:29] op_sel:[0,0,1] op_sel_hi:[1,0,0] neg_lo:[1,0,0] neg_hi:[1,0,0]
	v_pk_add_f32 v[28:29], v[12:13], v[30:31]
	v_pk_add_f32 v[12:13], v[12:13], v[30:31] neg_lo:[0,1] neg_hi:[0,1]
	s_nop 0
	v_pk_mul_f32 v[30:31], v[12:13], s[10:11]
	s_nop 0
	v_pk_fma_f32 v[12:13], v[12:13], s[14:15], v[30:31] op_sel:[0,0,1] op_sel_hi:[1,0,0] neg_lo:[1,0,0] neg_hi:[1,0,0]
	v_pk_add_f32 v[30:31], v[14:15], v[24:25]
	v_pk_add_f32 v[14:15], v[14:15], v[24:25] neg_lo:[0,1] neg_hi:[0,1]
	s_nop 0
	v_pk_mul_f32 v[24:25], v[14:15], s[18:19]
	s_nop 0
	v_pk_fma_f32 v[14:15], v[14:15], s[30:31], v[24:25] op_sel:[0,0,1] op_sel_hi:[1,0,0] neg_lo:[1,0,0] neg_hi:[1,0,0]
	v_pk_add_f32 v[24:25], v[82:83], v[22:23]
	v_pk_add_f32 v[22:23], v[82:83], v[22:23] neg_lo:[0,1] neg_hi:[0,1]
	v_pk_add_f32 v[82:83], v[16:17], v[26:27]
	v_pk_add_f32 v[16:17], v[16:17], v[26:27] neg_lo:[0,1] neg_hi:[0,1]
	s_nop 0
	v_pk_mul_f32 v[26:27], v[16:17], s[10:11]
	s_nop 0
	v_pk_fma_f32 v[16:17], v[16:17], s[14:15], v[26:27] op_sel:[0,0,1] op_sel_hi:[1,0,0]
	v_pk_add_f32 v[26:27], v[18:19], v[28:29]
	v_pk_add_f32 v[18:19], v[18:19], v[28:29] neg_lo:[0,1] neg_hi:[0,1]
	v_pk_add_f32 v[28:29], v[20:21], v[30:31]
	v_pk_add_f32 v[20:21], v[20:21], v[30:31] neg_lo:[0,1] neg_hi:[0,1]
	s_nop 0
	v_pk_mul_f32 v[30:31], v[20:21], s[10:11]
	s_nop 0
	v_pk_fma_f32 v[20:21], v[20:21], s[14:15], v[30:31] op_sel:[0,0,1] op_sel_hi:[1,0,0] neg_lo:[1,0,0] neg_hi:[1,0,0]
	v_pk_add_f32 v[30:31], v[0:1], v[8:9] op_sel:[0,1] op_sel_hi:[1,0] neg_hi:[0,1]
	v_pk_add_f32 v[0:1], v[0:1], v[8:9] op_sel:[0,1] op_sel_hi:[1,0] neg_lo:[0,1]
	v_pk_add_f32 v[8:9], v[2:3], v[10:11]
	v_pk_add_f32 v[2:3], v[2:3], v[10:11] neg_lo:[0,1] neg_hi:[0,1]
	s_nop 0
	v_pk_mul_f32 v[10:11], v[2:3], s[10:11]
	s_nop 0
	v_pk_fma_f32 v[2:3], v[2:3], s[14:15], v[10:11] op_sel:[0,0,1] op_sel_hi:[1,0,0]
	v_pk_add_f32 v[10:11], v[4:5], v[12:13]
	v_pk_add_f32 v[4:5], v[4:5], v[12:13] neg_lo:[0,1] neg_hi:[0,1]
	v_pk_add_f32 v[12:13], v[6:7], v[14:15]
	v_pk_add_f32 v[6:7], v[6:7], v[14:15] neg_lo:[0,1] neg_hi:[0,1]
	s_nop 0
	v_pk_mul_f32 v[14:15], v[6:7], s[10:11]
	s_nop 0
	v_pk_fma_f32 v[6:7], v[6:7], s[14:15], v[14:15] op_sel:[0,0,1] op_sel_hi:[1,0,0] neg_lo:[1,0,0] neg_hi:[1,0,0]
	v_pk_add_f32 v[14:15], v[24:25], v[26:27]
	v_pk_add_f32 v[24:25], v[24:25], v[26:27] neg_lo:[0,1] neg_hi:[0,1]
	v_pk_add_f32 v[26:27], v[82:83], v[28:29]
	v_pk_add_f32 v[28:29], v[82:83], v[28:29] neg_lo:[0,1] neg_hi:[0,1]
	v_pk_add_f32 v[82:83], v[22:23], v[18:19] op_sel:[0,1] op_sel_hi:[1,0] neg_hi:[0,1]
	v_pk_add_f32 v[18:19], v[22:23], v[18:19] op_sel:[0,1] op_sel_hi:[1,0] neg_lo:[0,1]
	v_pk_add_f32 v[22:23], v[16:17], v[20:21]
	v_pk_add_f32 v[16:17], v[16:17], v[20:21] neg_lo:[0,1] neg_hi:[0,1]
	v_pk_add_f32 v[20:21], v[30:31], v[10:11]
	v_pk_add_f32 v[10:11], v[30:31], v[10:11] neg_lo:[0,1] neg_hi:[0,1]
	v_pk_add_f32 v[30:31], v[8:9], v[12:13]
	v_pk_add_f32 v[8:9], v[8:9], v[12:13] neg_lo:[0,1] neg_hi:[0,1]
	v_pk_add_f32 v[12:13], v[0:1], v[4:5] op_sel:[0,1] op_sel_hi:[1,0] neg_hi:[0,1]
	v_pk_add_f32 v[0:1], v[0:1], v[4:5] op_sel:[0,1] op_sel_hi:[1,0] neg_lo:[0,1]
	v_pk_add_f32 v[4:5], v[2:3], v[6:7]
	v_pk_add_f32 v[2:3], v[2:3], v[6:7] neg_lo:[0,1] neg_hi:[0,1]
	s_nop 0
	v_pk_mul_f32 v[2:3], v[2:3], s[22:23]
	v_pk_add_f32 v[6:7], v[14:15], v[26:27]
	v_pk_add_f32 v[14:15], v[14:15], v[26:27] neg_lo:[0,1] neg_hi:[0,1]
	v_pk_add_f32 v[26:27], v[24:25], v[28:29] op_sel:[0,1] op_sel_hi:[1,0] neg_hi:[0,1]
	v_pk_add_f32 v[24:25], v[24:25], v[28:29] op_sel:[0,1] op_sel_hi:[1,0] neg_lo:[0,1]
	v_pk_add_f32 v[28:29], v[82:83], v[22:23]
	v_pk_add_f32 v[22:23], v[82:83], v[22:23] neg_lo:[0,1] neg_hi:[0,1]
	v_pk_add_f32 v[82:83], v[18:19], v[16:17] op_sel:[0,1] op_sel_hi:[1,0] neg_hi:[0,1]
	v_pk_add_f32 v[16:17], v[18:19], v[16:17] op_sel:[0,1] op_sel_hi:[1,0] neg_lo:[0,1]
	v_pk_add_f32 v[18:19], v[20:21], v[30:31]
	v_pk_add_f32 v[20:21], v[20:21], v[30:31] neg_lo:[0,1] neg_hi:[0,1]
	v_pk_add_f32 v[30:31], v[10:11], v[8:9] op_sel:[0,1] op_sel_hi:[1,0] neg_hi:[0,1]
	v_pk_add_f32 v[8:9], v[10:11], v[8:9] op_sel:[0,1] op_sel_hi:[1,0] neg_lo:[0,1]
	v_pk_add_f32 v[10:11], v[12:13], v[4:5]
	v_pk_add_f32 v[4:5], v[12:13], v[4:5] neg_lo:[0,1] neg_hi:[0,1]
	v_pk_add_f32 v[12:13], v[0:1], v[2:3] op_sel:[0,1] op_sel_hi:[1,0]
	v_pk_add_f32 v[0:1], v[0:1], v[2:3] op_sel:[0,1] op_sel_hi:[1,0] neg_lo:[0,1] neg_hi:[0,1]
	v_lshlrev_b32_e32 v2, 4, v37
	v_and_or_b32 v2, v2, s7, v47
	v_ashrrev_i32_e32 v3, 4, v2
	v_lshlrev_b32_e32 v3, 3, v3
	v_lshlrev_b32_e32 v2, 3, v2
	v_add3_u32 v2, 0, v3, v2
	v_add_u32_e32 v3, 0x800, v2
	v_mov_b32_e32 v37, v32
	ds_write2_b64 v2, v[6:7], v[18:19] offset1:34
	ds_write2_b64 v3, v[14:15], v[20:21] offset0:16 offset1:50
	ds_write2_b64 v2, v[26:27], v[30:31] offset0:136 offset1:170
	ds_write2_b64 v3, v[24:25], v[8:9] offset0:152 offset1:186
	ds_write2_b64 v2, v[28:29], v[10:11] offset0:68 offset1:102
	ds_write2_b64 v3, v[22:23], v[4:5] offset0:84 offset1:118
	ds_write2_b64 v2, v[82:83], v[12:13] offset0:204 offset1:238
	ds_write2_b64 v3, v[16:17], v[0:1] offset0:220 offset1:254
	s_waitcnt lgkmcnt(0)
	s_barrier
	s_nop 0
	v_and_b32_e32 v47, 0x1ff, v37
	v_cvt_f32_u32_e32 v24, v47
	v_ashrrev_i32_e32 v0, 4, v37
	v_lshlrev_b32_e32 v0, 3, v0
	v_lshlrev_b32_e32 v1, 3, v37
	v_mul_f32_e32 v81, 0x39000000, v24
	v_sin_f32_e32 v24, v81
	v_cos_f32_e32 v84, v81
	v_add3_u32 v25, 0, v0, v1
	ds_read_b64 v[0:1], v25
	ds_read_b64 v[2:3], v25 offset:4352
	ds_read_b64 v[4:5], v25 offset:8704
	ds_read_b64 v[6:7], v25 offset:13056
	ds_read_b64 v[8:9], v25 offset:17408
	ds_read_b64 v[10:11], v25 offset:21760
	ds_read_b64 v[12:13], v25 offset:26112
	ds_read_b64 v[14:15], v25 offset:30464
	v_xor_b32_e32 v85, 0x80000000, v24
	s_waitcnt lgkmcnt(6)
	v_pk_mul_f32 v[118:119], v[2:3], v[24:25] op_sel:[1,0] op_sel_hi:[0,0] neg_hi:[0,1]
	v_pk_fma_f32 v[2:3], v[2:3], v[84:85], v[118:119] op_sel_hi:[1,0,1]
	v_pk_mul_f32 v[118:119], v[24:25], v[84:85] op_sel:[0,1] op_sel_hi:[0,0] neg_hi:[1,0]
	v_pk_fma_f32 v[118:119], v[84:85], v[84:85], v[118:119] op_sel_hi:[0,1,1]
	ds_read_b64 v[16:17], v25 offset:34816
	ds_read_b64 v[18:19], v25 offset:39168
	ds_read_b64 v[20:21], v25 offset:43520
	ds_read_b64 v[22:23], v25 offset:47872
	s_waitcnt lgkmcnt(9)
	v_pk_mul_f32 v[120:121], v[4:5], v[118:119] op_sel:[1,1] op_sel_hi:[0,1] neg_lo:[0,1]
	v_pk_fma_f32 v[4:5], v[4:5], v[118:119], v[120:121] op_sel_hi:[1,0,1]
	v_pk_mul_f32 v[120:121], v[24:25], v[118:119] op_sel:[0,1] op_sel_hi:[0,0] neg_hi:[1,0]
	v_pk_fma_f32 v[118:119], v[84:85], v[118:119], v[120:121] op_sel_hi:[0,1,1]
	ds_read_b64 v[26:27], v25 offset:52224
	ds_read_b64 v[28:29], v25 offset:56576
	ds_read_b64 v[30:31], v25 offset:60928
	ds_read_b64 v[82:83], v25 offset:65280
	s_waitcnt lgkmcnt(12)
	v_pk_mul_f32 v[120:121], v[6:7], v[118:119] op_sel:[1,1] op_sel_hi:[0,1] neg_lo:[0,1]
	v_pk_fma_f32 v[6:7], v[6:7], v[118:119], v[120:121] op_sel_hi:[1,0,1]
	v_pk_mul_f32 v[120:121], v[24:25], v[118:119] op_sel:[0,1] op_sel_hi:[0,0] neg_hi:[1,0]
	v_pk_fma_f32 v[118:119], v[84:85], v[118:119], v[120:121] op_sel_hi:[0,1,1]
	s_waitcnt lgkmcnt(0)
	v_pk_mul_f32 v[120:121], v[8:9], v[118:119] op_sel:[1,1] op_sel_hi:[0,1] neg_lo:[0,1]
	v_pk_fma_f32 v[8:9], v[8:9], v[118:119], v[120:121] op_sel_hi:[1,0,1]
	v_pk_mul_f32 v[120:121], v[24:25], v[118:119] op_sel:[0,1] op_sel_hi:[0,0] neg_hi:[1,0]
	v_pk_fma_f32 v[118:119], v[84:85], v[118:119], v[120:121] op_sel_hi:[0,1,1]
	s_barrier
	v_pk_mul_f32 v[120:121], v[10:11], v[118:119] op_sel:[1,1] op_sel_hi:[0,1] neg_lo:[0,1]
	v_pk_fma_f32 v[10:11], v[10:11], v[118:119], v[120:121] op_sel_hi:[1,0,1]
	v_pk_mul_f32 v[120:121], v[24:25], v[118:119] op_sel:[0,1] op_sel_hi:[0,0] neg_hi:[1,0]
	v_pk_fma_f32 v[118:119], v[84:85], v[118:119], v[120:121] op_sel_hi:[0,1,1]
	s_nop 0
	v_pk_mul_f32 v[120:121], v[12:13], v[118:119] op_sel:[1,1] op_sel_hi:[0,1] neg_lo:[0,1]
	v_pk_fma_f32 v[12:13], v[12:13], v[118:119], v[120:121] op_sel_hi:[1,0,1]
	v_pk_mul_f32 v[120:121], v[24:25], v[118:119] op_sel:[0,1] op_sel_hi:[0,0] neg_hi:[1,0]
	v_pk_fma_f32 v[118:119], v[84:85], v[118:119], v[120:121] op_sel_hi:[0,1,1]
	s_nop 0
	v_pk_mul_f32 v[120:121], v[14:15], v[118:119] op_sel:[1,1] op_sel_hi:[0,1] neg_lo:[0,1]
	v_pk_fma_f32 v[14:15], v[14:15], v[118:119], v[120:121] op_sel_hi:[1,0,1]
	v_pk_mul_f32 v[120:121], v[24:25], v[118:119] op_sel:[0,1] op_sel_hi:[0,0] neg_hi:[1,0]
	v_pk_fma_f32 v[118:119], v[84:85], v[118:119], v[120:121] op_sel_hi:[0,1,1]
	s_nop 0
	v_pk_mul_f32 v[120:121], v[16:17], v[118:119] op_sel:[1,1] op_sel_hi:[0,1] neg_lo:[0,1]
	v_pk_fma_f32 v[16:17], v[16:17], v[118:119], v[120:121] op_sel_hi:[1,0,1]
	v_pk_mul_f32 v[120:121], v[24:25], v[118:119] op_sel:[0,1] op_sel_hi:[0,0] neg_hi:[1,0]
	v_pk_fma_f32 v[118:119], v[84:85], v[118:119], v[120:121] op_sel_hi:[0,1,1]
	s_nop 0
	v_pk_mul_f32 v[120:121], v[18:19], v[118:119] op_sel:[1,1] op_sel_hi:[0,1] neg_lo:[0,1]
	v_pk_fma_f32 v[18:19], v[18:19], v[118:119], v[120:121] op_sel_hi:[1,0,1]
	v_pk_mul_f32 v[120:121], v[24:25], v[118:119] op_sel:[0,1] op_sel_hi:[0,0] neg_hi:[1,0]
	v_pk_fma_f32 v[118:119], v[84:85], v[118:119], v[120:121] op_sel_hi:[0,1,1]
	s_nop 0
	v_pk_mul_f32 v[120:121], v[20:21], v[118:119] op_sel:[1,1] op_sel_hi:[0,1] neg_lo:[0,1]
	v_pk_fma_f32 v[20:21], v[20:21], v[118:119], v[120:121] op_sel_hi:[1,0,1]
	v_pk_mul_f32 v[120:121], v[24:25], v[118:119] op_sel:[0,1] op_sel_hi:[0,0] neg_hi:[1,0]
	v_pk_fma_f32 v[118:119], v[84:85], v[118:119], v[120:121] op_sel_hi:[0,1,1]
	s_nop 0
	v_pk_mul_f32 v[120:121], v[22:23], v[118:119] op_sel:[1,1] op_sel_hi:[0,1] neg_lo:[0,1]
	v_pk_fma_f32 v[22:23], v[22:23], v[118:119], v[120:121] op_sel_hi:[1,0,1]
	v_pk_mul_f32 v[120:121], v[24:25], v[118:119] op_sel:[0,1] op_sel_hi:[0,0] neg_hi:[1,0]
	v_pk_fma_f32 v[118:119], v[84:85], v[118:119], v[120:121] op_sel_hi:[0,1,1]
	s_nop 0
	v_pk_mul_f32 v[120:121], v[26:27], v[118:119] op_sel:[1,1] op_sel_hi:[0,1] neg_lo:[0,1]
	v_pk_fma_f32 v[26:27], v[26:27], v[118:119], v[120:121] op_sel_hi:[1,0,1]
	v_pk_mul_f32 v[120:121], v[24:25], v[118:119] op_sel:[0,1] op_sel_hi:[0,0] neg_hi:[1,0]
	v_pk_fma_f32 v[118:119], v[84:85], v[118:119], v[120:121] op_sel_hi:[0,1,1]
	s_nop 0
	v_pk_mul_f32 v[120:121], v[28:29], v[118:119] op_sel:[1,1] op_sel_hi:[0,1] neg_lo:[0,1]
	v_pk_fma_f32 v[28:29], v[28:29], v[118:119], v[120:121] op_sel_hi:[1,0,1]
	v_pk_mul_f32 v[120:121], v[24:25], v[118:119] op_sel:[0,1] op_sel_hi:[0,0] neg_hi:[1,0]
	v_pk_fma_f32 v[118:119], v[84:85], v[118:119], v[120:121] op_sel_hi:[0,1,1]
	v_pk_mul_f32 v[24:25], v[24:25], v[118:119] op_sel:[0,1] op_sel_hi:[0,0] neg_hi:[1,0]
	v_pk_fma_f32 v[24:25], v[84:85], v[118:119], v[24:25] op_sel_hi:[0,1,1]
	v_pk_mul_f32 v[84:85], v[82:83], v[24:25] op_sel:[1,1] op_sel_hi:[0,1] neg_lo:[0,1]
	v_pk_fma_f32 v[24:25], v[82:83], v[24:25], v[84:85] op_sel_hi:[1,0,1]
	v_pk_add_f32 v[82:83], v[0:1], v[16:17]
	v_pk_add_f32 v[0:1], v[0:1], v[16:17] neg_lo:[0,1] neg_hi:[0,1]
	v_pk_add_f32 v[16:17], v[2:3], v[18:19]
	v_pk_add_f32 v[2:3], v[2:3], v[18:19] neg_lo:[0,1] neg_hi:[0,1]
	v_pk_mul_f32 v[120:121], v[30:31], v[118:119] op_sel:[1,1] op_sel_hi:[0,1] neg_lo:[0,1]
	v_pk_mul_f32 v[18:19], v[2:3], s[18:19]
	v_pk_fma_f32 v[30:31], v[30:31], v[118:119], v[120:121] op_sel_hi:[1,0,1]
	v_pk_fma_f32 v[2:3], v[2:3], s[30:31], v[18:19] op_sel:[0,0,1] op_sel_hi:[1,0,0]
	v_pk_add_f32 v[18:19], v[4:5], v[20:21]
	v_pk_add_f32 v[4:5], v[4:5], v[20:21] neg_lo:[0,1] neg_hi:[0,1]
	s_nop 0
	v_pk_mul_f32 v[20:21], v[4:5], s[10:11]
	s_nop 0
	v_pk_fma_f32 v[4:5], v[4:5], s[14:15], v[20:21] op_sel:[0,0,1] op_sel_hi:[1,0,0]
	v_pk_add_f32 v[20:21], v[6:7], v[22:23]
	v_pk_add_f32 v[6:7], v[6:7], v[22:23] neg_lo:[0,1] neg_hi:[0,1]
	s_nop 0
	v_pk_mul_f32 v[22:23], v[6:7], s[34:35]
	s_nop 0
	v_pk_fma_f32 v[6:7], v[6:7], s[0:1], v[22:23] op_sel:[0,0,1] op_sel_hi:[1,0,0]
	v_pk_add_f32 v[22:23], v[8:9], v[26:27]
	v_pk_add_f32 v[8:9], v[8:9], v[26:27] neg_lo:[0,1] neg_hi:[0,1]
	v_pk_add_f32 v[26:27], v[10:11], v[28:29]
	v_pk_add_f32 v[10:11], v[10:11], v[28:29] neg_lo:[0,1] neg_hi:[0,1]
	s_nop 0
	v_pk_mul_f32 v[28:29], v[10:11], s[34:35]
	s_nop 0
	v_pk_fma_f32 v[10:11], v[10:11], s[0:1], v[28:29] op_sel:[0,0,1] op_sel_hi:[1,0,0] neg_lo:[1,0,0] neg_hi:[1,0,0]
	v_pk_add_f32 v[28:29], v[12:13], v[30:31]
	v_pk_add_f32 v[12:13], v[12:13], v[30:31] neg_lo:[0,1] neg_hi:[0,1]
	s_nop 0
	v_pk_mul_f32 v[30:31], v[12:13], s[10:11]
	s_nop 0
	v_pk_fma_f32 v[12:13], v[12:13], s[14:15], v[30:31] op_sel:[0,0,1] op_sel_hi:[1,0,0] neg_lo:[1,0,0] neg_hi:[1,0,0]
	v_pk_add_f32 v[30:31], v[14:15], v[24:25]
	v_pk_add_f32 v[14:15], v[14:15], v[24:25] neg_lo:[0,1] neg_hi:[0,1]
	s_nop 0
	v_pk_mul_f32 v[24:25], v[14:15], s[18:19]
	s_nop 0
	v_pk_fma_f32 v[14:15], v[14:15], s[30:31], v[24:25] op_sel:[0,0,1] op_sel_hi:[1,0,0] neg_lo:[1,0,0] neg_hi:[1,0,0]
	v_pk_add_f32 v[24:25], v[82:83], v[22:23]
	v_pk_add_f32 v[22:23], v[82:83], v[22:23] neg_lo:[0,1] neg_hi:[0,1]
	v_pk_add_f32 v[82:83], v[16:17], v[26:27]
	v_pk_add_f32 v[16:17], v[16:17], v[26:27] neg_lo:[0,1] neg_hi:[0,1]
	s_nop 0
	v_pk_mul_f32 v[26:27], v[16:17], s[10:11]
	s_nop 0
	v_pk_fma_f32 v[16:17], v[16:17], s[14:15], v[26:27] op_sel:[0,0,1] op_sel_hi:[1,0,0]
	v_pk_add_f32 v[26:27], v[18:19], v[28:29]
	v_pk_add_f32 v[18:19], v[18:19], v[28:29] neg_lo:[0,1] neg_hi:[0,1]
	v_pk_add_f32 v[28:29], v[20:21], v[30:31]
	v_pk_add_f32 v[20:21], v[20:21], v[30:31] neg_lo:[0,1] neg_hi:[0,1]
	s_nop 0
	v_pk_mul_f32 v[30:31], v[20:21], s[10:11]
	s_nop 0
	v_pk_fma_f32 v[20:21], v[20:21], s[14:15], v[30:31] op_sel:[0,0,1] op_sel_hi:[1,0,0] neg_lo:[1,0,0] neg_hi:[1,0,0]
	v_pk_add_f32 v[30:31], v[0:1], v[8:9] op_sel:[0,1] op_sel_hi:[1,0] neg_hi:[0,1]
	v_pk_add_f32 v[0:1], v[0:1], v[8:9] op_sel:[0,1] op_sel_hi:[1,0] neg_lo:[0,1]
	v_pk_add_f32 v[8:9], v[2:3], v[10:11]
	v_pk_add_f32 v[2:3], v[2:3], v[10:11] neg_lo:[0,1] neg_hi:[0,1]
	s_nop 0
	v_pk_mul_f32 v[10:11], v[2:3], s[10:11]
	s_nop 0
	v_pk_fma_f32 v[2:3], v[2:3], s[14:15], v[10:11] op_sel:[0,0,1] op_sel_hi:[1,0,0]
	v_pk_add_f32 v[10:11], v[4:5], v[12:13]
	v_pk_add_f32 v[4:5], v[4:5], v[12:13] neg_lo:[0,1] neg_hi:[0,1]
	v_pk_add_f32 v[12:13], v[6:7], v[14:15]
	v_pk_add_f32 v[6:7], v[6:7], v[14:15] neg_lo:[0,1] neg_hi:[0,1]
	s_nop 0
	v_pk_mul_f32 v[14:15], v[6:7], s[10:11]
	s_nop 0
	v_pk_fma_f32 v[6:7], v[6:7], s[14:15], v[14:15] op_sel:[0,0,1] op_sel_hi:[1,0,0] neg_lo:[1,0,0] neg_hi:[1,0,0]
	v_pk_add_f32 v[14:15], v[24:25], v[26:27]
	v_pk_add_f32 v[24:25], v[24:25], v[26:27] neg_lo:[0,1] neg_hi:[0,1]
	v_pk_add_f32 v[26:27], v[82:83], v[28:29]
	v_pk_add_f32 v[28:29], v[82:83], v[28:29] neg_lo:[0,1] neg_hi:[0,1]
	v_pk_add_f32 v[82:83], v[22:23], v[18:19] op_sel:[0,1] op_sel_hi:[1,0] neg_hi:[0,1]
	v_pk_add_f32 v[18:19], v[22:23], v[18:19] op_sel:[0,1] op_sel_hi:[1,0] neg_lo:[0,1]
	v_pk_add_f32 v[22:23], v[16:17], v[20:21]
	v_pk_add_f32 v[16:17], v[16:17], v[20:21] neg_lo:[0,1] neg_hi:[0,1]
	v_pk_add_f32 v[20:21], v[30:31], v[10:11]
	v_pk_add_f32 v[10:11], v[30:31], v[10:11] neg_lo:[0,1] neg_hi:[0,1]
	v_pk_add_f32 v[30:31], v[8:9], v[12:13]
	v_pk_add_f32 v[8:9], v[8:9], v[12:13] neg_lo:[0,1] neg_hi:[0,1]
	v_pk_add_f32 v[12:13], v[0:1], v[4:5] op_sel:[0,1] op_sel_hi:[1,0] neg_hi:[0,1]
	v_pk_add_f32 v[0:1], v[0:1], v[4:5] op_sel:[0,1] op_sel_hi:[1,0] neg_lo:[0,1]
	v_pk_add_f32 v[4:5], v[2:3], v[6:7]
	v_pk_add_f32 v[2:3], v[2:3], v[6:7] neg_lo:[0,1] neg_hi:[0,1]
	s_nop 0
	v_pk_mul_f32 v[2:3], v[2:3], s[22:23]
	v_pk_add_f32 v[6:7], v[14:15], v[26:27]
	v_pk_add_f32 v[14:15], v[14:15], v[26:27] neg_lo:[0,1] neg_hi:[0,1]
	v_pk_add_f32 v[26:27], v[24:25], v[28:29] op_sel:[0,1] op_sel_hi:[1,0] neg_hi:[0,1]
	v_pk_add_f32 v[24:25], v[24:25], v[28:29] op_sel:[0,1] op_sel_hi:[1,0] neg_lo:[0,1]
	v_pk_add_f32 v[28:29], v[82:83], v[22:23]
	v_pk_add_f32 v[22:23], v[82:83], v[22:23] neg_lo:[0,1] neg_hi:[0,1]
	v_pk_add_f32 v[82:83], v[18:19], v[16:17] op_sel:[0,1] op_sel_hi:[1,0] neg_hi:[0,1]
	v_pk_add_f32 v[16:17], v[18:19], v[16:17] op_sel:[0,1] op_sel_hi:[1,0] neg_lo:[0,1]
	v_pk_add_f32 v[18:19], v[20:21], v[30:31]
	v_pk_add_f32 v[20:21], v[20:21], v[30:31] neg_lo:[0,1] neg_hi:[0,1]
	v_pk_add_f32 v[30:31], v[10:11], v[8:9] op_sel:[0,1] op_sel_hi:[1,0] neg_hi:[0,1]
	v_pk_add_f32 v[8:9], v[10:11], v[8:9] op_sel:[0,1] op_sel_hi:[1,0] neg_lo:[0,1]
	v_pk_add_f32 v[10:11], v[12:13], v[4:5]
	v_pk_add_f32 v[4:5], v[12:13], v[4:5] neg_lo:[0,1] neg_hi:[0,1]
	v_pk_add_f32 v[12:13], v[0:1], v[2:3] op_sel:[0,1] op_sel_hi:[1,0]
	v_pk_add_f32 v[0:1], v[0:1], v[2:3] op_sel:[0,1] op_sel_hi:[1,0] neg_lo:[0,1] neg_hi:[0,1]
	v_lshlrev_b32_e32 v2, 4, v37
	v_and_or_b32 v2, v2, s15, v47
	v_ashrrev_i32_e32 v3, 4, v2
	v_lshlrev_b32_e32 v3, 3, v3
	v_lshlrev_b32_e32 v2, 3, v2
	v_add3_u32 v2, 0, v3, v2
	ds_write_b64 v2, v[6:7]
	ds_write_b64 v2, v[14:15] offset:34816
	ds_write_b64 v2, v[26:27] offset:17408
	ds_write_b64 v2, v[24:25] offset:52224
	ds_write_b64 v2, v[28:29] offset:8704
	ds_write_b64 v2, v[22:23] offset:43520
	ds_write_b64 v2, v[82:83] offset:26112
	ds_write_b64 v2, v[16:17] offset:60928
	ds_write_b64 v2, v[18:19] offset:4352
	ds_write_b64 v2, v[20:21] offset:39168
	ds_write_b64 v2, v[30:31] offset:21760
	ds_write_b64 v2, v[8:9] offset:56576
	ds_write_b64 v2, v[10:11] offset:13056
	ds_write_b64 v2, v[4:5] offset:47872
	ds_write_b64 v2, v[12:13] offset:30464
	ds_write_b64 v2, v[0:1] offset:65280
	s_waitcnt lgkmcnt(0)
	s_barrier
	s_and_saveexec_b64 s[0:1], s[42:43]
	s_cbranch_execz .LBB0_500
	v_lshl_add_u64 v[2:3], v[78:79], 0, v[172:173]
	s_mov_b64 s[4:5], 0x80000
	v_lshl_add_u64 v[0:1], v[2:3], 0, s[4:5]
	v_add_co_u32_e32 v2, vcc, 0x80000, v2
	v_cmp_ne_u32_e64 s[42:43], 0, v39
	s_nop 0
	v_addc_co_u32_e32 v3, vcc, 0, v3, vcc
	global_load_dwordx4 v[12:15], v[2:3], off
	global_load_dwordx4 v[8:11], v[0:1], off offset:16
	v_mov_b32_e32 v19, 0
	v_mov_b32_e32 v21, 0
	s_and_saveexec_b64 s[4:5], s[42:43]
	s_cbranch_execz .LBB0_493
	global_load_ushort v2, v[0:1], off offset:-2
	s_waitcnt vmcnt(0)
	v_lshlrev_b32_e32 v21, 16, v2

.LBB0_596:
	s_or_b64 exec, exec, s[4:5]
	s_waitcnt vmcnt(0)
	ds_write_b64 v35, v[0:1] offset:65280
	s_waitcnt lgkmcnt(0)
	s_barrier
	s_and_saveexec_b64 s[0:1], s[40:41]
	s_xor_b64 s[0:1], exec, s[0:1]
	s_cbranch_execz .LBB0_598
	v_add3_u32 v33, s26, v41, v157
	ds_read_b64 v[0:1], v33 offset:2176
	ds_read_b64 v[2:3], v33 offset:4352
	ds_read_b64 v[4:5], v33 offset:6528
	ds_read_b64 v[6:7], v33 offset:8704
	ds_read_b64 v[8:9], v33 offset:10880
	ds_read_b64 v[10:11], v33 offset:13056
	ds_read_b64 v[12:13], v33 offset:15232
	ds_read_b64 v[14:15], v33 offset:17408
	ds_read_b64 v[16:17], v33 offset:19584
	ds_read_b64 v[18:19], v33 offset:21760
	ds_read_b64 v[20:21], v33 offset:23936
	ds_read_b64 v[22:23], v33 offset:26112
	ds_read_b64 v[24:25], v33 offset:34816
	ds_read_b64 v[26:27], v33 offset:36992
	ds_read_b64 v[28:29], v33 offset:39168
	ds_read_b64 v[30:31], v33 offset:41344
	ds_read_b64 v[48:49], v33 offset:43520
	ds_read_b64 v[50:51], v33 offset:45696
	ds_read_b64 v[52:53], v33 offset:47872
	ds_read_b64 v[54:55], v33 offset:50048
	ds_read_b64 v[56:57], v33 offset:52224
	ds_read_b64 v[58:59], v33 offset:54400
	ds_read_b64 v[60:61], v33 offset:56576
	ds_read_b64 v[62:63], v33 offset:58752
	ds_read_b64 v[64:65], v33
	ds_read_b64 v[66:67], v33 offset:60928
	ds_read_b64 v[68:69], v33 offset:63104
	ds_read_b64 v[70:71], v33 offset:65280
	s_mov_b32 s11, s14
	s_waitcnt lgkmcnt(3)
	v_pk_add_f32 v[80:81], v[64:65], v[24:25]
	v_pk_add_f32 v[24:25], v[64:65], v[24:25] neg_lo:[0,1] neg_hi:[0,1]
	v_pk_add_f32 v[64:65], v[0:1], v[26:27]
	v_pk_add_f32 v[0:1], v[0:1], v[26:27] neg_lo:[0,1] neg_hi:[0,1]
	s_mov_b32 s13, s86
	v_pk_mul_f32 v[26:27], v[0:1], s[16:17]
	s_mov_b32 s4, s21
	v_pk_fma_f32 v[0:1], v[0:1], s[6:7], v[26:27] op_sel:[0,0,1] op_sel_hi:[1,0,0]
	v_pk_add_f32 v[26:27], v[2:3], v[28:29]
	v_pk_add_f32 v[2:3], v[2:3], v[28:29] neg_lo:[0,1] neg_hi:[0,1]
	s_mov_b32 s35, s30
	v_pk_mul_f32 v[28:29], v[2:3], s[18:19]
	s_mov_b32 s8, s19
	v_pk_fma_f32 v[2:3], v[2:3], s[30:31], v[28:29] op_sel:[0,0,1] op_sel_hi:[1,0,0]
	v_pk_add_f32 v[28:29], v[4:5], v[30:31]
	v_pk_add_f32 v[4:5], v[4:5], v[30:31] neg_lo:[0,1] neg_hi:[0,1]
	s_mov_b32 s77, s6
	v_pk_mul_f32 v[30:31], v[4:5], s[20:21]
	s_mov_b32 s28, s17
	v_pk_fma_f32 v[4:5], v[4:5], s[86:87], v[30:31] op_sel:[0,0,1] op_sel_hi:[1,0,0]
	v_pk_add_f32 v[30:31], v[6:7], v[48:49]
	v_pk_add_f32 v[6:7], v[6:7], v[48:49] neg_lo:[0,1] neg_hi:[0,1]
	v_add_u32_e32 v35, 0x10780, v33
	v_pk_mul_f32 v[48:49], v[6:7], s[10:11]
	ds_read_b64 v[72:73], v33 offset:28288
	ds_read_b64 v[74:75], v33 offset:30464
	ds_read_b64 v[76:77], v33 offset:32640
	ds_read_b64 v[78:79], v35
	v_pk_fma_f32 v[6:7], v[6:7], s[14:15], v[48:49] op_sel:[0,0,1] op_sel_hi:[1,0,0]
	v_pk_add_f32 v[48:49], v[8:9], v[50:51]
	v_pk_add_f32 v[8:9], v[8:9], v[50:51] neg_lo:[0,1] neg_hi:[0,1]
	s_nop 0
	v_pk_mul_f32 v[50:51], v[8:9], s[12:13]
	s_nop 0
	v_pk_fma_f32 v[8:9], v[8:9], s[4:5], v[50:51] op_sel:[0,0,1] op_sel_hi:[1,0,0]
	v_pk_add_f32 v[50:51], v[10:11], v[52:53]
	v_pk_add_f32 v[10:11], v[10:11], v[52:53] neg_lo:[0,1] neg_hi:[0,1]
	s_nop 0
	v_pk_mul_f32 v[52:53], v[10:11], s[34:35]
	s_nop 0
	v_pk_fma_f32 v[10:11], v[10:11], s[8:9], v[52:53] op_sel:[0,0,1] op_sel_hi:[1,0,0]
	v_pk_add_f32 v[52:53], v[12:13], v[54:55]
	v_pk_add_f32 v[12:13], v[12:13], v[54:55] neg_lo:[0,1] neg_hi:[0,1]
	s_nop 0
	v_pk_mul_f32 v[54:55], v[12:13], s[76:77]
	s_nop 0
	v_pk_fma_f32 v[12:13], v[12:13], s[28:29], v[54:55] op_sel:[0,0,1] op_sel_hi:[1,0,0]
	v_pk_add_f32 v[54:55], v[14:15], v[56:57]
	v_pk_add_f32 v[14:15], v[14:15], v[56:57] neg_lo:[0,1] neg_hi:[0,1]
	v_pk_add_f32 v[56:57], v[16:17], v[58:59]
	v_pk_add_f32 v[16:17], v[16:17], v[58:59] neg_lo:[0,1] neg_hi:[0,1]
	s_nop 0
	v_pk_mul_f32 v[58:59], v[16:17], s[76:77]
	s_nop 0
	v_pk_fma_f32 v[16:17], v[16:17], s[28:29], v[58:59] op_sel:[0,0,1] op_sel_hi:[1,0,0] neg_lo:[1,0,0] neg_hi:[1,0,0]
	v_pk_add_f32 v[58:59], v[18:19], v[60:61]
	v_pk_add_f32 v[18:19], v[18:19], v[60:61] neg_lo:[0,1] neg_hi:[0,1]
	s_nop 0
	v_pk_mul_f32 v[60:61], v[18:19], s[34:35]
	s_nop 0
	v_pk_fma_f32 v[18:19], v[18:19], s[8:9], v[60:61] op_sel:[0,0,1] op_sel_hi:[1,0,0] neg_lo:[1,0,0] neg_hi:[1,0,0]
	v_pk_add_f32 v[60:61], v[20:21], v[62:63]
	v_pk_add_f32 v[20:21], v[20:21], v[62:63] neg_lo:[0,1] neg_hi:[0,1]
	s_nop 0
	v_pk_mul_f32 v[62:63], v[20:21], s[12:13]
	s_nop 0
	v_pk_fma_f32 v[20:21], v[20:21], s[4:5], v[62:63] op_sel:[0,0,1] op_sel_hi:[1,0,0] neg_lo:[1,0,0] neg_hi:[1,0,0]
	s_waitcnt lgkmcnt(6)
	v_pk_add_f32 v[62:63], v[22:23], v[66:67]
	v_pk_add_f32 v[22:23], v[22:23], v[66:67] neg_lo:[0,1] neg_hi:[0,1]
	s_nop 0
	v_pk_mul_f32 v[66:67], v[22:23], s[10:11]
	s_nop 0
	v_pk_fma_f32 v[22:23], v[22:23], s[14:15], v[66:67] op_sel:[0,0,1] op_sel_hi:[1,0,0] neg_lo:[1,0,0] neg_hi:[1,0,0]
	s_waitcnt lgkmcnt(3)
	v_pk_add_f32 v[66:67], v[72:73], v[68:69]
	v_pk_add_f32 v[68:69], v[72:73], v[68:69] neg_lo:[0,1] neg_hi:[0,1]
	s_nop 0
	v_pk_mul_f32 v[72:73], v[68:69], s[20:21]
	s_nop 0
	v_pk_fma_f32 v[68:69], v[68:69], s[86:87], v[72:73] op_sel:[0,0,1] op_sel_hi:[1,0,0] neg_lo:[1,0,0] neg_hi:[1,0,0]
	s_waitcnt lgkmcnt(2)
	v_pk_add_f32 v[72:73], v[74:75], v[70:71]
	v_pk_add_f32 v[70:71], v[74:75], v[70:71] neg_lo:[0,1] neg_hi:[0,1]
	s_nop 0
	v_pk_mul_f32 v[74:75], v[70:71], s[18:19]
	s_nop 0
	v_pk_fma_f32 v[70:71], v[70:71], s[30:31], v[74:75] op_sel:[0,0,1] op_sel_hi:[1,0,0] neg_lo:[1,0,0] neg_hi:[1,0,0]
	s_waitcnt lgkmcnt(0)
	v_pk_add_f32 v[74:75], v[76:77], v[78:79]
	v_pk_add_f32 v[76:77], v[76:77], v[78:79] neg_lo:[0,1] neg_hi:[0,1]
	s_nop 0
	v_pk_mul_f32 v[78:79], v[76:77], s[16:17]
	s_nop 0
	v_pk_fma_f32 v[76:77], v[76:77], s[6:7], v[78:79] op_sel:[0,0,1] op_sel_hi:[1,0,0] neg_lo:[1,0,0] neg_hi:[1,0,0]
	v_pk_add_f32 v[78:79], v[80:81], v[54:55]
	v_pk_add_f32 v[54:55], v[80:81], v[54:55] neg_lo:[0,1] neg_hi:[0,1]
	v_pk_add_f32 v[80:81], v[64:65], v[56:57]
	v_pk_add_f32 v[56:57], v[64:65], v[56:57] neg_lo:[0,1] neg_hi:[0,1]
	s_nop 0
	v_pk_mul_f32 v[64:65], v[56:57], s[18:19]
	s_nop 0
	v_pk_fma_f32 v[56:57], v[56:57], s[30:31], v[64:65] op_sel:[0,0,1] op_sel_hi:[1,0,0]
	v_pk_add_f32 v[64:65], v[26:27], v[58:59]
	v_pk_add_f32 v[26:27], v[26:27], v[58:59] neg_lo:[0,1] neg_hi:[0,1]
	s_nop 0
	v_pk_mul_f32 v[58:59], v[26:27], s[10:11]
	s_nop 0
	v_pk_fma_f32 v[26:27], v[26:27], s[14:15], v[58:59] op_sel:[0,0,1] op_sel_hi:[1,0,0]
	v_pk_add_f32 v[58:59], v[28:29], v[60:61]
	v_pk_add_f32 v[28:29], v[28:29], v[60:61] neg_lo:[0,1] neg_hi:[0,1]
	s_nop 0
	v_pk_mul_f32 v[60:61], v[28:29], s[34:35]
	s_nop 0
	v_pk_fma_f32 v[28:29], v[28:29], s[8:9], v[60:61] op_sel:[0,0,1] op_sel_hi:[1,0,0]
	v_pk_add_f32 v[60:61], v[30:31], v[62:63]
	v_pk_add_f32 v[30:31], v[30:31], v[62:63] neg_lo:[0,1] neg_hi:[0,1]
	v_pk_add_f32 v[62:63], v[48:49], v[66:67]
	v_pk_add_f32 v[48:49], v[48:49], v[66:67] neg_lo:[0,1] neg_hi:[0,1]
	s_nop 0
	v_pk_mul_f32 v[66:67], v[48:49], s[34:35]
	s_nop 0
	v_pk_fma_f32 v[48:49], v[48:49], s[8:9], v[66:67] op_sel:[0,0,1] op_sel_hi:[1,0,0] neg_lo:[1,0,0] neg_hi:[1,0,0]
	v_pk_add_f32 v[66:67], v[50:51], v[72:73]
	v_pk_add_f32 v[50:51], v[50:51], v[72:73] neg_lo:[0,1] neg_hi:[0,1]
	s_nop 0
	v_pk_mul_f32 v[72:73], v[50:51], s[10:11]
	s_nop 0
	v_pk_fma_f32 v[50:51], v[50:51], s[14:15], v[72:73] op_sel:[0,0,1] op_sel_hi:[1,0,0] neg_lo:[1,0,0] neg_hi:[1,0,0]
	v_pk_add_f32 v[72:73], v[52:53], v[74:75]
	v_pk_add_f32 v[52:53], v[52:53], v[74:75] neg_lo:[0,1] neg_hi:[0,1]
	s_nop 0
	v_pk_mul_f32 v[74:75], v[52:53], s[18:19]
	s_nop 0
	v_pk_fma_f32 v[52:53], v[52:53], s[30:31], v[74:75] op_sel:[0,0,1] op_sel_hi:[1,0,0] neg_lo:[1,0,0] neg_hi:[1,0,0]
	v_pk_add_f32 v[74:75], v[24:25], v[14:15] op_sel:[0,1] op_sel_hi:[1,0] neg_hi:[0,1]
	v_pk_add_f32 v[14:15], v[24:25], v[14:15] op_sel:[0,1] op_sel_hi:[1,0] neg_lo:[0,1]
	v_pk_add_f32 v[24:25], v[0:1], v[16:17]
	v_pk_add_f32 v[0:1], v[0:1], v[16:17] neg_lo:[0,1] neg_hi:[0,1]
	s_nop 0
	v_pk_mul_f32 v[16:17], v[0:1], s[18:19]
	s_nop 0
	v_pk_fma_f32 v[0:1], v[0:1], s[30:31], v[16:17] op_sel:[0,0,1] op_sel_hi:[1,0,0]
	v_pk_add_f32 v[16:17], v[2:3], v[18:19]
	v_pk_add_f32 v[2:3], v[2:3], v[18:19] neg_lo:[0,1] neg_hi:[0,1]
	s_nop 0
	v_pk_mul_f32 v[18:19], v[2:3], s[10:11]
	s_nop 0
	v_pk_fma_f32 v[2:3], v[2:3], s[14:15], v[18:19] op_sel:[0,0,1] op_sel_hi:[1,0,0]
	v_pk_add_f32 v[18:19], v[4:5], v[20:21]
	v_pk_add_f32 v[4:5], v[4:5], v[20:21] neg_lo:[0,1] neg_hi:[0,1]
	s_nop 0
	v_pk_mul_f32 v[20:21], v[4:5], s[34:35]
	s_nop 0
	v_pk_fma_f32 v[4:5], v[4:5], s[8:9], v[20:21] op_sel:[0,0,1] op_sel_hi:[1,0,0]
	v_pk_add_f32 v[20:21], v[6:7], v[22:23]
	v_pk_add_f32 v[6:7], v[6:7], v[22:23] neg_lo:[0,1] neg_hi:[0,1]
	v_pk_add_f32 v[22:23], v[8:9], v[68:69]
	v_pk_add_f32 v[8:9], v[8:9], v[68:69] neg_lo:[0,1] neg_hi:[0,1]
	s_nop 0
	v_pk_mul_f32 v[68:69], v[8:9], s[34:35]
	s_nop 0
	v_pk_fma_f32 v[8:9], v[8:9], s[8:9], v[68:69] op_sel:[0,0,1] op_sel_hi:[1,0,0] neg_lo:[1,0,0] neg_hi:[1,0,0]
	v_pk_add_f32 v[68:69], v[10:11], v[70:71]
	v_pk_add_f32 v[10:11], v[10:11], v[70:71] neg_lo:[0,1] neg_hi:[0,1]
	s_nop 0
	v_pk_mul_f32 v[70:71], v[10:11], s[10:11]
	s_nop 0
	v_pk_fma_f32 v[10:11], v[10:11], s[14:15], v[70:71] op_sel:[0,0,1] op_sel_hi:[1,0,0] neg_lo:[1,0,0] neg_hi:[1,0,0]
	v_pk_add_f32 v[70:71], v[12:13], v[76:77]
	v_pk_add_f32 v[12:13], v[12:13], v[76:77] neg_lo:[0,1] neg_hi:[0,1]
	s_nop 0
	v_pk_mul_f32 v[76:77], v[12:13], s[18:19]
	s_nop 0
	v_pk_fma_f32 v[12:13], v[12:13], s[30:31], v[76:77] op_sel:[0,0,1] op_sel_hi:[1,0,0] neg_lo:[1,0,0] neg_hi:[1,0,0]
	v_pk_add_f32 v[76:77], v[78:79], v[60:61]
	v_pk_add_f32 v[60:61], v[78:79], v[60:61] neg_lo:[0,1] neg_hi:[0,1]
	v_pk_add_f32 v[78:79], v[80:81], v[62:63]
	v_pk_add_f32 v[62:63], v[80:81], v[62:63] neg_lo:[0,1] neg_hi:[0,1]
	s_nop 0
	v_pk_mul_f32 v[80:81], v[62:63], s[10:11]
	s_nop 0
	v_pk_fma_f32 v[62:63], v[62:63], s[14:15], v[80:81] op_sel:[0,0,1] op_sel_hi:[1,0,0]
	v_pk_add_f32 v[80:81], v[64:65], v[66:67]
	v_pk_add_f32 v[64:65], v[64:65], v[66:67] neg_lo:[0,1] neg_hi:[0,1]
	v_pk_add_f32 v[66:67], v[58:59], v[72:73]
	v_pk_add_f32 v[58:59], v[58:59], v[72:73] neg_lo:[0,1] neg_hi:[0,1]
	s_nop 0
	v_pk_mul_f32 v[72:73], v[58:59], s[10:11]
	s_nop 0
	v_pk_fma_f32 v[58:59], v[58:59], s[14:15], v[72:73] op_sel:[0,0,1] op_sel_hi:[1,0,0] neg_lo:[1,0,0] neg_hi:[1,0,0]
	v_pk_add_f32 v[72:73], v[54:55], v[30:31] op_sel:[0,1] op_sel_hi:[1,0] neg_hi:[0,1]
	v_pk_add_f32 v[30:31], v[54:55], v[30:31] op_sel:[0,1] op_sel_hi:[1,0] neg_lo:[0,1]
	v_pk_add_f32 v[54:55], v[56:57], v[48:49]
	v_pk_add_f32 v[48:49], v[56:57], v[48:49] neg_lo:[0,1] neg_hi:[0,1]
	v_pk_add_f32 v[82:83], v[62:63], v[58:59]
	v_pk_mul_f32 v[56:57], v[48:49], s[10:11]
	v_pk_add_f32 v[58:59], v[62:63], v[58:59] neg_lo:[0,1] neg_hi:[0,1]
	v_pk_fma_f32 v[48:49], v[48:49], s[14:15], v[56:57] op_sel:[0,0,1] op_sel_hi:[1,0,0]
	v_pk_add_f32 v[56:57], v[26:27], v[50:51]
	v_pk_add_f32 v[26:27], v[26:27], v[50:51] neg_lo:[0,1] neg_hi:[0,1]
	v_pk_add_f32 v[50:51], v[28:29], v[52:53]
	v_pk_add_f32 v[28:29], v[28:29], v[52:53] neg_lo:[0,1] neg_hi:[0,1]
	s_nop 0
	v_pk_mul_f32 v[52:53], v[28:29], s[10:11]
	v_pk_add_f32 v[88:89], v[54:55], v[50:51]
	v_pk_fma_f32 v[28:29], v[28:29], s[14:15], v[52:53] op_sel:[0,0,1] op_sel_hi:[1,0,0] neg_lo:[1,0,0] neg_hi:[1,0,0]
	v_pk_add_f32 v[52:53], v[74:75], v[20:21]
	v_pk_add_f32 v[20:21], v[74:75], v[20:21] neg_lo:[0,1] neg_hi:[0,1]
	v_pk_add_f32 v[74:75], v[24:25], v[22:23]
	v_pk_add_f32 v[22:23], v[24:25], v[22:23] neg_lo:[0,1] neg_hi:[0,1]
	v_pk_add_f32 v[50:51], v[54:55], v[50:51] neg_lo:[0,1] neg_hi:[0,1]
	v_pk_mul_f32 v[24:25], v[22:23], s[10:11]
	v_pk_add_f32 v[90:91], v[30:31], v[26:27] op_sel:[0,1] op_sel_hi:[1,0] neg_hi:[0,1]
	v_pk_fma_f32 v[22:23], v[22:23], s[14:15], v[24:25] op_sel:[0,0,1] op_sel_hi:[1,0,0]
	v_pk_add_f32 v[24:25], v[16:17], v[68:69]
	v_pk_add_f32 v[16:17], v[16:17], v[68:69] neg_lo:[0,1] neg_hi:[0,1]
	v_pk_add_f32 v[68:69], v[18:19], v[70:71]
	v_pk_add_f32 v[18:19], v[18:19], v[70:71] neg_lo:[0,1] neg_hi:[0,1]
	s_nop 0
	v_pk_mul_f32 v[70:71], v[18:19], s[10:11]
	v_pk_add_f32 v[26:27], v[30:31], v[26:27] op_sel:[0,1] op_sel_hi:[1,0] neg_lo:[0,1]
	v_pk_fma_f32 v[18:19], v[18:19], s[14:15], v[70:71] op_sel:[0,0,1] op_sel_hi:[1,0,0] neg_lo:[1,0,0] neg_hi:[1,0,0]
	v_pk_add_f32 v[70:71], v[14:15], v[6:7] op_sel:[0,1] op_sel_hi:[1,0] neg_hi:[0,1]
	v_pk_add_f32 v[6:7], v[14:15], v[6:7] op_sel:[0,1] op_sel_hi:[1,0] neg_lo:[0,1]
	v_pk_add_f32 v[14:15], v[0:1], v[8:9]
	v_pk_add_f32 v[0:1], v[0:1], v[8:9] neg_lo:[0,1] neg_hi:[0,1]
	v_pk_add_f32 v[30:31], v[48:49], v[28:29]
	v_pk_mul_f32 v[8:9], v[0:1], s[10:11]
	v_pk_add_f32 v[28:29], v[48:49], v[28:29] neg_lo:[0,1] neg_hi:[0,1]
	v_pk_fma_f32 v[0:1], v[0:1], s[14:15], v[8:9] op_sel:[0,0,1] op_sel_hi:[1,0,0]
	v_pk_add_f32 v[8:9], v[2:3], v[10:11]
	v_pk_add_f32 v[2:3], v[2:3], v[10:11] neg_lo:[0,1] neg_hi:[0,1]
	v_pk_add_f32 v[10:11], v[4:5], v[12:13]
	v_pk_add_f32 v[4:5], v[4:5], v[12:13] neg_lo:[0,1] neg_hi:[0,1]
	s_nop 0
	v_pk_mul_f32 v[12:13], v[4:5], s[10:11]
	v_pk_add_f32 v[92:93], v[52:53], v[24:25]
	v_pk_fma_f32 v[4:5], v[4:5], s[14:15], v[12:13] op_sel:[0,0,1] op_sel_hi:[1,0,0] neg_lo:[1,0,0] neg_hi:[1,0,0]
	v_pk_add_f32 v[12:13], v[76:77], v[80:81]
	v_pk_add_f32 v[76:77], v[76:77], v[80:81] neg_lo:[0,1] neg_hi:[0,1]
	v_pk_add_f32 v[80:81], v[78:79], v[66:67]
	v_pk_add_f32 v[66:67], v[78:79], v[66:67] neg_lo:[0,1] neg_hi:[0,1]
	v_pk_add_f32 v[94:95], v[52:53], v[24:25] neg_lo:[0,1] neg_hi:[0,1]
	v_pk_add_f32 v[96:97], v[74:75], v[68:69]
	v_pk_add_f32 v[24:25], v[74:75], v[68:69] neg_lo:[0,1] neg_hi:[0,1]
	v_pk_add_f32 v[74:75], v[20:21], v[16:17] op_sel:[0,1] op_sel_hi:[1,0] neg_hi:[0,1]
	v_pk_add_f32 v[98:99], v[20:21], v[16:17] op_sel:[0,1] op_sel_hi:[1,0] neg_lo:[0,1]
	v_pk_add_f32 v[16:17], v[22:23], v[18:19] neg_lo:[0,1] neg_hi:[0,1]
	v_pk_add_f32 v[104:105], v[70:71], v[8:9]
	v_pk_add_f32 v[106:107], v[70:71], v[8:9] neg_lo:[0,1] neg_hi:[0,1]
	v_pk_add_f32 v[8:9], v[14:15], v[10:11] neg_lo:[0,1] neg_hi:[0,1]
	v_pk_add_f32 v[110:111], v[6:7], v[2:3] op_sel:[0,1] op_sel_hi:[1,0] neg_hi:[0,1]
	v_pk_add_f32 v[112:113], v[6:7], v[2:3] op_sel:[0,1] op_sel_hi:[1,0] neg_lo:[0,1]
	v_pk_add_f32 v[2:3], v[0:1], v[4:5]
	v_pk_add_f32 v[0:1], v[0:1], v[4:5] neg_lo:[0,1] neg_hi:[0,1]
	v_pk_add_f32 v[78:79], v[60:61], v[64:65] op_sel:[0,1] op_sel_hi:[1,0] neg_hi:[0,1]
	v_pk_add_f32 v[64:65], v[60:61], v[64:65] op_sel:[0,1] op_sel_hi:[1,0] neg_lo:[0,1]
	v_pk_mul_f32 v[84:85], v[58:59], s[22:23]
	v_pk_add_f32 v[86:87], v[72:73], v[56:57]
	v_pk_add_f32 v[72:73], v[72:73], v[56:57] neg_lo:[0,1] neg_hi:[0,1]
	v_pk_mul_f32 v[48:49], v[28:29], s[22:23]
	v_pk_mul_f32 v[68:69], v[24:25], s[22:23]
	v_pk_add_f32 v[100:101], v[22:23], v[18:19]
	v_pk_mul_f32 v[102:103], v[16:17], s[22:23]
	v_pk_add_f32 v[70:71], v[14:15], v[10:11]
	v_pk_mul_f32 v[108:109], v[8:9], s[22:23]
	v_pk_mul_f32 v[114:115], v[0:1], s[22:23]
	v_pk_add_f32 v[28:29], v[12:13], v[80:81]
	v_pk_add_f32 v[62:63], v[12:13], v[80:81] neg_lo:[0,1] neg_hi:[0,1]
	v_pk_add_f32 v[24:25], v[76:77], v[66:67] op_sel:[0,1] op_sel_hi:[1,0] neg_hi:[0,1]
	v_pk_add_f32 v[60:61], v[76:77], v[66:67] op_sel:[0,1] op_sel_hi:[1,0] neg_lo:[0,1]
	v_pk_add_f32 v[20:21], v[78:79], v[82:83]
	v_pk_add_f32 v[58:59], v[78:79], v[82:83] neg_lo:[0,1] neg_hi:[0,1]
	v_pk_add_f32 v[16:17], v[64:65], v[84:85] op_sel:[0,1] op_sel_hi:[1,0]
	v_pk_add_f32 v[56:57], v[64:65], v[84:85] op_sel:[0,1] op_sel_hi:[1,0] neg_lo:[0,1] neg_hi:[0,1]
	v_pk_add_f32 v[12:13], v[86:87], v[88:89]
	v_pk_add_f32 v[54:55], v[86:87], v[88:89] neg_lo:[0,1] neg_hi:[0,1]
	v_pk_add_f32 v[8:9], v[72:73], v[50:51] op_sel:[0,1] op_sel_hi:[1,0] neg_hi:[0,1]
	v_pk_add_f32 v[52:53], v[72:73], v[50:51] op_sel:[0,1] op_sel_hi:[1,0] neg_lo:[0,1]
	v_pk_add_f32 v[4:5], v[90:91], v[30:31]
	v_pk_add_f32 v[50:51], v[90:91], v[30:31] neg_lo:[0,1] neg_hi:[0,1]
	v_pk_add_f32 v[0:1], v[26:27], v[48:49] op_sel:[0,1] op_sel_hi:[1,0]
	v_pk_add_f32 v[48:49], v[26:27], v[48:49] op_sel:[0,1] op_sel_hi:[1,0] neg_lo:[0,1] neg_hi:[0,1]
	v_pk_add_f32 v[30:31], v[92:93], v[96:97]
	v_pk_add_f32 v[78:79], v[92:93], v[96:97] neg_lo:[0,1] neg_hi:[0,1]
	v_pk_add_f32 v[26:27], v[94:95], v[68:69] op_sel:[0,1] op_sel_hi:[1,0]
	v_pk_add_f32 v[76:77], v[94:95], v[68:69] op_sel:[0,1] op_sel_hi:[1,0] neg_lo:[0,1] neg_hi:[0,1]
	v_pk_add_f32 v[22:23], v[74:75], v[100:101]
	v_pk_add_f32 v[74:75], v[74:75], v[100:101] neg_lo:[0,1] neg_hi:[0,1]
	v_pk_add_f32 v[18:19], v[98:99], v[102:103] op_sel:[0,1] op_sel_hi:[1,0]
	v_pk_add_f32 v[72:73], v[98:99], v[102:103] op_sel:[0,1] op_sel_hi:[1,0] neg_lo:[0,1] neg_hi:[0,1]
	v_pk_add_f32 v[14:15], v[104:105], v[70:71]
	v_pk_add_f32 v[70:71], v[104:105], v[70:71] neg_lo:[0,1] neg_hi:[0,1]
	v_pk_add_f32 v[10:11], v[106:107], v[108:109] op_sel:[0,1] op_sel_hi:[1,0]
	v_pk_add_f32 v[68:69], v[106:107], v[108:109] op_sel:[0,1] op_sel_hi:[1,0] neg_lo:[0,1] neg_hi:[0,1]
	v_pk_add_f32 v[6:7], v[110:111], v[2:3]
	v_pk_add_f32 v[66:67], v[110:111], v[2:3] neg_lo:[0,1] neg_hi:[0,1]
	v_pk_add_f32 v[2:3], v[112:113], v[114:115] op_sel:[0,1] op_sel_hi:[1,0]
	v_pk_add_f32 v[64:65], v[112:113], v[114:115] op_sel:[0,1] op_sel_hi:[1,0] neg_lo:[0,1] neg_hi:[0,1]

.LBB0_600:
	s_or_b64 exec, exec, s[0:1]
	v_mov_b32_e32 v33, v32
	s_waitcnt lgkmcnt(0)
	s_barrier
	s_mov_b32 s11, s14
	v_and_b32_e32 v35, 31, v33
	v_cvt_f32_ubyte0_e32 v24, v35
	v_mul_f32_e32 v37, 0x3b000000, v24
	v_sin_f32_e32 v24, v37
	v_ashrrev_i32_e32 v0, 4, v33
	v_lshlrev_b32_e32 v0, 3, v0
	v_lshlrev_b32_e32 v1, 3, v33
	v_cos_f32_e32 v50, v37
	v_add3_u32 v25, s26, v0, v1
	ds_read_b64 v[0:1], v25
	ds_read_b64 v[2:3], v25 offset:4352
	ds_read_b64 v[4:5], v25 offset:8704
	ds_read_b64 v[6:7], v25 offset:13056
	ds_read_b64 v[8:9], v25 offset:17408
	ds_read_b64 v[10:11], v25 offset:21760
	ds_read_b64 v[12:13], v25 offset:26112
	ds_read_b64 v[14:15], v25 offset:30464
	ds_read_b64 v[16:17], v25 offset:34816
	ds_read_b64 v[18:19], v25 offset:39168
	ds_read_b64 v[20:21], v25 offset:43520
	ds_read_b64 v[22:23], v25 offset:47872
	v_xor_b32_e32 v51, 0x80000000, v24
	s_waitcnt lgkmcnt(10)
	v_pk_mul_f32 v[52:53], v[2:3], v[24:25] op_sel:[1,0] op_sel_hi:[0,0] neg_hi:[0,1]
	v_pk_fma_f32 v[2:3], v[2:3], v[50:51], v[52:53] op_sel_hi:[1,0,1]
	v_pk_mul_f32 v[52:53], v[24:25], v[50:51] op_sel:[0,1] op_sel_hi:[0,0] neg_hi:[1,0]
	v_pk_fma_f32 v[52:53], v[50:51], v[50:51], v[52:53] op_sel_hi:[0,1,1]
	ds_read_b64 v[26:27], v25 offset:52224
	ds_read_b64 v[28:29], v25 offset:56576
	ds_read_b64 v[30:31], v25 offset:60928
	ds_read_b64 v[48:49], v25 offset:65280
	s_waitcnt lgkmcnt(13)
	v_pk_mul_f32 v[54:55], v[4:5], v[52:53] op_sel:[1,1] op_sel_hi:[0,1] neg_lo:[0,1]
	v_pk_fma_f32 v[4:5], v[4:5], v[52:53], v[54:55] op_sel_hi:[1,0,1]
	v_pk_mul_f32 v[54:55], v[24:25], v[52:53] op_sel:[0,1] op_sel_hi:[0,0] neg_hi:[1,0]
	v_pk_fma_f32 v[52:53], v[50:51], v[52:53], v[54:55] op_sel_hi:[0,1,1]
	s_mov_b32 s35, s30
	s_waitcnt lgkmcnt(12)
	v_pk_mul_f32 v[54:55], v[6:7], v[52:53] op_sel:[1,1] op_sel_hi:[0,1] neg_lo:[0,1]
	v_pk_fma_f32 v[6:7], v[6:7], v[52:53], v[54:55] op_sel_hi:[1,0,1]
	v_pk_mul_f32 v[54:55], v[24:25], v[52:53] op_sel:[0,1] op_sel_hi:[0,0] neg_hi:[1,0]
	v_pk_fma_f32 v[52:53], v[50:51], v[52:53], v[54:55] op_sel_hi:[0,1,1]
	s_mov_b32 s0, s19
	s_waitcnt lgkmcnt(11)
	v_pk_mul_f32 v[54:55], v[8:9], v[52:53] op_sel:[1,1] op_sel_hi:[0,1] neg_lo:[0,1]
	v_pk_fma_f32 v[8:9], v[8:9], v[52:53], v[54:55] op_sel_hi:[1,0,1]
	v_pk_mul_f32 v[54:55], v[24:25], v[52:53] op_sel:[0,1] op_sel_hi:[0,0] neg_hi:[1,0]
	v_pk_fma_f32 v[52:53], v[50:51], v[52:53], v[54:55] op_sel_hi:[0,1,1]
	s_waitcnt lgkmcnt(0)
	v_pk_mul_f32 v[54:55], v[10:11], v[52:53] op_sel:[1,1] op_sel_hi:[0,1] neg_lo:[0,1]
	v_pk_fma_f32 v[10:11], v[10:11], v[52:53], v[54:55] op_sel_hi:[1,0,1]
	v_pk_mul_f32 v[54:55], v[24:25], v[52:53] op_sel:[0,1] op_sel_hi:[0,0] neg_hi:[1,0]
	v_pk_fma_f32 v[52:53], v[50:51], v[52:53], v[54:55] op_sel_hi:[0,1,1]
	s_barrier
	v_pk_mul_f32 v[54:55], v[12:13], v[52:53] op_sel:[1,1] op_sel_hi:[0,1] neg_lo:[0,1]
	v_pk_fma_f32 v[12:13], v[12:13], v[52:53], v[54:55] op_sel_hi:[1,0,1]
	v_pk_mul_f32 v[54:55], v[24:25], v[52:53] op_sel:[0,1] op_sel_hi:[0,0] neg_hi:[1,0]
	v_pk_fma_f32 v[52:53], v[50:51], v[52:53], v[54:55] op_sel_hi:[0,1,1]
	s_nop 0
	v_pk_mul_f32 v[54:55], v[14:15], v[52:53] op_sel:[1,1] op_sel_hi:[0,1] neg_lo:[0,1]
	v_pk_fma_f32 v[14:15], v[14:15], v[52:53], v[54:55] op_sel_hi:[1,0,1]
	v_pk_mul_f32 v[54:55], v[24:25], v[52:53] op_sel:[0,1] op_sel_hi:[0,0] neg_hi:[1,0]
	v_pk_fma_f32 v[52:53], v[50:51], v[52:53], v[54:55] op_sel_hi:[0,1,1]
	s_add_u32 s46, s60, 0x99b2000
	v_pk_mul_f32 v[54:55], v[16:17], v[52:53] op_sel:[1,1] op_sel_hi:[0,1] neg_lo:[0,1]
	v_pk_fma_f32 v[16:17], v[16:17], v[52:53], v[54:55] op_sel_hi:[1,0,1]
	v_pk_mul_f32 v[54:55], v[24:25], v[52:53] op_sel:[0,1] op_sel_hi:[0,0] neg_hi:[1,0]
	v_pk_fma_f32 v[52:53], v[50:51], v[52:53], v[54:55] op_sel_hi:[0,1,1]
	s_addc_u32 s47, s61, 0
	v_pk_mul_f32 v[54:55], v[18:19], v[52:53] op_sel:[1,1] op_sel_hi:[0,1] neg_lo:[0,1]
	v_pk_fma_f32 v[18:19], v[18:19], v[52:53], v[54:55] op_sel_hi:[1,0,1]
	v_pk_mul_f32 v[54:55], v[24:25], v[52:53] op_sel:[0,1] op_sel_hi:[0,0] neg_hi:[1,0]
	v_pk_fma_f32 v[52:53], v[50:51], v[52:53], v[54:55] op_sel_hi:[0,1,1]
	s_mov_b32 s4, 0
	v_pk_mul_f32 v[54:55], v[20:21], v[52:53] op_sel:[1,1] op_sel_hi:[0,1] neg_lo:[0,1]
	v_pk_fma_f32 v[20:21], v[20:21], v[52:53], v[54:55] op_sel_hi:[1,0,1]
	v_pk_mul_f32 v[54:55], v[24:25], v[52:53] op_sel:[0,1] op_sel_hi:[0,0] neg_hi:[1,0]
	v_pk_fma_f32 v[52:53], v[50:51], v[52:53], v[54:55] op_sel_hi:[0,1,1]
	v_cmp_lt_i32_e64 s[42:43], 0, v32
	v_pk_mul_f32 v[54:55], v[22:23], v[52:53] op_sel:[1,1] op_sel_hi:[0,1] neg_lo:[0,1]
	v_pk_fma_f32 v[22:23], v[22:23], v[52:53], v[54:55] op_sel_hi:[1,0,1]
	v_pk_mul_f32 v[54:55], v[24:25], v[52:53] op_sel:[0,1] op_sel_hi:[0,0] neg_hi:[1,0]
	v_pk_fma_f32 v[52:53], v[50:51], v[52:53], v[54:55] op_sel_hi:[0,1,1]
	v_mov_b32_e32 v47, v46
	v_pk_mul_f32 v[54:55], v[26:27], v[52:53] op_sel:[1,1] op_sel_hi:[0,1] neg_lo:[0,1]
	v_pk_fma_f32 v[26:27], v[26:27], v[52:53], v[54:55] op_sel_hi:[1,0,1]
	v_pk_mul_f32 v[54:55], v[24:25], v[52:53] op_sel:[0,1] op_sel_hi:[0,0] neg_hi:[1,0]
	v_pk_fma_f32 v[52:53], v[50:51], v[52:53], v[54:55] op_sel_hi:[0,1,1]
	v_mov_b32_e32 v39, v38
	v_pk_mul_f32 v[54:55], v[28:29], v[52:53] op_sel:[1,1] op_sel_hi:[0,1] neg_lo:[0,1]
	v_pk_fma_f32 v[28:29], v[28:29], v[52:53], v[54:55] op_sel_hi:[1,0,1]
	v_pk_mul_f32 v[54:55], v[24:25], v[52:53] op_sel:[0,1] op_sel_hi:[0,0] neg_hi:[1,0]
	v_pk_fma_f32 v[52:53], v[50:51], v[52:53], v[54:55] op_sel_hi:[0,1,1]
	v_pk_mul_f32 v[24:25], v[24:25], v[52:53] op_sel:[0,1] op_sel_hi:[0,0] neg_hi:[1,0]
	v_pk_fma_f32 v[24:25], v[50:51], v[52:53], v[24:25] op_sel_hi:[0,1,1]
	v_pk_mul_f32 v[50:51], v[48:49], v[24:25] op_sel:[1,1] op_sel_hi:[0,1] neg_lo:[0,1]
	v_pk_fma_f32 v[24:25], v[48:49], v[24:25], v[50:51] op_sel_hi:[1,0,1]
	v_pk_add_f32 v[48:49], v[0:1], v[16:17]
	v_pk_add_f32 v[0:1], v[0:1], v[16:17] neg_lo:[0,1] neg_hi:[0,1]
	v_pk_add_f32 v[16:17], v[2:3], v[18:19]
	v_pk_add_f32 v[2:3], v[2:3], v[18:19] neg_lo:[0,1] neg_hi:[0,1]
	v_pk_mul_f32 v[54:55], v[30:31], v[52:53] op_sel:[1,1] op_sel_hi:[0,1] neg_lo:[0,1]
	v_pk_mul_f32 v[18:19], v[2:3], s[18:19]
	v_pk_fma_f32 v[30:31], v[30:31], v[52:53], v[54:55] op_sel_hi:[1,0,1]
	v_pk_fma_f32 v[2:3], v[2:3], s[30:31], v[18:19] op_sel:[0,0,1] op_sel_hi:[1,0,0]
	v_pk_add_f32 v[18:19], v[4:5], v[20:21]
	v_pk_add_f32 v[4:5], v[4:5], v[20:21] neg_lo:[0,1] neg_hi:[0,1]
	v_add_u32_e32 v122, v157, v41
	v_pk_mul_f32 v[20:21], v[4:5], s[10:11]
	s_nop 0
	v_pk_fma_f32 v[4:5], v[4:5], s[14:15], v[20:21] op_sel:[0,0,1] op_sel_hi:[1,0,0]
	v_pk_add_f32 v[20:21], v[6:7], v[22:23]
	v_pk_add_f32 v[6:7], v[6:7], v[22:23] neg_lo:[0,1] neg_hi:[0,1]
	s_nop 0
	v_pk_mul_f32 v[22:23], v[6:7], s[34:35]
	s_nop 0
	v_pk_fma_f32 v[6:7], v[6:7], s[0:1], v[22:23] op_sel:[0,0,1] op_sel_hi:[1,0,0]
	v_pk_add_f32 v[22:23], v[8:9], v[26:27]
	v_pk_add_f32 v[8:9], v[8:9], v[26:27] neg_lo:[0,1] neg_hi:[0,1]
	v_pk_add_f32 v[26:27], v[10:11], v[28:29]
	v_pk_add_f32 v[10:11], v[10:11], v[28:29] neg_lo:[0,1] neg_hi:[0,1]
	s_nop 0
	v_pk_mul_f32 v[28:29], v[10:11], s[34:35]
	s_nop 0
	v_pk_fma_f32 v[10:11], v[10:11], s[0:1], v[28:29] op_sel:[0,0,1] op_sel_hi:[1,0,0] neg_lo:[1,0,0] neg_hi:[1,0,0]
	v_pk_add_f32 v[28:29], v[12:13], v[30:31]
	v_pk_add_f32 v[12:13], v[12:13], v[30:31] neg_lo:[0,1] neg_hi:[0,1]
	s_nop 0
	v_pk_mul_f32 v[30:31], v[12:13], s[10:11]
	s_nop 0
	v_pk_fma_f32 v[12:13], v[12:13], s[14:15], v[30:31] op_sel:[0,0,1] op_sel_hi:[1,0,0] neg_lo:[1,0,0] neg_hi:[1,0,0]
	v_pk_add_f32 v[30:31], v[14:15], v[24:25]
	v_pk_add_f32 v[14:15], v[14:15], v[24:25] neg_lo:[0,1] neg_hi:[0,1]
	s_nop 0
	v_pk_mul_f32 v[24:25], v[14:15], s[18:19]
	s_nop 0
	v_pk_fma_f32 v[14:15], v[14:15], s[30:31], v[24:25] op_sel:[0,0,1] op_sel_hi:[1,0,0] neg_lo:[1,0,0] neg_hi:[1,0,0]
	v_pk_add_f32 v[24:25], v[48:49], v[22:23]
	v_pk_add_f32 v[22:23], v[48:49], v[22:23] neg_lo:[0,1] neg_hi:[0,1]
	v_pk_add_f32 v[48:49], v[16:17], v[26:27]
	v_pk_add_f32 v[16:17], v[16:17], v[26:27] neg_lo:[0,1] neg_hi:[0,1]
	s_nop 0
	v_pk_mul_f32 v[26:27], v[16:17], s[10:11]
	s_nop 0
	v_pk_fma_f32 v[16:17], v[16:17], s[14:15], v[26:27] op_sel:[0,0,1] op_sel_hi:[1,0,0]
	v_pk_add_f32 v[26:27], v[18:19], v[28:29]
	v_pk_add_f32 v[18:19], v[18:19], v[28:29] neg_lo:[0,1] neg_hi:[0,1]
	v_pk_add_f32 v[28:29], v[20:21], v[30:31]
	v_pk_add_f32 v[20:21], v[20:21], v[30:31] neg_lo:[0,1] neg_hi:[0,1]
	s_nop 0
	v_pk_mul_f32 v[30:31], v[20:21], s[10:11]
	s_nop 0
	v_pk_fma_f32 v[20:21], v[20:21], s[14:15], v[30:31] op_sel:[0,0,1] op_sel_hi:[1,0,0] neg_lo:[1,0,0] neg_hi:[1,0,0]
	v_pk_add_f32 v[30:31], v[0:1], v[8:9] op_sel:[0,1] op_sel_hi:[1,0] neg_hi:[0,1]
	v_pk_add_f32 v[0:1], v[0:1], v[8:9] op_sel:[0,1] op_sel_hi:[1,0] neg_lo:[0,1]
	v_pk_add_f32 v[8:9], v[2:3], v[10:11]
	v_pk_add_f32 v[2:3], v[2:3], v[10:11] neg_lo:[0,1] neg_hi:[0,1]
	s_nop 0
	v_pk_mul_f32 v[10:11], v[2:3], s[10:11]
	s_nop 0
	v_pk_fma_f32 v[2:3], v[2:3], s[14:15], v[10:11] op_sel:[0,0,1] op_sel_hi:[1,0,0]
	v_pk_add_f32 v[10:11], v[4:5], v[12:13]
	v_pk_add_f32 v[4:5], v[4:5], v[12:13] neg_lo:[0,1] neg_hi:[0,1]
	v_pk_add_f32 v[12:13], v[6:7], v[14:15]
	v_pk_add_f32 v[6:7], v[6:7], v[14:15] neg_lo:[0,1] neg_hi:[0,1]
	s_nop 0
	v_pk_mul_f32 v[14:15], v[6:7], s[10:11]
	s_nop 0
	v_pk_fma_f32 v[6:7], v[6:7], s[14:15], v[14:15] op_sel:[0,0,1] op_sel_hi:[1,0,0] neg_lo:[1,0,0] neg_hi:[1,0,0]
	v_pk_add_f32 v[14:15], v[24:25], v[26:27]
	v_pk_add_f32 v[24:25], v[24:25], v[26:27] neg_lo:[0,1] neg_hi:[0,1]
	v_pk_add_f32 v[26:27], v[48:49], v[28:29]
	v_pk_add_f32 v[28:29], v[48:49], v[28:29] neg_lo:[0,1] neg_hi:[0,1]
	v_pk_add_f32 v[48:49], v[22:23], v[18:19] op_sel:[0,1] op_sel_hi:[1,0] neg_hi:[0,1]
	v_pk_add_f32 v[18:19], v[22:23], v[18:19] op_sel:[0,1] op_sel_hi:[1,0] neg_lo:[0,1]
	v_pk_add_f32 v[22:23], v[16:17], v[20:21]
	v_pk_add_f32 v[16:17], v[16:17], v[20:21] neg_lo:[0,1] neg_hi:[0,1]
	v_pk_add_f32 v[20:21], v[30:31], v[10:11]
	v_pk_add_f32 v[10:11], v[30:31], v[10:11] neg_lo:[0,1] neg_hi:[0,1]
	v_pk_add_f32 v[30:31], v[8:9], v[12:13]
	v_pk_add_f32 v[8:9], v[8:9], v[12:13] neg_lo:[0,1] neg_hi:[0,1]
	v_pk_add_f32 v[12:13], v[0:1], v[4:5] op_sel:[0,1] op_sel_hi:[1,0] neg_hi:[0,1]
	v_pk_add_f32 v[0:1], v[0:1], v[4:5] op_sel:[0,1] op_sel_hi:[1,0] neg_lo:[0,1]
	v_pk_add_f32 v[4:5], v[2:3], v[6:7]
	v_pk_add_f32 v[2:3], v[2:3], v[6:7] neg_lo:[0,1] neg_hi:[0,1]
	s_nop 0
	v_pk_mul_f32 v[2:3], v[2:3], s[22:23]
	v_pk_add_f32 v[6:7], v[14:15], v[26:27]
	v_pk_add_f32 v[14:15], v[14:15], v[26:27] neg_lo:[0,1] neg_hi:[0,1]
	v_pk_add_f32 v[26:27], v[24:25], v[28:29] op_sel:[0,1] op_sel_hi:[1,0] neg_hi:[0,1]
	v_pk_add_f32 v[24:25], v[24:25], v[28:29] op_sel:[0,1] op_sel_hi:[1,0] neg_lo:[0,1]
	v_pk_add_f32 v[28:29], v[48:49], v[22:23]
	v_pk_add_f32 v[22:23], v[48:49], v[22:23] neg_lo:[0,1] neg_hi:[0,1]
	v_pk_add_f32 v[48:49], v[18:19], v[16:17] op_sel:[0,1] op_sel_hi:[1,0] neg_hi:[0,1]
	v_pk_add_f32 v[16:17], v[18:19], v[16:17] op_sel:[0,1] op_sel_hi:[1,0] neg_lo:[0,1]
	v_pk_add_f32 v[18:19], v[20:21], v[30:31]
	v_pk_add_f32 v[20:21], v[20:21], v[30:31] neg_lo:[0,1] neg_hi:[0,1]
	v_pk_add_f32 v[30:31], v[10:11], v[8:9] op_sel:[0,1] op_sel_hi:[1,0] neg_hi:[0,1]
	v_pk_add_f32 v[8:9], v[10:11], v[8:9] op_sel:[0,1] op_sel_hi:[1,0] neg_lo:[0,1]
	v_pk_add_f32 v[10:11], v[12:13], v[4:5]
	v_pk_add_f32 v[4:5], v[12:13], v[4:5] neg_lo:[0,1] neg_hi:[0,1]
	v_pk_add_f32 v[12:13], v[0:1], v[2:3] op_sel:[0,1] op_sel_hi:[1,0]
	v_pk_add_f32 v[0:1], v[0:1], v[2:3] op_sel:[0,1] op_sel_hi:[1,0] neg_lo:[0,1] neg_hi:[0,1]
	v_lshlrev_b32_e32 v2, 4, v33
	v_and_or_b32 v2, v2, s7, v35
	v_ashrrev_i32_e32 v3, 4, v2
	v_lshlrev_b32_e32 v3, 3, v3
	v_lshlrev_b32_e32 v2, 3, v2
	v_add3_u32 v2, s26, v3, v2
	v_add_u32_e32 v3, 0x800, v2
	v_mov_b32_e32 v33, v32
	ds_write2_b64 v2, v[6:7], v[18:19] offset1:34
	ds_write2_b64 v3, v[14:15], v[20:21] offset0:16 offset1:50
	ds_write2_b64 v2, v[26:27], v[30:31] offset0:136 offset1:170
	ds_write2_b64 v3, v[24:25], v[8:9] offset0:152 offset1:186
	ds_write2_b64 v2, v[28:29], v[10:11] offset0:68 offset1:102
	ds_write2_b64 v3, v[22:23], v[4:5] offset0:84 offset1:118
	ds_write2_b64 v2, v[48:49], v[12:13] offset0:204 offset1:238
	ds_write2_b64 v3, v[16:17], v[0:1] offset0:220 offset1:254
	s_waitcnt lgkmcnt(0)
	s_barrier
	s_nop 0
	v_and_b32_e32 v35, 0x1ff, v33
	v_cvt_f32_u32_e32 v24, v35
	v_ashrrev_i32_e32 v0, 4, v33
	v_lshlrev_b32_e32 v0, 3, v0
	v_lshlrev_b32_e32 v1, 3, v33
	v_mul_f32_e32 v37, 0x39000000, v24
	v_sin_f32_e32 v24, v37
	v_cos_f32_e32 v50, v37
	v_add3_u32 v25, s26, v0, v1
	ds_read_b64 v[0:1], v25
	ds_read_b64 v[2:3], v25 offset:4352
	ds_read_b64 v[4:5], v25 offset:8704
	ds_read_b64 v[6:7], v25 offset:13056
	ds_read_b64 v[8:9], v25 offset:17408
	ds_read_b64 v[10:11], v25 offset:21760
	ds_read_b64 v[12:13], v25 offset:26112
	ds_read_b64 v[14:15], v25 offset:30464
	v_xor_b32_e32 v51, 0x80000000, v24
	s_waitcnt lgkmcnt(6)
	v_pk_mul_f32 v[52:53], v[2:3], v[24:25] op_sel:[1,0] op_sel_hi:[0,0] neg_hi:[0,1]
	v_pk_fma_f32 v[2:3], v[2:3], v[50:51], v[52:53] op_sel_hi:[1,0,1]
	v_pk_mul_f32 v[52:53], v[24:25], v[50:51] op_sel:[0,1] op_sel_hi:[0,0] neg_hi:[1,0]
	v_pk_fma_f32 v[52:53], v[50:51], v[50:51], v[52:53] op_sel_hi:[0,1,1]
	ds_read_b64 v[16:17], v25 offset:34816
	ds_read_b64 v[18:19], v25 offset:39168
	ds_read_b64 v[20:21], v25 offset:43520
	ds_read_b64 v[22:23], v25 offset:47872
	s_waitcnt lgkmcnt(9)
	v_pk_mul_f32 v[54:55], v[4:5], v[52:53] op_sel:[1,1] op_sel_hi:[0,1] neg_lo:[0,1]
	v_pk_fma_f32 v[4:5], v[4:5], v[52:53], v[54:55] op_sel_hi:[1,0,1]
	v_pk_mul_f32 v[54:55], v[24:25], v[52:53] op_sel:[0,1] op_sel_hi:[0,0] neg_hi:[1,0]
	v_pk_fma_f32 v[52:53], v[50:51], v[52:53], v[54:55] op_sel_hi:[0,1,1]
	ds_read_b64 v[26:27], v25 offset:52224
	ds_read_b64 v[28:29], v25 offset:56576
	ds_read_b64 v[30:31], v25 offset:60928
	ds_read_b64 v[48:49], v25 offset:65280
	s_waitcnt lgkmcnt(12)
	v_pk_mul_f32 v[54:55], v[6:7], v[52:53] op_sel:[1,1] op_sel_hi:[0,1] neg_lo:[0,1]
	v_pk_fma_f32 v[6:7], v[6:7], v[52:53], v[54:55] op_sel_hi:[1,0,1]
	v_pk_mul_f32 v[54:55], v[24:25], v[52:53] op_sel:[0,1] op_sel_hi:[0,0] neg_hi:[1,0]
	v_pk_fma_f32 v[52:53], v[50:51], v[52:53], v[54:55] op_sel_hi:[0,1,1]
	s_waitcnt lgkmcnt(0)
	v_pk_mul_f32 v[54:55], v[8:9], v[52:53] op_sel:[1,1] op_sel_hi:[0,1] neg_lo:[0,1]
	v_pk_fma_f32 v[8:9], v[8:9], v[52:53], v[54:55] op_sel_hi:[1,0,1]
	v_pk_mul_f32 v[54:55], v[24:25], v[52:53] op_sel:[0,1] op_sel_hi:[0,0] neg_hi:[1,0]
	v_pk_fma_f32 v[52:53], v[50:51], v[52:53], v[54:55] op_sel_hi:[0,1,1]
	s_barrier
	v_pk_mul_f32 v[54:55], v[10:11], v[52:53] op_sel:[1,1] op_sel_hi:[0,1] neg_lo:[0,1]
	v_pk_fma_f32 v[10:11], v[10:11], v[52:53], v[54:55] op_sel_hi:[1,0,1]
	v_pk_mul_f32 v[54:55], v[24:25], v[52:53] op_sel:[0,1] op_sel_hi:[0,0] neg_hi:[1,0]
	v_pk_fma_f32 v[52:53], v[50:51], v[52:53], v[54:55] op_sel_hi:[0,1,1]
	s_nop 0
	v_pk_mul_f32 v[54:55], v[12:13], v[52:53] op_sel:[1,1] op_sel_hi:[0,1] neg_lo:[0,1]
	v_pk_fma_f32 v[12:13], v[12:13], v[52:53], v[54:55] op_sel_hi:[1,0,1]
	v_pk_mul_f32 v[54:55], v[24:25], v[52:53] op_sel:[0,1] op_sel_hi:[0,0] neg_hi:[1,0]
	v_pk_fma_f32 v[52:53], v[50:51], v[52:53], v[54:55] op_sel_hi:[0,1,1]
	v_mov_b32_e32 v37, v36
	v_pk_mul_f32 v[54:55], v[14:15], v[52:53] op_sel:[1,1] op_sel_hi:[0,1] neg_lo:[0,1]
	v_pk_fma_f32 v[14:15], v[14:15], v[52:53], v[54:55] op_sel_hi:[1,0,1]
	v_pk_mul_f32 v[54:55], v[24:25], v[52:53] op_sel:[0,1] op_sel_hi:[0,0] neg_hi:[1,0]
	v_pk_fma_f32 v[52:53], v[50:51], v[52:53], v[54:55] op_sel_hi:[0,1,1]
	s_nop 0
	v_pk_mul_f32 v[54:55], v[16:17], v[52:53] op_sel:[1,1] op_sel_hi:[0,1] neg_lo:[0,1]
	v_pk_fma_f32 v[16:17], v[16:17], v[52:53], v[54:55] op_sel_hi:[1,0,1]
	v_pk_mul_f32 v[54:55], v[24:25], v[52:53] op_sel:[0,1] op_sel_hi:[0,0] neg_hi:[1,0]
	v_pk_fma_f32 v[52:53], v[50:51], v[52:53], v[54:55] op_sel_hi:[0,1,1]
	s_nop 0
	v_pk_mul_f32 v[54:55], v[18:19], v[52:53] op_sel:[1,1] op_sel_hi:[0,1] neg_lo:[0,1]
	v_pk_fma_f32 v[18:19], v[18:19], v[52:53], v[54:55] op_sel_hi:[1,0,1]
	v_pk_mul_f32 v[54:55], v[24:25], v[52:53] op_sel:[0,1] op_sel_hi:[0,0] neg_hi:[1,0]
	v_pk_fma_f32 v[52:53], v[50:51], v[52:53], v[54:55] op_sel_hi:[0,1,1]
	s_nop 0
	v_pk_mul_f32 v[54:55], v[20:21], v[52:53] op_sel:[1,1] op_sel_hi:[0,1] neg_lo:[0,1]
	v_pk_fma_f32 v[20:21], v[20:21], v[52:53], v[54:55] op_sel_hi:[1,0,1]
	v_pk_mul_f32 v[54:55], v[24:25], v[52:53] op_sel:[0,1] op_sel_hi:[0,0] neg_hi:[1,0]
	v_pk_fma_f32 v[52:53], v[50:51], v[52:53], v[54:55] op_sel_hi:[0,1,1]
	s_nop 0
	v_pk_mul_f32 v[54:55], v[22:23], v[52:53] op_sel:[1,1] op_sel_hi:[0,1] neg_lo:[0,1]
	v_pk_fma_f32 v[22:23], v[22:23], v[52:53], v[54:55] op_sel_hi:[1,0,1]
	v_pk_mul_f32 v[54:55], v[24:25], v[52:53] op_sel:[0,1] op_sel_hi:[0,0] neg_hi:[1,0]
	v_pk_fma_f32 v[52:53], v[50:51], v[52:53], v[54:55] op_sel_hi:[0,1,1]
	s_nop 0
	v_pk_mul_f32 v[54:55], v[26:27], v[52:53] op_sel:[1,1] op_sel_hi:[0,1] neg_lo:[0,1]
	v_pk_fma_f32 v[26:27], v[26:27], v[52:53], v[54:55] op_sel_hi:[1,0,1]
	v_pk_mul_f32 v[54:55], v[24:25], v[52:53] op_sel:[0,1] op_sel_hi:[0,0] neg_hi:[1,0]
	v_pk_fma_f32 v[52:53], v[50:51], v[52:53], v[54:55] op_sel_hi:[0,1,1]
	s_nop 0
	v_pk_mul_f32 v[54:55], v[28:29], v[52:53] op_sel:[1,1] op_sel_hi:[0,1] neg_lo:[0,1]
	v_pk_fma_f32 v[28:29], v[28:29], v[52:53], v[54:55] op_sel_hi:[1,0,1]
	v_pk_mul_f32 v[54:55], v[24:25], v[52:53] op_sel:[0,1] op_sel_hi:[0,0] neg_hi:[1,0]
	v_pk_fma_f32 v[52:53], v[50:51], v[52:53], v[54:55] op_sel_hi:[0,1,1]
	v_pk_mul_f32 v[24:25], v[24:25], v[52:53] op_sel:[0,1] op_sel_hi:[0,0] neg_hi:[1,0]
	v_pk_fma_f32 v[24:25], v[50:51], v[52:53], v[24:25] op_sel_hi:[0,1,1]
	v_pk_mul_f32 v[50:51], v[48:49], v[24:25] op_sel:[1,1] op_sel_hi:[0,1] neg_lo:[0,1]
	v_pk_fma_f32 v[24:25], v[48:49], v[24:25], v[50:51] op_sel_hi:[1,0,1]
	v_pk_add_f32 v[48:49], v[0:1], v[16:17]
	v_pk_add_f32 v[0:1], v[0:1], v[16:17] neg_lo:[0,1] neg_hi:[0,1]
	v_pk_add_f32 v[16:17], v[2:3], v[18:19]
	v_pk_add_f32 v[2:3], v[2:3], v[18:19] neg_lo:[0,1] neg_hi:[0,1]
	v_pk_mul_f32 v[54:55], v[30:31], v[52:53] op_sel:[1,1] op_sel_hi:[0,1] neg_lo:[0,1]
	v_pk_mul_f32 v[18:19], v[2:3], s[18:19]
	v_pk_fma_f32 v[30:31], v[30:31], v[52:53], v[54:55] op_sel_hi:[1,0,1]
	v_pk_fma_f32 v[2:3], v[2:3], s[30:31], v[18:19] op_sel:[0,0,1] op_sel_hi:[1,0,0]
	v_pk_add_f32 v[18:19], v[4:5], v[20:21]
	v_pk_add_f32 v[4:5], v[4:5], v[20:21] neg_lo:[0,1] neg_hi:[0,1]
	v_mov_b32_e32 v50, v45
	v_pk_mul_f32 v[20:21], v[4:5], s[10:11]
	v_mov_b32_e32 v51, v44
	v_pk_fma_f32 v[4:5], v[4:5], s[14:15], v[20:21] op_sel:[0,0,1] op_sel_hi:[1,0,0]
	v_pk_add_f32 v[20:21], v[6:7], v[22:23]
	v_pk_add_f32 v[6:7], v[6:7], v[22:23] neg_lo:[0,1] neg_hi:[0,1]
	v_mov_b32_e32 v52, v43
	v_pk_mul_f32 v[22:23], v[6:7], s[34:35]
	v_mov_b32_e32 v53, v42
	v_pk_fma_f32 v[6:7], v[6:7], s[0:1], v[22:23] op_sel:[0,0,1] op_sel_hi:[1,0,0]
	v_pk_add_f32 v[22:23], v[8:9], v[26:27]
	v_pk_add_f32 v[8:9], v[8:9], v[26:27] neg_lo:[0,1] neg_hi:[0,1]
	v_pk_add_f32 v[26:27], v[10:11], v[28:29]
	v_pk_add_f32 v[10:11], v[10:11], v[28:29] neg_lo:[0,1] neg_hi:[0,1]
	s_nop 0
	v_pk_mul_f32 v[28:29], v[10:11], s[34:35]
	v_mov_b32_e32 v54, v40
	v_pk_fma_f32 v[10:11], v[10:11], s[0:1], v[28:29] op_sel:[0,0,1] op_sel_hi:[1,0,0] neg_lo:[1,0,0] neg_hi:[1,0,0]
	v_pk_add_f32 v[28:29], v[12:13], v[30:31]
	v_pk_add_f32 v[12:13], v[12:13], v[30:31] neg_lo:[0,1] neg_hi:[0,1]
	s_movk_i32 s0, 0xff
	v_pk_mul_f32 v[30:31], v[12:13], s[10:11]
	v_cmp_ne_u32_e64 s[44:45], s0, v32
	v_pk_fma_f32 v[12:13], v[12:13], s[14:15], v[30:31] op_sel:[0,0,1] op_sel_hi:[1,0,0] neg_lo:[1,0,0] neg_hi:[1,0,0]
	v_pk_add_f32 v[30:31], v[14:15], v[24:25]
	v_pk_add_f32 v[14:15], v[14:15], v[24:25] neg_lo:[0,1] neg_hi:[0,1]
	v_mov_b32_e32 v55, v40
	v_pk_mul_f32 v[24:25], v[14:15], s[18:19]
	s_mov_b64 s[0:1], -1
	v_pk_fma_f32 v[14:15], v[14:15], s[30:31], v[24:25] op_sel:[0,0,1] op_sel_hi:[1,0,0] neg_lo:[1,0,0] neg_hi:[1,0,0]
	v_pk_add_f32 v[24:25], v[48:49], v[22:23]
	v_pk_add_f32 v[22:23], v[48:49], v[22:23] neg_lo:[0,1] neg_hi:[0,1]
	v_pk_add_f32 v[48:49], v[16:17], v[26:27]
	v_pk_add_f32 v[16:17], v[16:17], v[26:27] neg_lo:[0,1] neg_hi:[0,1]
	s_nop 0
	v_pk_mul_f32 v[26:27], v[16:17], s[10:11]
	s_nop 0
	v_pk_fma_f32 v[16:17], v[16:17], s[14:15], v[26:27] op_sel:[0,0,1] op_sel_hi:[1,0,0]
	v_pk_add_f32 v[26:27], v[18:19], v[28:29]
	v_pk_add_f32 v[18:19], v[18:19], v[28:29] neg_lo:[0,1] neg_hi:[0,1]
	v_pk_add_f32 v[28:29], v[20:21], v[30:31]
	v_pk_add_f32 v[20:21], v[20:21], v[30:31] neg_lo:[0,1] neg_hi:[0,1]
	s_nop 0
	v_pk_mul_f32 v[30:31], v[20:21], s[10:11]
	s_nop 0
	v_pk_fma_f32 v[20:21], v[20:21], s[14:15], v[30:31] op_sel:[0,0,1] op_sel_hi:[1,0,0] neg_lo:[1,0,0] neg_hi:[1,0,0]
	v_pk_add_f32 v[30:31], v[0:1], v[8:9] op_sel:[0,1] op_sel_hi:[1,0] neg_hi:[0,1]
	v_pk_add_f32 v[0:1], v[0:1], v[8:9] op_sel:[0,1] op_sel_hi:[1,0] neg_lo:[0,1]
	v_pk_add_f32 v[8:9], v[2:3], v[10:11]
	v_pk_add_f32 v[2:3], v[2:3], v[10:11] neg_lo:[0,1] neg_hi:[0,1]
	s_nop 0
	v_pk_mul_f32 v[10:11], v[2:3], s[10:11]
	s_nop 0
	v_pk_fma_f32 v[2:3], v[2:3], s[14:15], v[10:11] op_sel:[0,0,1] op_sel_hi:[1,0,0]
	v_pk_add_f32 v[10:11], v[4:5], v[12:13]
	v_pk_add_f32 v[4:5], v[4:5], v[12:13] neg_lo:[0,1] neg_hi:[0,1]
	v_pk_add_f32 v[12:13], v[6:7], v[14:15]
	v_pk_add_f32 v[6:7], v[6:7], v[14:15] neg_lo:[0,1] neg_hi:[0,1]
	s_nop 0
	v_pk_mul_f32 v[14:15], v[6:7], s[10:11]
	s_nop 0
	v_pk_fma_f32 v[6:7], v[6:7], s[14:15], v[14:15] op_sel:[0,0,1] op_sel_hi:[1,0,0] neg_lo:[1,0,0] neg_hi:[1,0,0]
	v_pk_add_f32 v[14:15], v[24:25], v[26:27]
	v_pk_add_f32 v[24:25], v[24:25], v[26:27] neg_lo:[0,1] neg_hi:[0,1]
	v_pk_add_f32 v[26:27], v[48:49], v[28:29]
	v_pk_add_f32 v[28:29], v[48:49], v[28:29] neg_lo:[0,1] neg_hi:[0,1]
	v_pk_add_f32 v[48:49], v[22:23], v[18:19] op_sel:[0,1] op_sel_hi:[1,0] neg_hi:[0,1]
	v_pk_add_f32 v[18:19], v[22:23], v[18:19] op_sel:[0,1] op_sel_hi:[1,0] neg_lo:[0,1]
	v_pk_add_f32 v[22:23], v[16:17], v[20:21]
	v_pk_add_f32 v[16:17], v[16:17], v[20:21] neg_lo:[0,1] neg_hi:[0,1]
	v_pk_add_f32 v[20:21], v[30:31], v[10:11]
	v_pk_add_f32 v[10:11], v[30:31], v[10:11] neg_lo:[0,1] neg_hi:[0,1]
	v_pk_add_f32 v[30:31], v[8:9], v[12:13]
	v_pk_add_f32 v[8:9], v[8:9], v[12:13] neg_lo:[0,1] neg_hi:[0,1]
	v_pk_add_f32 v[12:13], v[0:1], v[4:5] op_sel:[0,1] op_sel_hi:[1,0] neg_hi:[0,1]
	v_pk_add_f32 v[0:1], v[0:1], v[4:5] op_sel:[0,1] op_sel_hi:[1,0] neg_lo:[0,1]
	v_pk_add_f32 v[4:5], v[2:3], v[6:7]
	v_pk_add_f32 v[2:3], v[2:3], v[6:7] neg_lo:[0,1] neg_hi:[0,1]
	s_nop 0
	v_pk_mul_f32 v[2:3], v[2:3], s[22:23]
	v_pk_add_f32 v[6:7], v[14:15], v[26:27]
	v_pk_add_f32 v[14:15], v[14:15], v[26:27] neg_lo:[0,1] neg_hi:[0,1]
	v_pk_add_f32 v[26:27], v[24:25], v[28:29] op_sel:[0,1] op_sel_hi:[1,0] neg_hi:[0,1]
	v_pk_add_f32 v[24:25], v[24:25], v[28:29] op_sel:[0,1] op_sel_hi:[1,0] neg_lo:[0,1]
	v_pk_add_f32 v[28:29], v[48:49], v[22:23]
	v_pk_add_f32 v[22:23], v[48:49], v[22:23] neg_lo:[0,1] neg_hi:[0,1]
	v_pk_add_f32 v[48:49], v[18:19], v[16:17] op_sel:[0,1] op_sel_hi:[1,0] neg_hi:[0,1]
	v_pk_add_f32 v[16:17], v[18:19], v[16:17] op_sel:[0,1] op_sel_hi:[1,0] neg_lo:[0,1]
	v_pk_add_f32 v[18:19], v[20:21], v[30:31]
	v_pk_add_f32 v[20:21], v[20:21], v[30:31] neg_lo:[0,1] neg_hi:[0,1]
	v_pk_add_f32 v[30:31], v[10:11], v[8:9] op_sel:[0,1] op_sel_hi:[1,0] neg_hi:[0,1]
	v_pk_add_f32 v[8:9], v[10:11], v[8:9] op_sel:[0,1] op_sel_hi:[1,0] neg_lo:[0,1]
	v_pk_add_f32 v[10:11], v[12:13], v[4:5]
	v_pk_add_f32 v[4:5], v[12:13], v[4:5] neg_lo:[0,1] neg_hi:[0,1]
	v_pk_add_f32 v[12:13], v[0:1], v[2:3] op_sel:[0,1] op_sel_hi:[1,0]
	v_pk_add_f32 v[0:1], v[0:1], v[2:3] op_sel:[0,1] op_sel_hi:[1,0] neg_lo:[0,1] neg_hi:[0,1]
	v_lshlrev_b32_e32 v2, 4, v33
	v_and_or_b32 v2, v2, s15, v35
	v_ashrrev_i32_e32 v3, 4, v2
	v_lshlrev_b32_e32 v3, 3, v3
	v_lshlrev_b32_e32 v2, 3, v2
	v_add3_u32 v2, s26, v3, v2
	ds_write_b64 v2, v[6:7]
	ds_write_b64 v2, v[14:15] offset:34816
	ds_write_b64 v2, v[26:27] offset:17408
	ds_write_b64 v2, v[24:25] offset:52224
	ds_write_b64 v2, v[28:29] offset:8704
	ds_write_b64 v2, v[22:23] offset:43520
	ds_write_b64 v2, v[48:49] offset:26112
	ds_write_b64 v2, v[16:17] offset:60928
	ds_write_b64 v2, v[18:19] offset:4352
	ds_write_b64 v2, v[20:21] offset:39168
	ds_write_b64 v2, v[30:31] offset:21760
	ds_write_b64 v2, v[8:9] offset:56576
	ds_write_b64 v2, v[10:11] offset:13056
	ds_write_b64 v2, v[4:5] offset:47872
	ds_write_b64 v2, v[12:13] offset:30464
	ds_write_b64 v2, v[0:1] offset:65280
	v_lshlrev_b32_e32 v48, 4, v32
	v_ashrrev_i32_e32 v49, 31, v48
	v_mov_b32_e32 v172, v48
	v_add_u32_e32 v33, 0x10780, v153
	v_mov_b32_e32 v35, v34
	s_waitcnt lgkmcnt(0)
	s_barrier
	s_branch .LBB0_603

.LBB0_613:
	s_or_b64 exec, exec, s[28:29]
	s_xor_b64 s[0:1], s[0:1], -1
	v_cndmask_b32_e64 v76, 0, v24, s[40:41]
	v_cndmask_b32_e64 v77, 0, v58, s[40:41]
	v_cndmask_b32_e64 v70, 0, v25, s[40:41]
	v_cndmask_b32_e64 v71, 0, v59, s[40:41]
	v_cndmask_b32_e64 v90, 0, v22, s[40:41]
	v_cndmask_b32_e64 v91, 0, v30, s[40:41]
	v_cndmask_b32_e64 v82, 0, v23, s[40:41]
	v_cndmask_b32_e64 v83, 0, v31, s[40:41]
	v_cndmask_b32_e64 v74, 0, v20, s[40:41]
	v_cndmask_b32_e64 v75, 0, v28, s[40:41]
	v_cndmask_b32_e64 v66, 0, v21, s[40:41]
	v_cndmask_b32_e64 v67, 0, v29, s[40:41]
	v_cndmask_b32_e64 v88, 0, v16, s[40:41]
	v_cndmask_b32_e64 v89, 0, v26, s[40:41]
	v_cndmask_b32_e64 v80, 0, v17, s[40:41]
	v_cndmask_b32_e64 v81, 0, v27, s[40:41]
	v_cndmask_b32_e64 v72, 0, v14, s[40:41]
	v_cndmask_b32_e64 v73, 0, v6, s[40:41]
	v_cndmask_b32_e64 v64, 0, v15, s[40:41]
	v_cndmask_b32_e64 v65, 0, v7, s[40:41]
	v_cndmask_b32_e64 v84, 0, v12, s[40:41]
	v_cndmask_b32_e64 v85, 0, v4, s[40:41]
	v_cndmask_b32_e64 v78, 0, v13, s[40:41]
	v_cndmask_b32_e64 v79, 0, v5, s[40:41]
	v_cndmask_b32_e64 v68, 0, v10, s[40:41]
	v_cndmask_b32_e64 v69, 0, v2, s[40:41]
	v_cndmask_b32_e64 v62, 0, v11, s[40:41]
	v_cndmask_b32_e64 v63, 0, v3, s[40:41]
	v_cndmask_b32_e64 v60, 0, v8, s[40:41]
	v_cndmask_b32_e64 v61, 0, v0, s[40:41]
	v_cndmask_b32_e64 v58, 0, v9, s[40:41]
	v_cndmask_b32_e64 v59, 0, v1, s[40:41]
	ds_write2_b64 v152, v[76:77], v[70:71] offset1:1
	ds_write2_b64 v152, v[90:91], v[82:83] offset0:2 offset1:3
	ds_write2_b64 v152, v[74:75], v[66:67] offset0:4 offset1:5
	ds_write2_b64 v152, v[88:89], v[80:81] offset0:6 offset1:7
	ds_write2_b64 v152, v[72:73], v[64:65] offset0:8 offset1:9
	ds_write2_b64 v152, v[84:85], v[78:79] offset0:10 offset1:11
	ds_write2_b64 v152, v[68:69], v[62:63] offset0:12 offset1:13
	ds_write2_b64 v152, v[60:61], v[58:59] offset0:14 offset1:15
	s_waitcnt lgkmcnt(0)
	s_barrier
	s_and_saveexec_b64 s[28:29], s[40:41]
	s_cbranch_execz .LBB0_615
	ds_read_b64 v[0:1], v153
	ds_read_b64 v[2:3], v153 offset:2176
	ds_read_b64 v[4:5], v153 offset:4352
	ds_read_b64 v[6:7], v153 offset:6528
	ds_read_b64 v[8:9], v153 offset:8704
	ds_read_b64 v[10:11], v153 offset:10880
	ds_read_b64 v[12:13], v153 offset:13056
	ds_read_b64 v[14:15], v153 offset:15232
	ds_read_b64 v[16:17], v153 offset:17408
	ds_read_b64 v[18:19], v153 offset:19584
	ds_read_b64 v[20:21], v153 offset:21760
	ds_read_b64 v[22:23], v153 offset:23936
	ds_read_b64 v[24:25], v153 offset:26112
	ds_read_b64 v[26:27], v153 offset:28288
	ds_read_b64 v[28:29], v153 offset:30464
	ds_read_b64 v[30:31], v153 offset:32640
	ds_read_b64 v[86:87], v153 offset:34816
	ds_read_b64 v[92:93], v153 offset:41344
	ds_read_b64 v[94:95], v153 offset:43520
	ds_read_b64 v[96:97], v153 offset:45696
	ds_read_b64 v[98:99], v153 offset:47872
	ds_read_b64 v[100:101], v153 offset:50048
	ds_read_b64 v[102:103], v153 offset:52224
	ds_read_b64 v[104:105], v153 offset:54400
	ds_read_b64 v[106:107], v153 offset:56576
	ds_read_b64 v[108:109], v153 offset:58752
	ds_read_b64 v[110:111], v153 offset:60928
	ds_read_b64 v[112:113], v153 offset:63104
	ds_read_b64 v[114:115], v153 offset:65280
	ds_read_b64 v[116:117], v153 offset:36992
	ds_read_b64 v[118:119], v153 offset:39168
	ds_read_b64 v[120:121], v33
	s_waitcnt lgkmcnt(14)
	v_pk_add_f32 v[124:125], v[0:1], v[86:87]
	v_pk_add_f32 v[0:1], v[0:1], v[86:87] neg_lo:[0,1] neg_hi:[0,1]
	s_waitcnt lgkmcnt(2)
	v_pk_add_f32 v[86:87], v[2:3], v[116:117]
	v_pk_add_f32 v[2:3], v[2:3], v[116:117] neg_lo:[0,1] neg_hi:[0,1]
	s_mov_b32 s11, s14
	v_pk_mul_f32 v[116:117], v[2:3], s[16:17]
	s_mov_b32 s13, s86
	v_pk_fma_f32 v[2:3], v[2:3], s[6:7], v[116:117] op_sel:[0,0,1] op_sel_hi:[1,0,0]
	s_waitcnt lgkmcnt(1)
	v_pk_add_f32 v[116:117], v[4:5], v[118:119]
	v_pk_add_f32 v[4:5], v[4:5], v[118:119] neg_lo:[0,1] neg_hi:[0,1]
	s_mov_b32 s4, s21
	v_pk_mul_f32 v[118:119], v[4:5], s[18:19]
	s_mov_b32 s35, s30
	v_pk_fma_f32 v[4:5], v[4:5], s[30:31], v[118:119] op_sel:[0,0,1] op_sel_hi:[1,0,0]
	v_pk_add_f32 v[118:119], v[6:7], v[92:93]
	v_pk_add_f32 v[6:7], v[6:7], v[92:93] neg_lo:[0,1] neg_hi:[0,1]
	s_mov_b32 s8, s19
	v_pk_mul_f32 v[92:93], v[6:7], s[20:21]
	s_mov_b32 s77, s6
	v_pk_fma_f32 v[6:7], v[6:7], s[86:87], v[92:93] op_sel:[0,0,1] op_sel_hi:[1,0,0]
	v_pk_add_f32 v[92:93], v[8:9], v[94:95]
	v_pk_add_f32 v[8:9], v[8:9], v[94:95] neg_lo:[0,1] neg_hi:[0,1]
	s_mov_b32 s26, s17
	v_pk_mul_f32 v[94:95], v[8:9], s[10:11]
	s_nop 0
	v_pk_fma_f32 v[8:9], v[8:9], s[14:15], v[94:95] op_sel:[0,0,1] op_sel_hi:[1,0,0]
	v_pk_add_f32 v[94:95], v[10:11], v[96:97]
	v_pk_add_f32 v[10:11], v[10:11], v[96:97] neg_lo:[0,1] neg_hi:[0,1]
	s_nop 0
	v_pk_mul_f32 v[96:97], v[10:11], s[12:13]
	s_nop 0
	v_pk_fma_f32 v[10:11], v[10:11], s[4:5], v[96:97] op_sel:[0,0,1] op_sel_hi:[1,0,0]
	v_pk_add_f32 v[96:97], v[12:13], v[98:99]
	v_pk_add_f32 v[12:13], v[12:13], v[98:99] neg_lo:[0,1] neg_hi:[0,1]
	s_nop 0
	v_pk_mul_f32 v[98:99], v[12:13], s[34:35]
	s_nop 0
	v_pk_fma_f32 v[12:13], v[12:13], s[8:9], v[98:99] op_sel:[0,0,1] op_sel_hi:[1,0,0]
	v_pk_add_f32 v[98:99], v[14:15], v[100:101]
	v_pk_add_f32 v[14:15], v[14:15], v[100:101] neg_lo:[0,1] neg_hi:[0,1]
	s_nop 0
	v_pk_mul_f32 v[100:101], v[14:15], s[76:77]
	s_nop 0
	v_pk_fma_f32 v[14:15], v[14:15], s[26:27], v[100:101] op_sel:[0,0,1] op_sel_hi:[1,0,0]
	v_pk_add_f32 v[100:101], v[16:17], v[102:103]
	v_pk_add_f32 v[16:17], v[16:17], v[102:103] neg_lo:[0,1] neg_hi:[0,1]
	v_pk_add_f32 v[102:103], v[18:19], v[104:105]
	v_pk_add_f32 v[18:19], v[18:19], v[104:105] neg_lo:[0,1] neg_hi:[0,1]
	s_nop 0
	v_pk_mul_f32 v[104:105], v[18:19], s[76:77]
	s_nop 0
	v_pk_fma_f32 v[18:19], v[18:19], s[26:27], v[104:105] op_sel:[0,0,1] op_sel_hi:[1,0,0] neg_lo:[1,0,0] neg_hi:[1,0,0]
	v_pk_add_f32 v[104:105], v[20:21], v[106:107]
	v_pk_add_f32 v[20:21], v[20:21], v[106:107] neg_lo:[0,1] neg_hi:[0,1]
	s_nop 0
	v_pk_mul_f32 v[106:107], v[20:21], s[34:35]
	s_nop 0
	v_pk_fma_f32 v[20:21], v[20:21], s[8:9], v[106:107] op_sel:[0,0,1] op_sel_hi:[1,0,0] neg_lo:[1,0,0] neg_hi:[1,0,0]
	v_pk_add_f32 v[106:107], v[22:23], v[108:109]
	v_pk_add_f32 v[22:23], v[22:23], v[108:109] neg_lo:[0,1] neg_hi:[0,1]
	s_nop 0
	v_pk_mul_f32 v[108:109], v[22:23], s[12:13]
	s_nop 0
	v_pk_fma_f32 v[22:23], v[22:23], s[4:5], v[108:109] op_sel:[0,0,1] op_sel_hi:[1,0,0] neg_lo:[1,0,0] neg_hi:[1,0,0]
	v_pk_add_f32 v[108:109], v[24:25], v[110:111]
	v_pk_add_f32 v[24:25], v[24:25], v[110:111] neg_lo:[0,1] neg_hi:[0,1]
	s_nop 0
	v_pk_mul_f32 v[110:111], v[24:25], s[10:11]
	s_nop 0
	v_pk_fma_f32 v[24:25], v[24:25], s[14:15], v[110:111] op_sel:[0,0,1] op_sel_hi:[1,0,0] neg_lo:[1,0,0] neg_hi:[1,0,0]
	v_pk_add_f32 v[110:111], v[26:27], v[112:113]
	v_pk_add_f32 v[26:27], v[26:27], v[112:113] neg_lo:[0,1] neg_hi:[0,1]
	s_nop 0
	v_pk_mul_f32 v[112:113], v[26:27], s[20:21]
	s_nop 0
	v_pk_fma_f32 v[26:27], v[26:27], s[86:87], v[112:113] op_sel:[0,0,1] op_sel_hi:[1,0,0] neg_lo:[1,0,0] neg_hi:[1,0,0]
	v_pk_add_f32 v[112:113], v[28:29], v[114:115]
	v_pk_add_f32 v[28:29], v[28:29], v[114:115] neg_lo:[0,1] neg_hi:[0,1]
	s_nop 0
	v_pk_mul_f32 v[114:115], v[28:29], s[18:19]
	s_nop 0
	v_pk_fma_f32 v[28:29], v[28:29], s[30:31], v[114:115] op_sel:[0,0,1] op_sel_hi:[1,0,0] neg_lo:[1,0,0] neg_hi:[1,0,0]
	s_waitcnt lgkmcnt(0)
	v_pk_add_f32 v[114:115], v[30:31], v[120:121]
	v_pk_add_f32 v[30:31], v[30:31], v[120:121] neg_lo:[0,1] neg_hi:[0,1]
	s_nop 0
	v_pk_mul_f32 v[120:121], v[30:31], s[16:17]
	s_nop 0
	v_pk_fma_f32 v[30:31], v[30:31], s[6:7], v[120:121] op_sel:[0,0,1] op_sel_hi:[1,0,0] neg_lo:[1,0,0] neg_hi:[1,0,0]
	v_pk_add_f32 v[120:121], v[124:125], v[100:101]
	v_pk_add_f32 v[100:101], v[124:125], v[100:101] neg_lo:[0,1] neg_hi:[0,1]
	v_pk_add_f32 v[124:125], v[86:87], v[102:103]
	v_pk_add_f32 v[86:87], v[86:87], v[102:103] neg_lo:[0,1] neg_hi:[0,1]
	s_nop 0
	v_pk_mul_f32 v[102:103], v[86:87], s[18:19]
	s_nop 0
	v_pk_fma_f32 v[86:87], v[86:87], s[30:31], v[102:103] op_sel:[0,0,1] op_sel_hi:[1,0,0]
	v_pk_add_f32 v[102:103], v[116:117], v[104:105]
	v_pk_add_f32 v[104:105], v[116:117], v[104:105] neg_lo:[0,1] neg_hi:[0,1]
	s_nop 0
	v_pk_mul_f32 v[116:117], v[104:105], s[10:11]
	s_nop 0
	v_pk_fma_f32 v[104:105], v[104:105], s[14:15], v[116:117] op_sel:[0,0,1] op_sel_hi:[1,0,0]
	v_pk_add_f32 v[116:117], v[118:119], v[106:107]
	v_pk_add_f32 v[106:107], v[118:119], v[106:107] neg_lo:[0,1] neg_hi:[0,1]
	s_nop 0
	v_pk_mul_f32 v[118:119], v[106:107], s[34:35]
	s_nop 0
	v_pk_fma_f32 v[106:107], v[106:107], s[8:9], v[118:119] op_sel:[0,0,1] op_sel_hi:[1,0,0]
	v_pk_add_f32 v[118:119], v[92:93], v[108:109]
	v_pk_add_f32 v[92:93], v[92:93], v[108:109] neg_lo:[0,1] neg_hi:[0,1]
	v_pk_add_f32 v[108:109], v[94:95], v[110:111]
	v_pk_add_f32 v[94:95], v[94:95], v[110:111] neg_lo:[0,1] neg_hi:[0,1]
	s_nop 0
	v_pk_mul_f32 v[110:111], v[94:95], s[34:35]
	s_nop 0
	v_pk_fma_f32 v[94:95], v[94:95], s[8:9], v[110:111] op_sel:[0,0,1] op_sel_hi:[1,0,0] neg_lo:[1,0,0] neg_hi:[1,0,0]
	v_pk_add_f32 v[110:111], v[96:97], v[112:113]
	v_pk_add_f32 v[96:97], v[96:97], v[112:113] neg_lo:[0,1] neg_hi:[0,1]
	s_nop 0
	v_pk_mul_f32 v[112:113], v[96:97], s[10:11]
	s_nop 0
	v_pk_fma_f32 v[96:97], v[96:97], s[14:15], v[112:113] op_sel:[0,0,1] op_sel_hi:[1,0,0] neg_lo:[1,0,0] neg_hi:[1,0,0]
	v_pk_add_f32 v[112:113], v[98:99], v[114:115]
	v_pk_add_f32 v[98:99], v[98:99], v[114:115] neg_lo:[0,1] neg_hi:[0,1]
	s_nop 0
	v_pk_mul_f32 v[114:115], v[98:99], s[18:19]
	s_nop 0
	v_pk_fma_f32 v[98:99], v[98:99], s[30:31], v[114:115] op_sel:[0,0,1] op_sel_hi:[1,0,0] neg_lo:[1,0,0] neg_hi:[1,0,0]
	v_pk_add_f32 v[114:115], v[0:1], v[16:17] op_sel:[0,1] op_sel_hi:[1,0] neg_hi:[0,1]
	v_pk_add_f32 v[0:1], v[0:1], v[16:17] op_sel:[0,1] op_sel_hi:[1,0] neg_lo:[0,1]
	v_pk_add_f32 v[16:17], v[2:3], v[18:19]
	v_pk_add_f32 v[2:3], v[2:3], v[18:19] neg_lo:[0,1] neg_hi:[0,1]
	s_nop 0
	v_pk_mul_f32 v[18:19], v[2:3], s[18:19]
	s_nop 0
	v_pk_fma_f32 v[2:3], v[2:3], s[30:31], v[18:19] op_sel:[0,0,1] op_sel_hi:[1,0,0]
	v_pk_add_f32 v[18:19], v[4:5], v[20:21]
	v_pk_add_f32 v[4:5], v[4:5], v[20:21] neg_lo:[0,1] neg_hi:[0,1]
	s_nop 0
	v_pk_mul_f32 v[20:21], v[4:5], s[10:11]
	s_nop 0
	v_pk_fma_f32 v[4:5], v[4:5], s[14:15], v[20:21] op_sel:[0,0,1] op_sel_hi:[1,0,0]
	v_pk_add_f32 v[20:21], v[6:7], v[22:23]
	v_pk_add_f32 v[6:7], v[6:7], v[22:23] neg_lo:[0,1] neg_hi:[0,1]
	s_nop 0
	v_pk_mul_f32 v[22:23], v[6:7], s[34:35]
	s_nop 0
	v_pk_fma_f32 v[6:7], v[6:7], s[8:9], v[22:23] op_sel:[0,0,1] op_sel_hi:[1,0,0]
	v_pk_add_f32 v[22:23], v[8:9], v[24:25]
	v_pk_add_f32 v[8:9], v[8:9], v[24:25] neg_lo:[0,1] neg_hi:[0,1]
	v_pk_add_f32 v[24:25], v[10:11], v[26:27]
	v_pk_add_f32 v[10:11], v[10:11], v[26:27] neg_lo:[0,1] neg_hi:[0,1]
	s_nop 0
	v_pk_mul_f32 v[26:27], v[10:11], s[34:35]
	s_nop 0
	v_pk_fma_f32 v[10:11], v[10:11], s[8:9], v[26:27] op_sel:[0,0,1] op_sel_hi:[1,0,0] neg_lo:[1,0,0] neg_hi:[1,0,0]
	v_pk_add_f32 v[26:27], v[12:13], v[28:29]
	v_pk_add_f32 v[12:13], v[12:13], v[28:29] neg_lo:[0,1] neg_hi:[0,1]
	s_nop 0
	v_pk_mul_f32 v[28:29], v[12:13], s[10:11]
	s_nop 0
	v_pk_fma_f32 v[12:13], v[12:13], s[14:15], v[28:29] op_sel:[0,0,1] op_sel_hi:[1,0,0] neg_lo:[1,0,0] neg_hi:[1,0,0]
	v_pk_add_f32 v[28:29], v[14:15], v[30:31]
	v_pk_add_f32 v[14:15], v[14:15], v[30:31] neg_lo:[0,1] neg_hi:[0,1]
	s_nop 0
	v_pk_mul_f32 v[30:31], v[14:15], s[18:19]
	s_nop 0
	v_pk_fma_f32 v[14:15], v[14:15], s[30:31], v[30:31] op_sel:[0,0,1] op_sel_hi:[1,0,0] neg_lo:[1,0,0] neg_hi:[1,0,0]
	v_pk_add_f32 v[30:31], v[120:121], v[118:119]
	v_pk_add_f32 v[118:119], v[120:121], v[118:119] neg_lo:[0,1] neg_hi:[0,1]
	v_pk_add_f32 v[120:121], v[124:125], v[108:109]
	v_pk_add_f32 v[108:109], v[124:125], v[108:109] neg_lo:[0,1] neg_hi:[0,1]
	s_nop 0
	v_pk_mul_f32 v[124:125], v[108:109], s[10:11]
	s_nop 0
	v_pk_fma_f32 v[108:109], v[108:109], s[14:15], v[124:125] op_sel:[0,0,1] op_sel_hi:[1,0,0]
	v_pk_add_f32 v[124:125], v[102:103], v[110:111]
	v_pk_add_f32 v[102:103], v[102:103], v[110:111] neg_lo:[0,1] neg_hi:[0,1]
	v_pk_add_f32 v[110:111], v[116:117], v[112:113]
	v_pk_add_f32 v[112:113], v[116:117], v[112:113] neg_lo:[0,1] neg_hi:[0,1]
	s_nop 0
	v_pk_mul_f32 v[116:117], v[112:113], s[10:11]
	s_nop 0
	v_pk_fma_f32 v[112:113], v[112:113], s[14:15], v[116:117] op_sel:[0,0,1] op_sel_hi:[1,0,0] neg_lo:[1,0,0] neg_hi:[1,0,0]
	v_pk_add_f32 v[116:117], v[100:101], v[92:93] op_sel:[0,1] op_sel_hi:[1,0] neg_hi:[0,1]
	v_pk_add_f32 v[92:93], v[100:101], v[92:93] op_sel:[0,1] op_sel_hi:[1,0] neg_lo:[0,1]
	v_pk_add_f32 v[100:101], v[86:87], v[94:95]
	v_pk_add_f32 v[86:87], v[86:87], v[94:95] neg_lo:[0,1] neg_hi:[0,1]
	v_pk_add_f32 v[126:127], v[108:109], v[112:113]
	v_pk_mul_f32 v[94:95], v[86:87], s[10:11]
	s_nop 0
	v_pk_fma_f32 v[86:87], v[86:87], s[14:15], v[94:95] op_sel:[0,0,1] op_sel_hi:[1,0,0]
	v_pk_add_f32 v[94:95], v[104:105], v[96:97]
	v_pk_add_f32 v[96:97], v[104:105], v[96:97] neg_lo:[0,1] neg_hi:[0,1]
	v_pk_add_f32 v[104:105], v[106:107], v[98:99]
	v_pk_add_f32 v[98:99], v[106:107], v[98:99] neg_lo:[0,1] neg_hi:[0,1]
	s_nop 0
	v_pk_mul_f32 v[106:107], v[98:99], s[10:11]
	v_pk_add_f32 v[130:131], v[92:93], v[96:97] op_sel:[0,1] op_sel_hi:[1,0] neg_hi:[0,1]
	v_pk_fma_f32 v[98:99], v[98:99], s[14:15], v[106:107] op_sel:[0,0,1] op_sel_hi:[1,0,0] neg_lo:[1,0,0] neg_hi:[1,0,0]
	v_pk_add_f32 v[106:107], v[114:115], v[22:23]
	v_pk_add_f32 v[22:23], v[114:115], v[22:23] neg_lo:[0,1] neg_hi:[0,1]
	v_pk_add_f32 v[114:115], v[16:17], v[24:25]
	v_pk_add_f32 v[16:17], v[16:17], v[24:25] neg_lo:[0,1] neg_hi:[0,1]
	v_pk_add_f32 v[132:133], v[92:93], v[96:97] op_sel:[0,1] op_sel_hi:[1,0] neg_lo:[0,1]
	v_pk_mul_f32 v[24:25], v[16:17], s[10:11]
	v_pk_add_f32 v[92:93], v[86:87], v[98:99]
	v_pk_fma_f32 v[16:17], v[16:17], s[14:15], v[24:25] op_sel:[0,0,1] op_sel_hi:[1,0,0]
	v_pk_add_f32 v[24:25], v[18:19], v[26:27]
	v_pk_add_f32 v[18:19], v[18:19], v[26:27] neg_lo:[0,1] neg_hi:[0,1]
	v_pk_add_f32 v[26:27], v[20:21], v[28:29]
	v_pk_add_f32 v[20:21], v[20:21], v[28:29] neg_lo:[0,1] neg_hi:[0,1]
	s_nop 0
	v_pk_mul_f32 v[28:29], v[20:21], s[10:11]
	v_pk_add_f32 v[86:87], v[86:87], v[98:99] neg_lo:[0,1] neg_hi:[0,1]
	v_pk_fma_f32 v[20:21], v[20:21], s[14:15], v[28:29] op_sel:[0,0,1] op_sel_hi:[1,0,0] neg_lo:[1,0,0] neg_hi:[1,0,0]
	v_pk_add_f32 v[28:29], v[0:1], v[8:9] op_sel:[0,1] op_sel_hi:[1,0] neg_hi:[0,1]
	v_pk_add_f32 v[0:1], v[0:1], v[8:9] op_sel:[0,1] op_sel_hi:[1,0] neg_lo:[0,1]
	v_pk_add_f32 v[8:9], v[2:3], v[10:11]
	v_pk_add_f32 v[2:3], v[2:3], v[10:11] neg_lo:[0,1] neg_hi:[0,1]
	v_pk_add_f32 v[134:135], v[106:107], v[24:25]
	v_pk_mul_f32 v[10:11], v[2:3], s[10:11]
	v_pk_add_f32 v[106:107], v[106:107], v[24:25] neg_lo:[0,1] neg_hi:[0,1]
	v_pk_fma_f32 v[2:3], v[2:3], s[14:15], v[10:11] op_sel:[0,0,1] op_sel_hi:[1,0,0]
	v_pk_add_f32 v[10:11], v[4:5], v[12:13]
	v_pk_add_f32 v[4:5], v[4:5], v[12:13] neg_lo:[0,1] neg_hi:[0,1]
	v_pk_add_f32 v[12:13], v[6:7], v[14:15]
	v_pk_add_f32 v[6:7], v[6:7], v[14:15] neg_lo:[0,1] neg_hi:[0,1]
	s_nop 0
	v_pk_mul_f32 v[14:15], v[6:7], s[10:11]
	v_pk_add_f32 v[24:25], v[114:115], v[26:27] neg_lo:[0,1] neg_hi:[0,1]
	v_pk_fma_f32 v[6:7], v[6:7], s[14:15], v[14:15] op_sel:[0,0,1] op_sel_hi:[1,0,0] neg_lo:[1,0,0] neg_hi:[1,0,0]
	v_pk_add_f32 v[14:15], v[30:31], v[124:125]
	v_pk_add_f32 v[30:31], v[30:31], v[124:125] neg_lo:[0,1] neg_hi:[0,1]
	v_pk_add_f32 v[124:125], v[120:121], v[110:111]
	v_pk_add_f32 v[110:111], v[120:121], v[110:111] neg_lo:[0,1] neg_hi:[0,1]
	v_pk_add_f32 v[120:121], v[118:119], v[102:103] op_sel:[0,1] op_sel_hi:[1,0] neg_hi:[0,1]
	v_pk_add_f32 v[118:119], v[118:119], v[102:103] op_sel:[0,1] op_sel_hi:[1,0] neg_lo:[0,1]
	v_pk_add_f32 v[102:103], v[108:109], v[112:113] neg_lo:[0,1] neg_hi:[0,1]
	v_pk_add_f32 v[112:113], v[116:117], v[94:95]
	v_pk_add_f32 v[94:95], v[116:117], v[94:95] neg_lo:[0,1] neg_hi:[0,1]
	v_pk_add_f32 v[116:117], v[100:101], v[104:105]
	v_pk_add_f32 v[100:101], v[100:101], v[104:105] neg_lo:[0,1] neg_hi:[0,1]
	v_pk_add_f32 v[138:139], v[22:23], v[18:19] op_sel:[0,1] op_sel_hi:[1,0] neg_hi:[0,1]
	v_pk_add_f32 v[140:141], v[22:23], v[18:19] op_sel:[0,1] op_sel_hi:[1,0] neg_lo:[0,1]
	v_pk_add_f32 v[18:19], v[16:17], v[20:21]
	v_pk_add_f32 v[16:17], v[16:17], v[20:21] neg_lo:[0,1] neg_hi:[0,1]
	v_pk_add_f32 v[144:145], v[28:29], v[10:11]
	v_pk_add_f32 v[158:159], v[28:29], v[10:11] neg_lo:[0,1] neg_hi:[0,1]
	v_pk_add_f32 v[10:11], v[8:9], v[12:13]
	v_pk_add_f32 v[8:9], v[8:9], v[12:13] neg_lo:[0,1] neg_hi:[0,1]
	v_pk_add_f32 v[162:163], v[0:1], v[4:5] op_sel:[0,1] op_sel_hi:[1,0] neg_hi:[0,1]
	v_pk_add_f32 v[164:165], v[0:1], v[4:5] op_sel:[0,1] op_sel_hi:[1,0] neg_lo:[0,1]
	v_pk_add_f32 v[0:1], v[2:3], v[6:7] neg_lo:[0,1] neg_hi:[0,1]
	v_pk_mul_f32 v[108:109], v[102:103], s[22:23]
	v_pk_mul_f32 v[128:129], v[100:101], s[22:23]
	v_pk_add_f32 v[136:137], v[114:115], v[26:27]
	v_pk_mul_f32 v[114:115], v[24:25], s[22:23]
	v_pk_mul_f32 v[142:143], v[16:17], s[22:23]
	v_pk_mul_f32 v[160:161], v[8:9], s[22:23]
	v_pk_add_f32 v[166:167], v[2:3], v[6:7]
	v_pk_mul_f32 v[168:169], v[0:1], s[22:23]
	v_pk_add_f32 v[28:29], v[14:15], v[124:125]
	v_pk_add_f32 v[104:105], v[14:15], v[124:125] neg_lo:[0,1] neg_hi:[0,1]
	v_pk_add_f32 v[24:25], v[30:31], v[110:111] op_sel:[0,1] op_sel_hi:[1,0] neg_hi:[0,1]
	v_pk_add_f32 v[102:103], v[30:31], v[110:111] op_sel:[0,1] op_sel_hi:[1,0] neg_lo:[0,1]
	v_pk_add_f32 v[20:21], v[120:121], v[126:127]
	v_pk_add_f32 v[100:101], v[120:121], v[126:127] neg_lo:[0,1] neg_hi:[0,1]
	v_pk_add_f32 v[16:17], v[118:119], v[108:109] op_sel:[0,1] op_sel_hi:[1,0]
	v_pk_add_f32 v[98:99], v[118:119], v[108:109] op_sel:[0,1] op_sel_hi:[1,0] neg_lo:[0,1] neg_hi:[0,1]
	v_pk_add_f32 v[12:13], v[112:113], v[116:117]
	v_pk_add_f32 v[96:97], v[112:113], v[116:117] neg_lo:[0,1] neg_hi:[0,1]
	v_pk_add_f32 v[8:9], v[94:95], v[128:129] op_sel:[0,1] op_sel_hi:[1,0]
	v_pk_add_f32 v[94:95], v[94:95], v[128:129] op_sel:[0,1] op_sel_hi:[1,0] neg_lo:[0,1] neg_hi:[0,1]
	v_pk_add_f32 v[4:5], v[130:131], v[92:93]
	v_pk_add_f32 v[92:93], v[130:131], v[92:93] neg_lo:[0,1] neg_hi:[0,1]
	v_pk_add_f32 v[0:1], v[132:133], v[86:87] op_sel:[0,1] op_sel_hi:[1,0] neg_hi:[0,1]
	v_pk_add_f32 v[86:87], v[132:133], v[86:87] op_sel:[0,1] op_sel_hi:[1,0] neg_lo:[0,1]
	v_pk_add_f32 v[30:31], v[134:135], v[136:137]
	v_pk_add_f32 v[120:121], v[134:135], v[136:137] neg_lo:[0,1] neg_hi:[0,1]
	v_pk_add_f32 v[26:27], v[106:107], v[114:115] op_sel:[0,1] op_sel_hi:[1,0]
	v_pk_add_f32 v[118:119], v[106:107], v[114:115] op_sel:[0,1] op_sel_hi:[1,0] neg_lo:[0,1] neg_hi:[0,1]
	v_pk_add_f32 v[22:23], v[138:139], v[18:19]
	v_pk_add_f32 v[116:117], v[138:139], v[18:19] neg_lo:[0,1] neg_hi:[0,1]
	v_pk_add_f32 v[18:19], v[140:141], v[142:143] op_sel:[0,1] op_sel_hi:[1,0]
	v_pk_add_f32 v[114:115], v[140:141], v[142:143] op_sel:[0,1] op_sel_hi:[1,0] neg_lo:[0,1] neg_hi:[0,1]
	v_pk_add_f32 v[14:15], v[144:145], v[10:11]
	v_pk_add_f32 v[112:113], v[144:145], v[10:11] neg_lo:[0,1] neg_hi:[0,1]
	v_pk_add_f32 v[10:11], v[158:159], v[160:161] op_sel:[0,1] op_sel_hi:[1,0]
	v_pk_add_f32 v[110:111], v[158:159], v[160:161] op_sel:[0,1] op_sel_hi:[1,0] neg_lo:[0,1] neg_hi:[0,1]
	v_pk_add_f32 v[6:7], v[162:163], v[166:167]
	v_pk_add_f32 v[108:109], v[162:163], v[166:167] neg_lo:[0,1] neg_hi:[0,1]
	v_pk_add_f32 v[2:3], v[164:165], v[168:169] op_sel:[0,1] op_sel_hi:[1,0]
	v_pk_add_f32 v[106:107], v[164:165], v[168:169] op_sel:[0,1] op_sel_hi:[1,0] neg_lo:[0,1] neg_hi:[0,1]

.LBB0_617:
	s_or_b64 exec, exec, s[4:5]
	v_mov_b32_e32 v41, v32
	s_waitcnt lgkmcnt(0)
	s_barrier
	s_mov_b32 s11, s14
	v_and_b32_e32 v98, 31, v41
	v_cvt_f32_ubyte0_e32 v24, v98
	v_mul_f32_e32 v92, 0x3b000000, v24
	v_sin_f32_e32 v24, v92
	v_ashrrev_i32_e32 v0, 4, v41
	v_lshlrev_b32_e32 v0, 3, v0
	v_lshlrev_b32_e32 v1, 3, v41
	v_cos_f32_e32 v92, v92
	v_add3_u32 v25, 0, v0, v1
	ds_read_b64 v[0:1], v25
	ds_read_b64 v[2:3], v25 offset:4352
	ds_read_b64 v[4:5], v25 offset:8704
	ds_read_b64 v[6:7], v25 offset:13056
	ds_read_b64 v[8:9], v25 offset:17408
	ds_read_b64 v[10:11], v25 offset:21760
	ds_read_b64 v[12:13], v25 offset:26112
	ds_read_b64 v[14:15], v25 offset:30464
	ds_read_b64 v[16:17], v25 offset:34816
	ds_read_b64 v[18:19], v25 offset:39168
	ds_read_b64 v[20:21], v25 offset:43520
	ds_read_b64 v[22:23], v25 offset:47872
	v_xor_b32_e32 v93, 0x80000000, v24
	s_waitcnt lgkmcnt(10)
	v_pk_mul_f32 v[94:95], v[2:3], v[24:25] op_sel:[1,0] op_sel_hi:[0,0] neg_hi:[0,1]
	v_pk_fma_f32 v[2:3], v[2:3], v[92:93], v[94:95] op_sel_hi:[1,0,1]
	v_pk_mul_f32 v[94:95], v[24:25], v[92:93] op_sel:[0,1] op_sel_hi:[0,0] neg_hi:[1,0]
	v_pk_fma_f32 v[94:95], v[92:93], v[92:93], v[94:95] op_sel_hi:[0,1,1]
	ds_read_b64 v[26:27], v25 offset:52224
	ds_read_b64 v[28:29], v25 offset:56576
	ds_read_b64 v[30:31], v25 offset:60928
	ds_read_b64 v[86:87], v25 offset:65280
	s_waitcnt lgkmcnt(13)
	v_pk_mul_f32 v[96:97], v[4:5], v[94:95] op_sel:[1,1] op_sel_hi:[0,1] neg_lo:[0,1]
	v_pk_fma_f32 v[4:5], v[4:5], v[94:95], v[96:97] op_sel_hi:[1,0,1]
	v_pk_mul_f32 v[96:97], v[24:25], v[94:95] op_sel:[0,1] op_sel_hi:[0,0] neg_hi:[1,0]
	v_pk_fma_f32 v[94:95], v[92:93], v[94:95], v[96:97] op_sel_hi:[0,1,1]
	s_mov_b32 s35, s30
	s_waitcnt lgkmcnt(12)
	v_pk_mul_f32 v[96:97], v[6:7], v[94:95] op_sel:[1,1] op_sel_hi:[0,1] neg_lo:[0,1]
	v_pk_fma_f32 v[6:7], v[6:7], v[94:95], v[96:97] op_sel_hi:[1,0,1]
	v_pk_mul_f32 v[96:97], v[24:25], v[94:95] op_sel:[0,1] op_sel_hi:[0,0] neg_hi:[1,0]
	v_pk_fma_f32 v[94:95], v[92:93], v[94:95], v[96:97] op_sel_hi:[0,1,1]
	s_mov_b32 s26, s19
	s_waitcnt lgkmcnt(11)
	v_pk_mul_f32 v[96:97], v[8:9], v[94:95] op_sel:[1,1] op_sel_hi:[0,1] neg_lo:[0,1]
	v_pk_fma_f32 v[8:9], v[8:9], v[94:95], v[96:97] op_sel_hi:[1,0,1]
	v_pk_mul_f32 v[96:97], v[24:25], v[94:95] op_sel:[0,1] op_sel_hi:[0,0] neg_hi:[1,0]
	v_pk_fma_f32 v[94:95], v[92:93], v[94:95], v[96:97] op_sel_hi:[0,1,1]
	s_waitcnt lgkmcnt(0)
	v_pk_mul_f32 v[96:97], v[10:11], v[94:95] op_sel:[1,1] op_sel_hi:[0,1] neg_lo:[0,1]
	v_pk_fma_f32 v[10:11], v[10:11], v[94:95], v[96:97] op_sel_hi:[1,0,1]
	v_pk_mul_f32 v[96:97], v[24:25], v[94:95] op_sel:[0,1] op_sel_hi:[0,0] neg_hi:[1,0]
	v_pk_fma_f32 v[94:95], v[92:93], v[94:95], v[96:97] op_sel_hi:[0,1,1]
	s_barrier
	v_pk_mul_f32 v[96:97], v[12:13], v[94:95] op_sel:[1,1] op_sel_hi:[0,1] neg_lo:[0,1]
	v_pk_fma_f32 v[12:13], v[12:13], v[94:95], v[96:97] op_sel_hi:[1,0,1]
	v_pk_mul_f32 v[96:97], v[24:25], v[94:95] op_sel:[0,1] op_sel_hi:[0,0] neg_hi:[1,0]
	v_pk_fma_f32 v[94:95], v[92:93], v[94:95], v[96:97] op_sel_hi:[0,1,1]
	s_nop 0
	v_pk_mul_f32 v[96:97], v[14:15], v[94:95] op_sel:[1,1] op_sel_hi:[0,1] neg_lo:[0,1]
	v_pk_fma_f32 v[14:15], v[14:15], v[94:95], v[96:97] op_sel_hi:[1,0,1]
	v_pk_mul_f32 v[96:97], v[24:25], v[94:95] op_sel:[0,1] op_sel_hi:[0,0] neg_hi:[1,0]
	v_pk_fma_f32 v[94:95], v[92:93], v[94:95], v[96:97] op_sel_hi:[0,1,1]
	s_mov_b32 s4, 0
	v_pk_mul_f32 v[96:97], v[16:17], v[94:95] op_sel:[1,1] op_sel_hi:[0,1] neg_lo:[0,1]
	v_pk_fma_f32 v[16:17], v[16:17], v[94:95], v[96:97] op_sel_hi:[1,0,1]
	v_pk_mul_f32 v[96:97], v[24:25], v[94:95] op_sel:[0,1] op_sel_hi:[0,0] neg_hi:[1,0]
	v_pk_fma_f32 v[94:95], v[92:93], v[94:95], v[96:97] op_sel_hi:[0,1,1]
	s_nop 0
	v_pk_mul_f32 v[96:97], v[18:19], v[94:95] op_sel:[1,1] op_sel_hi:[0,1] neg_lo:[0,1]
	v_pk_fma_f32 v[18:19], v[18:19], v[94:95], v[96:97] op_sel_hi:[1,0,1]
	v_pk_mul_f32 v[96:97], v[24:25], v[94:95] op_sel:[0,1] op_sel_hi:[0,0] neg_hi:[1,0]
	v_pk_fma_f32 v[94:95], v[92:93], v[94:95], v[96:97] op_sel_hi:[0,1,1]
	s_nop 0
	v_pk_mul_f32 v[96:97], v[20:21], v[94:95] op_sel:[1,1] op_sel_hi:[0,1] neg_lo:[0,1]
	v_pk_fma_f32 v[20:21], v[20:21], v[94:95], v[96:97] op_sel_hi:[1,0,1]
	v_pk_mul_f32 v[96:97], v[24:25], v[94:95] op_sel:[0,1] op_sel_hi:[0,0] neg_hi:[1,0]
	v_pk_fma_f32 v[94:95], v[92:93], v[94:95], v[96:97] op_sel_hi:[0,1,1]
	s_nop 0
	v_pk_mul_f32 v[96:97], v[22:23], v[94:95] op_sel:[1,1] op_sel_hi:[0,1] neg_lo:[0,1]
	v_pk_fma_f32 v[22:23], v[22:23], v[94:95], v[96:97] op_sel_hi:[1,0,1]
	v_pk_mul_f32 v[96:97], v[24:25], v[94:95] op_sel:[0,1] op_sel_hi:[0,0] neg_hi:[1,0]
	v_pk_fma_f32 v[94:95], v[92:93], v[94:95], v[96:97] op_sel_hi:[0,1,1]
	s_nop 0
	v_pk_mul_f32 v[96:97], v[26:27], v[94:95] op_sel:[1,1] op_sel_hi:[0,1] neg_lo:[0,1]
	v_pk_fma_f32 v[26:27], v[26:27], v[94:95], v[96:97] op_sel_hi:[1,0,1]
	v_pk_mul_f32 v[96:97], v[24:25], v[94:95] op_sel:[0,1] op_sel_hi:[0,0] neg_hi:[1,0]
	v_pk_fma_f32 v[94:95], v[92:93], v[94:95], v[96:97] op_sel_hi:[0,1,1]
	s_nop 0
	v_pk_mul_f32 v[96:97], v[28:29], v[94:95] op_sel:[1,1] op_sel_hi:[0,1] neg_lo:[0,1]
	v_pk_fma_f32 v[28:29], v[28:29], v[94:95], v[96:97] op_sel_hi:[1,0,1]
	v_pk_mul_f32 v[96:97], v[24:25], v[94:95] op_sel:[0,1] op_sel_hi:[0,0] neg_hi:[1,0]
	v_pk_fma_f32 v[94:95], v[92:93], v[94:95], v[96:97] op_sel_hi:[0,1,1]
	v_pk_mul_f32 v[24:25], v[24:25], v[94:95] op_sel:[0,1] op_sel_hi:[0,0] neg_hi:[1,0]
	v_pk_fma_f32 v[24:25], v[92:93], v[94:95], v[24:25] op_sel_hi:[0,1,1]
	v_pk_mul_f32 v[92:93], v[86:87], v[24:25] op_sel:[1,1] op_sel_hi:[0,1] neg_lo:[0,1]
	v_pk_fma_f32 v[24:25], v[86:87], v[24:25], v[92:93] op_sel_hi:[1,0,1]
	v_pk_add_f32 v[86:87], v[0:1], v[16:17]
	v_pk_add_f32 v[0:1], v[0:1], v[16:17] neg_lo:[0,1] neg_hi:[0,1]
	v_pk_add_f32 v[16:17], v[2:3], v[18:19]
	v_pk_add_f32 v[2:3], v[2:3], v[18:19] neg_lo:[0,1] neg_hi:[0,1]
	v_pk_mul_f32 v[96:97], v[30:31], v[94:95] op_sel:[1,1] op_sel_hi:[0,1] neg_lo:[0,1]
	v_pk_mul_f32 v[18:19], v[2:3], s[18:19]
	v_pk_fma_f32 v[30:31], v[30:31], v[94:95], v[96:97] op_sel_hi:[1,0,1]
	v_pk_fma_f32 v[2:3], v[2:3], s[30:31], v[18:19] op_sel:[0,0,1] op_sel_hi:[1,0,0]
	v_pk_add_f32 v[18:19], v[4:5], v[20:21]
	v_pk_add_f32 v[4:5], v[4:5], v[20:21] neg_lo:[0,1] neg_hi:[0,1]
	s_nop 0
	v_pk_mul_f32 v[20:21], v[4:5], s[10:11]
	s_nop 0
	v_pk_fma_f32 v[4:5], v[4:5], s[14:15], v[20:21] op_sel:[0,0,1] op_sel_hi:[1,0,0]
	v_pk_add_f32 v[20:21], v[6:7], v[22:23]
	v_pk_add_f32 v[6:7], v[6:7], v[22:23] neg_lo:[0,1] neg_hi:[0,1]
	s_nop 0
	v_pk_mul_f32 v[22:23], v[6:7], s[34:35]
	s_nop 0
	v_pk_fma_f32 v[6:7], v[6:7], s[26:27], v[22:23] op_sel:[0,0,1] op_sel_hi:[1,0,0]
	v_pk_add_f32 v[22:23], v[8:9], v[26:27]
	v_pk_add_f32 v[8:9], v[8:9], v[26:27] neg_lo:[0,1] neg_hi:[0,1]
	v_pk_add_f32 v[26:27], v[10:11], v[28:29]
	v_pk_add_f32 v[10:11], v[10:11], v[28:29] neg_lo:[0,1] neg_hi:[0,1]
	s_nop 0
	v_pk_mul_f32 v[28:29], v[10:11], s[34:35]
	s_nop 0
	v_pk_fma_f32 v[10:11], v[10:11], s[26:27], v[28:29] op_sel:[0,0,1] op_sel_hi:[1,0,0] neg_lo:[1,0,0] neg_hi:[1,0,0]
	v_pk_add_f32 v[28:29], v[12:13], v[30:31]
	v_pk_add_f32 v[12:13], v[12:13], v[30:31] neg_lo:[0,1] neg_hi:[0,1]
	s_nop 0
	v_pk_mul_f32 v[30:31], v[12:13], s[10:11]
	s_nop 0
	v_pk_fma_f32 v[12:13], v[12:13], s[14:15], v[30:31] op_sel:[0,0,1] op_sel_hi:[1,0,0] neg_lo:[1,0,0] neg_hi:[1,0,0]
	v_pk_add_f32 v[30:31], v[14:15], v[24:25]
	v_pk_add_f32 v[14:15], v[14:15], v[24:25] neg_lo:[0,1] neg_hi:[0,1]
	s_nop 0
	v_pk_mul_f32 v[24:25], v[14:15], s[18:19]
	s_nop 0
	v_pk_fma_f32 v[14:15], v[14:15], s[30:31], v[24:25] op_sel:[0,0,1] op_sel_hi:[1,0,0] neg_lo:[1,0,0] neg_hi:[1,0,0]
	v_pk_add_f32 v[24:25], v[86:87], v[22:23]
	v_pk_add_f32 v[22:23], v[86:87], v[22:23] neg_lo:[0,1] neg_hi:[0,1]
	v_pk_add_f32 v[86:87], v[16:17], v[26:27]
	v_pk_add_f32 v[16:17], v[16:17], v[26:27] neg_lo:[0,1] neg_hi:[0,1]
	s_nop 0
	v_pk_mul_f32 v[26:27], v[16:17], s[10:11]
	s_nop 0
	v_pk_fma_f32 v[16:17], v[16:17], s[14:15], v[26:27] op_sel:[0,0,1] op_sel_hi:[1,0,0]
	v_pk_add_f32 v[26:27], v[18:19], v[28:29]
	v_pk_add_f32 v[18:19], v[18:19], v[28:29] neg_lo:[0,1] neg_hi:[0,1]
	v_pk_add_f32 v[28:29], v[20:21], v[30:31]
	v_pk_add_f32 v[20:21], v[20:21], v[30:31] neg_lo:[0,1] neg_hi:[0,1]
	s_nop 0
	v_pk_mul_f32 v[30:31], v[20:21], s[10:11]
	s_nop 0
	v_pk_fma_f32 v[20:21], v[20:21], s[14:15], v[30:31] op_sel:[0,0,1] op_sel_hi:[1,0,0] neg_lo:[1,0,0] neg_hi:[1,0,0]
	v_pk_add_f32 v[30:31], v[0:1], v[8:9] op_sel:[0,1] op_sel_hi:[1,0] neg_hi:[0,1]
	v_pk_add_f32 v[0:1], v[0:1], v[8:9] op_sel:[0,1] op_sel_hi:[1,0] neg_lo:[0,1]
	v_pk_add_f32 v[8:9], v[2:3], v[10:11]
	v_pk_add_f32 v[2:3], v[2:3], v[10:11] neg_lo:[0,1] neg_hi:[0,1]
	s_nop 0
	v_pk_mul_f32 v[10:11], v[2:3], s[10:11]
	s_nop 0
	v_pk_fma_f32 v[2:3], v[2:3], s[14:15], v[10:11] op_sel:[0,0,1] op_sel_hi:[1,0,0]
	v_pk_add_f32 v[10:11], v[4:5], v[12:13]
	v_pk_add_f32 v[4:5], v[4:5], v[12:13] neg_lo:[0,1] neg_hi:[0,1]
	v_pk_add_f32 v[12:13], v[6:7], v[14:15]
	v_pk_add_f32 v[6:7], v[6:7], v[14:15] neg_lo:[0,1] neg_hi:[0,1]
	s_nop 0
	v_pk_mul_f32 v[14:15], v[6:7], s[10:11]
	s_nop 0
	v_pk_fma_f32 v[6:7], v[6:7], s[14:15], v[14:15] op_sel:[0,0,1] op_sel_hi:[1,0,0] neg_lo:[1,0,0] neg_hi:[1,0,0]
	v_pk_add_f32 v[14:15], v[24:25], v[26:27]
	v_pk_add_f32 v[24:25], v[24:25], v[26:27] neg_lo:[0,1] neg_hi:[0,1]
	v_pk_add_f32 v[26:27], v[86:87], v[28:29]
	v_pk_add_f32 v[28:29], v[86:87], v[28:29] neg_lo:[0,1] neg_hi:[0,1]
	v_pk_add_f32 v[86:87], v[22:23], v[18:19] op_sel:[0,1] op_sel_hi:[1,0] neg_hi:[0,1]
	v_pk_add_f32 v[18:19], v[22:23], v[18:19] op_sel:[0,1] op_sel_hi:[1,0] neg_lo:[0,1]
	v_pk_add_f32 v[22:23], v[16:17], v[20:21]
	v_pk_add_f32 v[16:17], v[16:17], v[20:21] neg_lo:[0,1] neg_hi:[0,1]
	v_pk_add_f32 v[20:21], v[30:31], v[10:11]
	v_pk_add_f32 v[10:11], v[30:31], v[10:11] neg_lo:[0,1] neg_hi:[0,1]
	v_pk_add_f32 v[30:31], v[8:9], v[12:13]
	v_pk_add_f32 v[8:9], v[8:9], v[12:13] neg_lo:[0,1] neg_hi:[0,1]
	v_pk_add_f32 v[12:13], v[0:1], v[4:5] op_sel:[0,1] op_sel_hi:[1,0] neg_hi:[0,1]
	v_pk_add_f32 v[0:1], v[0:1], v[4:5] op_sel:[0,1] op_sel_hi:[1,0] neg_lo:[0,1]
	v_pk_add_f32 v[4:5], v[2:3], v[6:7]
	v_pk_add_f32 v[2:3], v[2:3], v[6:7] neg_lo:[0,1] neg_hi:[0,1]
	s_nop 0
	v_pk_mul_f32 v[2:3], v[2:3], s[22:23]
	v_pk_add_f32 v[6:7], v[14:15], v[26:27]
	v_pk_add_f32 v[14:15], v[14:15], v[26:27] neg_lo:[0,1] neg_hi:[0,1]
	v_pk_add_f32 v[26:27], v[24:25], v[28:29] op_sel:[0,1] op_sel_hi:[1,0] neg_hi:[0,1]
	v_pk_add_f32 v[24:25], v[24:25], v[28:29] op_sel:[0,1] op_sel_hi:[1,0] neg_lo:[0,1]
	v_pk_add_f32 v[28:29], v[86:87], v[22:23]
	v_pk_add_f32 v[22:23], v[86:87], v[22:23] neg_lo:[0,1] neg_hi:[0,1]
	v_pk_add_f32 v[86:87], v[18:19], v[16:17] op_sel:[0,1] op_sel_hi:[1,0] neg_hi:[0,1]
	v_pk_add_f32 v[16:17], v[18:19], v[16:17] op_sel:[0,1] op_sel_hi:[1,0] neg_lo:[0,1]
	v_pk_add_f32 v[18:19], v[20:21], v[30:31]
	v_pk_add_f32 v[20:21], v[20:21], v[30:31] neg_lo:[0,1] neg_hi:[0,1]
	v_pk_add_f32 v[30:31], v[10:11], v[8:9] op_sel:[0,1] op_sel_hi:[1,0] neg_hi:[0,1]
	v_pk_add_f32 v[8:9], v[10:11], v[8:9] op_sel:[0,1] op_sel_hi:[1,0] neg_lo:[0,1]
	v_pk_add_f32 v[10:11], v[12:13], v[4:5]
	v_pk_add_f32 v[4:5], v[12:13], v[4:5] neg_lo:[0,1] neg_hi:[0,1]
	v_pk_add_f32 v[12:13], v[0:1], v[2:3] op_sel:[0,1] op_sel_hi:[1,0]
	v_pk_add_f32 v[0:1], v[0:1], v[2:3] op_sel:[0,1] op_sel_hi:[1,0] neg_lo:[0,1] neg_hi:[0,1]
	v_lshlrev_b32_e32 v2, 4, v41
	v_and_or_b32 v2, v2, s7, v98
	v_ashrrev_i32_e32 v3, 4, v2
	v_lshlrev_b32_e32 v3, 3, v3
	v_lshlrev_b32_e32 v2, 3, v2
	v_add3_u32 v2, 0, v3, v2
	v_add_u32_e32 v3, 0x800, v2
	v_mov_b32_e32 v41, v32
	ds_write2_b64 v2, v[6:7], v[18:19] offset1:34
	ds_write2_b64 v3, v[14:15], v[20:21] offset0:16 offset1:50
	ds_write2_b64 v2, v[26:27], v[30:31] offset0:136 offset1:170
	ds_write2_b64 v3, v[24:25], v[8:9] offset0:152 offset1:186
	ds_write2_b64 v2, v[28:29], v[10:11] offset0:68 offset1:102
	ds_write2_b64 v3, v[22:23], v[4:5] offset0:84 offset1:118
	ds_write2_b64 v2, v[86:87], v[12:13] offset0:204 offset1:238
	ds_write2_b64 v3, v[16:17], v[0:1] offset0:220 offset1:254
	s_waitcnt lgkmcnt(0)
	s_barrier
	s_nop 0
	v_and_b32_e32 v98, 0x1ff, v41
	v_cvt_f32_u32_e32 v24, v98
	v_ashrrev_i32_e32 v0, 4, v41
	v_lshlrev_b32_e32 v0, 3, v0
	v_lshlrev_b32_e32 v1, 3, v41
	v_mul_f32_e32 v92, 0x39000000, v24
	v_sin_f32_e32 v24, v92
	v_cos_f32_e32 v92, v92
	v_add3_u32 v25, 0, v0, v1
	ds_read_b64 v[0:1], v25
	ds_read_b64 v[2:3], v25 offset:4352
	ds_read_b64 v[4:5], v25 offset:8704
	ds_read_b64 v[6:7], v25 offset:13056
	ds_read_b64 v[8:9], v25 offset:17408
	ds_read_b64 v[10:11], v25 offset:21760
	ds_read_b64 v[12:13], v25 offset:26112
	ds_read_b64 v[14:15], v25 offset:30464
	v_xor_b32_e32 v93, 0x80000000, v24
	s_waitcnt lgkmcnt(6)
	v_pk_mul_f32 v[94:95], v[2:3], v[24:25] op_sel:[1,0] op_sel_hi:[0,0] neg_hi:[0,1]
	v_pk_fma_f32 v[2:3], v[2:3], v[92:93], v[94:95] op_sel_hi:[1,0,1]
	v_pk_mul_f32 v[94:95], v[24:25], v[92:93] op_sel:[0,1] op_sel_hi:[0,0] neg_hi:[1,0]
	v_pk_fma_f32 v[94:95], v[92:93], v[92:93], v[94:95] op_sel_hi:[0,1,1]
	ds_read_b64 v[16:17], v25 offset:34816
	ds_read_b64 v[18:19], v25 offset:39168
	ds_read_b64 v[20:21], v25 offset:43520
	ds_read_b64 v[22:23], v25 offset:47872
	s_waitcnt lgkmcnt(9)
	v_pk_mul_f32 v[96:97], v[4:5], v[94:95] op_sel:[1,1] op_sel_hi:[0,1] neg_lo:[0,1]
	v_pk_fma_f32 v[4:5], v[4:5], v[94:95], v[96:97] op_sel_hi:[1,0,1]
	v_pk_mul_f32 v[96:97], v[24:25], v[94:95] op_sel:[0,1] op_sel_hi:[0,0] neg_hi:[1,0]
	v_pk_fma_f32 v[94:95], v[92:93], v[94:95], v[96:97] op_sel_hi:[0,1,1]
	ds_read_b64 v[26:27], v25 offset:52224
	ds_read_b64 v[28:29], v25 offset:56576
	ds_read_b64 v[30:31], v25 offset:60928
	ds_read_b64 v[86:87], v25 offset:65280
	s_waitcnt lgkmcnt(12)
	v_pk_mul_f32 v[96:97], v[6:7], v[94:95] op_sel:[1,1] op_sel_hi:[0,1] neg_lo:[0,1]
	v_pk_fma_f32 v[6:7], v[6:7], v[94:95], v[96:97] op_sel_hi:[1,0,1]
	v_pk_mul_f32 v[96:97], v[24:25], v[94:95] op_sel:[0,1] op_sel_hi:[0,0] neg_hi:[1,0]
	v_pk_fma_f32 v[94:95], v[92:93], v[94:95], v[96:97] op_sel_hi:[0,1,1]
	s_waitcnt lgkmcnt(0)
	v_pk_mul_f32 v[96:97], v[8:9], v[94:95] op_sel:[1,1] op_sel_hi:[0,1] neg_lo:[0,1]
	v_pk_fma_f32 v[8:9], v[8:9], v[94:95], v[96:97] op_sel_hi:[1,0,1]
	v_pk_mul_f32 v[96:97], v[24:25], v[94:95] op_sel:[0,1] op_sel_hi:[0,0] neg_hi:[1,0]
	v_pk_fma_f32 v[94:95], v[92:93], v[94:95], v[96:97] op_sel_hi:[0,1,1]
	s_barrier
	v_pk_mul_f32 v[96:97], v[10:11], v[94:95] op_sel:[1,1] op_sel_hi:[0,1] neg_lo:[0,1]
	v_pk_fma_f32 v[10:11], v[10:11], v[94:95], v[96:97] op_sel_hi:[1,0,1]
	v_pk_mul_f32 v[96:97], v[24:25], v[94:95] op_sel:[0,1] op_sel_hi:[0,0] neg_hi:[1,0]
	v_pk_fma_f32 v[94:95], v[92:93], v[94:95], v[96:97] op_sel_hi:[0,1,1]
	s_nop 0
	v_pk_mul_f32 v[96:97], v[12:13], v[94:95] op_sel:[1,1] op_sel_hi:[0,1] neg_lo:[0,1]
	v_pk_fma_f32 v[12:13], v[12:13], v[94:95], v[96:97] op_sel_hi:[1,0,1]
	v_pk_mul_f32 v[96:97], v[24:25], v[94:95] op_sel:[0,1] op_sel_hi:[0,0] neg_hi:[1,0]
	v_pk_fma_f32 v[94:95], v[92:93], v[94:95], v[96:97] op_sel_hi:[0,1,1]
	s_nop 0
	v_pk_mul_f32 v[96:97], v[14:15], v[94:95] op_sel:[1,1] op_sel_hi:[0,1] neg_lo:[0,1]
	v_pk_fma_f32 v[14:15], v[14:15], v[94:95], v[96:97] op_sel_hi:[1,0,1]
	v_pk_mul_f32 v[96:97], v[24:25], v[94:95] op_sel:[0,1] op_sel_hi:[0,0] neg_hi:[1,0]
	v_pk_fma_f32 v[94:95], v[92:93], v[94:95], v[96:97] op_sel_hi:[0,1,1]
	s_nop 0
	v_pk_mul_f32 v[96:97], v[16:17], v[94:95] op_sel:[1,1] op_sel_hi:[0,1] neg_lo:[0,1]
	v_pk_fma_f32 v[16:17], v[16:17], v[94:95], v[96:97] op_sel_hi:[1,0,1]
	v_pk_mul_f32 v[96:97], v[24:25], v[94:95] op_sel:[0,1] op_sel_hi:[0,0] neg_hi:[1,0]
	v_pk_fma_f32 v[94:95], v[92:93], v[94:95], v[96:97] op_sel_hi:[0,1,1]
	s_nop 0
	v_pk_mul_f32 v[96:97], v[18:19], v[94:95] op_sel:[1,1] op_sel_hi:[0,1] neg_lo:[0,1]
	v_pk_fma_f32 v[18:19], v[18:19], v[94:95], v[96:97] op_sel_hi:[1,0,1]
	v_pk_mul_f32 v[96:97], v[24:25], v[94:95] op_sel:[0,1] op_sel_hi:[0,0] neg_hi:[1,0]
	v_pk_fma_f32 v[94:95], v[92:93], v[94:95], v[96:97] op_sel_hi:[0,1,1]
	s_nop 0
	v_pk_mul_f32 v[96:97], v[20:21], v[94:95] op_sel:[1,1] op_sel_hi:[0,1] neg_lo:[0,1]
	v_pk_fma_f32 v[20:21], v[20:21], v[94:95], v[96:97] op_sel_hi:[1,0,1]
	v_pk_mul_f32 v[96:97], v[24:25], v[94:95] op_sel:[0,1] op_sel_hi:[0,0] neg_hi:[1,0]
	v_pk_fma_f32 v[94:95], v[92:93], v[94:95], v[96:97] op_sel_hi:[0,1,1]
	s_nop 0
	v_pk_mul_f32 v[96:97], v[22:23], v[94:95] op_sel:[1,1] op_sel_hi:[0,1] neg_lo:[0,1]
	v_pk_fma_f32 v[22:23], v[22:23], v[94:95], v[96:97] op_sel_hi:[1,0,1]
	v_pk_mul_f32 v[96:97], v[24:25], v[94:95] op_sel:[0,1] op_sel_hi:[0,0] neg_hi:[1,0]
	v_pk_fma_f32 v[94:95], v[92:93], v[94:95], v[96:97] op_sel_hi:[0,1,1]
	s_nop 0
	v_pk_mul_f32 v[96:97], v[26:27], v[94:95] op_sel:[1,1] op_sel_hi:[0,1] neg_lo:[0,1]
	v_pk_fma_f32 v[26:27], v[26:27], v[94:95], v[96:97] op_sel_hi:[1,0,1]
	v_pk_mul_f32 v[96:97], v[24:25], v[94:95] op_sel:[0,1] op_sel_hi:[0,0] neg_hi:[1,0]
	v_pk_fma_f32 v[94:95], v[92:93], v[94:95], v[96:97] op_sel_hi:[0,1,1]
	s_nop 0
	v_pk_mul_f32 v[96:97], v[28:29], v[94:95] op_sel:[1,1] op_sel_hi:[0,1] neg_lo:[0,1]
	v_pk_fma_f32 v[28:29], v[28:29], v[94:95], v[96:97] op_sel_hi:[1,0,1]
	v_pk_mul_f32 v[96:97], v[24:25], v[94:95] op_sel:[0,1] op_sel_hi:[0,0] neg_hi:[1,0]
	v_pk_fma_f32 v[94:95], v[92:93], v[94:95], v[96:97] op_sel_hi:[0,1,1]
	v_pk_mul_f32 v[24:25], v[24:25], v[94:95] op_sel:[0,1] op_sel_hi:[0,0] neg_hi:[1,0]
	v_pk_fma_f32 v[24:25], v[92:93], v[94:95], v[24:25] op_sel_hi:[0,1,1]
	v_pk_mul_f32 v[92:93], v[86:87], v[24:25] op_sel:[1,1] op_sel_hi:[0,1] neg_lo:[0,1]
	v_pk_fma_f32 v[24:25], v[86:87], v[24:25], v[92:93] op_sel_hi:[1,0,1]
	v_pk_add_f32 v[86:87], v[0:1], v[16:17]
	v_pk_add_f32 v[0:1], v[0:1], v[16:17] neg_lo:[0,1] neg_hi:[0,1]
	v_pk_add_f32 v[16:17], v[2:3], v[18:19]
	v_pk_add_f32 v[2:3], v[2:3], v[18:19] neg_lo:[0,1] neg_hi:[0,1]
	v_pk_mul_f32 v[96:97], v[30:31], v[94:95] op_sel:[1,1] op_sel_hi:[0,1] neg_lo:[0,1]
	v_pk_mul_f32 v[18:19], v[2:3], s[18:19]
	v_pk_fma_f32 v[30:31], v[30:31], v[94:95], v[96:97] op_sel_hi:[1,0,1]
	v_pk_fma_f32 v[2:3], v[2:3], s[30:31], v[18:19] op_sel:[0,0,1] op_sel_hi:[1,0,0]
	v_pk_add_f32 v[18:19], v[4:5], v[20:21]
	v_pk_add_f32 v[4:5], v[4:5], v[20:21] neg_lo:[0,1] neg_hi:[0,1]
	s_nop 0
	v_pk_mul_f32 v[20:21], v[4:5], s[10:11]
	s_nop 0
	v_pk_fma_f32 v[4:5], v[4:5], s[14:15], v[20:21] op_sel:[0,0,1] op_sel_hi:[1,0,0]
	v_pk_add_f32 v[20:21], v[6:7], v[22:23]
	v_pk_add_f32 v[6:7], v[6:7], v[22:23] neg_lo:[0,1] neg_hi:[0,1]
	s_nop 0
	v_pk_mul_f32 v[22:23], v[6:7], s[34:35]
	s_nop 0
	v_pk_fma_f32 v[6:7], v[6:7], s[26:27], v[22:23] op_sel:[0,0,1] op_sel_hi:[1,0,0]
	v_pk_add_f32 v[22:23], v[8:9], v[26:27]
	v_pk_add_f32 v[8:9], v[8:9], v[26:27] neg_lo:[0,1] neg_hi:[0,1]
	v_pk_add_f32 v[26:27], v[10:11], v[28:29]
	v_pk_add_f32 v[10:11], v[10:11], v[28:29] neg_lo:[0,1] neg_hi:[0,1]
	s_nop 0
	v_pk_mul_f32 v[28:29], v[10:11], s[34:35]
	s_nop 0
	v_pk_fma_f32 v[10:11], v[10:11], s[26:27], v[28:29] op_sel:[0,0,1] op_sel_hi:[1,0,0] neg_lo:[1,0,0] neg_hi:[1,0,0]
	v_pk_add_f32 v[28:29], v[12:13], v[30:31]
	v_pk_add_f32 v[12:13], v[12:13], v[30:31] neg_lo:[0,1] neg_hi:[0,1]
	s_nop 0
	v_pk_mul_f32 v[30:31], v[12:13], s[10:11]
	s_nop 0
	v_pk_fma_f32 v[12:13], v[12:13], s[14:15], v[30:31] op_sel:[0,0,1] op_sel_hi:[1,0,0] neg_lo:[1,0,0] neg_hi:[1,0,0]
	v_pk_add_f32 v[30:31], v[14:15], v[24:25]
	v_pk_add_f32 v[14:15], v[14:15], v[24:25] neg_lo:[0,1] neg_hi:[0,1]
	s_nop 0
	v_pk_mul_f32 v[24:25], v[14:15], s[18:19]
	s_nop 0
	v_pk_fma_f32 v[14:15], v[14:15], s[30:31], v[24:25] op_sel:[0,0,1] op_sel_hi:[1,0,0] neg_lo:[1,0,0] neg_hi:[1,0,0]
	v_pk_add_f32 v[24:25], v[86:87], v[22:23]
	v_pk_add_f32 v[22:23], v[86:87], v[22:23] neg_lo:[0,1] neg_hi:[0,1]
	v_pk_add_f32 v[86:87], v[16:17], v[26:27]
	v_pk_add_f32 v[16:17], v[16:17], v[26:27] neg_lo:[0,1] neg_hi:[0,1]
	s_nop 0
	v_pk_mul_f32 v[26:27], v[16:17], s[10:11]
	s_nop 0
	v_pk_fma_f32 v[16:17], v[16:17], s[14:15], v[26:27] op_sel:[0,0,1] op_sel_hi:[1,0,0]
	v_pk_add_f32 v[26:27], v[18:19], v[28:29]
	v_pk_add_f32 v[18:19], v[18:19], v[28:29] neg_lo:[0,1] neg_hi:[0,1]
	v_pk_add_f32 v[28:29], v[20:21], v[30:31]
	v_pk_add_f32 v[20:21], v[20:21], v[30:31] neg_lo:[0,1] neg_hi:[0,1]
	s_nop 0
	v_pk_mul_f32 v[30:31], v[20:21], s[10:11]
	s_nop 0
	v_pk_fma_f32 v[20:21], v[20:21], s[14:15], v[30:31] op_sel:[0,0,1] op_sel_hi:[1,0,0] neg_lo:[1,0,0] neg_hi:[1,0,0]
	v_pk_add_f32 v[30:31], v[0:1], v[8:9] op_sel:[0,1] op_sel_hi:[1,0] neg_hi:[0,1]
	v_pk_add_f32 v[0:1], v[0:1], v[8:9] op_sel:[0,1] op_sel_hi:[1,0] neg_lo:[0,1]
	v_pk_add_f32 v[8:9], v[2:3], v[10:11]
	v_pk_add_f32 v[2:3], v[2:3], v[10:11] neg_lo:[0,1] neg_hi:[0,1]
	s_nop 0
	v_pk_mul_f32 v[10:11], v[2:3], s[10:11]
	s_nop 0
	v_pk_fma_f32 v[2:3], v[2:3], s[14:15], v[10:11] op_sel:[0,0,1] op_sel_hi:[1,0,0]
	v_pk_add_f32 v[10:11], v[4:5], v[12:13]
	v_pk_add_f32 v[4:5], v[4:5], v[12:13] neg_lo:[0,1] neg_hi:[0,1]
	v_pk_add_f32 v[12:13], v[6:7], v[14:15]
	v_pk_add_f32 v[6:7], v[6:7], v[14:15] neg_lo:[0,1] neg_hi:[0,1]
	s_nop 0
	v_pk_mul_f32 v[14:15], v[6:7], s[10:11]
	s_nop 0
	v_pk_fma_f32 v[6:7], v[6:7], s[14:15], v[14:15] op_sel:[0,0,1] op_sel_hi:[1,0,0] neg_lo:[1,0,0] neg_hi:[1,0,0]
	v_pk_add_f32 v[14:15], v[24:25], v[26:27]
	v_pk_add_f32 v[24:25], v[24:25], v[26:27] neg_lo:[0,1] neg_hi:[0,1]
	v_pk_add_f32 v[26:27], v[86:87], v[28:29]
	v_pk_add_f32 v[28:29], v[86:87], v[28:29] neg_lo:[0,1] neg_hi:[0,1]
	v_pk_add_f32 v[86:87], v[22:23], v[18:19] op_sel:[0,1] op_sel_hi:[1,0] neg_hi:[0,1]
	v_pk_add_f32 v[18:19], v[22:23], v[18:19] op_sel:[0,1] op_sel_hi:[1,0] neg_lo:[0,1]
	v_pk_add_f32 v[22:23], v[16:17], v[20:21]
	v_pk_add_f32 v[16:17], v[16:17], v[20:21] neg_lo:[0,1] neg_hi:[0,1]
	v_pk_add_f32 v[20:21], v[30:31], v[10:11]
	v_pk_add_f32 v[10:11], v[30:31], v[10:11] neg_lo:[0,1] neg_hi:[0,1]
	v_pk_add_f32 v[30:31], v[8:9], v[12:13]
	v_pk_add_f32 v[8:9], v[8:9], v[12:13] neg_lo:[0,1] neg_hi:[0,1]
	v_pk_add_f32 v[12:13], v[0:1], v[4:5] op_sel:[0,1] op_sel_hi:[1,0] neg_hi:[0,1]
	v_pk_add_f32 v[0:1], v[0:1], v[4:5] op_sel:[0,1] op_sel_hi:[1,0] neg_lo:[0,1]
	v_pk_add_f32 v[4:5], v[2:3], v[6:7]
	v_pk_add_f32 v[2:3], v[2:3], v[6:7] neg_lo:[0,1] neg_hi:[0,1]
	s_nop 0
	v_pk_mul_f32 v[2:3], v[2:3], s[22:23]
	v_pk_add_f32 v[6:7], v[14:15], v[26:27]
	v_pk_add_f32 v[14:15], v[14:15], v[26:27] neg_lo:[0,1] neg_hi:[0,1]
	v_pk_add_f32 v[26:27], v[24:25], v[28:29] op_sel:[0,1] op_sel_hi:[1,0] neg_hi:[0,1]
	v_pk_add_f32 v[24:25], v[24:25], v[28:29] op_sel:[0,1] op_sel_hi:[1,0] neg_lo:[0,1]
	v_pk_add_f32 v[28:29], v[86:87], v[22:23]
	v_pk_add_f32 v[22:23], v[86:87], v[22:23] neg_lo:[0,1] neg_hi:[0,1]
	v_pk_add_f32 v[86:87], v[18:19], v[16:17] op_sel:[0,1] op_sel_hi:[1,0] neg_hi:[0,1]
	v_pk_add_f32 v[16:17], v[18:19], v[16:17] op_sel:[0,1] op_sel_hi:[1,0] neg_lo:[0,1]
	v_pk_add_f32 v[18:19], v[20:21], v[30:31]
	v_pk_add_f32 v[20:21], v[20:21], v[30:31] neg_lo:[0,1] neg_hi:[0,1]
	v_pk_add_f32 v[30:31], v[10:11], v[8:9] op_sel:[0,1] op_sel_hi:[1,0] neg_hi:[0,1]
	v_pk_add_f32 v[8:9], v[10:11], v[8:9] op_sel:[0,1] op_sel_hi:[1,0] neg_lo:[0,1]
	v_pk_add_f32 v[10:11], v[12:13], v[4:5]
	v_pk_add_f32 v[4:5], v[12:13], v[4:5] neg_lo:[0,1] neg_hi:[0,1]
	v_pk_add_f32 v[12:13], v[0:1], v[2:3] op_sel:[0,1] op_sel_hi:[1,0]
	v_pk_add_f32 v[0:1], v[0:1], v[2:3] op_sel:[0,1] op_sel_hi:[1,0] neg_lo:[0,1] neg_hi:[0,1]
	v_lshlrev_b32_e32 v2, 4, v41
	v_and_or_b32 v2, v2, s15, v98
	v_ashrrev_i32_e32 v3, 4, v2
	v_lshlrev_b32_e32 v3, 3, v3
	v_lshlrev_b32_e32 v2, 3, v2
	v_add3_u32 v2, 0, v3, v2
	ds_write_b64 v2, v[6:7]
	ds_write_b64 v2, v[14:15] offset:34816
	ds_write_b64 v2, v[26:27] offset:17408
	ds_write_b64 v2, v[24:25] offset:52224
	ds_write_b64 v2, v[28:29] offset:8704
	ds_write_b64 v2, v[22:23] offset:43520
	ds_write_b64 v2, v[86:87] offset:26112
	ds_write_b64 v2, v[16:17] offset:60928
	ds_write_b64 v2, v[18:19] offset:4352
	ds_write_b64 v2, v[20:21] offset:39168
	ds_write_b64 v2, v[30:31] offset:21760
	ds_write_b64 v2, v[8:9] offset:56576
	ds_write_b64 v2, v[10:11] offset:13056
	ds_write_b64 v2, v[4:5] offset:47872
	ds_write_b64 v2, v[12:13] offset:30464
	ds_write_b64 v2, v[0:1] offset:65280
	v_mov_b32_e32 v0, v154
	v_mov_b32_e32 v1, v156
	v_mov_b32_e32 v2, v155
	v_mov_b32_e32 v3, v122
	s_waitcnt lgkmcnt(0)
	s_barrier
.LBB0_618:
	v_or_b32_e32 v4, s4, v32
	v_cmp_ne_u32_e32 vcc, 0, v4
	v_add_u32_e32 v13, 0, v2
	v_add_u32_e32 v4, 0x11000, v13
	v_cndmask_b32_e32 v6, 0, v0, vcc
	v_lshl_add_u32 v6, v6, 3, 0
	v_add_u32_e32 v6, 0x11000, v6
	ds_read_b64 v[4:5], v4
	ds_read_b64 v[6:7], v6
	v_add_u32_e32 v12, 0, v3
	ds_read_b64 v[8:9], v12
	s_add_i32 s4, s4, 2
	v_add_u32_e32 v3, 0x2200, v3
	s_waitcnt lgkmcnt(1)
	v_sub_f32_e32 v5, v5, v7
	v_add_f32_e32 v4, v4, v6
	v_mul_f32_e32 v6, 0.5, v5
	v_mul_f32_e32 v4, 0.5, v4
	s_waitcnt lgkmcnt(0)
	v_pk_mul_f32 v[6:7], v[8:9], v[6:7] op_sel:[1,0] op_sel_hi:[0,0]
	v_pk_fma_f32 v[10:11], v[8:9], v[4:5], v[6:7] neg_lo:[0,0,1] neg_hi:[0,0,1]
	v_pk_fma_f32 v[4:5], v[8:9], v[4:5], v[6:7] op_sel_hi:[1,0,1]
	v_add_u32_e32 v6, 0, v1
	v_mov_b32_e32 v11, v5
	v_pk_mul_f32 v[4:5], v[10:11], s[24:25]
	ds_write_b64 v12, v[4:5]
	v_add_u32_e32 v4, 0x12100, v13
	v_add_u32_e32 v6, 0x1ff00, v6
	ds_read_b64 v[4:5], v4
	ds_read_b64 v[6:7], v6
	ds_read_b64 v[8:9], v12 offset:4352
	v_add_u32_e32 v2, 0x2200, v2
	v_add_u32_e32 v1, 0xffffde00, v1
	v_add_u32_e32 v0, 0xfffffbc0, v0
	s_waitcnt lgkmcnt(1)
	v_sub_f32_e32 v5, v5, v7
	v_add_f32_e32 v4, v4, v6
	v_mul_f32_e32 v6, 0.5, v5
	v_mul_f32_e32 v4, 0.5, v4
	s_waitcnt lgkmcnt(0)
	v_pk_mul_f32 v[6:7], v[8:9], v[6:7] op_sel:[1,0] op_sel_hi:[0,0]
	v_pk_fma_f32 v[10:11], v[8:9], v[4:5], v[6:7] neg_lo:[0,0,1] neg_hi:[0,0,1]
	v_pk_fma_f32 v[4:5], v[8:9], v[4:5], v[6:7] op_sel_hi:[1,0,1]
	s_cmp_lg_u32 s4, 16
	v_mov_b32_e32 v11, v5
	v_pk_mul_f32 v[4:5], v[10:11], s[24:25]
	ds_write_b64 v12, v[4:5] offset:4352
	s_cbranch_scc1 .LBB0_618
	s_waitcnt lgkmcnt(0)
	s_barrier
	s_and_saveexec_b64 s[28:29], s[40:41]
	s_cbranch_execz .LBB0_621
	ds_read_b64 v[0:1], v153
	ds_read_b64 v[2:3], v153 offset:2176
	ds_read_b64 v[4:5], v153 offset:4352
	ds_read_b64 v[6:7], v153 offset:6528
	ds_read_b64 v[8:9], v153 offset:8704
	ds_read_b64 v[10:11], v153 offset:10880
	ds_read_b64 v[12:13], v153 offset:13056
	ds_read_b64 v[14:15], v153 offset:15232
	ds_read_b64 v[16:17], v153 offset:17408
	ds_read_b64 v[18:19], v153 offset:19584
	ds_read_b64 v[20:21], v153 offset:21760
	ds_read_b64 v[22:23], v153 offset:23936
	ds_read_b64 v[24:25], v153 offset:26112
	ds_read_b64 v[26:27], v153 offset:28288
	ds_read_b64 v[28:29], v153 offset:30464
	ds_read_b64 v[30:31], v153 offset:32640
	ds_read_b64 v[86:87], v153 offset:34816
	ds_read_b64 v[92:93], v153 offset:41344
	ds_read_b64 v[94:95], v153 offset:43520
	ds_read_b64 v[96:97], v153 offset:45696
	ds_read_b64 v[98:99], v153 offset:47872
	ds_read_b64 v[100:101], v153 offset:50048
	ds_read_b64 v[102:103], v153 offset:52224
	ds_read_b64 v[104:105], v153 offset:54400
	ds_read_b64 v[106:107], v153 offset:56576
	ds_read_b64 v[108:109], v153 offset:58752
	ds_read_b64 v[110:111], v153 offset:60928
	ds_read_b64 v[112:113], v153 offset:63104
	ds_read_b64 v[114:115], v153 offset:65280
	ds_read_b64 v[116:117], v153 offset:36992
	ds_read_b64 v[118:119], v153 offset:39168
	ds_read_b64 v[120:121], v33
	s_waitcnt lgkmcnt(14)
	v_pk_add_f32 v[124:125], v[0:1], v[86:87]
	v_pk_add_f32 v[0:1], v[0:1], v[86:87] neg_lo:[0,1] neg_hi:[0,1]
	s_waitcnt lgkmcnt(2)
	v_pk_add_f32 v[86:87], v[2:3], v[116:117]
	v_pk_add_f32 v[2:3], v[2:3], v[116:117] neg_lo:[0,1] neg_hi:[0,1]
	s_mov_b32 s11, s14
	v_pk_mul_f32 v[116:117], v[2:3], s[16:17]
	s_mov_b32 s13, s86
	v_pk_fma_f32 v[2:3], v[2:3], s[6:7], v[116:117] op_sel:[0,0,1] op_sel_hi:[1,0,0]
	s_waitcnt lgkmcnt(1)
	v_pk_add_f32 v[116:117], v[4:5], v[118:119]
	v_pk_add_f32 v[4:5], v[4:5], v[118:119] neg_lo:[0,1] neg_hi:[0,1]
	s_mov_b32 s4, s21
	v_pk_mul_f32 v[118:119], v[4:5], s[18:19]
	s_mov_b32 s35, s30
	v_pk_fma_f32 v[4:5], v[4:5], s[30:31], v[118:119] op_sel:[0,0,1] op_sel_hi:[1,0,0]
	v_pk_add_f32 v[118:119], v[6:7], v[92:93]
	v_pk_add_f32 v[6:7], v[6:7], v[92:93] neg_lo:[0,1] neg_hi:[0,1]
	s_mov_b32 s8, s19
	v_pk_mul_f32 v[92:93], v[6:7], s[20:21]
	s_mov_b32 s77, s6
	v_pk_fma_f32 v[6:7], v[6:7], s[86:87], v[92:93] op_sel:[0,0,1] op_sel_hi:[1,0,0]
	v_pk_add_f32 v[92:93], v[8:9], v[94:95]
	v_pk_add_f32 v[8:9], v[8:9], v[94:95] neg_lo:[0,1] neg_hi:[0,1]
	s_mov_b32 s26, s17
	v_pk_mul_f32 v[94:95], v[8:9], s[10:11]
	s_nop 0
	v_pk_fma_f32 v[8:9], v[8:9], s[14:15], v[94:95] op_sel:[0,0,1] op_sel_hi:[1,0,0]
	v_pk_add_f32 v[94:95], v[10:11], v[96:97]
	v_pk_add_f32 v[10:11], v[10:11], v[96:97] neg_lo:[0,1] neg_hi:[0,1]
	s_nop 0
	v_pk_mul_f32 v[96:97], v[10:11], s[12:13]
	s_nop 0
	v_pk_fma_f32 v[10:11], v[10:11], s[4:5], v[96:97] op_sel:[0,0,1] op_sel_hi:[1,0,0]
	v_pk_add_f32 v[96:97], v[12:13], v[98:99]
	v_pk_add_f32 v[12:13], v[12:13], v[98:99] neg_lo:[0,1] neg_hi:[0,1]
	s_nop 0
	v_pk_mul_f32 v[98:99], v[12:13], s[34:35]
	s_nop 0
	v_pk_fma_f32 v[12:13], v[12:13], s[8:9], v[98:99] op_sel:[0,0,1] op_sel_hi:[1,0,0]
	v_pk_add_f32 v[98:99], v[14:15], v[100:101]
	v_pk_add_f32 v[14:15], v[14:15], v[100:101] neg_lo:[0,1] neg_hi:[0,1]
	s_nop 0
	v_pk_mul_f32 v[100:101], v[14:15], s[76:77]
	s_nop 0
	v_pk_fma_f32 v[14:15], v[14:15], s[26:27], v[100:101] op_sel:[0,0,1] op_sel_hi:[1,0,0]
	v_pk_add_f32 v[100:101], v[16:17], v[102:103]
	v_pk_add_f32 v[16:17], v[16:17], v[102:103] neg_lo:[0,1] neg_hi:[0,1]
	v_pk_add_f32 v[102:103], v[18:19], v[104:105]
	v_pk_add_f32 v[18:19], v[18:19], v[104:105] neg_lo:[0,1] neg_hi:[0,1]
	s_nop 0
	v_pk_mul_f32 v[104:105], v[18:19], s[76:77]
	s_nop 0
	v_pk_fma_f32 v[18:19], v[18:19], s[26:27], v[104:105] op_sel:[0,0,1] op_sel_hi:[1,0,0] neg_lo:[1,0,0] neg_hi:[1,0,0]
	v_pk_add_f32 v[104:105], v[20:21], v[106:107]
	v_pk_add_f32 v[20:21], v[20:21], v[106:107] neg_lo:[0,1] neg_hi:[0,1]
	s_nop 0
	v_pk_mul_f32 v[106:107], v[20:21], s[34:35]
	s_nop 0
	v_pk_fma_f32 v[20:21], v[20:21], s[8:9], v[106:107] op_sel:[0,0,1] op_sel_hi:[1,0,0] neg_lo:[1,0,0] neg_hi:[1,0,0]
	v_pk_add_f32 v[106:107], v[22:23], v[108:109]
	v_pk_add_f32 v[22:23], v[22:23], v[108:109] neg_lo:[0,1] neg_hi:[0,1]
	s_nop 0
	v_pk_mul_f32 v[108:109], v[22:23], s[12:13]
	s_nop 0
	v_pk_fma_f32 v[22:23], v[22:23], s[4:5], v[108:109] op_sel:[0,0,1] op_sel_hi:[1,0,0] neg_lo:[1,0,0] neg_hi:[1,0,0]
	v_pk_add_f32 v[108:109], v[24:25], v[110:111]
	v_pk_add_f32 v[24:25], v[24:25], v[110:111] neg_lo:[0,1] neg_hi:[0,1]
	s_nop 0
	v_pk_mul_f32 v[110:111], v[24:25], s[10:11]
	s_nop 0
	v_pk_fma_f32 v[24:25], v[24:25], s[14:15], v[110:111] op_sel:[0,0,1] op_sel_hi:[1,0,0] neg_lo:[1,0,0] neg_hi:[1,0,0]
	v_pk_add_f32 v[110:111], v[26:27], v[112:113]
	v_pk_add_f32 v[26:27], v[26:27], v[112:113] neg_lo:[0,1] neg_hi:[0,1]
	s_nop 0
	v_pk_mul_f32 v[112:113], v[26:27], s[20:21]
	s_nop 0
	v_pk_fma_f32 v[26:27], v[26:27], s[86:87], v[112:113] op_sel:[0,0,1] op_sel_hi:[1,0,0] neg_lo:[1,0,0] neg_hi:[1,0,0]
	v_pk_add_f32 v[112:113], v[28:29], v[114:115]
	v_pk_add_f32 v[28:29], v[28:29], v[114:115] neg_lo:[0,1] neg_hi:[0,1]
	s_nop 0
	v_pk_mul_f32 v[114:115], v[28:29], s[18:19]
	s_nop 0
	v_pk_fma_f32 v[28:29], v[28:29], s[30:31], v[114:115] op_sel:[0,0,1] op_sel_hi:[1,0,0] neg_lo:[1,0,0] neg_hi:[1,0,0]
	s_waitcnt lgkmcnt(0)
	v_pk_add_f32 v[114:115], v[30:31], v[120:121]
	v_pk_add_f32 v[30:31], v[30:31], v[120:121] neg_lo:[0,1] neg_hi:[0,1]
	s_nop 0
	v_pk_mul_f32 v[120:121], v[30:31], s[16:17]
	s_nop 0
	v_pk_fma_f32 v[30:31], v[30:31], s[6:7], v[120:121] op_sel:[0,0,1] op_sel_hi:[1,0,0] neg_lo:[1,0,0] neg_hi:[1,0,0]
	v_pk_add_f32 v[120:121], v[124:125], v[100:101]
	v_pk_add_f32 v[100:101], v[124:125], v[100:101] neg_lo:[0,1] neg_hi:[0,1]
	v_pk_add_f32 v[124:125], v[86:87], v[102:103]
	v_pk_add_f32 v[86:87], v[86:87], v[102:103] neg_lo:[0,1] neg_hi:[0,1]
	s_nop 0
	v_pk_mul_f32 v[102:103], v[86:87], s[18:19]
	s_nop 0
	v_pk_fma_f32 v[86:87], v[86:87], s[30:31], v[102:103] op_sel:[0,0,1] op_sel_hi:[1,0,0]
	v_pk_add_f32 v[102:103], v[116:117], v[104:105]
	v_pk_add_f32 v[104:105], v[116:117], v[104:105] neg_lo:[0,1] neg_hi:[0,1]
	s_nop 0
	v_pk_mul_f32 v[116:117], v[104:105], s[10:11]
	s_nop 0
	v_pk_fma_f32 v[104:105], v[104:105], s[14:15], v[116:117] op_sel:[0,0,1] op_sel_hi:[1,0,0]
	v_pk_add_f32 v[116:117], v[118:119], v[106:107]
	v_pk_add_f32 v[106:107], v[118:119], v[106:107] neg_lo:[0,1] neg_hi:[0,1]
	s_nop 0
	v_pk_mul_f32 v[118:119], v[106:107], s[34:35]
	s_nop 0
	v_pk_fma_f32 v[106:107], v[106:107], s[8:9], v[118:119] op_sel:[0,0,1] op_sel_hi:[1,0,0]
	v_pk_add_f32 v[118:119], v[92:93], v[108:109]
	v_pk_add_f32 v[92:93], v[92:93], v[108:109] neg_lo:[0,1] neg_hi:[0,1]
	v_pk_add_f32 v[108:109], v[94:95], v[110:111]
	v_pk_add_f32 v[94:95], v[94:95], v[110:111] neg_lo:[0,1] neg_hi:[0,1]
	s_nop 0
	v_pk_mul_f32 v[110:111], v[94:95], s[34:35]
	s_nop 0
	v_pk_fma_f32 v[94:95], v[94:95], s[8:9], v[110:111] op_sel:[0,0,1] op_sel_hi:[1,0,0] neg_lo:[1,0,0] neg_hi:[1,0,0]
	v_pk_add_f32 v[110:111], v[96:97], v[112:113]
	v_pk_add_f32 v[96:97], v[96:97], v[112:113] neg_lo:[0,1] neg_hi:[0,1]
	s_nop 0
	v_pk_mul_f32 v[112:113], v[96:97], s[10:11]
	s_nop 0
	v_pk_fma_f32 v[96:97], v[96:97], s[14:15], v[112:113] op_sel:[0,0,1] op_sel_hi:[1,0,0] neg_lo:[1,0,0] neg_hi:[1,0,0]
	v_pk_add_f32 v[112:113], v[98:99], v[114:115]
	v_pk_add_f32 v[98:99], v[98:99], v[114:115] neg_lo:[0,1] neg_hi:[0,1]
	s_nop 0
	v_pk_mul_f32 v[114:115], v[98:99], s[18:19]
	s_nop 0
	v_pk_fma_f32 v[98:99], v[98:99], s[30:31], v[114:115] op_sel:[0,0,1] op_sel_hi:[1,0,0] neg_lo:[1,0,0] neg_hi:[1,0,0]
	v_pk_add_f32 v[114:115], v[0:1], v[16:17] op_sel:[0,1] op_sel_hi:[1,0] neg_hi:[0,1]
	v_pk_add_f32 v[0:1], v[0:1], v[16:17] op_sel:[0,1] op_sel_hi:[1,0] neg_lo:[0,1]
	v_pk_add_f32 v[16:17], v[2:3], v[18:19]
	v_pk_add_f32 v[2:3], v[2:3], v[18:19] neg_lo:[0,1] neg_hi:[0,1]
	s_nop 0
	v_pk_mul_f32 v[18:19], v[2:3], s[18:19]
	s_nop 0
	v_pk_fma_f32 v[2:3], v[2:3], s[30:31], v[18:19] op_sel:[0,0,1] op_sel_hi:[1,0,0]
	v_pk_add_f32 v[18:19], v[4:5], v[20:21]
	v_pk_add_f32 v[4:5], v[4:5], v[20:21] neg_lo:[0,1] neg_hi:[0,1]
	s_nop 0
	v_pk_mul_f32 v[20:21], v[4:5], s[10:11]
	s_nop 0
	v_pk_fma_f32 v[4:5], v[4:5], s[14:15], v[20:21] op_sel:[0,0,1] op_sel_hi:[1,0,0]
	v_pk_add_f32 v[20:21], v[6:7], v[22:23]
	v_pk_add_f32 v[6:7], v[6:7], v[22:23] neg_lo:[0,1] neg_hi:[0,1]
	s_nop 0
	v_pk_mul_f32 v[22:23], v[6:7], s[34:35]
	s_nop 0
	v_pk_fma_f32 v[6:7], v[6:7], s[8:9], v[22:23] op_sel:[0,0,1] op_sel_hi:[1,0,0]
	v_pk_add_f32 v[22:23], v[8:9], v[24:25]
	v_pk_add_f32 v[8:9], v[8:9], v[24:25] neg_lo:[0,1] neg_hi:[0,1]
	v_pk_add_f32 v[24:25], v[10:11], v[26:27]
	v_pk_add_f32 v[10:11], v[10:11], v[26:27] neg_lo:[0,1] neg_hi:[0,1]
	s_nop 0
	v_pk_mul_f32 v[26:27], v[10:11], s[34:35]
	s_nop 0
	v_pk_fma_f32 v[10:11], v[10:11], s[8:9], v[26:27] op_sel:[0,0,1] op_sel_hi:[1,0,0] neg_lo:[1,0,0] neg_hi:[1,0,0]
	v_pk_add_f32 v[26:27], v[12:13], v[28:29]
	v_pk_add_f32 v[12:13], v[12:13], v[28:29] neg_lo:[0,1] neg_hi:[0,1]
	s_nop 0
	v_pk_mul_f32 v[28:29], v[12:13], s[10:11]
	s_nop 0
	v_pk_fma_f32 v[12:13], v[12:13], s[14:15], v[28:29] op_sel:[0,0,1] op_sel_hi:[1,0,0] neg_lo:[1,0,0] neg_hi:[1,0,0]
	v_pk_add_f32 v[28:29], v[14:15], v[30:31]
	v_pk_add_f32 v[14:15], v[14:15], v[30:31] neg_lo:[0,1] neg_hi:[0,1]
	s_nop 0
	v_pk_mul_f32 v[30:31], v[14:15], s[18:19]
	s_nop 0
	v_pk_fma_f32 v[14:15], v[14:15], s[30:31], v[30:31] op_sel:[0,0,1] op_sel_hi:[1,0,0] neg_lo:[1,0,0] neg_hi:[1,0,0]
	v_pk_add_f32 v[30:31], v[120:121], v[118:119]
	v_pk_add_f32 v[118:119], v[120:121], v[118:119] neg_lo:[0,1] neg_hi:[0,1]
	v_pk_add_f32 v[120:121], v[124:125], v[108:109]
	v_pk_add_f32 v[108:109], v[124:125], v[108:109] neg_lo:[0,1] neg_hi:[0,1]
	s_nop 0
	v_pk_mul_f32 v[124:125], v[108:109], s[10:11]
	s_nop 0
	v_pk_fma_f32 v[108:109], v[108:109], s[14:15], v[124:125] op_sel:[0,0,1] op_sel_hi:[1,0,0]
	v_pk_add_f32 v[124:125], v[102:103], v[110:111]
	v_pk_add_f32 v[102:103], v[102:103], v[110:111] neg_lo:[0,1] neg_hi:[0,1]
	v_pk_add_f32 v[110:111], v[116:117], v[112:113]
	v_pk_add_f32 v[112:113], v[116:117], v[112:113] neg_lo:[0,1] neg_hi:[0,1]
	s_nop 0
	v_pk_mul_f32 v[116:117], v[112:113], s[10:11]
	s_nop 0
	v_pk_fma_f32 v[112:113], v[112:113], s[14:15], v[116:117] op_sel:[0,0,1] op_sel_hi:[1,0,0] neg_lo:[1,0,0] neg_hi:[1,0,0]
	v_pk_add_f32 v[116:117], v[100:101], v[92:93] op_sel:[0,1] op_sel_hi:[1,0] neg_hi:[0,1]
	v_pk_add_f32 v[92:93], v[100:101], v[92:93] op_sel:[0,1] op_sel_hi:[1,0] neg_lo:[0,1]
	v_pk_add_f32 v[100:101], v[86:87], v[94:95]
	v_pk_add_f32 v[86:87], v[86:87], v[94:95] neg_lo:[0,1] neg_hi:[0,1]
	v_pk_add_f32 v[126:127], v[108:109], v[112:113]
	v_pk_mul_f32 v[94:95], v[86:87], s[10:11]
	s_nop 0
	v_pk_fma_f32 v[86:87], v[86:87], s[14:15], v[94:95] op_sel:[0,0,1] op_sel_hi:[1,0,0]
	v_pk_add_f32 v[94:95], v[104:105], v[96:97]
	v_pk_add_f32 v[96:97], v[104:105], v[96:97] neg_lo:[0,1] neg_hi:[0,1]
	v_pk_add_f32 v[104:105], v[106:107], v[98:99]
	v_pk_add_f32 v[98:99], v[106:107], v[98:99] neg_lo:[0,1] neg_hi:[0,1]
	s_nop 0
	v_pk_mul_f32 v[106:107], v[98:99], s[10:11]
	v_pk_add_f32 v[130:131], v[92:93], v[96:97] op_sel:[0,1] op_sel_hi:[1,0] neg_hi:[0,1]
	v_pk_fma_f32 v[98:99], v[98:99], s[14:15], v[106:107] op_sel:[0,0,1] op_sel_hi:[1,0,0] neg_lo:[1,0,0] neg_hi:[1,0,0]
	v_pk_add_f32 v[106:107], v[114:115], v[22:23]
	v_pk_add_f32 v[22:23], v[114:115], v[22:23] neg_lo:[0,1] neg_hi:[0,1]
	v_pk_add_f32 v[114:115], v[16:17], v[24:25]
	v_pk_add_f32 v[16:17], v[16:17], v[24:25] neg_lo:[0,1] neg_hi:[0,1]
	v_pk_add_f32 v[132:133], v[92:93], v[96:97] op_sel:[0,1] op_sel_hi:[1,0] neg_lo:[0,1]
	v_pk_mul_f32 v[24:25], v[16:17], s[10:11]
	v_pk_add_f32 v[92:93], v[86:87], v[98:99]
	v_pk_fma_f32 v[16:17], v[16:17], s[14:15], v[24:25] op_sel:[0,0,1] op_sel_hi:[1,0,0]
	v_pk_add_f32 v[24:25], v[18:19], v[26:27]
	v_pk_add_f32 v[18:19], v[18:19], v[26:27] neg_lo:[0,1] neg_hi:[0,1]
	v_pk_add_f32 v[26:27], v[20:21], v[28:29]
	v_pk_add_f32 v[20:21], v[20:21], v[28:29] neg_lo:[0,1] neg_hi:[0,1]
	s_nop 0
	v_pk_mul_f32 v[28:29], v[20:21], s[10:11]
	v_pk_add_f32 v[86:87], v[86:87], v[98:99] neg_lo:[0,1] neg_hi:[0,1]
	v_pk_fma_f32 v[20:21], v[20:21], s[14:15], v[28:29] op_sel:[0,0,1] op_sel_hi:[1,0,0] neg_lo:[1,0,0] neg_hi:[1,0,0]
	v_pk_add_f32 v[28:29], v[0:1], v[8:9] op_sel:[0,1] op_sel_hi:[1,0] neg_hi:[0,1]
	v_pk_add_f32 v[0:1], v[0:1], v[8:9] op_sel:[0,1] op_sel_hi:[1,0] neg_lo:[0,1]
	v_pk_add_f32 v[8:9], v[2:3], v[10:11]
	v_pk_add_f32 v[2:3], v[2:3], v[10:11] neg_lo:[0,1] neg_hi:[0,1]
	v_pk_add_f32 v[134:135], v[106:107], v[24:25]
	v_pk_mul_f32 v[10:11], v[2:3], s[10:11]
	v_pk_add_f32 v[106:107], v[106:107], v[24:25] neg_lo:[0,1] neg_hi:[0,1]
	v_pk_fma_f32 v[2:3], v[2:3], s[14:15], v[10:11] op_sel:[0,0,1] op_sel_hi:[1,0,0]
	v_pk_add_f32 v[10:11], v[4:5], v[12:13]
	v_pk_add_f32 v[4:5], v[4:5], v[12:13] neg_lo:[0,1] neg_hi:[0,1]
	v_pk_add_f32 v[12:13], v[6:7], v[14:15]
	v_pk_add_f32 v[6:7], v[6:7], v[14:15] neg_lo:[0,1] neg_hi:[0,1]
	s_nop 0
	v_pk_mul_f32 v[14:15], v[6:7], s[10:11]
	v_pk_add_f32 v[24:25], v[114:115], v[26:27] neg_lo:[0,1] neg_hi:[0,1]
	v_pk_fma_f32 v[6:7], v[6:7], s[14:15], v[14:15] op_sel:[0,0,1] op_sel_hi:[1,0,0] neg_lo:[1,0,0] neg_hi:[1,0,0]
	v_pk_add_f32 v[14:15], v[30:31], v[124:125]
	v_pk_add_f32 v[30:31], v[30:31], v[124:125] neg_lo:[0,1] neg_hi:[0,1]
	v_pk_add_f32 v[124:125], v[120:121], v[110:111]
	v_pk_add_f32 v[110:111], v[120:121], v[110:111] neg_lo:[0,1] neg_hi:[0,1]
	v_pk_add_f32 v[120:121], v[118:119], v[102:103] op_sel:[0,1] op_sel_hi:[1,0] neg_hi:[0,1]
	v_pk_add_f32 v[118:119], v[118:119], v[102:103] op_sel:[0,1] op_sel_hi:[1,0] neg_lo:[0,1]
	v_pk_add_f32 v[102:103], v[108:109], v[112:113] neg_lo:[0,1] neg_hi:[0,1]
	v_pk_add_f32 v[112:113], v[116:117], v[94:95]
	v_pk_add_f32 v[94:95], v[116:117], v[94:95] neg_lo:[0,1] neg_hi:[0,1]
	v_pk_add_f32 v[116:117], v[100:101], v[104:105]
	v_pk_add_f32 v[100:101], v[100:101], v[104:105] neg_lo:[0,1] neg_hi:[0,1]
	v_pk_add_f32 v[138:139], v[22:23], v[18:19] op_sel:[0,1] op_sel_hi:[1,0] neg_hi:[0,1]
	v_pk_add_f32 v[140:141], v[22:23], v[18:19] op_sel:[0,1] op_sel_hi:[1,0] neg_lo:[0,1]
	v_pk_add_f32 v[18:19], v[16:17], v[20:21]
	v_pk_add_f32 v[16:17], v[16:17], v[20:21] neg_lo:[0,1] neg_hi:[0,1]
	v_pk_add_f32 v[144:145], v[28:29], v[10:11]
	v_pk_add_f32 v[158:159], v[28:29], v[10:11] neg_lo:[0,1] neg_hi:[0,1]
	v_pk_add_f32 v[10:11], v[8:9], v[12:13]
	v_pk_add_f32 v[8:9], v[8:9], v[12:13] neg_lo:[0,1] neg_hi:[0,1]
	v_pk_add_f32 v[162:163], v[0:1], v[4:5] op_sel:[0,1] op_sel_hi:[1,0] neg_hi:[0,1]
	v_pk_add_f32 v[164:165], v[0:1], v[4:5] op_sel:[0,1] op_sel_hi:[1,0] neg_lo:[0,1]
	v_pk_add_f32 v[0:1], v[2:3], v[6:7] neg_lo:[0,1] neg_hi:[0,1]
	v_pk_mul_f32 v[108:109], v[102:103], s[22:23]
	v_pk_mul_f32 v[128:129], v[100:101], s[22:23]
	v_pk_add_f32 v[136:137], v[114:115], v[26:27]
	v_pk_mul_f32 v[114:115], v[24:25], s[22:23]
	v_pk_mul_f32 v[142:143], v[16:17], s[22:23]
	v_pk_mul_f32 v[160:161], v[8:9], s[22:23]
	v_pk_add_f32 v[166:167], v[2:3], v[6:7]
	v_pk_mul_f32 v[168:169], v[0:1], s[22:23]
	v_pk_add_f32 v[28:29], v[14:15], v[124:125]
	v_pk_add_f32 v[104:105], v[14:15], v[124:125] neg_lo:[0,1] neg_hi:[0,1]
	v_pk_add_f32 v[24:25], v[30:31], v[110:111] op_sel:[0,1] op_sel_hi:[1,0] neg_hi:[0,1]
	v_pk_add_f32 v[102:103], v[30:31], v[110:111] op_sel:[0,1] op_sel_hi:[1,0] neg_lo:[0,1]
	v_pk_add_f32 v[20:21], v[120:121], v[126:127]
	v_pk_add_f32 v[100:101], v[120:121], v[126:127] neg_lo:[0,1] neg_hi:[0,1]
	v_pk_add_f32 v[16:17], v[118:119], v[108:109] op_sel:[0,1] op_sel_hi:[1,0]
	v_pk_add_f32 v[98:99], v[118:119], v[108:109] op_sel:[0,1] op_sel_hi:[1,0] neg_lo:[0,1] neg_hi:[0,1]
	v_pk_add_f32 v[12:13], v[112:113], v[116:117]
	v_pk_add_f32 v[96:97], v[112:113], v[116:117] neg_lo:[0,1] neg_hi:[0,1]
	v_pk_add_f32 v[8:9], v[94:95], v[128:129] op_sel:[0,1] op_sel_hi:[1,0]
	v_pk_add_f32 v[94:95], v[94:95], v[128:129] op_sel:[0,1] op_sel_hi:[1,0] neg_lo:[0,1] neg_hi:[0,1]
	v_pk_add_f32 v[4:5], v[130:131], v[92:93]
	v_pk_add_f32 v[92:93], v[130:131], v[92:93] neg_lo:[0,1] neg_hi:[0,1]
	v_pk_add_f32 v[0:1], v[132:133], v[86:87] op_sel:[0,1] op_sel_hi:[1,0] neg_hi:[0,1]
	v_pk_add_f32 v[86:87], v[132:133], v[86:87] op_sel:[0,1] op_sel_hi:[1,0] neg_lo:[0,1]
	v_pk_add_f32 v[30:31], v[134:135], v[136:137]
	v_pk_add_f32 v[120:121], v[134:135], v[136:137] neg_lo:[0,1] neg_hi:[0,1]
	v_pk_add_f32 v[26:27], v[106:107], v[114:115] op_sel:[0,1] op_sel_hi:[1,0]
	v_pk_add_f32 v[118:119], v[106:107], v[114:115] op_sel:[0,1] op_sel_hi:[1,0] neg_lo:[0,1] neg_hi:[0,1]
	v_pk_add_f32 v[22:23], v[138:139], v[18:19]
	v_pk_add_f32 v[116:117], v[138:139], v[18:19] neg_lo:[0,1] neg_hi:[0,1]
	v_pk_add_f32 v[18:19], v[140:141], v[142:143] op_sel:[0,1] op_sel_hi:[1,0]
	v_pk_add_f32 v[114:115], v[140:141], v[142:143] op_sel:[0,1] op_sel_hi:[1,0] neg_lo:[0,1] neg_hi:[0,1]
	v_pk_add_f32 v[14:15], v[144:145], v[10:11]
	v_pk_add_f32 v[112:113], v[144:145], v[10:11] neg_lo:[0,1] neg_hi:[0,1]
	v_pk_add_f32 v[10:11], v[158:159], v[160:161] op_sel:[0,1] op_sel_hi:[1,0]
	v_pk_add_f32 v[110:111], v[158:159], v[160:161] op_sel:[0,1] op_sel_hi:[1,0] neg_lo:[0,1] neg_hi:[0,1]
	v_pk_add_f32 v[6:7], v[162:163], v[166:167]
	v_pk_add_f32 v[108:109], v[162:163], v[166:167] neg_lo:[0,1] neg_hi:[0,1]
	v_pk_add_f32 v[2:3], v[164:165], v[168:169] op_sel:[0,1] op_sel_hi:[1,0]
	v_pk_add_f32 v[106:107], v[164:165], v[168:169] op_sel:[0,1] op_sel_hi:[1,0] neg_lo:[0,1] neg_hi:[0,1]

.LBB0_623:
	s_or_b64 exec, exec, s[4:5]
	v_mov_b32_e32 v41, v32
	s_waitcnt lgkmcnt(0)
	s_barrier
	s_mov_b32 s11, s14
	v_and_b32_e32 v98, 31, v41
	v_cvt_f32_ubyte0_e32 v24, v98
	v_mul_f32_e32 v92, 0x3b000000, v24
	v_sin_f32_e32 v24, v92
	v_ashrrev_i32_e32 v0, 4, v41
	v_lshlrev_b32_e32 v0, 3, v0
	v_lshlrev_b32_e32 v1, 3, v41
	v_cos_f32_e32 v92, v92
	v_add3_u32 v25, 0, v0, v1
	ds_read_b64 v[0:1], v25
	ds_read_b64 v[2:3], v25 offset:4352
	ds_read_b64 v[4:5], v25 offset:8704
	ds_read_b64 v[6:7], v25 offset:13056
	ds_read_b64 v[8:9], v25 offset:17408
	ds_read_b64 v[10:11], v25 offset:21760
	ds_read_b64 v[12:13], v25 offset:26112
	ds_read_b64 v[14:15], v25 offset:30464
	ds_read_b64 v[16:17], v25 offset:34816
	ds_read_b64 v[18:19], v25 offset:39168
	ds_read_b64 v[20:21], v25 offset:43520
	ds_read_b64 v[22:23], v25 offset:47872
	v_xor_b32_e32 v93, 0x80000000, v24
	s_waitcnt lgkmcnt(10)
	v_pk_mul_f32 v[94:95], v[2:3], v[24:25] op_sel:[1,0] op_sel_hi:[0,0] neg_hi:[0,1]
	v_pk_fma_f32 v[2:3], v[2:3], v[92:93], v[94:95] op_sel_hi:[1,0,1]
	v_pk_mul_f32 v[94:95], v[24:25], v[92:93] op_sel:[0,1] op_sel_hi:[0,0] neg_hi:[1,0]
	v_pk_fma_f32 v[94:95], v[92:93], v[92:93], v[94:95] op_sel_hi:[0,1,1]
	ds_read_b64 v[26:27], v25 offset:52224
	ds_read_b64 v[28:29], v25 offset:56576
	ds_read_b64 v[30:31], v25 offset:60928
	ds_read_b64 v[86:87], v25 offset:65280
	s_waitcnt lgkmcnt(13)
	v_pk_mul_f32 v[96:97], v[4:5], v[94:95] op_sel:[1,1] op_sel_hi:[0,1] neg_lo:[0,1]
	v_pk_fma_f32 v[4:5], v[4:5], v[94:95], v[96:97] op_sel_hi:[1,0,1]
	v_pk_mul_f32 v[96:97], v[24:25], v[94:95] op_sel:[0,1] op_sel_hi:[0,0] neg_hi:[1,0]
	v_pk_fma_f32 v[94:95], v[92:93], v[94:95], v[96:97] op_sel_hi:[0,1,1]
	s_mov_b32 s35, s30
	s_waitcnt lgkmcnt(12)
	v_pk_mul_f32 v[96:97], v[6:7], v[94:95] op_sel:[1,1] op_sel_hi:[0,1] neg_lo:[0,1]
	v_pk_fma_f32 v[6:7], v[6:7], v[94:95], v[96:97] op_sel_hi:[1,0,1]
	v_pk_mul_f32 v[96:97], v[24:25], v[94:95] op_sel:[0,1] op_sel_hi:[0,0] neg_hi:[1,0]
	v_pk_fma_f32 v[94:95], v[92:93], v[94:95], v[96:97] op_sel_hi:[0,1,1]
	s_mov_b32 s26, s19
	s_waitcnt lgkmcnt(11)
	v_pk_mul_f32 v[96:97], v[8:9], v[94:95] op_sel:[1,1] op_sel_hi:[0,1] neg_lo:[0,1]
	v_pk_fma_f32 v[8:9], v[8:9], v[94:95], v[96:97] op_sel_hi:[1,0,1]
	v_pk_mul_f32 v[96:97], v[24:25], v[94:95] op_sel:[0,1] op_sel_hi:[0,0] neg_hi:[1,0]
	v_pk_fma_f32 v[94:95], v[92:93], v[94:95], v[96:97] op_sel_hi:[0,1,1]
	s_waitcnt lgkmcnt(0)
	v_pk_mul_f32 v[96:97], v[10:11], v[94:95] op_sel:[1,1] op_sel_hi:[0,1] neg_lo:[0,1]
	v_pk_fma_f32 v[10:11], v[10:11], v[94:95], v[96:97] op_sel_hi:[1,0,1]
	v_pk_mul_f32 v[96:97], v[24:25], v[94:95] op_sel:[0,1] op_sel_hi:[0,0] neg_hi:[1,0]
	v_pk_fma_f32 v[94:95], v[92:93], v[94:95], v[96:97] op_sel_hi:[0,1,1]
	s_barrier
	v_pk_mul_f32 v[96:97], v[12:13], v[94:95] op_sel:[1,1] op_sel_hi:[0,1] neg_lo:[0,1]
	v_pk_fma_f32 v[12:13], v[12:13], v[94:95], v[96:97] op_sel_hi:[1,0,1]
	v_pk_mul_f32 v[96:97], v[24:25], v[94:95] op_sel:[0,1] op_sel_hi:[0,0] neg_hi:[1,0]
	v_pk_fma_f32 v[94:95], v[92:93], v[94:95], v[96:97] op_sel_hi:[0,1,1]
	s_nop 0
	v_pk_mul_f32 v[96:97], v[14:15], v[94:95] op_sel:[1,1] op_sel_hi:[0,1] neg_lo:[0,1]
	v_pk_fma_f32 v[14:15], v[14:15], v[94:95], v[96:97] op_sel_hi:[1,0,1]
	v_pk_mul_f32 v[96:97], v[24:25], v[94:95] op_sel:[0,1] op_sel_hi:[0,0] neg_hi:[1,0]
	v_pk_fma_f32 v[94:95], v[92:93], v[94:95], v[96:97] op_sel_hi:[0,1,1]
	s_nop 0
	v_pk_mul_f32 v[96:97], v[16:17], v[94:95] op_sel:[1,1] op_sel_hi:[0,1] neg_lo:[0,1]
	v_pk_fma_f32 v[16:17], v[16:17], v[94:95], v[96:97] op_sel_hi:[1,0,1]
	v_pk_mul_f32 v[96:97], v[24:25], v[94:95] op_sel:[0,1] op_sel_hi:[0,0] neg_hi:[1,0]
	v_pk_fma_f32 v[94:95], v[92:93], v[94:95], v[96:97] op_sel_hi:[0,1,1]
	s_nop 0
	v_pk_mul_f32 v[96:97], v[18:19], v[94:95] op_sel:[1,1] op_sel_hi:[0,1] neg_lo:[0,1]
	v_pk_fma_f32 v[18:19], v[18:19], v[94:95], v[96:97] op_sel_hi:[1,0,1]
	v_pk_mul_f32 v[96:97], v[24:25], v[94:95] op_sel:[0,1] op_sel_hi:[0,0] neg_hi:[1,0]
	v_pk_fma_f32 v[94:95], v[92:93], v[94:95], v[96:97] op_sel_hi:[0,1,1]
	s_nop 0
	v_pk_mul_f32 v[96:97], v[20:21], v[94:95] op_sel:[1,1] op_sel_hi:[0,1] neg_lo:[0,1]
	v_pk_fma_f32 v[20:21], v[20:21], v[94:95], v[96:97] op_sel_hi:[1,0,1]
	v_pk_mul_f32 v[96:97], v[24:25], v[94:95] op_sel:[0,1] op_sel_hi:[0,0] neg_hi:[1,0]
	v_pk_fma_f32 v[94:95], v[92:93], v[94:95], v[96:97] op_sel_hi:[0,1,1]
	s_nop 0
	v_pk_mul_f32 v[96:97], v[22:23], v[94:95] op_sel:[1,1] op_sel_hi:[0,1] neg_lo:[0,1]
	v_pk_fma_f32 v[22:23], v[22:23], v[94:95], v[96:97] op_sel_hi:[1,0,1]
	v_pk_mul_f32 v[96:97], v[24:25], v[94:95] op_sel:[0,1] op_sel_hi:[0,0] neg_hi:[1,0]
	v_pk_fma_f32 v[94:95], v[92:93], v[94:95], v[96:97] op_sel_hi:[0,1,1]
	s_nop 0
	v_pk_mul_f32 v[96:97], v[26:27], v[94:95] op_sel:[1,1] op_sel_hi:[0,1] neg_lo:[0,1]
	v_pk_fma_f32 v[26:27], v[26:27], v[94:95], v[96:97] op_sel_hi:[1,0,1]
	v_pk_mul_f32 v[96:97], v[24:25], v[94:95] op_sel:[0,1] op_sel_hi:[0,0] neg_hi:[1,0]
	v_pk_fma_f32 v[94:95], v[92:93], v[94:95], v[96:97] op_sel_hi:[0,1,1]
	s_nop 0
	v_pk_mul_f32 v[96:97], v[28:29], v[94:95] op_sel:[1,1] op_sel_hi:[0,1] neg_lo:[0,1]
	v_pk_fma_f32 v[28:29], v[28:29], v[94:95], v[96:97] op_sel_hi:[1,0,1]
	v_pk_mul_f32 v[96:97], v[24:25], v[94:95] op_sel:[0,1] op_sel_hi:[0,0] neg_hi:[1,0]
	v_pk_fma_f32 v[94:95], v[92:93], v[94:95], v[96:97] op_sel_hi:[0,1,1]
	v_pk_mul_f32 v[24:25], v[24:25], v[94:95] op_sel:[0,1] op_sel_hi:[0,0] neg_hi:[1,0]
	v_pk_fma_f32 v[24:25], v[92:93], v[94:95], v[24:25] op_sel_hi:[0,1,1]
	v_pk_mul_f32 v[92:93], v[86:87], v[24:25] op_sel:[1,1] op_sel_hi:[0,1] neg_lo:[0,1]
	v_pk_fma_f32 v[24:25], v[86:87], v[24:25], v[92:93] op_sel_hi:[1,0,1]
	v_pk_add_f32 v[86:87], v[0:1], v[16:17]
	v_pk_add_f32 v[0:1], v[0:1], v[16:17] neg_lo:[0,1] neg_hi:[0,1]
	v_pk_add_f32 v[16:17], v[2:3], v[18:19]
	v_pk_add_f32 v[2:3], v[2:3], v[18:19] neg_lo:[0,1] neg_hi:[0,1]
	v_pk_mul_f32 v[96:97], v[30:31], v[94:95] op_sel:[1,1] op_sel_hi:[0,1] neg_lo:[0,1]
	v_pk_mul_f32 v[18:19], v[2:3], s[18:19]
	v_pk_fma_f32 v[30:31], v[30:31], v[94:95], v[96:97] op_sel_hi:[1,0,1]
	v_pk_fma_f32 v[2:3], v[2:3], s[30:31], v[18:19] op_sel:[0,0,1] op_sel_hi:[1,0,0]
	v_pk_add_f32 v[18:19], v[4:5], v[20:21]
	v_pk_add_f32 v[4:5], v[4:5], v[20:21] neg_lo:[0,1] neg_hi:[0,1]
	s_nop 0
	v_pk_mul_f32 v[20:21], v[4:5], s[10:11]
	s_nop 0
	v_pk_fma_f32 v[4:5], v[4:5], s[14:15], v[20:21] op_sel:[0,0,1] op_sel_hi:[1,0,0]
	v_pk_add_f32 v[20:21], v[6:7], v[22:23]
	v_pk_add_f32 v[6:7], v[6:7], v[22:23] neg_lo:[0,1] neg_hi:[0,1]
	s_nop 0
	v_pk_mul_f32 v[22:23], v[6:7], s[34:35]
	s_nop 0
	v_pk_fma_f32 v[6:7], v[6:7], s[26:27], v[22:23] op_sel:[0,0,1] op_sel_hi:[1,0,0]
	v_pk_add_f32 v[22:23], v[8:9], v[26:27]
	v_pk_add_f32 v[8:9], v[8:9], v[26:27] neg_lo:[0,1] neg_hi:[0,1]
	v_pk_add_f32 v[26:27], v[10:11], v[28:29]
	v_pk_add_f32 v[10:11], v[10:11], v[28:29] neg_lo:[0,1] neg_hi:[0,1]
	s_nop 0
	v_pk_mul_f32 v[28:29], v[10:11], s[34:35]
	s_nop 0
	v_pk_fma_f32 v[10:11], v[10:11], s[26:27], v[28:29] op_sel:[0,0,1] op_sel_hi:[1,0,0] neg_lo:[1,0,0] neg_hi:[1,0,0]
	v_pk_add_f32 v[28:29], v[12:13], v[30:31]
	v_pk_add_f32 v[12:13], v[12:13], v[30:31] neg_lo:[0,1] neg_hi:[0,1]
	s_nop 0
	v_pk_mul_f32 v[30:31], v[12:13], s[10:11]
	s_nop 0
	v_pk_fma_f32 v[12:13], v[12:13], s[14:15], v[30:31] op_sel:[0,0,1] op_sel_hi:[1,0,0] neg_lo:[1,0,0] neg_hi:[1,0,0]
	v_pk_add_f32 v[30:31], v[14:15], v[24:25]
	v_pk_add_f32 v[14:15], v[14:15], v[24:25] neg_lo:[0,1] neg_hi:[0,1]
	s_nop 0
	v_pk_mul_f32 v[24:25], v[14:15], s[18:19]
	s_nop 0
	v_pk_fma_f32 v[14:15], v[14:15], s[30:31], v[24:25] op_sel:[0,0,1] op_sel_hi:[1,0,0] neg_lo:[1,0,0] neg_hi:[1,0,0]
	v_pk_add_f32 v[24:25], v[86:87], v[22:23]
	v_pk_add_f32 v[22:23], v[86:87], v[22:23] neg_lo:[0,1] neg_hi:[0,1]
	v_pk_add_f32 v[86:87], v[16:17], v[26:27]
	v_pk_add_f32 v[16:17], v[16:17], v[26:27] neg_lo:[0,1] neg_hi:[0,1]
	s_nop 0
	v_pk_mul_f32 v[26:27], v[16:17], s[10:11]
	s_nop 0
	v_pk_fma_f32 v[16:17], v[16:17], s[14:15], v[26:27] op_sel:[0,0,1] op_sel_hi:[1,0,0]
	v_pk_add_f32 v[26:27], v[18:19], v[28:29]
	v_pk_add_f32 v[18:19], v[18:19], v[28:29] neg_lo:[0,1] neg_hi:[0,1]
	v_pk_add_f32 v[28:29], v[20:21], v[30:31]
	v_pk_add_f32 v[20:21], v[20:21], v[30:31] neg_lo:[0,1] neg_hi:[0,1]
	s_nop 0
	v_pk_mul_f32 v[30:31], v[20:21], s[10:11]
	s_nop 0
	v_pk_fma_f32 v[20:21], v[20:21], s[14:15], v[30:31] op_sel:[0,0,1] op_sel_hi:[1,0,0] neg_lo:[1,0,0] neg_hi:[1,0,0]
	v_pk_add_f32 v[30:31], v[0:1], v[8:9] op_sel:[0,1] op_sel_hi:[1,0] neg_hi:[0,1]
	v_pk_add_f32 v[0:1], v[0:1], v[8:9] op_sel:[0,1] op_sel_hi:[1,0] neg_lo:[0,1]
	v_pk_add_f32 v[8:9], v[2:3], v[10:11]
	v_pk_add_f32 v[2:3], v[2:3], v[10:11] neg_lo:[0,1] neg_hi:[0,1]
	s_nop 0
	v_pk_mul_f32 v[10:11], v[2:3], s[10:11]
	s_nop 0
	v_pk_fma_f32 v[2:3], v[2:3], s[14:15], v[10:11] op_sel:[0,0,1] op_sel_hi:[1,0,0]
	v_pk_add_f32 v[10:11], v[4:5], v[12:13]
	v_pk_add_f32 v[4:5], v[4:5], v[12:13] neg_lo:[0,1] neg_hi:[0,1]
	v_pk_add_f32 v[12:13], v[6:7], v[14:15]
	v_pk_add_f32 v[6:7], v[6:7], v[14:15] neg_lo:[0,1] neg_hi:[0,1]
	s_nop 0
	v_pk_mul_f32 v[14:15], v[6:7], s[10:11]
	s_nop 0
	v_pk_fma_f32 v[6:7], v[6:7], s[14:15], v[14:15] op_sel:[0,0,1] op_sel_hi:[1,0,0] neg_lo:[1,0,0] neg_hi:[1,0,0]
	v_pk_add_f32 v[14:15], v[24:25], v[26:27]
	v_pk_add_f32 v[24:25], v[24:25], v[26:27] neg_lo:[0,1] neg_hi:[0,1]
	v_pk_add_f32 v[26:27], v[86:87], v[28:29]
	v_pk_add_f32 v[28:29], v[86:87], v[28:29] neg_lo:[0,1] neg_hi:[0,1]
	v_pk_add_f32 v[86:87], v[22:23], v[18:19] op_sel:[0,1] op_sel_hi:[1,0] neg_hi:[0,1]
	v_pk_add_f32 v[18:19], v[22:23], v[18:19] op_sel:[0,1] op_sel_hi:[1,0] neg_lo:[0,1]
	v_pk_add_f32 v[22:23], v[16:17], v[20:21]
	v_pk_add_f32 v[16:17], v[16:17], v[20:21] neg_lo:[0,1] neg_hi:[0,1]
	v_pk_add_f32 v[20:21], v[30:31], v[10:11]
	v_pk_add_f32 v[10:11], v[30:31], v[10:11] neg_lo:[0,1] neg_hi:[0,1]
	v_pk_add_f32 v[30:31], v[8:9], v[12:13]
	v_pk_add_f32 v[8:9], v[8:9], v[12:13] neg_lo:[0,1] neg_hi:[0,1]
	v_pk_add_f32 v[12:13], v[0:1], v[4:5] op_sel:[0,1] op_sel_hi:[1,0] neg_hi:[0,1]
	v_pk_add_f32 v[0:1], v[0:1], v[4:5] op_sel:[0,1] op_sel_hi:[1,0] neg_lo:[0,1]
	v_pk_add_f32 v[4:5], v[2:3], v[6:7]
	v_pk_add_f32 v[2:3], v[2:3], v[6:7] neg_lo:[0,1] neg_hi:[0,1]
	s_nop 0
	v_pk_mul_f32 v[2:3], v[2:3], s[22:23]
	v_pk_add_f32 v[6:7], v[14:15], v[26:27]
	v_pk_add_f32 v[14:15], v[14:15], v[26:27] neg_lo:[0,1] neg_hi:[0,1]
	v_pk_add_f32 v[26:27], v[24:25], v[28:29] op_sel:[0,1] op_sel_hi:[1,0] neg_hi:[0,1]
	v_pk_add_f32 v[24:25], v[24:25], v[28:29] op_sel:[0,1] op_sel_hi:[1,0] neg_lo:[0,1]
	v_pk_add_f32 v[28:29], v[86:87], v[22:23]
	v_pk_add_f32 v[22:23], v[86:87], v[22:23] neg_lo:[0,1] neg_hi:[0,1]
	v_pk_add_f32 v[86:87], v[18:19], v[16:17] op_sel:[0,1] op_sel_hi:[1,0] neg_hi:[0,1]
	v_pk_add_f32 v[16:17], v[18:19], v[16:17] op_sel:[0,1] op_sel_hi:[1,0] neg_lo:[0,1]
	v_pk_add_f32 v[18:19], v[20:21], v[30:31]
	v_pk_add_f32 v[20:21], v[20:21], v[30:31] neg_lo:[0,1] neg_hi:[0,1]
	v_pk_add_f32 v[30:31], v[10:11], v[8:9] op_sel:[0,1] op_sel_hi:[1,0] neg_hi:[0,1]
	v_pk_add_f32 v[8:9], v[10:11], v[8:9] op_sel:[0,1] op_sel_hi:[1,0] neg_lo:[0,1]
	v_pk_add_f32 v[10:11], v[12:13], v[4:5]
	v_pk_add_f32 v[4:5], v[12:13], v[4:5] neg_lo:[0,1] neg_hi:[0,1]
	v_pk_add_f32 v[12:13], v[0:1], v[2:3] op_sel:[0,1] op_sel_hi:[1,0]
	v_pk_add_f32 v[0:1], v[0:1], v[2:3] op_sel:[0,1] op_sel_hi:[1,0] neg_lo:[0,1] neg_hi:[0,1]
	v_lshlrev_b32_e32 v2, 4, v41
	v_and_or_b32 v2, v2, s7, v98
	v_ashrrev_i32_e32 v3, 4, v2
	v_lshlrev_b32_e32 v3, 3, v3
	v_lshlrev_b32_e32 v2, 3, v2
	v_add3_u32 v2, 0, v3, v2
	v_add_u32_e32 v3, 0x800, v2
	v_mov_b32_e32 v41, v32
	ds_write2_b64 v2, v[6:7], v[18:19] offset1:34
	ds_write2_b64 v3, v[14:15], v[20:21] offset0:16 offset1:50
	ds_write2_b64 v2, v[26:27], v[30:31] offset0:136 offset1:170
	ds_write2_b64 v3, v[24:25], v[8:9] offset0:152 offset1:186
	ds_write2_b64 v2, v[28:29], v[10:11] offset0:68 offset1:102
	ds_write2_b64 v3, v[22:23], v[4:5] offset0:84 offset1:118
	ds_write2_b64 v2, v[86:87], v[12:13] offset0:204 offset1:238
	ds_write2_b64 v3, v[16:17], v[0:1] offset0:220 offset1:254
	s_waitcnt lgkmcnt(0)
	s_barrier
	s_nop 0
	v_and_b32_e32 v98, 0x1ff, v41
	v_cvt_f32_u32_e32 v24, v98
	v_ashrrev_i32_e32 v0, 4, v41
	v_lshlrev_b32_e32 v0, 3, v0
	v_lshlrev_b32_e32 v1, 3, v41
	v_mul_f32_e32 v92, 0x39000000, v24
	v_sin_f32_e32 v24, v92
	v_cos_f32_e32 v92, v92
	v_add3_u32 v25, 0, v0, v1
	ds_read_b64 v[0:1], v25
	ds_read_b64 v[2:3], v25 offset:4352
	ds_read_b64 v[4:5], v25 offset:8704
	ds_read_b64 v[6:7], v25 offset:13056
	ds_read_b64 v[8:9], v25 offset:17408
	ds_read_b64 v[10:11], v25 offset:21760
	ds_read_b64 v[12:13], v25 offset:26112
	ds_read_b64 v[14:15], v25 offset:30464
	v_xor_b32_e32 v93, 0x80000000, v24
	s_waitcnt lgkmcnt(6)
	v_pk_mul_f32 v[94:95], v[2:3], v[24:25] op_sel:[1,0] op_sel_hi:[0,0] neg_hi:[0,1]
	v_pk_fma_f32 v[2:3], v[2:3], v[92:93], v[94:95] op_sel_hi:[1,0,1]
	v_pk_mul_f32 v[94:95], v[24:25], v[92:93] op_sel:[0,1] op_sel_hi:[0,0] neg_hi:[1,0]
	v_pk_fma_f32 v[94:95], v[92:93], v[92:93], v[94:95] op_sel_hi:[0,1,1]
	ds_read_b64 v[16:17], v25 offset:34816
	ds_read_b64 v[18:19], v25 offset:39168
	ds_read_b64 v[20:21], v25 offset:43520
	ds_read_b64 v[22:23], v25 offset:47872
	s_waitcnt lgkmcnt(9)
	v_pk_mul_f32 v[96:97], v[4:5], v[94:95] op_sel:[1,1] op_sel_hi:[0,1] neg_lo:[0,1]
	v_pk_fma_f32 v[4:5], v[4:5], v[94:95], v[96:97] op_sel_hi:[1,0,1]
	v_pk_mul_f32 v[96:97], v[24:25], v[94:95] op_sel:[0,1] op_sel_hi:[0,0] neg_hi:[1,0]
	v_pk_fma_f32 v[94:95], v[92:93], v[94:95], v[96:97] op_sel_hi:[0,1,1]
	ds_read_b64 v[26:27], v25 offset:52224
	ds_read_b64 v[28:29], v25 offset:56576
	ds_read_b64 v[30:31], v25 offset:60928
	ds_read_b64 v[86:87], v25 offset:65280
	s_waitcnt lgkmcnt(12)
	v_pk_mul_f32 v[96:97], v[6:7], v[94:95] op_sel:[1,1] op_sel_hi:[0,1] neg_lo:[0,1]
	v_pk_fma_f32 v[6:7], v[6:7], v[94:95], v[96:97] op_sel_hi:[1,0,1]
	v_pk_mul_f32 v[96:97], v[24:25], v[94:95] op_sel:[0,1] op_sel_hi:[0,0] neg_hi:[1,0]
	v_pk_fma_f32 v[94:95], v[92:93], v[94:95], v[96:97] op_sel_hi:[0,1,1]
	s_waitcnt lgkmcnt(0)
	v_pk_mul_f32 v[96:97], v[8:9], v[94:95] op_sel:[1,1] op_sel_hi:[0,1] neg_lo:[0,1]
	v_pk_fma_f32 v[8:9], v[8:9], v[94:95], v[96:97] op_sel_hi:[1,0,1]
	v_pk_mul_f32 v[96:97], v[24:25], v[94:95] op_sel:[0,1] op_sel_hi:[0,0] neg_hi:[1,0]
	v_pk_fma_f32 v[94:95], v[92:93], v[94:95], v[96:97] op_sel_hi:[0,1,1]
	s_barrier
	v_pk_mul_f32 v[96:97], v[10:11], v[94:95] op_sel:[1,1] op_sel_hi:[0,1] neg_lo:[0,1]
	v_pk_fma_f32 v[10:11], v[10:11], v[94:95], v[96:97] op_sel_hi:[1,0,1]
	v_pk_mul_f32 v[96:97], v[24:25], v[94:95] op_sel:[0,1] op_sel_hi:[0,0] neg_hi:[1,0]
	v_pk_fma_f32 v[94:95], v[92:93], v[94:95], v[96:97] op_sel_hi:[0,1,1]
	s_nop 0
	v_pk_mul_f32 v[96:97], v[12:13], v[94:95] op_sel:[1,1] op_sel_hi:[0,1] neg_lo:[0,1]
	v_pk_fma_f32 v[12:13], v[12:13], v[94:95], v[96:97] op_sel_hi:[1,0,1]
	v_pk_mul_f32 v[96:97], v[24:25], v[94:95] op_sel:[0,1] op_sel_hi:[0,0] neg_hi:[1,0]
	v_pk_fma_f32 v[94:95], v[92:93], v[94:95], v[96:97] op_sel_hi:[0,1,1]
	s_nop 0
	v_pk_mul_f32 v[96:97], v[14:15], v[94:95] op_sel:[1,1] op_sel_hi:[0,1] neg_lo:[0,1]
	v_pk_fma_f32 v[14:15], v[14:15], v[94:95], v[96:97] op_sel_hi:[1,0,1]
	v_pk_mul_f32 v[96:97], v[24:25], v[94:95] op_sel:[0,1] op_sel_hi:[0,0] neg_hi:[1,0]
	v_pk_fma_f32 v[94:95], v[92:93], v[94:95], v[96:97] op_sel_hi:[0,1,1]
	s_nop 0
	v_pk_mul_f32 v[96:97], v[16:17], v[94:95] op_sel:[1,1] op_sel_hi:[0,1] neg_lo:[0,1]
	v_pk_fma_f32 v[16:17], v[16:17], v[94:95], v[96:97] op_sel_hi:[1,0,1]
	v_pk_mul_f32 v[96:97], v[24:25], v[94:95] op_sel:[0,1] op_sel_hi:[0,0] neg_hi:[1,0]
	v_pk_fma_f32 v[94:95], v[92:93], v[94:95], v[96:97] op_sel_hi:[0,1,1]
	s_nop 0
	v_pk_mul_f32 v[96:97], v[18:19], v[94:95] op_sel:[1,1] op_sel_hi:[0,1] neg_lo:[0,1]
	v_pk_fma_f32 v[18:19], v[18:19], v[94:95], v[96:97] op_sel_hi:[1,0,1]
	v_pk_mul_f32 v[96:97], v[24:25], v[94:95] op_sel:[0,1] op_sel_hi:[0,0] neg_hi:[1,0]
	v_pk_fma_f32 v[94:95], v[92:93], v[94:95], v[96:97] op_sel_hi:[0,1,1]
	s_nop 0
	v_pk_mul_f32 v[96:97], v[20:21], v[94:95] op_sel:[1,1] op_sel_hi:[0,1] neg_lo:[0,1]
	v_pk_fma_f32 v[20:21], v[20:21], v[94:95], v[96:97] op_sel_hi:[1,0,1]
	v_pk_mul_f32 v[96:97], v[24:25], v[94:95] op_sel:[0,1] op_sel_hi:[0,0] neg_hi:[1,0]
	v_pk_fma_f32 v[94:95], v[92:93], v[94:95], v[96:97] op_sel_hi:[0,1,1]
	s_nop 0
	v_pk_mul_f32 v[96:97], v[22:23], v[94:95] op_sel:[1,1] op_sel_hi:[0,1] neg_lo:[0,1]
	v_pk_fma_f32 v[22:23], v[22:23], v[94:95], v[96:97] op_sel_hi:[1,0,1]
	v_pk_mul_f32 v[96:97], v[24:25], v[94:95] op_sel:[0,1] op_sel_hi:[0,0] neg_hi:[1,0]
	v_pk_fma_f32 v[94:95], v[92:93], v[94:95], v[96:97] op_sel_hi:[0,1,1]
	s_nop 0
	v_pk_mul_f32 v[96:97], v[26:27], v[94:95] op_sel:[1,1] op_sel_hi:[0,1] neg_lo:[0,1]
	v_pk_fma_f32 v[26:27], v[26:27], v[94:95], v[96:97] op_sel_hi:[1,0,1]
	v_pk_mul_f32 v[96:97], v[24:25], v[94:95] op_sel:[0,1] op_sel_hi:[0,0] neg_hi:[1,0]
	v_pk_fma_f32 v[94:95], v[92:93], v[94:95], v[96:97] op_sel_hi:[0,1,1]
	s_nop 0
	v_pk_mul_f32 v[96:97], v[28:29], v[94:95] op_sel:[1,1] op_sel_hi:[0,1] neg_lo:[0,1]
	v_pk_fma_f32 v[28:29], v[28:29], v[94:95], v[96:97] op_sel_hi:[1,0,1]
	v_pk_mul_f32 v[96:97], v[24:25], v[94:95] op_sel:[0,1] op_sel_hi:[0,0] neg_hi:[1,0]
	v_pk_fma_f32 v[94:95], v[92:93], v[94:95], v[96:97] op_sel_hi:[0,1,1]
	v_pk_mul_f32 v[24:25], v[24:25], v[94:95] op_sel:[0,1] op_sel_hi:[0,0] neg_hi:[1,0]
	v_pk_fma_f32 v[24:25], v[92:93], v[94:95], v[24:25] op_sel_hi:[0,1,1]
	v_pk_mul_f32 v[92:93], v[86:87], v[24:25] op_sel:[1,1] op_sel_hi:[0,1] neg_lo:[0,1]
	v_pk_fma_f32 v[24:25], v[86:87], v[24:25], v[92:93] op_sel_hi:[1,0,1]
	v_pk_add_f32 v[86:87], v[0:1], v[16:17]
	v_pk_add_f32 v[0:1], v[0:1], v[16:17] neg_lo:[0,1] neg_hi:[0,1]
	v_pk_add_f32 v[16:17], v[2:3], v[18:19]
	v_pk_add_f32 v[2:3], v[2:3], v[18:19] neg_lo:[0,1] neg_hi:[0,1]
	v_pk_mul_f32 v[96:97], v[30:31], v[94:95] op_sel:[1,1] op_sel_hi:[0,1] neg_lo:[0,1]
	v_pk_mul_f32 v[18:19], v[2:3], s[18:19]
	v_pk_fma_f32 v[30:31], v[30:31], v[94:95], v[96:97] op_sel_hi:[1,0,1]
	v_pk_fma_f32 v[2:3], v[2:3], s[30:31], v[18:19] op_sel:[0,0,1] op_sel_hi:[1,0,0]
	v_pk_add_f32 v[18:19], v[4:5], v[20:21]
	v_pk_add_f32 v[4:5], v[4:5], v[20:21] neg_lo:[0,1] neg_hi:[0,1]
	s_nop 0
	v_pk_mul_f32 v[20:21], v[4:5], s[10:11]
	s_nop 0
	v_pk_fma_f32 v[4:5], v[4:5], s[14:15], v[20:21] op_sel:[0,0,1] op_sel_hi:[1,0,0]
	v_pk_add_f32 v[20:21], v[6:7], v[22:23]
	v_pk_add_f32 v[6:7], v[6:7], v[22:23] neg_lo:[0,1] neg_hi:[0,1]
	s_nop 0
	v_pk_mul_f32 v[22:23], v[6:7], s[34:35]
	s_nop 0
	v_pk_fma_f32 v[6:7], v[6:7], s[26:27], v[22:23] op_sel:[0,0,1] op_sel_hi:[1,0,0]
	v_pk_add_f32 v[22:23], v[8:9], v[26:27]
	v_pk_add_f32 v[8:9], v[8:9], v[26:27] neg_lo:[0,1] neg_hi:[0,1]
	v_pk_add_f32 v[26:27], v[10:11], v[28:29]
	v_pk_add_f32 v[10:11], v[10:11], v[28:29] neg_lo:[0,1] neg_hi:[0,1]
	s_nop 0
	v_pk_mul_f32 v[28:29], v[10:11], s[34:35]
	s_nop 0
	v_pk_fma_f32 v[10:11], v[10:11], s[26:27], v[28:29] op_sel:[0,0,1] op_sel_hi:[1,0,0] neg_lo:[1,0,0] neg_hi:[1,0,0]
	v_pk_add_f32 v[28:29], v[12:13], v[30:31]
	v_pk_add_f32 v[12:13], v[12:13], v[30:31] neg_lo:[0,1] neg_hi:[0,1]
	s_nop 0
	v_pk_mul_f32 v[30:31], v[12:13], s[10:11]
	s_nop 0
	v_pk_fma_f32 v[12:13], v[12:13], s[14:15], v[30:31] op_sel:[0,0,1] op_sel_hi:[1,0,0] neg_lo:[1,0,0] neg_hi:[1,0,0]
	v_pk_add_f32 v[30:31], v[14:15], v[24:25]
	v_pk_add_f32 v[14:15], v[14:15], v[24:25] neg_lo:[0,1] neg_hi:[0,1]
	s_nop 0
	v_pk_mul_f32 v[24:25], v[14:15], s[18:19]
	s_nop 0
	v_pk_fma_f32 v[14:15], v[14:15], s[30:31], v[24:25] op_sel:[0,0,1] op_sel_hi:[1,0,0] neg_lo:[1,0,0] neg_hi:[1,0,0]
	v_pk_add_f32 v[24:25], v[86:87], v[22:23]
	v_pk_add_f32 v[22:23], v[86:87], v[22:23] neg_lo:[0,1] neg_hi:[0,1]
	v_pk_add_f32 v[86:87], v[16:17], v[26:27]
	v_pk_add_f32 v[16:17], v[16:17], v[26:27] neg_lo:[0,1] neg_hi:[0,1]
	s_nop 0
	v_pk_mul_f32 v[26:27], v[16:17], s[10:11]
	s_nop 0
	v_pk_fma_f32 v[16:17], v[16:17], s[14:15], v[26:27] op_sel:[0,0,1] op_sel_hi:[1,0,0]
	v_pk_add_f32 v[26:27], v[18:19], v[28:29]
	v_pk_add_f32 v[18:19], v[18:19], v[28:29] neg_lo:[0,1] neg_hi:[0,1]
	v_pk_add_f32 v[28:29], v[20:21], v[30:31]
	v_pk_add_f32 v[20:21], v[20:21], v[30:31] neg_lo:[0,1] neg_hi:[0,1]
	s_nop 0
	v_pk_mul_f32 v[30:31], v[20:21], s[10:11]
	s_nop 0
	v_pk_fma_f32 v[20:21], v[20:21], s[14:15], v[30:31] op_sel:[0,0,1] op_sel_hi:[1,0,0] neg_lo:[1,0,0] neg_hi:[1,0,0]
	v_pk_add_f32 v[30:31], v[0:1], v[8:9] op_sel:[0,1] op_sel_hi:[1,0] neg_hi:[0,1]
	v_pk_add_f32 v[0:1], v[0:1], v[8:9] op_sel:[0,1] op_sel_hi:[1,0] neg_lo:[0,1]
	v_pk_add_f32 v[8:9], v[2:3], v[10:11]
	v_pk_add_f32 v[2:3], v[2:3], v[10:11] neg_lo:[0,1] neg_hi:[0,1]
	s_nop 0
	v_pk_mul_f32 v[10:11], v[2:3], s[10:11]
	s_nop 0
	v_pk_fma_f32 v[2:3], v[2:3], s[14:15], v[10:11] op_sel:[0,0,1] op_sel_hi:[1,0,0]
	v_pk_add_f32 v[10:11], v[4:5], v[12:13]
	v_pk_add_f32 v[4:5], v[4:5], v[12:13] neg_lo:[0,1] neg_hi:[0,1]
	v_pk_add_f32 v[12:13], v[6:7], v[14:15]
	v_pk_add_f32 v[6:7], v[6:7], v[14:15] neg_lo:[0,1] neg_hi:[0,1]
	s_nop 0
	v_pk_mul_f32 v[14:15], v[6:7], s[10:11]
	s_nop 0
	v_pk_fma_f32 v[6:7], v[6:7], s[14:15], v[14:15] op_sel:[0,0,1] op_sel_hi:[1,0,0] neg_lo:[1,0,0] neg_hi:[1,0,0]
	v_pk_add_f32 v[14:15], v[24:25], v[26:27]
	v_pk_add_f32 v[24:25], v[24:25], v[26:27] neg_lo:[0,1] neg_hi:[0,1]
	v_pk_add_f32 v[26:27], v[86:87], v[28:29]
	v_pk_add_f32 v[28:29], v[86:87], v[28:29] neg_lo:[0,1] neg_hi:[0,1]
	v_pk_add_f32 v[86:87], v[22:23], v[18:19] op_sel:[0,1] op_sel_hi:[1,0] neg_hi:[0,1]
	v_pk_add_f32 v[18:19], v[22:23], v[18:19] op_sel:[0,1] op_sel_hi:[1,0] neg_lo:[0,1]
	v_pk_add_f32 v[22:23], v[16:17], v[20:21]
	v_pk_add_f32 v[16:17], v[16:17], v[20:21] neg_lo:[0,1] neg_hi:[0,1]
	v_pk_add_f32 v[20:21], v[30:31], v[10:11]
	v_pk_add_f32 v[10:11], v[30:31], v[10:11] neg_lo:[0,1] neg_hi:[0,1]
	v_pk_add_f32 v[30:31], v[8:9], v[12:13]
	v_pk_add_f32 v[8:9], v[8:9], v[12:13] neg_lo:[0,1] neg_hi:[0,1]
	v_pk_add_f32 v[12:13], v[0:1], v[4:5] op_sel:[0,1] op_sel_hi:[1,0] neg_hi:[0,1]
	v_pk_add_f32 v[0:1], v[0:1], v[4:5] op_sel:[0,1] op_sel_hi:[1,0] neg_lo:[0,1]
	v_pk_add_f32 v[4:5], v[2:3], v[6:7]
	v_pk_add_f32 v[2:3], v[2:3], v[6:7] neg_lo:[0,1] neg_hi:[0,1]
	s_nop 0
	v_pk_mul_f32 v[2:3], v[2:3], s[22:23]
	v_pk_add_f32 v[6:7], v[14:15], v[26:27]
	v_pk_add_f32 v[14:15], v[14:15], v[26:27] neg_lo:[0,1] neg_hi:[0,1]
	v_pk_add_f32 v[26:27], v[24:25], v[28:29] op_sel:[0,1] op_sel_hi:[1,0] neg_hi:[0,1]
	v_pk_add_f32 v[24:25], v[24:25], v[28:29] op_sel:[0,1] op_sel_hi:[1,0] neg_lo:[0,1]
	v_pk_add_f32 v[28:29], v[86:87], v[22:23]
	v_pk_add_f32 v[22:23], v[86:87], v[22:23] neg_lo:[0,1] neg_hi:[0,1]
	v_pk_add_f32 v[86:87], v[18:19], v[16:17] op_sel:[0,1] op_sel_hi:[1,0] neg_hi:[0,1]
	v_pk_add_f32 v[16:17], v[18:19], v[16:17] op_sel:[0,1] op_sel_hi:[1,0] neg_lo:[0,1]
	v_pk_add_f32 v[18:19], v[20:21], v[30:31]
	v_pk_add_f32 v[20:21], v[20:21], v[30:31] neg_lo:[0,1] neg_hi:[0,1]
	v_pk_add_f32 v[30:31], v[10:11], v[8:9] op_sel:[0,1] op_sel_hi:[1,0] neg_hi:[0,1]
	v_pk_add_f32 v[8:9], v[10:11], v[8:9] op_sel:[0,1] op_sel_hi:[1,0] neg_lo:[0,1]
	v_pk_add_f32 v[10:11], v[12:13], v[4:5]
	v_pk_add_f32 v[4:5], v[12:13], v[4:5] neg_lo:[0,1] neg_hi:[0,1]
	v_pk_add_f32 v[12:13], v[0:1], v[2:3] op_sel:[0,1] op_sel_hi:[1,0]
	v_pk_add_f32 v[0:1], v[0:1], v[2:3] op_sel:[0,1] op_sel_hi:[1,0] neg_lo:[0,1] neg_hi:[0,1]
	v_lshlrev_b32_e32 v2, 4, v41
	v_and_or_b32 v2, v2, s15, v98
	v_ashrrev_i32_e32 v3, 4, v2
	v_lshlrev_b32_e32 v3, 3, v3
	v_lshlrev_b32_e32 v2, 3, v2
	v_add3_u32 v2, 0, v3, v2
	ds_write_b64 v2, v[6:7]
	ds_write_b64 v2, v[14:15] offset:34816
	ds_write_b64 v2, v[26:27] offset:17408
	ds_write_b64 v2, v[24:25] offset:52224
	ds_write_b64 v2, v[28:29] offset:8704
	ds_write_b64 v2, v[22:23] offset:43520
	ds_write_b64 v2, v[86:87] offset:26112
	ds_write_b64 v2, v[16:17] offset:60928
	ds_write_b64 v2, v[18:19] offset:4352
	ds_write_b64 v2, v[20:21] offset:39168
	ds_write_b64 v2, v[30:31] offset:21760
	ds_write_b64 v2, v[8:9] offset:56576
	ds_write_b64 v2, v[10:11] offset:13056
	ds_write_b64 v2, v[4:5] offset:47872
	ds_write_b64 v2, v[12:13] offset:30464
	ds_write_b64 v2, v[0:1] offset:65280
	s_waitcnt lgkmcnt(0)
	s_barrier
	s_and_saveexec_b64 s[28:29], s[40:41]
	s_cbranch_execz .LBB0_633
	s_add_u32 s4, s38, 0x400000
	s_addc_u32 s5, s39, 0
	v_lshl_add_u64 v[0:1], v[48:49], 1, s[4:5]
	global_load_dwordx4 v[8:11], v[0:1], off offset:16
	global_load_dwordx4 v[12:15], v[0:1], off
	v_mov_b32_e32 v19, 0
	v_mov_b32_e32 v18, 0
	s_and_saveexec_b64 s[8:9], s[42:43]
	s_cbranch_execz .LBB0_626
	v_lshl_add_u64 v[2:3], v[172:173], 1, s[4:5]
	global_load_ushort v2, v[2:3], off offset:-2
	s_waitcnt vmcnt(0)
	v_lshlrev_b32_e32 v18, 16, v2

.LBB0_665:
	s_or_b64 exec, exec, s[4:5]
	s_barrier
	ds_write2_b64 v152, v[92:93], v[86:87] offset1:1
	ds_write2_b64 v152, v[76:77], v[70:71] offset0:2 offset1:3
	ds_write2_b64 v152, v[90:91], v[82:83] offset0:4 offset1:5
	ds_write2_b64 v152, v[74:75], v[66:67] offset0:6 offset1:7
	ds_write2_b64 v152, v[88:89], v[80:81] offset0:8 offset1:9
	ds_write2_b64 v152, v[72:73], v[64:65] offset0:10 offset1:11
	ds_write2_b64 v152, v[84:85], v[78:79] offset0:12 offset1:13
	ds_write2_b64 v152, v[68:69], v[62:63] offset0:14 offset1:15
	s_waitcnt lgkmcnt(0)
	s_barrier
	s_and_saveexec_b64 s[28:29], s[40:41]
	s_cbranch_execz .LBB0_667
	ds_read_b64 v[0:1], v153
	ds_read_b64 v[2:3], v153 offset:2176
	ds_read_b64 v[4:5], v153 offset:4352
	ds_read_b64 v[6:7], v153 offset:6528
	ds_read_b64 v[8:9], v153 offset:8704
	ds_read_b64 v[10:11], v153 offset:10880
	ds_read_b64 v[12:13], v153 offset:13056
	ds_read_b64 v[14:15], v153 offset:15232
	ds_read_b64 v[16:17], v153 offset:17408
	ds_read_b64 v[18:19], v153 offset:19584
	ds_read_b64 v[20:21], v153 offset:21760
	ds_read_b64 v[22:23], v153 offset:23936
	ds_read_b64 v[24:25], v153 offset:26112
	ds_read_b64 v[26:27], v153 offset:28288
	ds_read_b64 v[28:29], v153 offset:30464
	ds_read_b64 v[30:31], v153 offset:32640
	ds_read_b64 v[58:59], v153 offset:34816
	ds_read_b64 v[60:61], v153 offset:41344
	ds_read_b64 v[94:95], v153 offset:43520
	ds_read_b64 v[96:97], v153 offset:45696
	ds_read_b64 v[98:99], v153 offset:47872
	ds_read_b64 v[100:101], v153 offset:50048
	ds_read_b64 v[102:103], v153 offset:52224
	ds_read_b64 v[104:105], v153 offset:54400
	ds_read_b64 v[106:107], v153 offset:56576
	ds_read_b64 v[108:109], v153 offset:58752
	ds_read_b64 v[110:111], v153 offset:60928
	ds_read_b64 v[112:113], v153 offset:63104
	ds_read_b64 v[114:115], v153 offset:65280
	ds_read_b64 v[116:117], v153 offset:36992
	ds_read_b64 v[118:119], v153 offset:39168
	ds_read_b64 v[120:121], v33
	s_waitcnt lgkmcnt(14)
	v_pk_add_f32 v[124:125], v[0:1], v[58:59]
	v_pk_add_f32 v[0:1], v[0:1], v[58:59] neg_lo:[0,1] neg_hi:[0,1]
	s_waitcnt lgkmcnt(2)
	v_pk_add_f32 v[58:59], v[2:3], v[116:117]
	v_pk_add_f32 v[2:3], v[2:3], v[116:117] neg_lo:[0,1] neg_hi:[0,1]
	s_mov_b32 s11, s14
	v_pk_mul_f32 v[116:117], v[2:3], s[16:17]
	s_mov_b32 s13, s86
	v_pk_fma_f32 v[2:3], v[2:3], s[6:7], v[116:117] op_sel:[0,0,1] op_sel_hi:[1,0,0]
	s_waitcnt lgkmcnt(1)
	v_pk_add_f32 v[116:117], v[4:5], v[118:119]
	v_pk_add_f32 v[4:5], v[4:5], v[118:119] neg_lo:[0,1] neg_hi:[0,1]
	s_mov_b32 s4, s21
	v_pk_mul_f32 v[118:119], v[4:5], s[18:19]
	s_mov_b32 s35, s30
	v_pk_fma_f32 v[4:5], v[4:5], s[30:31], v[118:119] op_sel:[0,0,1] op_sel_hi:[1,0,0]
	v_pk_add_f32 v[118:119], v[6:7], v[60:61]
	v_pk_add_f32 v[6:7], v[6:7], v[60:61] neg_lo:[0,1] neg_hi:[0,1]
	s_mov_b32 s8, s19
	v_pk_mul_f32 v[60:61], v[6:7], s[20:21]
	s_mov_b32 s77, s6
	v_pk_fma_f32 v[6:7], v[6:7], s[86:87], v[60:61] op_sel:[0,0,1] op_sel_hi:[1,0,0]
	v_pk_add_f32 v[60:61], v[8:9], v[94:95]
	v_pk_add_f32 v[8:9], v[8:9], v[94:95] neg_lo:[0,1] neg_hi:[0,1]
	s_mov_b32 s26, s17
	v_pk_mul_f32 v[94:95], v[8:9], s[10:11]
	s_nop 0
	v_pk_fma_f32 v[8:9], v[8:9], s[14:15], v[94:95] op_sel:[0,0,1] op_sel_hi:[1,0,0]
	v_pk_add_f32 v[94:95], v[10:11], v[96:97]
	v_pk_add_f32 v[10:11], v[10:11], v[96:97] neg_lo:[0,1] neg_hi:[0,1]
	s_nop 0
	v_pk_mul_f32 v[96:97], v[10:11], s[12:13]
	s_nop 0
	v_pk_fma_f32 v[10:11], v[10:11], s[4:5], v[96:97] op_sel:[0,0,1] op_sel_hi:[1,0,0]
	v_pk_add_f32 v[96:97], v[12:13], v[98:99]
	v_pk_add_f32 v[12:13], v[12:13], v[98:99] neg_lo:[0,1] neg_hi:[0,1]
	s_nop 0
	v_pk_mul_f32 v[98:99], v[12:13], s[34:35]
	s_nop 0
	v_pk_fma_f32 v[12:13], v[12:13], s[8:9], v[98:99] op_sel:[0,0,1] op_sel_hi:[1,0,0]
	v_pk_add_f32 v[98:99], v[14:15], v[100:101]
	v_pk_add_f32 v[14:15], v[14:15], v[100:101] neg_lo:[0,1] neg_hi:[0,1]
	s_nop 0
	v_pk_mul_f32 v[100:101], v[14:15], s[76:77]
	s_nop 0
	v_pk_fma_f32 v[14:15], v[14:15], s[26:27], v[100:101] op_sel:[0,0,1] op_sel_hi:[1,0,0]
	v_pk_add_f32 v[100:101], v[16:17], v[102:103]
	v_pk_add_f32 v[16:17], v[16:17], v[102:103] neg_lo:[0,1] neg_hi:[0,1]
	v_pk_add_f32 v[102:103], v[18:19], v[104:105]
	v_pk_add_f32 v[18:19], v[18:19], v[104:105] neg_lo:[0,1] neg_hi:[0,1]
	s_nop 0
	v_pk_mul_f32 v[104:105], v[18:19], s[76:77]
	s_nop 0
	v_pk_fma_f32 v[18:19], v[18:19], s[26:27], v[104:105] op_sel:[0,0,1] op_sel_hi:[1,0,0] neg_lo:[1,0,0] neg_hi:[1,0,0]
	v_pk_add_f32 v[104:105], v[20:21], v[106:107]
	v_pk_add_f32 v[20:21], v[20:21], v[106:107] neg_lo:[0,1] neg_hi:[0,1]
	s_nop 0
	v_pk_mul_f32 v[106:107], v[20:21], s[34:35]
	s_nop 0
	v_pk_fma_f32 v[20:21], v[20:21], s[8:9], v[106:107] op_sel:[0,0,1] op_sel_hi:[1,0,0] neg_lo:[1,0,0] neg_hi:[1,0,0]
	v_pk_add_f32 v[106:107], v[22:23], v[108:109]
	v_pk_add_f32 v[22:23], v[22:23], v[108:109] neg_lo:[0,1] neg_hi:[0,1]
	s_nop 0
	v_pk_mul_f32 v[108:109], v[22:23], s[12:13]
	s_nop 0
	v_pk_fma_f32 v[22:23], v[22:23], s[4:5], v[108:109] op_sel:[0,0,1] op_sel_hi:[1,0,0] neg_lo:[1,0,0] neg_hi:[1,0,0]
	v_pk_add_f32 v[108:109], v[24:25], v[110:111]
	v_pk_add_f32 v[24:25], v[24:25], v[110:111] neg_lo:[0,1] neg_hi:[0,1]
	s_nop 0
	v_pk_mul_f32 v[110:111], v[24:25], s[10:11]
	s_nop 0
	v_pk_fma_f32 v[24:25], v[24:25], s[14:15], v[110:111] op_sel:[0,0,1] op_sel_hi:[1,0,0] neg_lo:[1,0,0] neg_hi:[1,0,0]
	v_pk_add_f32 v[110:111], v[26:27], v[112:113]
	v_pk_add_f32 v[26:27], v[26:27], v[112:113] neg_lo:[0,1] neg_hi:[0,1]
	s_nop 0
	v_pk_mul_f32 v[112:113], v[26:27], s[20:21]
	s_nop 0
	v_pk_fma_f32 v[26:27], v[26:27], s[86:87], v[112:113] op_sel:[0,0,1] op_sel_hi:[1,0,0] neg_lo:[1,0,0] neg_hi:[1,0,0]
	v_pk_add_f32 v[112:113], v[28:29], v[114:115]
	v_pk_add_f32 v[28:29], v[28:29], v[114:115] neg_lo:[0,1] neg_hi:[0,1]
	s_nop 0
	v_pk_mul_f32 v[114:115], v[28:29], s[18:19]
	s_nop 0
	v_pk_fma_f32 v[28:29], v[28:29], s[30:31], v[114:115] op_sel:[0,0,1] op_sel_hi:[1,0,0] neg_lo:[1,0,0] neg_hi:[1,0,0]
	s_waitcnt lgkmcnt(0)
	v_pk_add_f32 v[114:115], v[30:31], v[120:121]
	v_pk_add_f32 v[30:31], v[30:31], v[120:121] neg_lo:[0,1] neg_hi:[0,1]
	s_nop 0
	v_pk_mul_f32 v[120:121], v[30:31], s[16:17]
	s_nop 0
	v_pk_fma_f32 v[30:31], v[30:31], s[6:7], v[120:121] op_sel:[0,0,1] op_sel_hi:[1,0,0] neg_lo:[1,0,0] neg_hi:[1,0,0]
	v_pk_add_f32 v[120:121], v[124:125], v[100:101]
	v_pk_add_f32 v[100:101], v[124:125], v[100:101] neg_lo:[0,1] neg_hi:[0,1]
	v_pk_add_f32 v[124:125], v[58:59], v[102:103]
	v_pk_add_f32 v[58:59], v[58:59], v[102:103] neg_lo:[0,1] neg_hi:[0,1]
	s_nop 0
	v_pk_mul_f32 v[102:103], v[58:59], s[18:19]
	s_nop 0
	v_pk_fma_f32 v[58:59], v[58:59], s[30:31], v[102:103] op_sel:[0,0,1] op_sel_hi:[1,0,0]
	v_pk_add_f32 v[102:103], v[116:117], v[104:105]
	v_pk_add_f32 v[104:105], v[116:117], v[104:105] neg_lo:[0,1] neg_hi:[0,1]
	s_nop 0
	v_pk_mul_f32 v[116:117], v[104:105], s[10:11]
	s_nop 0
	v_pk_fma_f32 v[104:105], v[104:105], s[14:15], v[116:117] op_sel:[0,0,1] op_sel_hi:[1,0,0]
	v_pk_add_f32 v[116:117], v[118:119], v[106:107]
	v_pk_add_f32 v[106:107], v[118:119], v[106:107] neg_lo:[0,1] neg_hi:[0,1]
	s_nop 0
	v_pk_mul_f32 v[118:119], v[106:107], s[34:35]
	s_nop 0
	v_pk_fma_f32 v[106:107], v[106:107], s[8:9], v[118:119] op_sel:[0,0,1] op_sel_hi:[1,0,0]
	v_pk_add_f32 v[118:119], v[60:61], v[108:109]
	v_pk_add_f32 v[60:61], v[60:61], v[108:109] neg_lo:[0,1] neg_hi:[0,1]
	v_pk_add_f32 v[108:109], v[94:95], v[110:111]
	v_pk_add_f32 v[94:95], v[94:95], v[110:111] neg_lo:[0,1] neg_hi:[0,1]
	s_nop 0
	v_pk_mul_f32 v[110:111], v[94:95], s[34:35]
	s_nop 0
	v_pk_fma_f32 v[94:95], v[94:95], s[8:9], v[110:111] op_sel:[0,0,1] op_sel_hi:[1,0,0] neg_lo:[1,0,0] neg_hi:[1,0,0]
	v_pk_add_f32 v[110:111], v[96:97], v[112:113]
	v_pk_add_f32 v[96:97], v[96:97], v[112:113] neg_lo:[0,1] neg_hi:[0,1]
	s_nop 0
	v_pk_mul_f32 v[112:113], v[96:97], s[10:11]
	s_nop 0
	v_pk_fma_f32 v[96:97], v[96:97], s[14:15], v[112:113] op_sel:[0,0,1] op_sel_hi:[1,0,0] neg_lo:[1,0,0] neg_hi:[1,0,0]
	v_pk_add_f32 v[112:113], v[98:99], v[114:115]
	v_pk_add_f32 v[98:99], v[98:99], v[114:115] neg_lo:[0,1] neg_hi:[0,1]
	s_nop 0
	v_pk_mul_f32 v[114:115], v[98:99], s[18:19]
	s_nop 0
	v_pk_fma_f32 v[98:99], v[98:99], s[30:31], v[114:115] op_sel:[0,0,1] op_sel_hi:[1,0,0] neg_lo:[1,0,0] neg_hi:[1,0,0]
	v_pk_add_f32 v[114:115], v[0:1], v[16:17] op_sel:[0,1] op_sel_hi:[1,0] neg_hi:[0,1]
	v_pk_add_f32 v[0:1], v[0:1], v[16:17] op_sel:[0,1] op_sel_hi:[1,0] neg_lo:[0,1]
	v_pk_add_f32 v[16:17], v[2:3], v[18:19]
	v_pk_add_f32 v[2:3], v[2:3], v[18:19] neg_lo:[0,1] neg_hi:[0,1]
	s_nop 0
	v_pk_mul_f32 v[18:19], v[2:3], s[18:19]
	s_nop 0
	v_pk_fma_f32 v[2:3], v[2:3], s[30:31], v[18:19] op_sel:[0,0,1] op_sel_hi:[1,0,0]
	v_pk_add_f32 v[18:19], v[4:5], v[20:21]
	v_pk_add_f32 v[4:5], v[4:5], v[20:21] neg_lo:[0,1] neg_hi:[0,1]
	s_nop 0
	v_pk_mul_f32 v[20:21], v[4:5], s[10:11]
	s_nop 0
	v_pk_fma_f32 v[4:5], v[4:5], s[14:15], v[20:21] op_sel:[0,0,1] op_sel_hi:[1,0,0]
	v_pk_add_f32 v[20:21], v[6:7], v[22:23]
	v_pk_add_f32 v[6:7], v[6:7], v[22:23] neg_lo:[0,1] neg_hi:[0,1]
	s_nop 0
	v_pk_mul_f32 v[22:23], v[6:7], s[34:35]
	s_nop 0
	v_pk_fma_f32 v[6:7], v[6:7], s[8:9], v[22:23] op_sel:[0,0,1] op_sel_hi:[1,0,0]
	v_pk_add_f32 v[22:23], v[8:9], v[24:25]
	v_pk_add_f32 v[8:9], v[8:9], v[24:25] neg_lo:[0,1] neg_hi:[0,1]
	v_pk_add_f32 v[24:25], v[10:11], v[26:27]
	v_pk_add_f32 v[10:11], v[10:11], v[26:27] neg_lo:[0,1] neg_hi:[0,1]
	s_nop 0
	v_pk_mul_f32 v[26:27], v[10:11], s[34:35]
	s_nop 0
	v_pk_fma_f32 v[10:11], v[10:11], s[8:9], v[26:27] op_sel:[0,0,1] op_sel_hi:[1,0,0] neg_lo:[1,0,0] neg_hi:[1,0,0]
	v_pk_add_f32 v[26:27], v[12:13], v[28:29]
	v_pk_add_f32 v[12:13], v[12:13], v[28:29] neg_lo:[0,1] neg_hi:[0,1]
	s_nop 0
	v_pk_mul_f32 v[28:29], v[12:13], s[10:11]
	s_nop 0
	v_pk_fma_f32 v[12:13], v[12:13], s[14:15], v[28:29] op_sel:[0,0,1] op_sel_hi:[1,0,0] neg_lo:[1,0,0] neg_hi:[1,0,0]
	v_pk_add_f32 v[28:29], v[14:15], v[30:31]
	v_pk_add_f32 v[14:15], v[14:15], v[30:31] neg_lo:[0,1] neg_hi:[0,1]
	s_nop 0
	v_pk_mul_f32 v[30:31], v[14:15], s[18:19]
	s_nop 0
	v_pk_fma_f32 v[14:15], v[14:15], s[30:31], v[30:31] op_sel:[0,0,1] op_sel_hi:[1,0,0] neg_lo:[1,0,0] neg_hi:[1,0,0]
	v_pk_add_f32 v[30:31], v[120:121], v[118:119]
	v_pk_add_f32 v[118:119], v[120:121], v[118:119] neg_lo:[0,1] neg_hi:[0,1]
	v_pk_add_f32 v[120:121], v[124:125], v[108:109]
	v_pk_add_f32 v[108:109], v[124:125], v[108:109] neg_lo:[0,1] neg_hi:[0,1]
	s_nop 0
	v_pk_mul_f32 v[124:125], v[108:109], s[10:11]
	s_nop 0
	v_pk_fma_f32 v[108:109], v[108:109], s[14:15], v[124:125] op_sel:[0,0,1] op_sel_hi:[1,0,0]
	v_pk_add_f32 v[124:125], v[102:103], v[110:111]
	v_pk_add_f32 v[102:103], v[102:103], v[110:111] neg_lo:[0,1] neg_hi:[0,1]
	v_pk_add_f32 v[110:111], v[116:117], v[112:113]
	v_pk_add_f32 v[112:113], v[116:117], v[112:113] neg_lo:[0,1] neg_hi:[0,1]
	s_nop 0
	v_pk_mul_f32 v[116:117], v[112:113], s[10:11]
	s_nop 0
	v_pk_fma_f32 v[112:113], v[112:113], s[14:15], v[116:117] op_sel:[0,0,1] op_sel_hi:[1,0,0] neg_lo:[1,0,0] neg_hi:[1,0,0]
	v_pk_add_f32 v[116:117], v[100:101], v[60:61] op_sel:[0,1] op_sel_hi:[1,0] neg_hi:[0,1]
	v_pk_add_f32 v[60:61], v[100:101], v[60:61] op_sel:[0,1] op_sel_hi:[1,0] neg_lo:[0,1]
	v_pk_add_f32 v[100:101], v[58:59], v[94:95]
	v_pk_add_f32 v[58:59], v[58:59], v[94:95] neg_lo:[0,1] neg_hi:[0,1]
	v_pk_add_f32 v[126:127], v[108:109], v[112:113]
	v_pk_mul_f32 v[94:95], v[58:59], s[10:11]
	s_nop 0
	v_pk_fma_f32 v[58:59], v[58:59], s[14:15], v[94:95] op_sel:[0,0,1] op_sel_hi:[1,0,0]
	v_pk_add_f32 v[94:95], v[104:105], v[96:97]
	v_pk_add_f32 v[96:97], v[104:105], v[96:97] neg_lo:[0,1] neg_hi:[0,1]
	v_pk_add_f32 v[104:105], v[106:107], v[98:99]
	v_pk_add_f32 v[98:99], v[106:107], v[98:99] neg_lo:[0,1] neg_hi:[0,1]
	s_nop 0
	v_pk_mul_f32 v[106:107], v[98:99], s[10:11]
	v_pk_add_f32 v[130:131], v[60:61], v[96:97] op_sel:[0,1] op_sel_hi:[1,0] neg_hi:[0,1]
	v_pk_fma_f32 v[98:99], v[98:99], s[14:15], v[106:107] op_sel:[0,0,1] op_sel_hi:[1,0,0] neg_lo:[1,0,0] neg_hi:[1,0,0]
	v_pk_add_f32 v[106:107], v[114:115], v[22:23]
	v_pk_add_f32 v[22:23], v[114:115], v[22:23] neg_lo:[0,1] neg_hi:[0,1]
	v_pk_add_f32 v[114:115], v[16:17], v[24:25]
	v_pk_add_f32 v[16:17], v[16:17], v[24:25] neg_lo:[0,1] neg_hi:[0,1]
	v_pk_add_f32 v[132:133], v[60:61], v[96:97] op_sel:[0,1] op_sel_hi:[1,0] neg_lo:[0,1]
	v_pk_mul_f32 v[24:25], v[16:17], s[10:11]
	v_pk_add_f32 v[60:61], v[58:59], v[98:99]
	v_pk_fma_f32 v[16:17], v[16:17], s[14:15], v[24:25] op_sel:[0,0,1] op_sel_hi:[1,0,0]
	v_pk_add_f32 v[24:25], v[18:19], v[26:27]
	v_pk_add_f32 v[18:19], v[18:19], v[26:27] neg_lo:[0,1] neg_hi:[0,1]
	v_pk_add_f32 v[26:27], v[20:21], v[28:29]
	v_pk_add_f32 v[20:21], v[20:21], v[28:29] neg_lo:[0,1] neg_hi:[0,1]
	s_nop 0
	v_pk_mul_f32 v[28:29], v[20:21], s[10:11]
	v_pk_add_f32 v[58:59], v[58:59], v[98:99] neg_lo:[0,1] neg_hi:[0,1]
	v_pk_fma_f32 v[20:21], v[20:21], s[14:15], v[28:29] op_sel:[0,0,1] op_sel_hi:[1,0,0] neg_lo:[1,0,0] neg_hi:[1,0,0]
	v_pk_add_f32 v[28:29], v[0:1], v[8:9] op_sel:[0,1] op_sel_hi:[1,0] neg_hi:[0,1]
	v_pk_add_f32 v[0:1], v[0:1], v[8:9] op_sel:[0,1] op_sel_hi:[1,0] neg_lo:[0,1]
	v_pk_add_f32 v[8:9], v[2:3], v[10:11]
	v_pk_add_f32 v[2:3], v[2:3], v[10:11] neg_lo:[0,1] neg_hi:[0,1]
	v_pk_add_f32 v[134:135], v[106:107], v[24:25]
	v_pk_mul_f32 v[10:11], v[2:3], s[10:11]
	v_pk_add_f32 v[106:107], v[106:107], v[24:25] neg_lo:[0,1] neg_hi:[0,1]
	v_pk_fma_f32 v[2:3], v[2:3], s[14:15], v[10:11] op_sel:[0,0,1] op_sel_hi:[1,0,0]
	v_pk_add_f32 v[10:11], v[4:5], v[12:13]
	v_pk_add_f32 v[4:5], v[4:5], v[12:13] neg_lo:[0,1] neg_hi:[0,1]
	v_pk_add_f32 v[12:13], v[6:7], v[14:15]
	v_pk_add_f32 v[6:7], v[6:7], v[14:15] neg_lo:[0,1] neg_hi:[0,1]
	s_nop 0
	v_pk_mul_f32 v[14:15], v[6:7], s[10:11]
	v_pk_add_f32 v[24:25], v[114:115], v[26:27] neg_lo:[0,1] neg_hi:[0,1]
	v_pk_fma_f32 v[6:7], v[6:7], s[14:15], v[14:15] op_sel:[0,0,1] op_sel_hi:[1,0,0] neg_lo:[1,0,0] neg_hi:[1,0,0]
	v_pk_add_f32 v[14:15], v[30:31], v[124:125]
	v_pk_add_f32 v[30:31], v[30:31], v[124:125] neg_lo:[0,1] neg_hi:[0,1]
	v_pk_add_f32 v[124:125], v[120:121], v[110:111]
	v_pk_add_f32 v[110:111], v[120:121], v[110:111] neg_lo:[0,1] neg_hi:[0,1]
	v_pk_add_f32 v[120:121], v[118:119], v[102:103] op_sel:[0,1] op_sel_hi:[1,0] neg_hi:[0,1]
	v_pk_add_f32 v[118:119], v[118:119], v[102:103] op_sel:[0,1] op_sel_hi:[1,0] neg_lo:[0,1]
	v_pk_add_f32 v[102:103], v[108:109], v[112:113] neg_lo:[0,1] neg_hi:[0,1]
	v_pk_add_f32 v[112:113], v[116:117], v[94:95]
	v_pk_add_f32 v[94:95], v[116:117], v[94:95] neg_lo:[0,1] neg_hi:[0,1]
	v_pk_add_f32 v[116:117], v[100:101], v[104:105]
	v_pk_add_f32 v[100:101], v[100:101], v[104:105] neg_lo:[0,1] neg_hi:[0,1]
	v_pk_add_f32 v[138:139], v[22:23], v[18:19] op_sel:[0,1] op_sel_hi:[1,0] neg_hi:[0,1]
	v_pk_add_f32 v[140:141], v[22:23], v[18:19] op_sel:[0,1] op_sel_hi:[1,0] neg_lo:[0,1]
	v_pk_add_f32 v[18:19], v[16:17], v[20:21]
	v_pk_add_f32 v[16:17], v[16:17], v[20:21] neg_lo:[0,1] neg_hi:[0,1]
	v_pk_add_f32 v[144:145], v[28:29], v[10:11]
	v_pk_add_f32 v[158:159], v[28:29], v[10:11] neg_lo:[0,1] neg_hi:[0,1]
	v_pk_add_f32 v[10:11], v[8:9], v[12:13]
	v_pk_add_f32 v[8:9], v[8:9], v[12:13] neg_lo:[0,1] neg_hi:[0,1]
	v_pk_add_f32 v[162:163], v[0:1], v[4:5] op_sel:[0,1] op_sel_hi:[1,0] neg_hi:[0,1]
	v_pk_add_f32 v[164:165], v[0:1], v[4:5] op_sel:[0,1] op_sel_hi:[1,0] neg_lo:[0,1]
	v_pk_add_f32 v[0:1], v[2:3], v[6:7] neg_lo:[0,1] neg_hi:[0,1]
	v_pk_mul_f32 v[108:109], v[102:103], s[22:23]
	v_pk_mul_f32 v[128:129], v[100:101], s[22:23]
	v_pk_add_f32 v[136:137], v[114:115], v[26:27]
	v_pk_mul_f32 v[114:115], v[24:25], s[22:23]
	v_pk_mul_f32 v[142:143], v[16:17], s[22:23]
	v_pk_mul_f32 v[160:161], v[8:9], s[22:23]
	v_pk_add_f32 v[166:167], v[2:3], v[6:7]
	v_pk_mul_f32 v[168:169], v[0:1], s[22:23]
	v_pk_add_f32 v[28:29], v[14:15], v[124:125]
	v_pk_add_f32 v[104:105], v[14:15], v[124:125] neg_lo:[0,1] neg_hi:[0,1]
	v_pk_add_f32 v[24:25], v[30:31], v[110:111] op_sel:[0,1] op_sel_hi:[1,0] neg_hi:[0,1]
	v_pk_add_f32 v[102:103], v[30:31], v[110:111] op_sel:[0,1] op_sel_hi:[1,0] neg_lo:[0,1]
	v_pk_add_f32 v[20:21], v[120:121], v[126:127]
	v_pk_add_f32 v[100:101], v[120:121], v[126:127] neg_lo:[0,1] neg_hi:[0,1]
	v_pk_add_f32 v[16:17], v[118:119], v[108:109] op_sel:[0,1] op_sel_hi:[1,0]
	v_pk_add_f32 v[98:99], v[118:119], v[108:109] op_sel:[0,1] op_sel_hi:[1,0] neg_lo:[0,1] neg_hi:[0,1]
	v_pk_add_f32 v[12:13], v[112:113], v[116:117]
	v_pk_add_f32 v[96:97], v[112:113], v[116:117] neg_lo:[0,1] neg_hi:[0,1]
	v_pk_add_f32 v[8:9], v[94:95], v[128:129] op_sel:[0,1] op_sel_hi:[1,0]
	v_pk_add_f32 v[94:95], v[94:95], v[128:129] op_sel:[0,1] op_sel_hi:[1,0] neg_lo:[0,1] neg_hi:[0,1]
	v_pk_add_f32 v[4:5], v[130:131], v[60:61]
	v_pk_add_f32 v[60:61], v[130:131], v[60:61] neg_lo:[0,1] neg_hi:[0,1]
	v_pk_add_f32 v[0:1], v[132:133], v[58:59] op_sel:[0,1] op_sel_hi:[1,0] neg_hi:[0,1]
	v_pk_add_f32 v[58:59], v[132:133], v[58:59] op_sel:[0,1] op_sel_hi:[1,0] neg_lo:[0,1]
	v_pk_add_f32 v[30:31], v[134:135], v[136:137]
	v_pk_add_f32 v[120:121], v[134:135], v[136:137] neg_lo:[0,1] neg_hi:[0,1]
	v_pk_add_f32 v[26:27], v[106:107], v[114:115] op_sel:[0,1] op_sel_hi:[1,0]
	v_pk_add_f32 v[118:119], v[106:107], v[114:115] op_sel:[0,1] op_sel_hi:[1,0] neg_lo:[0,1] neg_hi:[0,1]
	v_pk_add_f32 v[22:23], v[138:139], v[18:19]
	v_pk_add_f32 v[116:117], v[138:139], v[18:19] neg_lo:[0,1] neg_hi:[0,1]
	v_pk_add_f32 v[18:19], v[140:141], v[142:143] op_sel:[0,1] op_sel_hi:[1,0]
	v_pk_add_f32 v[114:115], v[140:141], v[142:143] op_sel:[0,1] op_sel_hi:[1,0] neg_lo:[0,1] neg_hi:[0,1]
	v_pk_add_f32 v[14:15], v[144:145], v[10:11]
	v_pk_add_f32 v[112:113], v[144:145], v[10:11] neg_lo:[0,1] neg_hi:[0,1]
	v_pk_add_f32 v[10:11], v[158:159], v[160:161] op_sel:[0,1] op_sel_hi:[1,0]
	v_pk_add_f32 v[110:111], v[158:159], v[160:161] op_sel:[0,1] op_sel_hi:[1,0] neg_lo:[0,1] neg_hi:[0,1]
	v_pk_add_f32 v[6:7], v[162:163], v[166:167]
	v_pk_add_f32 v[108:109], v[162:163], v[166:167] neg_lo:[0,1] neg_hi:[0,1]
	v_pk_add_f32 v[2:3], v[164:165], v[168:169] op_sel:[0,1] op_sel_hi:[1,0]
	v_pk_add_f32 v[106:107], v[164:165], v[168:169] op_sel:[0,1] op_sel_hi:[1,0] neg_lo:[0,1] neg_hi:[0,1]

.LBB0_669:
	s_or_b64 exec, exec, s[4:5]
	v_mov_b32_e32 v41, v32
	s_waitcnt lgkmcnt(0)
	s_barrier
	s_mov_b32 s11, s14
	v_and_b32_e32 v98, 31, v41
	v_cvt_f32_ubyte0_e32 v24, v98
	v_mul_f32_e32 v60, 0x3b000000, v24
	v_sin_f32_e32 v24, v60
	v_ashrrev_i32_e32 v0, 4, v41
	v_lshlrev_b32_e32 v0, 3, v0
	v_lshlrev_b32_e32 v1, 3, v41
	v_cos_f32_e32 v60, v60
	v_add3_u32 v25, 0, v0, v1
	ds_read_b64 v[0:1], v25
	ds_read_b64 v[2:3], v25 offset:4352
	ds_read_b64 v[4:5], v25 offset:8704
	ds_read_b64 v[6:7], v25 offset:13056
	ds_read_b64 v[8:9], v25 offset:17408
	ds_read_b64 v[10:11], v25 offset:21760
	ds_read_b64 v[12:13], v25 offset:26112
	ds_read_b64 v[14:15], v25 offset:30464
	ds_read_b64 v[16:17], v25 offset:34816
	ds_read_b64 v[18:19], v25 offset:39168
	ds_read_b64 v[20:21], v25 offset:43520
	ds_read_b64 v[22:23], v25 offset:47872
	v_xor_b32_e32 v61, 0x80000000, v24
	s_waitcnt lgkmcnt(10)
	v_pk_mul_f32 v[94:95], v[2:3], v[24:25] op_sel:[1,0] op_sel_hi:[0,0] neg_hi:[0,1]
	v_pk_fma_f32 v[2:3], v[2:3], v[60:61], v[94:95] op_sel_hi:[1,0,1]
	v_pk_mul_f32 v[94:95], v[24:25], v[60:61] op_sel:[0,1] op_sel_hi:[0,0] neg_hi:[1,0]
	v_pk_fma_f32 v[94:95], v[60:61], v[60:61], v[94:95] op_sel_hi:[0,1,1]
	ds_read_b64 v[26:27], v25 offset:52224
	ds_read_b64 v[28:29], v25 offset:56576
	ds_read_b64 v[30:31], v25 offset:60928
	ds_read_b64 v[58:59], v25 offset:65280
	s_waitcnt lgkmcnt(13)
	v_pk_mul_f32 v[96:97], v[4:5], v[94:95] op_sel:[1,1] op_sel_hi:[0,1] neg_lo:[0,1]
	v_pk_fma_f32 v[4:5], v[4:5], v[94:95], v[96:97] op_sel_hi:[1,0,1]
	v_pk_mul_f32 v[96:97], v[24:25], v[94:95] op_sel:[0,1] op_sel_hi:[0,0] neg_hi:[1,0]
	v_pk_fma_f32 v[94:95], v[60:61], v[94:95], v[96:97] op_sel_hi:[0,1,1]
	s_mov_b32 s35, s30
	s_waitcnt lgkmcnt(12)
	v_pk_mul_f32 v[96:97], v[6:7], v[94:95] op_sel:[1,1] op_sel_hi:[0,1] neg_lo:[0,1]
	v_pk_fma_f32 v[6:7], v[6:7], v[94:95], v[96:97] op_sel_hi:[1,0,1]
	v_pk_mul_f32 v[96:97], v[24:25], v[94:95] op_sel:[0,1] op_sel_hi:[0,0] neg_hi:[1,0]
	v_pk_fma_f32 v[94:95], v[60:61], v[94:95], v[96:97] op_sel_hi:[0,1,1]
	s_mov_b32 s26, s19
	s_waitcnt lgkmcnt(11)
	v_pk_mul_f32 v[96:97], v[8:9], v[94:95] op_sel:[1,1] op_sel_hi:[0,1] neg_lo:[0,1]
	v_pk_fma_f32 v[8:9], v[8:9], v[94:95], v[96:97] op_sel_hi:[1,0,1]
	v_pk_mul_f32 v[96:97], v[24:25], v[94:95] op_sel:[0,1] op_sel_hi:[0,0] neg_hi:[1,0]
	v_pk_fma_f32 v[94:95], v[60:61], v[94:95], v[96:97] op_sel_hi:[0,1,1]
	s_waitcnt lgkmcnt(0)
	v_pk_mul_f32 v[96:97], v[10:11], v[94:95] op_sel:[1,1] op_sel_hi:[0,1] neg_lo:[0,1]
	v_pk_fma_f32 v[10:11], v[10:11], v[94:95], v[96:97] op_sel_hi:[1,0,1]
	v_pk_mul_f32 v[96:97], v[24:25], v[94:95] op_sel:[0,1] op_sel_hi:[0,0] neg_hi:[1,0]
	v_pk_fma_f32 v[94:95], v[60:61], v[94:95], v[96:97] op_sel_hi:[0,1,1]
	s_barrier
	v_pk_mul_f32 v[96:97], v[12:13], v[94:95] op_sel:[1,1] op_sel_hi:[0,1] neg_lo:[0,1]
	v_pk_fma_f32 v[12:13], v[12:13], v[94:95], v[96:97] op_sel_hi:[1,0,1]
	v_pk_mul_f32 v[96:97], v[24:25], v[94:95] op_sel:[0,1] op_sel_hi:[0,0] neg_hi:[1,0]
	v_pk_fma_f32 v[94:95], v[60:61], v[94:95], v[96:97] op_sel_hi:[0,1,1]
	s_nop 0
	v_pk_mul_f32 v[96:97], v[14:15], v[94:95] op_sel:[1,1] op_sel_hi:[0,1] neg_lo:[0,1]
	v_pk_fma_f32 v[14:15], v[14:15], v[94:95], v[96:97] op_sel_hi:[1,0,1]
	v_pk_mul_f32 v[96:97], v[24:25], v[94:95] op_sel:[0,1] op_sel_hi:[0,0] neg_hi:[1,0]
	v_pk_fma_f32 v[94:95], v[60:61], v[94:95], v[96:97] op_sel_hi:[0,1,1]
	s_mov_b32 s4, 0
	v_pk_mul_f32 v[96:97], v[16:17], v[94:95] op_sel:[1,1] op_sel_hi:[0,1] neg_lo:[0,1]
	v_pk_fma_f32 v[16:17], v[16:17], v[94:95], v[96:97] op_sel_hi:[1,0,1]
	v_pk_mul_f32 v[96:97], v[24:25], v[94:95] op_sel:[0,1] op_sel_hi:[0,0] neg_hi:[1,0]
	v_pk_fma_f32 v[94:95], v[60:61], v[94:95], v[96:97] op_sel_hi:[0,1,1]
	s_nop 0
	v_pk_mul_f32 v[96:97], v[18:19], v[94:95] op_sel:[1,1] op_sel_hi:[0,1] neg_lo:[0,1]
	v_pk_fma_f32 v[18:19], v[18:19], v[94:95], v[96:97] op_sel_hi:[1,0,1]
	v_pk_mul_f32 v[96:97], v[24:25], v[94:95] op_sel:[0,1] op_sel_hi:[0,0] neg_hi:[1,0]
	v_pk_fma_f32 v[94:95], v[60:61], v[94:95], v[96:97] op_sel_hi:[0,1,1]
	s_nop 0
	v_pk_mul_f32 v[96:97], v[20:21], v[94:95] op_sel:[1,1] op_sel_hi:[0,1] neg_lo:[0,1]
	v_pk_fma_f32 v[20:21], v[20:21], v[94:95], v[96:97] op_sel_hi:[1,0,1]
	v_pk_mul_f32 v[96:97], v[24:25], v[94:95] op_sel:[0,1] op_sel_hi:[0,0] neg_hi:[1,0]
	v_pk_fma_f32 v[94:95], v[60:61], v[94:95], v[96:97] op_sel_hi:[0,1,1]
	s_nop 0
	v_pk_mul_f32 v[96:97], v[22:23], v[94:95] op_sel:[1,1] op_sel_hi:[0,1] neg_lo:[0,1]
	v_pk_fma_f32 v[22:23], v[22:23], v[94:95], v[96:97] op_sel_hi:[1,0,1]
	v_pk_mul_f32 v[96:97], v[24:25], v[94:95] op_sel:[0,1] op_sel_hi:[0,0] neg_hi:[1,0]
	v_pk_fma_f32 v[94:95], v[60:61], v[94:95], v[96:97] op_sel_hi:[0,1,1]
	s_nop 0
	v_pk_mul_f32 v[96:97], v[26:27], v[94:95] op_sel:[1,1] op_sel_hi:[0,1] neg_lo:[0,1]
	v_pk_fma_f32 v[26:27], v[26:27], v[94:95], v[96:97] op_sel_hi:[1,0,1]
	v_pk_mul_f32 v[96:97], v[24:25], v[94:95] op_sel:[0,1] op_sel_hi:[0,0] neg_hi:[1,0]
	v_pk_fma_f32 v[94:95], v[60:61], v[94:95], v[96:97] op_sel_hi:[0,1,1]
	s_nop 0
	v_pk_mul_f32 v[96:97], v[28:29], v[94:95] op_sel:[1,1] op_sel_hi:[0,1] neg_lo:[0,1]
	v_pk_fma_f32 v[28:29], v[28:29], v[94:95], v[96:97] op_sel_hi:[1,0,1]
	v_pk_mul_f32 v[96:97], v[24:25], v[94:95] op_sel:[0,1] op_sel_hi:[0,0] neg_hi:[1,0]
	v_pk_fma_f32 v[94:95], v[60:61], v[94:95], v[96:97] op_sel_hi:[0,1,1]
	v_pk_mul_f32 v[24:25], v[24:25], v[94:95] op_sel:[0,1] op_sel_hi:[0,0] neg_hi:[1,0]
	v_pk_fma_f32 v[24:25], v[60:61], v[94:95], v[24:25] op_sel_hi:[0,1,1]
	v_pk_mul_f32 v[60:61], v[58:59], v[24:25] op_sel:[1,1] op_sel_hi:[0,1] neg_lo:[0,1]
	v_pk_fma_f32 v[24:25], v[58:59], v[24:25], v[60:61] op_sel_hi:[1,0,1]
	v_pk_add_f32 v[58:59], v[0:1], v[16:17]
	v_pk_add_f32 v[0:1], v[0:1], v[16:17] neg_lo:[0,1] neg_hi:[0,1]
	v_pk_add_f32 v[16:17], v[2:3], v[18:19]
	v_pk_add_f32 v[2:3], v[2:3], v[18:19] neg_lo:[0,1] neg_hi:[0,1]
	v_pk_mul_f32 v[96:97], v[30:31], v[94:95] op_sel:[1,1] op_sel_hi:[0,1] neg_lo:[0,1]
	v_pk_mul_f32 v[18:19], v[2:3], s[18:19]
	v_pk_fma_f32 v[30:31], v[30:31], v[94:95], v[96:97] op_sel_hi:[1,0,1]
	v_pk_fma_f32 v[2:3], v[2:3], s[30:31], v[18:19] op_sel:[0,0,1] op_sel_hi:[1,0,0]
	v_pk_add_f32 v[18:19], v[4:5], v[20:21]
	v_pk_add_f32 v[4:5], v[4:5], v[20:21] neg_lo:[0,1] neg_hi:[0,1]
	s_nop 0
	v_pk_mul_f32 v[20:21], v[4:5], s[10:11]
	s_nop 0
	v_pk_fma_f32 v[4:5], v[4:5], s[14:15], v[20:21] op_sel:[0,0,1] op_sel_hi:[1,0,0]
	v_pk_add_f32 v[20:21], v[6:7], v[22:23]
	v_pk_add_f32 v[6:7], v[6:7], v[22:23] neg_lo:[0,1] neg_hi:[0,1]
	s_nop 0
	v_pk_mul_f32 v[22:23], v[6:7], s[34:35]
	s_nop 0
	v_pk_fma_f32 v[6:7], v[6:7], s[26:27], v[22:23] op_sel:[0,0,1] op_sel_hi:[1,0,0]
	v_pk_add_f32 v[22:23], v[8:9], v[26:27]
	v_pk_add_f32 v[8:9], v[8:9], v[26:27] neg_lo:[0,1] neg_hi:[0,1]
	v_pk_add_f32 v[26:27], v[10:11], v[28:29]
	v_pk_add_f32 v[10:11], v[10:11], v[28:29] neg_lo:[0,1] neg_hi:[0,1]
	s_nop 0
	v_pk_mul_f32 v[28:29], v[10:11], s[34:35]
	s_nop 0
	v_pk_fma_f32 v[10:11], v[10:11], s[26:27], v[28:29] op_sel:[0,0,1] op_sel_hi:[1,0,0] neg_lo:[1,0,0] neg_hi:[1,0,0]
	v_pk_add_f32 v[28:29], v[12:13], v[30:31]
	v_pk_add_f32 v[12:13], v[12:13], v[30:31] neg_lo:[0,1] neg_hi:[0,1]
	s_nop 0
	v_pk_mul_f32 v[30:31], v[12:13], s[10:11]
	s_nop 0
	v_pk_fma_f32 v[12:13], v[12:13], s[14:15], v[30:31] op_sel:[0,0,1] op_sel_hi:[1,0,0] neg_lo:[1,0,0] neg_hi:[1,0,0]
	v_pk_add_f32 v[30:31], v[14:15], v[24:25]
	v_pk_add_f32 v[14:15], v[14:15], v[24:25] neg_lo:[0,1] neg_hi:[0,1]
	s_nop 0
	v_pk_mul_f32 v[24:25], v[14:15], s[18:19]
	s_nop 0
	v_pk_fma_f32 v[14:15], v[14:15], s[30:31], v[24:25] op_sel:[0,0,1] op_sel_hi:[1,0,0] neg_lo:[1,0,0] neg_hi:[1,0,0]
	v_pk_add_f32 v[24:25], v[58:59], v[22:23]
	v_pk_add_f32 v[22:23], v[58:59], v[22:23] neg_lo:[0,1] neg_hi:[0,1]
	v_pk_add_f32 v[58:59], v[16:17], v[26:27]
	v_pk_add_f32 v[16:17], v[16:17], v[26:27] neg_lo:[0,1] neg_hi:[0,1]
	s_nop 0
	v_pk_mul_f32 v[26:27], v[16:17], s[10:11]
	s_nop 0
	v_pk_fma_f32 v[16:17], v[16:17], s[14:15], v[26:27] op_sel:[0,0,1] op_sel_hi:[1,0,0]
	v_pk_add_f32 v[26:27], v[18:19], v[28:29]
	v_pk_add_f32 v[18:19], v[18:19], v[28:29] neg_lo:[0,1] neg_hi:[0,1]
	v_pk_add_f32 v[28:29], v[20:21], v[30:31]
	v_pk_add_f32 v[20:21], v[20:21], v[30:31] neg_lo:[0,1] neg_hi:[0,1]
	s_nop 0
	v_pk_mul_f32 v[30:31], v[20:21], s[10:11]
	s_nop 0
	v_pk_fma_f32 v[20:21], v[20:21], s[14:15], v[30:31] op_sel:[0,0,1] op_sel_hi:[1,0,0] neg_lo:[1,0,0] neg_hi:[1,0,0]
	v_pk_add_f32 v[30:31], v[0:1], v[8:9] op_sel:[0,1] op_sel_hi:[1,0] neg_hi:[0,1]
	v_pk_add_f32 v[0:1], v[0:1], v[8:9] op_sel:[0,1] op_sel_hi:[1,0] neg_lo:[0,1]
	v_pk_add_f32 v[8:9], v[2:3], v[10:11]
	v_pk_add_f32 v[2:3], v[2:3], v[10:11] neg_lo:[0,1] neg_hi:[0,1]
	s_nop 0
	v_pk_mul_f32 v[10:11], v[2:3], s[10:11]
	s_nop 0
	v_pk_fma_f32 v[2:3], v[2:3], s[14:15], v[10:11] op_sel:[0,0,1] op_sel_hi:[1,0,0]
	v_pk_add_f32 v[10:11], v[4:5], v[12:13]
	v_pk_add_f32 v[4:5], v[4:5], v[12:13] neg_lo:[0,1] neg_hi:[0,1]
	v_pk_add_f32 v[12:13], v[6:7], v[14:15]
	v_pk_add_f32 v[6:7], v[6:7], v[14:15] neg_lo:[0,1] neg_hi:[0,1]
	s_nop 0
	v_pk_mul_f32 v[14:15], v[6:7], s[10:11]
	s_nop 0
	v_pk_fma_f32 v[6:7], v[6:7], s[14:15], v[14:15] op_sel:[0,0,1] op_sel_hi:[1,0,0] neg_lo:[1,0,0] neg_hi:[1,0,0]
	v_pk_add_f32 v[14:15], v[24:25], v[26:27]
	v_pk_add_f32 v[24:25], v[24:25], v[26:27] neg_lo:[0,1] neg_hi:[0,1]
	v_pk_add_f32 v[26:27], v[58:59], v[28:29]
	v_pk_add_f32 v[28:29], v[58:59], v[28:29] neg_lo:[0,1] neg_hi:[0,1]
	v_pk_add_f32 v[58:59], v[22:23], v[18:19] op_sel:[0,1] op_sel_hi:[1,0] neg_hi:[0,1]
	v_pk_add_f32 v[18:19], v[22:23], v[18:19] op_sel:[0,1] op_sel_hi:[1,0] neg_lo:[0,1]
	v_pk_add_f32 v[22:23], v[16:17], v[20:21]
	v_pk_add_f32 v[16:17], v[16:17], v[20:21] neg_lo:[0,1] neg_hi:[0,1]
	v_pk_add_f32 v[20:21], v[30:31], v[10:11]
	v_pk_add_f32 v[10:11], v[30:31], v[10:11] neg_lo:[0,1] neg_hi:[0,1]
	v_pk_add_f32 v[30:31], v[8:9], v[12:13]
	v_pk_add_f32 v[8:9], v[8:9], v[12:13] neg_lo:[0,1] neg_hi:[0,1]
	v_pk_add_f32 v[12:13], v[0:1], v[4:5] op_sel:[0,1] op_sel_hi:[1,0] neg_hi:[0,1]
	v_pk_add_f32 v[0:1], v[0:1], v[4:5] op_sel:[0,1] op_sel_hi:[1,0] neg_lo:[0,1]
	v_pk_add_f32 v[4:5], v[2:3], v[6:7]
	v_pk_add_f32 v[2:3], v[2:3], v[6:7] neg_lo:[0,1] neg_hi:[0,1]
	s_nop 0
	v_pk_mul_f32 v[2:3], v[2:3], s[22:23]
	v_pk_add_f32 v[6:7], v[14:15], v[26:27]
	v_pk_add_f32 v[14:15], v[14:15], v[26:27] neg_lo:[0,1] neg_hi:[0,1]
	v_pk_add_f32 v[26:27], v[24:25], v[28:29] op_sel:[0,1] op_sel_hi:[1,0] neg_hi:[0,1]
	v_pk_add_f32 v[24:25], v[24:25], v[28:29] op_sel:[0,1] op_sel_hi:[1,0] neg_lo:[0,1]
	v_pk_add_f32 v[28:29], v[58:59], v[22:23]
	v_pk_add_f32 v[22:23], v[58:59], v[22:23] neg_lo:[0,1] neg_hi:[0,1]
	v_pk_add_f32 v[58:59], v[18:19], v[16:17] op_sel:[0,1] op_sel_hi:[1,0] neg_hi:[0,1]
	v_pk_add_f32 v[16:17], v[18:19], v[16:17] op_sel:[0,1] op_sel_hi:[1,0] neg_lo:[0,1]
	v_pk_add_f32 v[18:19], v[20:21], v[30:31]
	v_pk_add_f32 v[20:21], v[20:21], v[30:31] neg_lo:[0,1] neg_hi:[0,1]
	v_pk_add_f32 v[30:31], v[10:11], v[8:9] op_sel:[0,1] op_sel_hi:[1,0] neg_hi:[0,1]
	v_pk_add_f32 v[8:9], v[10:11], v[8:9] op_sel:[0,1] op_sel_hi:[1,0] neg_lo:[0,1]
	v_pk_add_f32 v[10:11], v[12:13], v[4:5]
	v_pk_add_f32 v[4:5], v[12:13], v[4:5] neg_lo:[0,1] neg_hi:[0,1]
	v_pk_add_f32 v[12:13], v[0:1], v[2:3] op_sel:[0,1] op_sel_hi:[1,0]
	v_pk_add_f32 v[0:1], v[0:1], v[2:3] op_sel:[0,1] op_sel_hi:[1,0] neg_lo:[0,1] neg_hi:[0,1]
	v_lshlrev_b32_e32 v2, 4, v41
	v_and_or_b32 v2, v2, s7, v98
	v_ashrrev_i32_e32 v3, 4, v2
	v_lshlrev_b32_e32 v3, 3, v3
	v_lshlrev_b32_e32 v2, 3, v2
	v_add3_u32 v2, 0, v3, v2
	v_add_u32_e32 v3, 0x800, v2
	v_mov_b32_e32 v41, v32
	ds_write2_b64 v2, v[6:7], v[18:19] offset1:34
	ds_write2_b64 v3, v[14:15], v[20:21] offset0:16 offset1:50
	ds_write2_b64 v2, v[26:27], v[30:31] offset0:136 offset1:170
	ds_write2_b64 v3, v[24:25], v[8:9] offset0:152 offset1:186
	ds_write2_b64 v2, v[28:29], v[10:11] offset0:68 offset1:102
	ds_write2_b64 v3, v[22:23], v[4:5] offset0:84 offset1:118
	ds_write2_b64 v2, v[58:59], v[12:13] offset0:204 offset1:238
	ds_write2_b64 v3, v[16:17], v[0:1] offset0:220 offset1:254
	s_waitcnt lgkmcnt(0)
	s_barrier
	s_nop 0
	v_and_b32_e32 v98, 0x1ff, v41
	v_cvt_f32_u32_e32 v24, v98
	v_ashrrev_i32_e32 v0, 4, v41
	v_lshlrev_b32_e32 v0, 3, v0
	v_lshlrev_b32_e32 v1, 3, v41
	v_mul_f32_e32 v60, 0x39000000, v24
	v_sin_f32_e32 v24, v60
	v_cos_f32_e32 v60, v60
	v_add3_u32 v25, 0, v0, v1
	ds_read_b64 v[0:1], v25
	ds_read_b64 v[2:3], v25 offset:4352
	ds_read_b64 v[4:5], v25 offset:8704
	ds_read_b64 v[6:7], v25 offset:13056
	ds_read_b64 v[8:9], v25 offset:17408
	ds_read_b64 v[10:11], v25 offset:21760
	ds_read_b64 v[12:13], v25 offset:26112
	ds_read_b64 v[14:15], v25 offset:30464
	v_xor_b32_e32 v61, 0x80000000, v24
	s_waitcnt lgkmcnt(6)
	v_pk_mul_f32 v[94:95], v[2:3], v[24:25] op_sel:[1,0] op_sel_hi:[0,0] neg_hi:[0,1]
	v_pk_fma_f32 v[2:3], v[2:3], v[60:61], v[94:95] op_sel_hi:[1,0,1]
	v_pk_mul_f32 v[94:95], v[24:25], v[60:61] op_sel:[0,1] op_sel_hi:[0,0] neg_hi:[1,0]
	v_pk_fma_f32 v[94:95], v[60:61], v[60:61], v[94:95] op_sel_hi:[0,1,1]
	ds_read_b64 v[16:17], v25 offset:34816
	ds_read_b64 v[18:19], v25 offset:39168
	ds_read_b64 v[20:21], v25 offset:43520
	ds_read_b64 v[22:23], v25 offset:47872
	s_waitcnt lgkmcnt(9)
	v_pk_mul_f32 v[96:97], v[4:5], v[94:95] op_sel:[1,1] op_sel_hi:[0,1] neg_lo:[0,1]
	v_pk_fma_f32 v[4:5], v[4:5], v[94:95], v[96:97] op_sel_hi:[1,0,1]
	v_pk_mul_f32 v[96:97], v[24:25], v[94:95] op_sel:[0,1] op_sel_hi:[0,0] neg_hi:[1,0]
	v_pk_fma_f32 v[94:95], v[60:61], v[94:95], v[96:97] op_sel_hi:[0,1,1]
	ds_read_b64 v[26:27], v25 offset:52224
	ds_read_b64 v[28:29], v25 offset:56576
	ds_read_b64 v[30:31], v25 offset:60928
	ds_read_b64 v[58:59], v25 offset:65280
	s_waitcnt lgkmcnt(12)
	v_pk_mul_f32 v[96:97], v[6:7], v[94:95] op_sel:[1,1] op_sel_hi:[0,1] neg_lo:[0,1]
	v_pk_fma_f32 v[6:7], v[6:7], v[94:95], v[96:97] op_sel_hi:[1,0,1]
	v_pk_mul_f32 v[96:97], v[24:25], v[94:95] op_sel:[0,1] op_sel_hi:[0,0] neg_hi:[1,0]
	v_pk_fma_f32 v[94:95], v[60:61], v[94:95], v[96:97] op_sel_hi:[0,1,1]
	s_waitcnt lgkmcnt(0)
	v_pk_mul_f32 v[96:97], v[8:9], v[94:95] op_sel:[1,1] op_sel_hi:[0,1] neg_lo:[0,1]
	v_pk_fma_f32 v[8:9], v[8:9], v[94:95], v[96:97] op_sel_hi:[1,0,1]
	v_pk_mul_f32 v[96:97], v[24:25], v[94:95] op_sel:[0,1] op_sel_hi:[0,0] neg_hi:[1,0]
	v_pk_fma_f32 v[94:95], v[60:61], v[94:95], v[96:97] op_sel_hi:[0,1,1]
	s_barrier
	v_pk_mul_f32 v[96:97], v[10:11], v[94:95] op_sel:[1,1] op_sel_hi:[0,1] neg_lo:[0,1]
	v_pk_fma_f32 v[10:11], v[10:11], v[94:95], v[96:97] op_sel_hi:[1,0,1]
	v_pk_mul_f32 v[96:97], v[24:25], v[94:95] op_sel:[0,1] op_sel_hi:[0,0] neg_hi:[1,0]
	v_pk_fma_f32 v[94:95], v[60:61], v[94:95], v[96:97] op_sel_hi:[0,1,1]
	s_nop 0
	v_pk_mul_f32 v[96:97], v[12:13], v[94:95] op_sel:[1,1] op_sel_hi:[0,1] neg_lo:[0,1]
	v_pk_fma_f32 v[12:13], v[12:13], v[94:95], v[96:97] op_sel_hi:[1,0,1]
	v_pk_mul_f32 v[96:97], v[24:25], v[94:95] op_sel:[0,1] op_sel_hi:[0,0] neg_hi:[1,0]
	v_pk_fma_f32 v[94:95], v[60:61], v[94:95], v[96:97] op_sel_hi:[0,1,1]
	s_nop 0
	v_pk_mul_f32 v[96:97], v[14:15], v[94:95] op_sel:[1,1] op_sel_hi:[0,1] neg_lo:[0,1]
	v_pk_fma_f32 v[14:15], v[14:15], v[94:95], v[96:97] op_sel_hi:[1,0,1]
	v_pk_mul_f32 v[96:97], v[24:25], v[94:95] op_sel:[0,1] op_sel_hi:[0,0] neg_hi:[1,0]
	v_pk_fma_f32 v[94:95], v[60:61], v[94:95], v[96:97] op_sel_hi:[0,1,1]
	s_nop 0
	v_pk_mul_f32 v[96:97], v[16:17], v[94:95] op_sel:[1,1] op_sel_hi:[0,1] neg_lo:[0,1]
	v_pk_fma_f32 v[16:17], v[16:17], v[94:95], v[96:97] op_sel_hi:[1,0,1]
	v_pk_mul_f32 v[96:97], v[24:25], v[94:95] op_sel:[0,1] op_sel_hi:[0,0] neg_hi:[1,0]
	v_pk_fma_f32 v[94:95], v[60:61], v[94:95], v[96:97] op_sel_hi:[0,1,1]
	s_nop 0
	v_pk_mul_f32 v[96:97], v[18:19], v[94:95] op_sel:[1,1] op_sel_hi:[0,1] neg_lo:[0,1]
	v_pk_fma_f32 v[18:19], v[18:19], v[94:95], v[96:97] op_sel_hi:[1,0,1]
	v_pk_mul_f32 v[96:97], v[24:25], v[94:95] op_sel:[0,1] op_sel_hi:[0,0] neg_hi:[1,0]
	v_pk_fma_f32 v[94:95], v[60:61], v[94:95], v[96:97] op_sel_hi:[0,1,1]
	s_nop 0
	v_pk_mul_f32 v[96:97], v[20:21], v[94:95] op_sel:[1,1] op_sel_hi:[0,1] neg_lo:[0,1]
	v_pk_fma_f32 v[20:21], v[20:21], v[94:95], v[96:97] op_sel_hi:[1,0,1]
	v_pk_mul_f32 v[96:97], v[24:25], v[94:95] op_sel:[0,1] op_sel_hi:[0,0] neg_hi:[1,0]
	v_pk_fma_f32 v[94:95], v[60:61], v[94:95], v[96:97] op_sel_hi:[0,1,1]
	s_nop 0
	v_pk_mul_f32 v[96:97], v[22:23], v[94:95] op_sel:[1,1] op_sel_hi:[0,1] neg_lo:[0,1]
	v_pk_fma_f32 v[22:23], v[22:23], v[94:95], v[96:97] op_sel_hi:[1,0,1]
	v_pk_mul_f32 v[96:97], v[24:25], v[94:95] op_sel:[0,1] op_sel_hi:[0,0] neg_hi:[1,0]
	v_pk_fma_f32 v[94:95], v[60:61], v[94:95], v[96:97] op_sel_hi:[0,1,1]
	s_nop 0
	v_pk_mul_f32 v[96:97], v[26:27], v[94:95] op_sel:[1,1] op_sel_hi:[0,1] neg_lo:[0,1]
	v_pk_fma_f32 v[26:27], v[26:27], v[94:95], v[96:97] op_sel_hi:[1,0,1]
	v_pk_mul_f32 v[96:97], v[24:25], v[94:95] op_sel:[0,1] op_sel_hi:[0,0] neg_hi:[1,0]
	v_pk_fma_f32 v[94:95], v[60:61], v[94:95], v[96:97] op_sel_hi:[0,1,1]
	s_nop 0
	v_pk_mul_f32 v[96:97], v[28:29], v[94:95] op_sel:[1,1] op_sel_hi:[0,1] neg_lo:[0,1]
	v_pk_fma_f32 v[28:29], v[28:29], v[94:95], v[96:97] op_sel_hi:[1,0,1]
	v_pk_mul_f32 v[96:97], v[24:25], v[94:95] op_sel:[0,1] op_sel_hi:[0,0] neg_hi:[1,0]
	v_pk_fma_f32 v[94:95], v[60:61], v[94:95], v[96:97] op_sel_hi:[0,1,1]
	v_pk_mul_f32 v[24:25], v[24:25], v[94:95] op_sel:[0,1] op_sel_hi:[0,0] neg_hi:[1,0]
	v_pk_fma_f32 v[24:25], v[60:61], v[94:95], v[24:25] op_sel_hi:[0,1,1]
	v_pk_mul_f32 v[60:61], v[58:59], v[24:25] op_sel:[1,1] op_sel_hi:[0,1] neg_lo:[0,1]
	v_pk_fma_f32 v[24:25], v[58:59], v[24:25], v[60:61] op_sel_hi:[1,0,1]
	v_pk_add_f32 v[58:59], v[0:1], v[16:17]
	v_pk_add_f32 v[0:1], v[0:1], v[16:17] neg_lo:[0,1] neg_hi:[0,1]
	v_pk_add_f32 v[16:17], v[2:3], v[18:19]
	v_pk_add_f32 v[2:3], v[2:3], v[18:19] neg_lo:[0,1] neg_hi:[0,1]
	v_pk_mul_f32 v[96:97], v[30:31], v[94:95] op_sel:[1,1] op_sel_hi:[0,1] neg_lo:[0,1]
	v_pk_mul_f32 v[18:19], v[2:3], s[18:19]
	v_pk_fma_f32 v[30:31], v[30:31], v[94:95], v[96:97] op_sel_hi:[1,0,1]
	v_pk_fma_f32 v[2:3], v[2:3], s[30:31], v[18:19] op_sel:[0,0,1] op_sel_hi:[1,0,0]
	v_pk_add_f32 v[18:19], v[4:5], v[20:21]
	v_pk_add_f32 v[4:5], v[4:5], v[20:21] neg_lo:[0,1] neg_hi:[0,1]
	s_nop 0
	v_pk_mul_f32 v[20:21], v[4:5], s[10:11]
	s_nop 0
	v_pk_fma_f32 v[4:5], v[4:5], s[14:15], v[20:21] op_sel:[0,0,1] op_sel_hi:[1,0,0]
	v_pk_add_f32 v[20:21], v[6:7], v[22:23]
	v_pk_add_f32 v[6:7], v[6:7], v[22:23] neg_lo:[0,1] neg_hi:[0,1]
	s_nop 0
	v_pk_mul_f32 v[22:23], v[6:7], s[34:35]
	s_nop 0
	v_pk_fma_f32 v[6:7], v[6:7], s[26:27], v[22:23] op_sel:[0,0,1] op_sel_hi:[1,0,0]
	v_pk_add_f32 v[22:23], v[8:9], v[26:27]
	v_pk_add_f32 v[8:9], v[8:9], v[26:27] neg_lo:[0,1] neg_hi:[0,1]
	v_pk_add_f32 v[26:27], v[10:11], v[28:29]
	v_pk_add_f32 v[10:11], v[10:11], v[28:29] neg_lo:[0,1] neg_hi:[0,1]
	s_nop 0
	v_pk_mul_f32 v[28:29], v[10:11], s[34:35]
	s_nop 0
	v_pk_fma_f32 v[10:11], v[10:11], s[26:27], v[28:29] op_sel:[0,0,1] op_sel_hi:[1,0,0] neg_lo:[1,0,0] neg_hi:[1,0,0]
	v_pk_add_f32 v[28:29], v[12:13], v[30:31]
	v_pk_add_f32 v[12:13], v[12:13], v[30:31] neg_lo:[0,1] neg_hi:[0,1]
	s_nop 0
	v_pk_mul_f32 v[30:31], v[12:13], s[10:11]
	s_nop 0
	v_pk_fma_f32 v[12:13], v[12:13], s[14:15], v[30:31] op_sel:[0,0,1] op_sel_hi:[1,0,0] neg_lo:[1,0,0] neg_hi:[1,0,0]
	v_pk_add_f32 v[30:31], v[14:15], v[24:25]
	v_pk_add_f32 v[14:15], v[14:15], v[24:25] neg_lo:[0,1] neg_hi:[0,1]
	s_nop 0
	v_pk_mul_f32 v[24:25], v[14:15], s[18:19]
	s_nop 0
	v_pk_fma_f32 v[14:15], v[14:15], s[30:31], v[24:25] op_sel:[0,0,1] op_sel_hi:[1,0,0] neg_lo:[1,0,0] neg_hi:[1,0,0]
	v_pk_add_f32 v[24:25], v[58:59], v[22:23]
	v_pk_add_f32 v[22:23], v[58:59], v[22:23] neg_lo:[0,1] neg_hi:[0,1]
	v_pk_add_f32 v[58:59], v[16:17], v[26:27]
	v_pk_add_f32 v[16:17], v[16:17], v[26:27] neg_lo:[0,1] neg_hi:[0,1]
	s_nop 0
	v_pk_mul_f32 v[26:27], v[16:17], s[10:11]
	s_nop 0
	v_pk_fma_f32 v[16:17], v[16:17], s[14:15], v[26:27] op_sel:[0,0,1] op_sel_hi:[1,0,0]
	v_pk_add_f32 v[26:27], v[18:19], v[28:29]
	v_pk_add_f32 v[18:19], v[18:19], v[28:29] neg_lo:[0,1] neg_hi:[0,1]
	v_pk_add_f32 v[28:29], v[20:21], v[30:31]
	v_pk_add_f32 v[20:21], v[20:21], v[30:31] neg_lo:[0,1] neg_hi:[0,1]
	s_nop 0
	v_pk_mul_f32 v[30:31], v[20:21], s[10:11]
	s_nop 0
	v_pk_fma_f32 v[20:21], v[20:21], s[14:15], v[30:31] op_sel:[0,0,1] op_sel_hi:[1,0,0] neg_lo:[1,0,0] neg_hi:[1,0,0]
	v_pk_add_f32 v[30:31], v[0:1], v[8:9] op_sel:[0,1] op_sel_hi:[1,0] neg_hi:[0,1]
	v_pk_add_f32 v[0:1], v[0:1], v[8:9] op_sel:[0,1] op_sel_hi:[1,0] neg_lo:[0,1]
	v_pk_add_f32 v[8:9], v[2:3], v[10:11]
	v_pk_add_f32 v[2:3], v[2:3], v[10:11] neg_lo:[0,1] neg_hi:[0,1]
	s_nop 0
	v_pk_mul_f32 v[10:11], v[2:3], s[10:11]
	s_nop 0
	v_pk_fma_f32 v[2:3], v[2:3], s[14:15], v[10:11] op_sel:[0,0,1] op_sel_hi:[1,0,0]
	v_pk_add_f32 v[10:11], v[4:5], v[12:13]
	v_pk_add_f32 v[4:5], v[4:5], v[12:13] neg_lo:[0,1] neg_hi:[0,1]
	v_pk_add_f32 v[12:13], v[6:7], v[14:15]
	v_pk_add_f32 v[6:7], v[6:7], v[14:15] neg_lo:[0,1] neg_hi:[0,1]
	s_nop 0
	v_pk_mul_f32 v[14:15], v[6:7], s[10:11]
	s_nop 0
	v_pk_fma_f32 v[6:7], v[6:7], s[14:15], v[14:15] op_sel:[0,0,1] op_sel_hi:[1,0,0] neg_lo:[1,0,0] neg_hi:[1,0,0]
	v_pk_add_f32 v[14:15], v[24:25], v[26:27]
	v_pk_add_f32 v[24:25], v[24:25], v[26:27] neg_lo:[0,1] neg_hi:[0,1]
	v_pk_add_f32 v[26:27], v[58:59], v[28:29]
	v_pk_add_f32 v[28:29], v[58:59], v[28:29] neg_lo:[0,1] neg_hi:[0,1]
	v_pk_add_f32 v[58:59], v[22:23], v[18:19] op_sel:[0,1] op_sel_hi:[1,0] neg_hi:[0,1]
	v_pk_add_f32 v[18:19], v[22:23], v[18:19] op_sel:[0,1] op_sel_hi:[1,0] neg_lo:[0,1]
	v_pk_add_f32 v[22:23], v[16:17], v[20:21]
	v_pk_add_f32 v[16:17], v[16:17], v[20:21] neg_lo:[0,1] neg_hi:[0,1]
	v_pk_add_f32 v[20:21], v[30:31], v[10:11]
	v_pk_add_f32 v[10:11], v[30:31], v[10:11] neg_lo:[0,1] neg_hi:[0,1]
	v_pk_add_f32 v[30:31], v[8:9], v[12:13]
	v_pk_add_f32 v[8:9], v[8:9], v[12:13] neg_lo:[0,1] neg_hi:[0,1]
	v_pk_add_f32 v[12:13], v[0:1], v[4:5] op_sel:[0,1] op_sel_hi:[1,0] neg_hi:[0,1]
	v_pk_add_f32 v[0:1], v[0:1], v[4:5] op_sel:[0,1] op_sel_hi:[1,0] neg_lo:[0,1]
	v_pk_add_f32 v[4:5], v[2:3], v[6:7]
	v_pk_add_f32 v[2:3], v[2:3], v[6:7] neg_lo:[0,1] neg_hi:[0,1]
	s_nop 0
	v_pk_mul_f32 v[2:3], v[2:3], s[22:23]
	v_pk_add_f32 v[6:7], v[14:15], v[26:27]
	v_pk_add_f32 v[14:15], v[14:15], v[26:27] neg_lo:[0,1] neg_hi:[0,1]
	v_pk_add_f32 v[26:27], v[24:25], v[28:29] op_sel:[0,1] op_sel_hi:[1,0] neg_hi:[0,1]
	v_pk_add_f32 v[24:25], v[24:25], v[28:29] op_sel:[0,1] op_sel_hi:[1,0] neg_lo:[0,1]
	v_pk_add_f32 v[28:29], v[58:59], v[22:23]
	v_pk_add_f32 v[22:23], v[58:59], v[22:23] neg_lo:[0,1] neg_hi:[0,1]
	v_pk_add_f32 v[58:59], v[18:19], v[16:17] op_sel:[0,1] op_sel_hi:[1,0] neg_hi:[0,1]
	v_pk_add_f32 v[16:17], v[18:19], v[16:17] op_sel:[0,1] op_sel_hi:[1,0] neg_lo:[0,1]
	v_pk_add_f32 v[18:19], v[20:21], v[30:31]
	v_pk_add_f32 v[20:21], v[20:21], v[30:31] neg_lo:[0,1] neg_hi:[0,1]
	v_pk_add_f32 v[30:31], v[10:11], v[8:9] op_sel:[0,1] op_sel_hi:[1,0] neg_hi:[0,1]
	v_pk_add_f32 v[8:9], v[10:11], v[8:9] op_sel:[0,1] op_sel_hi:[1,0] neg_lo:[0,1]
	v_pk_add_f32 v[10:11], v[12:13], v[4:5]
	v_pk_add_f32 v[4:5], v[12:13], v[4:5] neg_lo:[0,1] neg_hi:[0,1]
	v_pk_add_f32 v[12:13], v[0:1], v[2:3] op_sel:[0,1] op_sel_hi:[1,0]
	v_pk_add_f32 v[0:1], v[0:1], v[2:3] op_sel:[0,1] op_sel_hi:[1,0] neg_lo:[0,1] neg_hi:[0,1]
	v_lshlrev_b32_e32 v2, 4, v41
	v_and_or_b32 v2, v2, s15, v98
	v_ashrrev_i32_e32 v3, 4, v2
	v_lshlrev_b32_e32 v3, 3, v3
	v_lshlrev_b32_e32 v2, 3, v2
	v_add3_u32 v2, 0, v3, v2
	ds_write_b64 v2, v[6:7]
	ds_write_b64 v2, v[14:15] offset:34816
	ds_write_b64 v2, v[26:27] offset:17408
	ds_write_b64 v2, v[24:25] offset:52224
	ds_write_b64 v2, v[28:29] offset:8704
	ds_write_b64 v2, v[22:23] offset:43520
	ds_write_b64 v2, v[58:59] offset:26112
	ds_write_b64 v2, v[16:17] offset:60928
	ds_write_b64 v2, v[18:19] offset:4352
	ds_write_b64 v2, v[20:21] offset:39168
	ds_write_b64 v2, v[30:31] offset:21760
	ds_write_b64 v2, v[8:9] offset:56576
	ds_write_b64 v2, v[10:11] offset:13056
	ds_write_b64 v2, v[4:5] offset:47872
	ds_write_b64 v2, v[12:13] offset:30464
	ds_write_b64 v2, v[0:1] offset:65280
	v_mov_b32_e32 v0, v154
	v_mov_b32_e32 v1, v156
	v_mov_b32_e32 v2, v155
	s_waitcnt lgkmcnt(0)
	s_barrier
.LBB0_670:
	v_or_b32_e32 v3, s4, v32
	v_cmp_ne_u32_e32 vcc, 0, v3
	v_add_u32_e32 v9, 0, v2
	v_add_u32_e32 v4, 0x11000, v9
	v_cndmask_b32_e32 v3, 0, v0, vcc
	v_lshl_add_u32 v3, v3, 3, 0
	v_add_u32_e32 v3, 0x11000, v3
	ds_read_b64 v[4:5], v4
	ds_read_b64 v[6:7], v3
	s_add_i32 s4, s4, 2
	v_add_u32_e32 v2, 0x2200, v2
	v_add_u32_e32 v0, 0xfffffbc0, v0
	s_cmp_lg_u32 s4, 16
	s_waitcnt lgkmcnt(0)
	v_add_f32_e32 v3, v5, v7
	v_mul_f32_e32 v8, 0.5, v3
	v_sub_f32_e32 v3, v4, v6
	ds_read_b64 v[6:7], v9
	v_mul_f32_e32 v4, -0.5, v3
	v_add_u32_e32 v3, 0x12100, v9
	s_waitcnt lgkmcnt(0)
	v_pk_mul_f32 v[4:5], v[6:7], v[4:5] op_sel:[1,0] op_sel_hi:[0,0]
	v_pk_fma_f32 v[10:11], v[6:7], v[8:9], v[4:5] neg_lo:[0,0,1] neg_hi:[0,0,1]
	v_pk_fma_f32 v[4:5], v[6:7], v[8:9], v[4:5] op_sel_hi:[1,0,1]
	s_nop 0
	v_mov_b32_e32 v11, v5
	v_pk_mul_f32 v[4:5], v[10:11], s[24:25]
	ds_write_b64 v9, v[4:5]
	ds_read_b64 v[4:5], v3
	v_add_u32_e32 v3, 0, v1
	v_add_u32_e32 v3, 0x1ff00, v3
	ds_read_b64 v[6:7], v3
	v_add_u32_e32 v1, 0xffffde00, v1
	s_waitcnt lgkmcnt(0)
	v_add_f32_e32 v3, v5, v7
	v_mul_f32_e32 v8, 0.5, v3
	v_sub_f32_e32 v3, v4, v6
	ds_read_b64 v[6:7], v9 offset:4352
	v_mul_f32_e32 v4, -0.5, v3
	s_waitcnt lgkmcnt(0)
	v_pk_mul_f32 v[4:5], v[6:7], v[4:5] op_sel:[1,0] op_sel_hi:[0,0]
	v_pk_fma_f32 v[10:11], v[6:7], v[8:9], v[4:5] neg_lo:[0,0,1] neg_hi:[0,0,1]
	v_pk_fma_f32 v[4:5], v[6:7], v[8:9], v[4:5] op_sel_hi:[1,0,1]
	s_nop 0
	v_mov_b32_e32 v11, v5
	v_pk_mul_f32 v[4:5], v[10:11], s[24:25]
	ds_write_b64 v9, v[4:5] offset:4352
	s_cbranch_scc1 .LBB0_670
	s_waitcnt lgkmcnt(0)
	s_barrier
	s_and_saveexec_b64 s[28:29], s[40:41]
	s_cbranch_execz .LBB0_673
	ds_read_b64 v[0:1], v153
	ds_read_b64 v[2:3], v153 offset:2176
	ds_read_b64 v[4:5], v153 offset:4352
	ds_read_b64 v[6:7], v153 offset:6528
	ds_read_b64 v[8:9], v153 offset:8704
	ds_read_b64 v[10:11], v153 offset:10880
	ds_read_b64 v[12:13], v153 offset:13056
	ds_read_b64 v[14:15], v153 offset:15232
	ds_read_b64 v[16:17], v153 offset:17408
	ds_read_b64 v[18:19], v153 offset:19584
	ds_read_b64 v[20:21], v153 offset:21760
	ds_read_b64 v[22:23], v153 offset:23936
	ds_read_b64 v[24:25], v153 offset:26112
	ds_read_b64 v[26:27], v153 offset:28288
	ds_read_b64 v[28:29], v153 offset:30464
	ds_read_b64 v[30:31], v153 offset:32640
	ds_read_b64 v[58:59], v153 offset:34816
	ds_read_b64 v[60:61], v153 offset:41344
	ds_read_b64 v[94:95], v153 offset:43520
	ds_read_b64 v[96:97], v153 offset:45696
	ds_read_b64 v[98:99], v153 offset:47872
	ds_read_b64 v[100:101], v153 offset:50048
	ds_read_b64 v[102:103], v153 offset:52224
	ds_read_b64 v[104:105], v153 offset:54400
	ds_read_b64 v[106:107], v153 offset:56576
	ds_read_b64 v[108:109], v153 offset:58752
	ds_read_b64 v[110:111], v153 offset:60928
	ds_read_b64 v[112:113], v153 offset:63104
	ds_read_b64 v[114:115], v153 offset:65280
	ds_read_b64 v[116:117], v153 offset:36992
	ds_read_b64 v[118:119], v153 offset:39168
	ds_read_b64 v[120:121], v33
	s_waitcnt lgkmcnt(14)
	v_pk_add_f32 v[124:125], v[0:1], v[58:59]
	v_pk_add_f32 v[0:1], v[0:1], v[58:59] neg_lo:[0,1] neg_hi:[0,1]
	s_waitcnt lgkmcnt(2)
	v_pk_add_f32 v[58:59], v[2:3], v[116:117]
	v_pk_add_f32 v[2:3], v[2:3], v[116:117] neg_lo:[0,1] neg_hi:[0,1]
	s_mov_b32 s11, s14
	v_pk_mul_f32 v[116:117], v[2:3], s[16:17]
	s_mov_b32 s13, s86
	v_pk_fma_f32 v[2:3], v[2:3], s[6:7], v[116:117] op_sel:[0,0,1] op_sel_hi:[1,0,0]
	s_waitcnt lgkmcnt(1)
	v_pk_add_f32 v[116:117], v[4:5], v[118:119]
	v_pk_add_f32 v[4:5], v[4:5], v[118:119] neg_lo:[0,1] neg_hi:[0,1]
	s_mov_b32 s4, s21
	v_pk_mul_f32 v[118:119], v[4:5], s[18:19]
	s_mov_b32 s35, s30
	v_pk_fma_f32 v[4:5], v[4:5], s[30:31], v[118:119] op_sel:[0,0,1] op_sel_hi:[1,0,0]
	v_pk_add_f32 v[118:119], v[6:7], v[60:61]
	v_pk_add_f32 v[6:7], v[6:7], v[60:61] neg_lo:[0,1] neg_hi:[0,1]
	s_mov_b32 s8, s19
	v_pk_mul_f32 v[60:61], v[6:7], s[20:21]
	s_mov_b32 s77, s6
	v_pk_fma_f32 v[6:7], v[6:7], s[86:87], v[60:61] op_sel:[0,0,1] op_sel_hi:[1,0,0]
	v_pk_add_f32 v[60:61], v[8:9], v[94:95]
	v_pk_add_f32 v[8:9], v[8:9], v[94:95] neg_lo:[0,1] neg_hi:[0,1]
	s_mov_b32 s26, s17
	v_pk_mul_f32 v[94:95], v[8:9], s[10:11]
	s_nop 0
	v_pk_fma_f32 v[8:9], v[8:9], s[14:15], v[94:95] op_sel:[0,0,1] op_sel_hi:[1,0,0]
	v_pk_add_f32 v[94:95], v[10:11], v[96:97]
	v_pk_add_f32 v[10:11], v[10:11], v[96:97] neg_lo:[0,1] neg_hi:[0,1]
	s_nop 0
	v_pk_mul_f32 v[96:97], v[10:11], s[12:13]
	s_nop 0
	v_pk_fma_f32 v[10:11], v[10:11], s[4:5], v[96:97] op_sel:[0,0,1] op_sel_hi:[1,0,0]
	v_pk_add_f32 v[96:97], v[12:13], v[98:99]
	v_pk_add_f32 v[12:13], v[12:13], v[98:99] neg_lo:[0,1] neg_hi:[0,1]
	s_nop 0
	v_pk_mul_f32 v[98:99], v[12:13], s[34:35]
	s_nop 0
	v_pk_fma_f32 v[12:13], v[12:13], s[8:9], v[98:99] op_sel:[0,0,1] op_sel_hi:[1,0,0]
	v_pk_add_f32 v[98:99], v[14:15], v[100:101]
	v_pk_add_f32 v[14:15], v[14:15], v[100:101] neg_lo:[0,1] neg_hi:[0,1]
	s_nop 0
	v_pk_mul_f32 v[100:101], v[14:15], s[76:77]
	s_nop 0
	v_pk_fma_f32 v[14:15], v[14:15], s[26:27], v[100:101] op_sel:[0,0,1] op_sel_hi:[1,0,0]
	v_pk_add_f32 v[100:101], v[16:17], v[102:103]
	v_pk_add_f32 v[16:17], v[16:17], v[102:103] neg_lo:[0,1] neg_hi:[0,1]
	v_pk_add_f32 v[102:103], v[18:19], v[104:105]
	v_pk_add_f32 v[18:19], v[18:19], v[104:105] neg_lo:[0,1] neg_hi:[0,1]
	s_nop 0
	v_pk_mul_f32 v[104:105], v[18:19], s[76:77]
	s_nop 0
	v_pk_fma_f32 v[18:19], v[18:19], s[26:27], v[104:105] op_sel:[0,0,1] op_sel_hi:[1,0,0] neg_lo:[1,0,0] neg_hi:[1,0,0]
	v_pk_add_f32 v[104:105], v[20:21], v[106:107]
	v_pk_add_f32 v[20:21], v[20:21], v[106:107] neg_lo:[0,1] neg_hi:[0,1]
	s_nop 0
	v_pk_mul_f32 v[106:107], v[20:21], s[34:35]
	s_nop 0
	v_pk_fma_f32 v[20:21], v[20:21], s[8:9], v[106:107] op_sel:[0,0,1] op_sel_hi:[1,0,0] neg_lo:[1,0,0] neg_hi:[1,0,0]
	v_pk_add_f32 v[106:107], v[22:23], v[108:109]
	v_pk_add_f32 v[22:23], v[22:23], v[108:109] neg_lo:[0,1] neg_hi:[0,1]
	s_nop 0
	v_pk_mul_f32 v[108:109], v[22:23], s[12:13]
	s_nop 0
	v_pk_fma_f32 v[22:23], v[22:23], s[4:5], v[108:109] op_sel:[0,0,1] op_sel_hi:[1,0,0] neg_lo:[1,0,0] neg_hi:[1,0,0]
	v_pk_add_f32 v[108:109], v[24:25], v[110:111]
	v_pk_add_f32 v[24:25], v[24:25], v[110:111] neg_lo:[0,1] neg_hi:[0,1]
	s_nop 0
	v_pk_mul_f32 v[110:111], v[24:25], s[10:11]
	s_nop 0
	v_pk_fma_f32 v[24:25], v[24:25], s[14:15], v[110:111] op_sel:[0,0,1] op_sel_hi:[1,0,0] neg_lo:[1,0,0] neg_hi:[1,0,0]
	v_pk_add_f32 v[110:111], v[26:27], v[112:113]
	v_pk_add_f32 v[26:27], v[26:27], v[112:113] neg_lo:[0,1] neg_hi:[0,1]
	s_nop 0
	v_pk_mul_f32 v[112:113], v[26:27], s[20:21]
	s_nop 0
	v_pk_fma_f32 v[26:27], v[26:27], s[86:87], v[112:113] op_sel:[0,0,1] op_sel_hi:[1,0,0] neg_lo:[1,0,0] neg_hi:[1,0,0]
	v_pk_add_f32 v[112:113], v[28:29], v[114:115]
	v_pk_add_f32 v[28:29], v[28:29], v[114:115] neg_lo:[0,1] neg_hi:[0,1]
	s_nop 0
	v_pk_mul_f32 v[114:115], v[28:29], s[18:19]
	s_nop 0
	v_pk_fma_f32 v[28:29], v[28:29], s[30:31], v[114:115] op_sel:[0,0,1] op_sel_hi:[1,0,0] neg_lo:[1,0,0] neg_hi:[1,0,0]
	s_waitcnt lgkmcnt(0)
	v_pk_add_f32 v[114:115], v[30:31], v[120:121]
	v_pk_add_f32 v[30:31], v[30:31], v[120:121] neg_lo:[0,1] neg_hi:[0,1]
	s_nop 0
	v_pk_mul_f32 v[120:121], v[30:31], s[16:17]
	s_nop 0
	v_pk_fma_f32 v[30:31], v[30:31], s[6:7], v[120:121] op_sel:[0,0,1] op_sel_hi:[1,0,0] neg_lo:[1,0,0] neg_hi:[1,0,0]
	v_pk_add_f32 v[120:121], v[124:125], v[100:101]
	v_pk_add_f32 v[100:101], v[124:125], v[100:101] neg_lo:[0,1] neg_hi:[0,1]
	v_pk_add_f32 v[124:125], v[58:59], v[102:103]
	v_pk_add_f32 v[58:59], v[58:59], v[102:103] neg_lo:[0,1] neg_hi:[0,1]
	s_nop 0
	v_pk_mul_f32 v[102:103], v[58:59], s[18:19]
	s_nop 0
	v_pk_fma_f32 v[58:59], v[58:59], s[30:31], v[102:103] op_sel:[0,0,1] op_sel_hi:[1,0,0]
	v_pk_add_f32 v[102:103], v[116:117], v[104:105]
	v_pk_add_f32 v[104:105], v[116:117], v[104:105] neg_lo:[0,1] neg_hi:[0,1]
	s_nop 0
	v_pk_mul_f32 v[116:117], v[104:105], s[10:11]
	s_nop 0
	v_pk_fma_f32 v[104:105], v[104:105], s[14:15], v[116:117] op_sel:[0,0,1] op_sel_hi:[1,0,0]
	v_pk_add_f32 v[116:117], v[118:119], v[106:107]
	v_pk_add_f32 v[106:107], v[118:119], v[106:107] neg_lo:[0,1] neg_hi:[0,1]
	s_nop 0
	v_pk_mul_f32 v[118:119], v[106:107], s[34:35]
	s_nop 0
	v_pk_fma_f32 v[106:107], v[106:107], s[8:9], v[118:119] op_sel:[0,0,1] op_sel_hi:[1,0,0]
	v_pk_add_f32 v[118:119], v[60:61], v[108:109]
	v_pk_add_f32 v[60:61], v[60:61], v[108:109] neg_lo:[0,1] neg_hi:[0,1]
	v_pk_add_f32 v[108:109], v[94:95], v[110:111]
	v_pk_add_f32 v[94:95], v[94:95], v[110:111] neg_lo:[0,1] neg_hi:[0,1]
	s_nop 0
	v_pk_mul_f32 v[110:111], v[94:95], s[34:35]
	s_nop 0
	v_pk_fma_f32 v[94:95], v[94:95], s[8:9], v[110:111] op_sel:[0,0,1] op_sel_hi:[1,0,0] neg_lo:[1,0,0] neg_hi:[1,0,0]
	v_pk_add_f32 v[110:111], v[96:97], v[112:113]
	v_pk_add_f32 v[96:97], v[96:97], v[112:113] neg_lo:[0,1] neg_hi:[0,1]
	s_nop 0
	v_pk_mul_f32 v[112:113], v[96:97], s[10:11]
	s_nop 0
	v_pk_fma_f32 v[96:97], v[96:97], s[14:15], v[112:113] op_sel:[0,0,1] op_sel_hi:[1,0,0] neg_lo:[1,0,0] neg_hi:[1,0,0]
	v_pk_add_f32 v[112:113], v[98:99], v[114:115]
	v_pk_add_f32 v[98:99], v[98:99], v[114:115] neg_lo:[0,1] neg_hi:[0,1]
	s_nop 0
	v_pk_mul_f32 v[114:115], v[98:99], s[18:19]
	s_nop 0
	v_pk_fma_f32 v[98:99], v[98:99], s[30:31], v[114:115] op_sel:[0,0,1] op_sel_hi:[1,0,0] neg_lo:[1,0,0] neg_hi:[1,0,0]
	v_pk_add_f32 v[114:115], v[0:1], v[16:17] op_sel:[0,1] op_sel_hi:[1,0] neg_hi:[0,1]
	v_pk_add_f32 v[0:1], v[0:1], v[16:17] op_sel:[0,1] op_sel_hi:[1,0] neg_lo:[0,1]
	v_pk_add_f32 v[16:17], v[2:3], v[18:19]
	v_pk_add_f32 v[2:3], v[2:3], v[18:19] neg_lo:[0,1] neg_hi:[0,1]
	s_nop 0
	v_pk_mul_f32 v[18:19], v[2:3], s[18:19]
	s_nop 0
	v_pk_fma_f32 v[2:3], v[2:3], s[30:31], v[18:19] op_sel:[0,0,1] op_sel_hi:[1,0,0]
	v_pk_add_f32 v[18:19], v[4:5], v[20:21]
	v_pk_add_f32 v[4:5], v[4:5], v[20:21] neg_lo:[0,1] neg_hi:[0,1]
	s_nop 0
	v_pk_mul_f32 v[20:21], v[4:5], s[10:11]
	s_nop 0
	v_pk_fma_f32 v[4:5], v[4:5], s[14:15], v[20:21] op_sel:[0,0,1] op_sel_hi:[1,0,0]
	v_pk_add_f32 v[20:21], v[6:7], v[22:23]
	v_pk_add_f32 v[6:7], v[6:7], v[22:23] neg_lo:[0,1] neg_hi:[0,1]
	s_nop 0
	v_pk_mul_f32 v[22:23], v[6:7], s[34:35]
	s_nop 0
	v_pk_fma_f32 v[6:7], v[6:7], s[8:9], v[22:23] op_sel:[0,0,1] op_sel_hi:[1,0,0]
	v_pk_add_f32 v[22:23], v[8:9], v[24:25]
	v_pk_add_f32 v[8:9], v[8:9], v[24:25] neg_lo:[0,1] neg_hi:[0,1]
	v_pk_add_f32 v[24:25], v[10:11], v[26:27]
	v_pk_add_f32 v[10:11], v[10:11], v[26:27] neg_lo:[0,1] neg_hi:[0,1]
	s_nop 0
	v_pk_mul_f32 v[26:27], v[10:11], s[34:35]
	s_nop 0
	v_pk_fma_f32 v[10:11], v[10:11], s[8:9], v[26:27] op_sel:[0,0,1] op_sel_hi:[1,0,0] neg_lo:[1,0,0] neg_hi:[1,0,0]
	v_pk_add_f32 v[26:27], v[12:13], v[28:29]
	v_pk_add_f32 v[12:13], v[12:13], v[28:29] neg_lo:[0,1] neg_hi:[0,1]
	s_nop 0
	v_pk_mul_f32 v[28:29], v[12:13], s[10:11]
	s_nop 0
	v_pk_fma_f32 v[12:13], v[12:13], s[14:15], v[28:29] op_sel:[0,0,1] op_sel_hi:[1,0,0] neg_lo:[1,0,0] neg_hi:[1,0,0]
	v_pk_add_f32 v[28:29], v[14:15], v[30:31]
	v_pk_add_f32 v[14:15], v[14:15], v[30:31] neg_lo:[0,1] neg_hi:[0,1]
	s_nop 0
	v_pk_mul_f32 v[30:31], v[14:15], s[18:19]
	s_nop 0
	v_pk_fma_f32 v[14:15], v[14:15], s[30:31], v[30:31] op_sel:[0,0,1] op_sel_hi:[1,0,0] neg_lo:[1,0,0] neg_hi:[1,0,0]
	v_pk_add_f32 v[30:31], v[120:121], v[118:119]
	v_pk_add_f32 v[118:119], v[120:121], v[118:119] neg_lo:[0,1] neg_hi:[0,1]
	v_pk_add_f32 v[120:121], v[124:125], v[108:109]
	v_pk_add_f32 v[108:109], v[124:125], v[108:109] neg_lo:[0,1] neg_hi:[0,1]
	s_nop 0
	v_pk_mul_f32 v[124:125], v[108:109], s[10:11]
	s_nop 0
	v_pk_fma_f32 v[108:109], v[108:109], s[14:15], v[124:125] op_sel:[0,0,1] op_sel_hi:[1,0,0]
	v_pk_add_f32 v[124:125], v[102:103], v[110:111]
	v_pk_add_f32 v[102:103], v[102:103], v[110:111] neg_lo:[0,1] neg_hi:[0,1]
	v_pk_add_f32 v[110:111], v[116:117], v[112:113]
	v_pk_add_f32 v[112:113], v[116:117], v[112:113] neg_lo:[0,1] neg_hi:[0,1]
	s_nop 0
	v_pk_mul_f32 v[116:117], v[112:113], s[10:11]
	s_nop 0
	v_pk_fma_f32 v[112:113], v[112:113], s[14:15], v[116:117] op_sel:[0,0,1] op_sel_hi:[1,0,0] neg_lo:[1,0,0] neg_hi:[1,0,0]
	v_pk_add_f32 v[116:117], v[100:101], v[60:61] op_sel:[0,1] op_sel_hi:[1,0] neg_hi:[0,1]
	v_pk_add_f32 v[60:61], v[100:101], v[60:61] op_sel:[0,1] op_sel_hi:[1,0] neg_lo:[0,1]
	v_pk_add_f32 v[100:101], v[58:59], v[94:95]
	v_pk_add_f32 v[58:59], v[58:59], v[94:95] neg_lo:[0,1] neg_hi:[0,1]
	v_pk_add_f32 v[126:127], v[108:109], v[112:113]
	v_pk_mul_f32 v[94:95], v[58:59], s[10:11]
	s_nop 0
	v_pk_fma_f32 v[58:59], v[58:59], s[14:15], v[94:95] op_sel:[0,0,1] op_sel_hi:[1,0,0]
	v_pk_add_f32 v[94:95], v[104:105], v[96:97]
	v_pk_add_f32 v[96:97], v[104:105], v[96:97] neg_lo:[0,1] neg_hi:[0,1]
	v_pk_add_f32 v[104:105], v[106:107], v[98:99]
	v_pk_add_f32 v[98:99], v[106:107], v[98:99] neg_lo:[0,1] neg_hi:[0,1]
	s_nop 0
	v_pk_mul_f32 v[106:107], v[98:99], s[10:11]
	v_pk_add_f32 v[130:131], v[60:61], v[96:97] op_sel:[0,1] op_sel_hi:[1,0] neg_hi:[0,1]
	v_pk_fma_f32 v[98:99], v[98:99], s[14:15], v[106:107] op_sel:[0,0,1] op_sel_hi:[1,0,0] neg_lo:[1,0,0] neg_hi:[1,0,0]
	v_pk_add_f32 v[106:107], v[114:115], v[22:23]
	v_pk_add_f32 v[22:23], v[114:115], v[22:23] neg_lo:[0,1] neg_hi:[0,1]
	v_pk_add_f32 v[114:115], v[16:17], v[24:25]
	v_pk_add_f32 v[16:17], v[16:17], v[24:25] neg_lo:[0,1] neg_hi:[0,1]
	v_pk_add_f32 v[132:133], v[60:61], v[96:97] op_sel:[0,1] op_sel_hi:[1,0] neg_lo:[0,1]
	v_pk_mul_f32 v[24:25], v[16:17], s[10:11]
	v_pk_add_f32 v[60:61], v[58:59], v[98:99]
	v_pk_fma_f32 v[16:17], v[16:17], s[14:15], v[24:25] op_sel:[0,0,1] op_sel_hi:[1,0,0]
	v_pk_add_f32 v[24:25], v[18:19], v[26:27]
	v_pk_add_f32 v[18:19], v[18:19], v[26:27] neg_lo:[0,1] neg_hi:[0,1]
	v_pk_add_f32 v[26:27], v[20:21], v[28:29]
	v_pk_add_f32 v[20:21], v[20:21], v[28:29] neg_lo:[0,1] neg_hi:[0,1]
	s_nop 0
	v_pk_mul_f32 v[28:29], v[20:21], s[10:11]
	v_pk_add_f32 v[58:59], v[58:59], v[98:99] neg_lo:[0,1] neg_hi:[0,1]
	v_pk_fma_f32 v[20:21], v[20:21], s[14:15], v[28:29] op_sel:[0,0,1] op_sel_hi:[1,0,0] neg_lo:[1,0,0] neg_hi:[1,0,0]
	v_pk_add_f32 v[28:29], v[0:1], v[8:9] op_sel:[0,1] op_sel_hi:[1,0] neg_hi:[0,1]
	v_pk_add_f32 v[0:1], v[0:1], v[8:9] op_sel:[0,1] op_sel_hi:[1,0] neg_lo:[0,1]
	v_pk_add_f32 v[8:9], v[2:3], v[10:11]
	v_pk_add_f32 v[2:3], v[2:3], v[10:11] neg_lo:[0,1] neg_hi:[0,1]
	v_pk_add_f32 v[134:135], v[106:107], v[24:25]
	v_pk_mul_f32 v[10:11], v[2:3], s[10:11]
	v_pk_add_f32 v[106:107], v[106:107], v[24:25] neg_lo:[0,1] neg_hi:[0,1]
	v_pk_fma_f32 v[2:3], v[2:3], s[14:15], v[10:11] op_sel:[0,0,1] op_sel_hi:[1,0,0]
	v_pk_add_f32 v[10:11], v[4:5], v[12:13]
	v_pk_add_f32 v[4:5], v[4:5], v[12:13] neg_lo:[0,1] neg_hi:[0,1]
	v_pk_add_f32 v[12:13], v[6:7], v[14:15]
	v_pk_add_f32 v[6:7], v[6:7], v[14:15] neg_lo:[0,1] neg_hi:[0,1]
	s_nop 0
	v_pk_mul_f32 v[14:15], v[6:7], s[10:11]
	v_pk_add_f32 v[24:25], v[114:115], v[26:27] neg_lo:[0,1] neg_hi:[0,1]
	v_pk_fma_f32 v[6:7], v[6:7], s[14:15], v[14:15] op_sel:[0,0,1] op_sel_hi:[1,0,0] neg_lo:[1,0,0] neg_hi:[1,0,0]
	v_pk_add_f32 v[14:15], v[30:31], v[124:125]
	v_pk_add_f32 v[30:31], v[30:31], v[124:125] neg_lo:[0,1] neg_hi:[0,1]
	v_pk_add_f32 v[124:125], v[120:121], v[110:111]
	v_pk_add_f32 v[110:111], v[120:121], v[110:111] neg_lo:[0,1] neg_hi:[0,1]
	v_pk_add_f32 v[120:121], v[118:119], v[102:103] op_sel:[0,1] op_sel_hi:[1,0] neg_hi:[0,1]
	v_pk_add_f32 v[118:119], v[118:119], v[102:103] op_sel:[0,1] op_sel_hi:[1,0] neg_lo:[0,1]
	v_pk_add_f32 v[102:103], v[108:109], v[112:113] neg_lo:[0,1] neg_hi:[0,1]
	v_pk_add_f32 v[112:113], v[116:117], v[94:95]
	v_pk_add_f32 v[94:95], v[116:117], v[94:95] neg_lo:[0,1] neg_hi:[0,1]
	v_pk_add_f32 v[116:117], v[100:101], v[104:105]
	v_pk_add_f32 v[100:101], v[100:101], v[104:105] neg_lo:[0,1] neg_hi:[0,1]
	v_pk_add_f32 v[138:139], v[22:23], v[18:19] op_sel:[0,1] op_sel_hi:[1,0] neg_hi:[0,1]
	v_pk_add_f32 v[140:141], v[22:23], v[18:19] op_sel:[0,1] op_sel_hi:[1,0] neg_lo:[0,1]
	v_pk_add_f32 v[18:19], v[16:17], v[20:21]
	v_pk_add_f32 v[16:17], v[16:17], v[20:21] neg_lo:[0,1] neg_hi:[0,1]
	v_pk_add_f32 v[144:145], v[28:29], v[10:11]
	v_pk_add_f32 v[158:159], v[28:29], v[10:11] neg_lo:[0,1] neg_hi:[0,1]
	v_pk_add_f32 v[10:11], v[8:9], v[12:13]
	v_pk_add_f32 v[8:9], v[8:9], v[12:13] neg_lo:[0,1] neg_hi:[0,1]
	v_pk_add_f32 v[162:163], v[0:1], v[4:5] op_sel:[0,1] op_sel_hi:[1,0] neg_hi:[0,1]
	v_pk_add_f32 v[164:165], v[0:1], v[4:5] op_sel:[0,1] op_sel_hi:[1,0] neg_lo:[0,1]
	v_pk_add_f32 v[0:1], v[2:3], v[6:7] neg_lo:[0,1] neg_hi:[0,1]
	v_pk_mul_f32 v[108:109], v[102:103], s[22:23]
	v_pk_mul_f32 v[128:129], v[100:101], s[22:23]
	v_pk_add_f32 v[136:137], v[114:115], v[26:27]
	v_pk_mul_f32 v[114:115], v[24:25], s[22:23]
	v_pk_mul_f32 v[142:143], v[16:17], s[22:23]
	v_pk_mul_f32 v[160:161], v[8:9], s[22:23]
	v_pk_add_f32 v[166:167], v[2:3], v[6:7]
	v_pk_mul_f32 v[168:169], v[0:1], s[22:23]
	v_pk_add_f32 v[28:29], v[14:15], v[124:125]
	v_pk_add_f32 v[104:105], v[14:15], v[124:125] neg_lo:[0,1] neg_hi:[0,1]
	v_pk_add_f32 v[24:25], v[30:31], v[110:111] op_sel:[0,1] op_sel_hi:[1,0] neg_hi:[0,1]
	v_pk_add_f32 v[102:103], v[30:31], v[110:111] op_sel:[0,1] op_sel_hi:[1,0] neg_lo:[0,1]
	v_pk_add_f32 v[20:21], v[120:121], v[126:127]
	v_pk_add_f32 v[100:101], v[120:121], v[126:127] neg_lo:[0,1] neg_hi:[0,1]
	v_pk_add_f32 v[16:17], v[118:119], v[108:109] op_sel:[0,1] op_sel_hi:[1,0]
	v_pk_add_f32 v[98:99], v[118:119], v[108:109] op_sel:[0,1] op_sel_hi:[1,0] neg_lo:[0,1] neg_hi:[0,1]
	v_pk_add_f32 v[12:13], v[112:113], v[116:117]
	v_pk_add_f32 v[96:97], v[112:113], v[116:117] neg_lo:[0,1] neg_hi:[0,1]
	v_pk_add_f32 v[8:9], v[94:95], v[128:129] op_sel:[0,1] op_sel_hi:[1,0]
	v_pk_add_f32 v[94:95], v[94:95], v[128:129] op_sel:[0,1] op_sel_hi:[1,0] neg_lo:[0,1] neg_hi:[0,1]
	v_pk_add_f32 v[4:5], v[130:131], v[60:61]
	v_pk_add_f32 v[60:61], v[130:131], v[60:61] neg_lo:[0,1] neg_hi:[0,1]
	v_pk_add_f32 v[0:1], v[132:133], v[58:59] op_sel:[0,1] op_sel_hi:[1,0] neg_hi:[0,1]
	v_pk_add_f32 v[58:59], v[132:133], v[58:59] op_sel:[0,1] op_sel_hi:[1,0] neg_lo:[0,1]
	v_pk_add_f32 v[30:31], v[134:135], v[136:137]
	v_pk_add_f32 v[120:121], v[134:135], v[136:137] neg_lo:[0,1] neg_hi:[0,1]
	v_pk_add_f32 v[26:27], v[106:107], v[114:115] op_sel:[0,1] op_sel_hi:[1,0]
	v_pk_add_f32 v[118:119], v[106:107], v[114:115] op_sel:[0,1] op_sel_hi:[1,0] neg_lo:[0,1] neg_hi:[0,1]
	v_pk_add_f32 v[22:23], v[138:139], v[18:19]
	v_pk_add_f32 v[116:117], v[138:139], v[18:19] neg_lo:[0,1] neg_hi:[0,1]
	v_pk_add_f32 v[18:19], v[140:141], v[142:143] op_sel:[0,1] op_sel_hi:[1,0]
	v_pk_add_f32 v[114:115], v[140:141], v[142:143] op_sel:[0,1] op_sel_hi:[1,0] neg_lo:[0,1] neg_hi:[0,1]
	v_pk_add_f32 v[14:15], v[144:145], v[10:11]
	v_pk_add_f32 v[112:113], v[144:145], v[10:11] neg_lo:[0,1] neg_hi:[0,1]
	v_pk_add_f32 v[10:11], v[158:159], v[160:161] op_sel:[0,1] op_sel_hi:[1,0]
	v_pk_add_f32 v[110:111], v[158:159], v[160:161] op_sel:[0,1] op_sel_hi:[1,0] neg_lo:[0,1] neg_hi:[0,1]
	v_pk_add_f32 v[6:7], v[162:163], v[166:167]
	v_pk_add_f32 v[108:109], v[162:163], v[166:167] neg_lo:[0,1] neg_hi:[0,1]
	v_pk_add_f32 v[2:3], v[164:165], v[168:169] op_sel:[0,1] op_sel_hi:[1,0]
	v_pk_add_f32 v[106:107], v[164:165], v[168:169] op_sel:[0,1] op_sel_hi:[1,0] neg_lo:[0,1] neg_hi:[0,1]

.LBB0_675:
	s_or_b64 exec, exec, s[4:5]
	v_mov_b32_e32 v41, v32
	s_waitcnt lgkmcnt(0)
	s_barrier
	s_mov_b32 s11, s14
	v_and_b32_e32 v98, 31, v41
	v_cvt_f32_ubyte0_e32 v24, v98
	v_mul_f32_e32 v60, 0x3b000000, v24
	v_sin_f32_e32 v24, v60
	v_ashrrev_i32_e32 v0, 4, v41
	v_lshlrev_b32_e32 v0, 3, v0
	v_lshlrev_b32_e32 v1, 3, v41
	v_cos_f32_e32 v60, v60
	v_add3_u32 v25, 0, v0, v1
	ds_read_b64 v[0:1], v25
	ds_read_b64 v[2:3], v25 offset:4352
	ds_read_b64 v[4:5], v25 offset:8704
	ds_read_b64 v[6:7], v25 offset:13056
	ds_read_b64 v[8:9], v25 offset:17408
	ds_read_b64 v[10:11], v25 offset:21760
	ds_read_b64 v[12:13], v25 offset:26112
	ds_read_b64 v[14:15], v25 offset:30464
	ds_read_b64 v[16:17], v25 offset:34816
	ds_read_b64 v[18:19], v25 offset:39168
	ds_read_b64 v[20:21], v25 offset:43520
	ds_read_b64 v[22:23], v25 offset:47872
	v_xor_b32_e32 v61, 0x80000000, v24
	s_waitcnt lgkmcnt(10)
	v_pk_mul_f32 v[94:95], v[2:3], v[24:25] op_sel:[1,0] op_sel_hi:[0,0] neg_hi:[0,1]
	v_pk_fma_f32 v[2:3], v[2:3], v[60:61], v[94:95] op_sel_hi:[1,0,1]
	v_pk_mul_f32 v[94:95], v[24:25], v[60:61] op_sel:[0,1] op_sel_hi:[0,0] neg_hi:[1,0]
	v_pk_fma_f32 v[94:95], v[60:61], v[60:61], v[94:95] op_sel_hi:[0,1,1]
	ds_read_b64 v[26:27], v25 offset:52224
	ds_read_b64 v[28:29], v25 offset:56576
	ds_read_b64 v[30:31], v25 offset:60928
	ds_read_b64 v[58:59], v25 offset:65280
	s_waitcnt lgkmcnt(13)
	v_pk_mul_f32 v[96:97], v[4:5], v[94:95] op_sel:[1,1] op_sel_hi:[0,1] neg_lo:[0,1]
	v_pk_fma_f32 v[4:5], v[4:5], v[94:95], v[96:97] op_sel_hi:[1,0,1]
	v_pk_mul_f32 v[96:97], v[24:25], v[94:95] op_sel:[0,1] op_sel_hi:[0,0] neg_hi:[1,0]
	v_pk_fma_f32 v[94:95], v[60:61], v[94:95], v[96:97] op_sel_hi:[0,1,1]
	s_mov_b32 s35, s30
	s_waitcnt lgkmcnt(12)
	v_pk_mul_f32 v[96:97], v[6:7], v[94:95] op_sel:[1,1] op_sel_hi:[0,1] neg_lo:[0,1]
	v_pk_fma_f32 v[6:7], v[6:7], v[94:95], v[96:97] op_sel_hi:[1,0,1]
	v_pk_mul_f32 v[96:97], v[24:25], v[94:95] op_sel:[0,1] op_sel_hi:[0,0] neg_hi:[1,0]
	v_pk_fma_f32 v[94:95], v[60:61], v[94:95], v[96:97] op_sel_hi:[0,1,1]
	s_mov_b32 s26, s19
	s_waitcnt lgkmcnt(11)
	v_pk_mul_f32 v[96:97], v[8:9], v[94:95] op_sel:[1,1] op_sel_hi:[0,1] neg_lo:[0,1]
	v_pk_fma_f32 v[8:9], v[8:9], v[94:95], v[96:97] op_sel_hi:[1,0,1]
	v_pk_mul_f32 v[96:97], v[24:25], v[94:95] op_sel:[0,1] op_sel_hi:[0,0] neg_hi:[1,0]
	v_pk_fma_f32 v[94:95], v[60:61], v[94:95], v[96:97] op_sel_hi:[0,1,1]
	s_waitcnt lgkmcnt(0)
	v_pk_mul_f32 v[96:97], v[10:11], v[94:95] op_sel:[1,1] op_sel_hi:[0,1] neg_lo:[0,1]
	v_pk_fma_f32 v[10:11], v[10:11], v[94:95], v[96:97] op_sel_hi:[1,0,1]
	v_pk_mul_f32 v[96:97], v[24:25], v[94:95] op_sel:[0,1] op_sel_hi:[0,0] neg_hi:[1,0]
	v_pk_fma_f32 v[94:95], v[60:61], v[94:95], v[96:97] op_sel_hi:[0,1,1]
	s_barrier
	v_pk_mul_f32 v[96:97], v[12:13], v[94:95] op_sel:[1,1] op_sel_hi:[0,1] neg_lo:[0,1]
	v_pk_fma_f32 v[12:13], v[12:13], v[94:95], v[96:97] op_sel_hi:[1,0,1]
	v_pk_mul_f32 v[96:97], v[24:25], v[94:95] op_sel:[0,1] op_sel_hi:[0,0] neg_hi:[1,0]
	v_pk_fma_f32 v[94:95], v[60:61], v[94:95], v[96:97] op_sel_hi:[0,1,1]
	s_nop 0
	v_pk_mul_f32 v[96:97], v[14:15], v[94:95] op_sel:[1,1] op_sel_hi:[0,1] neg_lo:[0,1]
	v_pk_fma_f32 v[14:15], v[14:15], v[94:95], v[96:97] op_sel_hi:[1,0,1]
	v_pk_mul_f32 v[96:97], v[24:25], v[94:95] op_sel:[0,1] op_sel_hi:[0,0] neg_hi:[1,0]
	v_pk_fma_f32 v[94:95], v[60:61], v[94:95], v[96:97] op_sel_hi:[0,1,1]
	s_nop 0
	v_pk_mul_f32 v[96:97], v[16:17], v[94:95] op_sel:[1,1] op_sel_hi:[0,1] neg_lo:[0,1]
	v_pk_fma_f32 v[16:17], v[16:17], v[94:95], v[96:97] op_sel_hi:[1,0,1]
	v_pk_mul_f32 v[96:97], v[24:25], v[94:95] op_sel:[0,1] op_sel_hi:[0,0] neg_hi:[1,0]
	v_pk_fma_f32 v[94:95], v[60:61], v[94:95], v[96:97] op_sel_hi:[0,1,1]
	s_nop 0
	v_pk_mul_f32 v[96:97], v[18:19], v[94:95] op_sel:[1,1] op_sel_hi:[0,1] neg_lo:[0,1]
	v_pk_fma_f32 v[18:19], v[18:19], v[94:95], v[96:97] op_sel_hi:[1,0,1]
	v_pk_mul_f32 v[96:97], v[24:25], v[94:95] op_sel:[0,1] op_sel_hi:[0,0] neg_hi:[1,0]
	v_pk_fma_f32 v[94:95], v[60:61], v[94:95], v[96:97] op_sel_hi:[0,1,1]
	s_nop 0
	v_pk_mul_f32 v[96:97], v[20:21], v[94:95] op_sel:[1,1] op_sel_hi:[0,1] neg_lo:[0,1]
	v_pk_fma_f32 v[20:21], v[20:21], v[94:95], v[96:97] op_sel_hi:[1,0,1]
	v_pk_mul_f32 v[96:97], v[24:25], v[94:95] op_sel:[0,1] op_sel_hi:[0,0] neg_hi:[1,0]
	v_pk_fma_f32 v[94:95], v[60:61], v[94:95], v[96:97] op_sel_hi:[0,1,1]
	s_nop 0
	v_pk_mul_f32 v[96:97], v[22:23], v[94:95] op_sel:[1,1] op_sel_hi:[0,1] neg_lo:[0,1]
	v_pk_fma_f32 v[22:23], v[22:23], v[94:95], v[96:97] op_sel_hi:[1,0,1]
	v_pk_mul_f32 v[96:97], v[24:25], v[94:95] op_sel:[0,1] op_sel_hi:[0,0] neg_hi:[1,0]
	v_pk_fma_f32 v[94:95], v[60:61], v[94:95], v[96:97] op_sel_hi:[0,1,1]
	s_nop 0
	v_pk_mul_f32 v[96:97], v[26:27], v[94:95] op_sel:[1,1] op_sel_hi:[0,1] neg_lo:[0,1]
	v_pk_fma_f32 v[26:27], v[26:27], v[94:95], v[96:97] op_sel_hi:[1,0,1]
	v_pk_mul_f32 v[96:97], v[24:25], v[94:95] op_sel:[0,1] op_sel_hi:[0,0] neg_hi:[1,0]
	v_pk_fma_f32 v[94:95], v[60:61], v[94:95], v[96:97] op_sel_hi:[0,1,1]
	s_nop 0
	v_pk_mul_f32 v[96:97], v[28:29], v[94:95] op_sel:[1,1] op_sel_hi:[0,1] neg_lo:[0,1]
	v_pk_fma_f32 v[28:29], v[28:29], v[94:95], v[96:97] op_sel_hi:[1,0,1]
	v_pk_mul_f32 v[96:97], v[24:25], v[94:95] op_sel:[0,1] op_sel_hi:[0,0] neg_hi:[1,0]
	v_pk_fma_f32 v[94:95], v[60:61], v[94:95], v[96:97] op_sel_hi:[0,1,1]
	v_pk_mul_f32 v[24:25], v[24:25], v[94:95] op_sel:[0,1] op_sel_hi:[0,0] neg_hi:[1,0]
	v_pk_fma_f32 v[24:25], v[60:61], v[94:95], v[24:25] op_sel_hi:[0,1,1]
	v_pk_mul_f32 v[60:61], v[58:59], v[24:25] op_sel:[1,1] op_sel_hi:[0,1] neg_lo:[0,1]
	v_pk_fma_f32 v[24:25], v[58:59], v[24:25], v[60:61] op_sel_hi:[1,0,1]
	v_pk_add_f32 v[58:59], v[0:1], v[16:17]
	v_pk_add_f32 v[0:1], v[0:1], v[16:17] neg_lo:[0,1] neg_hi:[0,1]
	v_pk_add_f32 v[16:17], v[2:3], v[18:19]
	v_pk_add_f32 v[2:3], v[2:3], v[18:19] neg_lo:[0,1] neg_hi:[0,1]
	v_pk_mul_f32 v[96:97], v[30:31], v[94:95] op_sel:[1,1] op_sel_hi:[0,1] neg_lo:[0,1]
	v_pk_mul_f32 v[18:19], v[2:3], s[18:19]
	v_pk_fma_f32 v[30:31], v[30:31], v[94:95], v[96:97] op_sel_hi:[1,0,1]
	v_pk_fma_f32 v[2:3], v[2:3], s[30:31], v[18:19] op_sel:[0,0,1] op_sel_hi:[1,0,0]
	v_pk_add_f32 v[18:19], v[4:5], v[20:21]
	v_pk_add_f32 v[4:5], v[4:5], v[20:21] neg_lo:[0,1] neg_hi:[0,1]
	s_nop 0
	v_pk_mul_f32 v[20:21], v[4:5], s[10:11]
	s_nop 0
	v_pk_fma_f32 v[4:5], v[4:5], s[14:15], v[20:21] op_sel:[0,0,1] op_sel_hi:[1,0,0]
	v_pk_add_f32 v[20:21], v[6:7], v[22:23]
	v_pk_add_f32 v[6:7], v[6:7], v[22:23] neg_lo:[0,1] neg_hi:[0,1]
	s_nop 0
	v_pk_mul_f32 v[22:23], v[6:7], s[34:35]
	s_nop 0
	v_pk_fma_f32 v[6:7], v[6:7], s[26:27], v[22:23] op_sel:[0,0,1] op_sel_hi:[1,0,0]
	v_pk_add_f32 v[22:23], v[8:9], v[26:27]
	v_pk_add_f32 v[8:9], v[8:9], v[26:27] neg_lo:[0,1] neg_hi:[0,1]
	v_pk_add_f32 v[26:27], v[10:11], v[28:29]
	v_pk_add_f32 v[10:11], v[10:11], v[28:29] neg_lo:[0,1] neg_hi:[0,1]
	s_nop 0
	v_pk_mul_f32 v[28:29], v[10:11], s[34:35]
	s_nop 0
	v_pk_fma_f32 v[10:11], v[10:11], s[26:27], v[28:29] op_sel:[0,0,1] op_sel_hi:[1,0,0] neg_lo:[1,0,0] neg_hi:[1,0,0]
	v_pk_add_f32 v[28:29], v[12:13], v[30:31]
	v_pk_add_f32 v[12:13], v[12:13], v[30:31] neg_lo:[0,1] neg_hi:[0,1]
	s_nop 0
	v_pk_mul_f32 v[30:31], v[12:13], s[10:11]
	s_nop 0
	v_pk_fma_f32 v[12:13], v[12:13], s[14:15], v[30:31] op_sel:[0,0,1] op_sel_hi:[1,0,0] neg_lo:[1,0,0] neg_hi:[1,0,0]
	v_pk_add_f32 v[30:31], v[14:15], v[24:25]
	v_pk_add_f32 v[14:15], v[14:15], v[24:25] neg_lo:[0,1] neg_hi:[0,1]
	s_nop 0
	v_pk_mul_f32 v[24:25], v[14:15], s[18:19]
	s_nop 0
	v_pk_fma_f32 v[14:15], v[14:15], s[30:31], v[24:25] op_sel:[0,0,1] op_sel_hi:[1,0,0] neg_lo:[1,0,0] neg_hi:[1,0,0]
	v_pk_add_f32 v[24:25], v[58:59], v[22:23]
	v_pk_add_f32 v[22:23], v[58:59], v[22:23] neg_lo:[0,1] neg_hi:[0,1]
	v_pk_add_f32 v[58:59], v[16:17], v[26:27]
	v_pk_add_f32 v[16:17], v[16:17], v[26:27] neg_lo:[0,1] neg_hi:[0,1]
	s_nop 0
	v_pk_mul_f32 v[26:27], v[16:17], s[10:11]
	s_nop 0
	v_pk_fma_f32 v[16:17], v[16:17], s[14:15], v[26:27] op_sel:[0,0,1] op_sel_hi:[1,0,0]
	v_pk_add_f32 v[26:27], v[18:19], v[28:29]
	v_pk_add_f32 v[18:19], v[18:19], v[28:29] neg_lo:[0,1] neg_hi:[0,1]
	v_pk_add_f32 v[28:29], v[20:21], v[30:31]
	v_pk_add_f32 v[20:21], v[20:21], v[30:31] neg_lo:[0,1] neg_hi:[0,1]
	s_nop 0
	v_pk_mul_f32 v[30:31], v[20:21], s[10:11]
	s_nop 0
	v_pk_fma_f32 v[20:21], v[20:21], s[14:15], v[30:31] op_sel:[0,0,1] op_sel_hi:[1,0,0] neg_lo:[1,0,0] neg_hi:[1,0,0]
	v_pk_add_f32 v[30:31], v[0:1], v[8:9] op_sel:[0,1] op_sel_hi:[1,0] neg_hi:[0,1]
	v_pk_add_f32 v[0:1], v[0:1], v[8:9] op_sel:[0,1] op_sel_hi:[1,0] neg_lo:[0,1]
	v_pk_add_f32 v[8:9], v[2:3], v[10:11]
	v_pk_add_f32 v[2:3], v[2:3], v[10:11] neg_lo:[0,1] neg_hi:[0,1]
	s_nop 0
	v_pk_mul_f32 v[10:11], v[2:3], s[10:11]
	s_nop 0
	v_pk_fma_f32 v[2:3], v[2:3], s[14:15], v[10:11] op_sel:[0,0,1] op_sel_hi:[1,0,0]
	v_pk_add_f32 v[10:11], v[4:5], v[12:13]
	v_pk_add_f32 v[4:5], v[4:5], v[12:13] neg_lo:[0,1] neg_hi:[0,1]
	v_pk_add_f32 v[12:13], v[6:7], v[14:15]
	v_pk_add_f32 v[6:7], v[6:7], v[14:15] neg_lo:[0,1] neg_hi:[0,1]
	s_nop 0
	v_pk_mul_f32 v[14:15], v[6:7], s[10:11]
	s_nop 0
	v_pk_fma_f32 v[6:7], v[6:7], s[14:15], v[14:15] op_sel:[0,0,1] op_sel_hi:[1,0,0] neg_lo:[1,0,0] neg_hi:[1,0,0]
	v_pk_add_f32 v[14:15], v[24:25], v[26:27]
	v_pk_add_f32 v[24:25], v[24:25], v[26:27] neg_lo:[0,1] neg_hi:[0,1]
	v_pk_add_f32 v[26:27], v[58:59], v[28:29]
	v_pk_add_f32 v[28:29], v[58:59], v[28:29] neg_lo:[0,1] neg_hi:[0,1]
	v_pk_add_f32 v[58:59], v[22:23], v[18:19] op_sel:[0,1] op_sel_hi:[1,0] neg_hi:[0,1]
	v_pk_add_f32 v[18:19], v[22:23], v[18:19] op_sel:[0,1] op_sel_hi:[1,0] neg_lo:[0,1]
	v_pk_add_f32 v[22:23], v[16:17], v[20:21]
	v_pk_add_f32 v[16:17], v[16:17], v[20:21] neg_lo:[0,1] neg_hi:[0,1]
	v_pk_add_f32 v[20:21], v[30:31], v[10:11]
	v_pk_add_f32 v[10:11], v[30:31], v[10:11] neg_lo:[0,1] neg_hi:[0,1]
	v_pk_add_f32 v[30:31], v[8:9], v[12:13]
	v_pk_add_f32 v[8:9], v[8:9], v[12:13] neg_lo:[0,1] neg_hi:[0,1]
	v_pk_add_f32 v[12:13], v[0:1], v[4:5] op_sel:[0,1] op_sel_hi:[1,0] neg_hi:[0,1]
	v_pk_add_f32 v[0:1], v[0:1], v[4:5] op_sel:[0,1] op_sel_hi:[1,0] neg_lo:[0,1]
	v_pk_add_f32 v[4:5], v[2:3], v[6:7]
	v_pk_add_f32 v[2:3], v[2:3], v[6:7] neg_lo:[0,1] neg_hi:[0,1]
	s_nop 0
	v_pk_mul_f32 v[2:3], v[2:3], s[22:23]
	v_pk_add_f32 v[6:7], v[14:15], v[26:27]
	v_pk_add_f32 v[14:15], v[14:15], v[26:27] neg_lo:[0,1] neg_hi:[0,1]
	v_pk_add_f32 v[26:27], v[24:25], v[28:29] op_sel:[0,1] op_sel_hi:[1,0] neg_hi:[0,1]
	v_pk_add_f32 v[24:25], v[24:25], v[28:29] op_sel:[0,1] op_sel_hi:[1,0] neg_lo:[0,1]
	v_pk_add_f32 v[28:29], v[58:59], v[22:23]
	v_pk_add_f32 v[22:23], v[58:59], v[22:23] neg_lo:[0,1] neg_hi:[0,1]
	v_pk_add_f32 v[58:59], v[18:19], v[16:17] op_sel:[0,1] op_sel_hi:[1,0] neg_hi:[0,1]
	v_pk_add_f32 v[16:17], v[18:19], v[16:17] op_sel:[0,1] op_sel_hi:[1,0] neg_lo:[0,1]
	v_pk_add_f32 v[18:19], v[20:21], v[30:31]
	v_pk_add_f32 v[20:21], v[20:21], v[30:31] neg_lo:[0,1] neg_hi:[0,1]
	v_pk_add_f32 v[30:31], v[10:11], v[8:9] op_sel:[0,1] op_sel_hi:[1,0] neg_hi:[0,1]
	v_pk_add_f32 v[8:9], v[10:11], v[8:9] op_sel:[0,1] op_sel_hi:[1,0] neg_lo:[0,1]
	v_pk_add_f32 v[10:11], v[12:13], v[4:5]
	v_pk_add_f32 v[4:5], v[12:13], v[4:5] neg_lo:[0,1] neg_hi:[0,1]
	v_pk_add_f32 v[12:13], v[0:1], v[2:3] op_sel:[0,1] op_sel_hi:[1,0]
	v_pk_add_f32 v[0:1], v[0:1], v[2:3] op_sel:[0,1] op_sel_hi:[1,0] neg_lo:[0,1] neg_hi:[0,1]
	v_lshlrev_b32_e32 v2, 4, v41
	v_and_or_b32 v2, v2, s7, v98
	v_ashrrev_i32_e32 v3, 4, v2
	v_lshlrev_b32_e32 v3, 3, v3
	v_lshlrev_b32_e32 v2, 3, v2
	v_add3_u32 v2, 0, v3, v2
	v_add_u32_e32 v3, 0x800, v2
	v_mov_b32_e32 v41, v32
	ds_write2_b64 v2, v[6:7], v[18:19] offset1:34
	ds_write2_b64 v3, v[14:15], v[20:21] offset0:16 offset1:50
	ds_write2_b64 v2, v[26:27], v[30:31] offset0:136 offset1:170
	ds_write2_b64 v3, v[24:25], v[8:9] offset0:152 offset1:186
	ds_write2_b64 v2, v[28:29], v[10:11] offset0:68 offset1:102
	ds_write2_b64 v3, v[22:23], v[4:5] offset0:84 offset1:118
	ds_write2_b64 v2, v[58:59], v[12:13] offset0:204 offset1:238
	ds_write2_b64 v3, v[16:17], v[0:1] offset0:220 offset1:254
	s_waitcnt lgkmcnt(0)
	s_barrier
	s_nop 0
	v_and_b32_e32 v98, 0x1ff, v41
	v_cvt_f32_u32_e32 v24, v98
	v_ashrrev_i32_e32 v0, 4, v41
	v_lshlrev_b32_e32 v0, 3, v0
	v_lshlrev_b32_e32 v1, 3, v41
	v_mul_f32_e32 v60, 0x39000000, v24
	v_sin_f32_e32 v24, v60
	v_cos_f32_e32 v60, v60
	v_add3_u32 v25, 0, v0, v1
	ds_read_b64 v[0:1], v25
	ds_read_b64 v[2:3], v25 offset:4352
	ds_read_b64 v[4:5], v25 offset:8704
	ds_read_b64 v[6:7], v25 offset:13056
	ds_read_b64 v[8:9], v25 offset:17408
	ds_read_b64 v[10:11], v25 offset:21760
	ds_read_b64 v[12:13], v25 offset:26112
	ds_read_b64 v[14:15], v25 offset:30464
	v_xor_b32_e32 v61, 0x80000000, v24
	s_waitcnt lgkmcnt(6)
	v_pk_mul_f32 v[94:95], v[2:3], v[24:25] op_sel:[1,0] op_sel_hi:[0,0] neg_hi:[0,1]
	v_pk_fma_f32 v[2:3], v[2:3], v[60:61], v[94:95] op_sel_hi:[1,0,1]
	v_pk_mul_f32 v[94:95], v[24:25], v[60:61] op_sel:[0,1] op_sel_hi:[0,0] neg_hi:[1,0]
	v_pk_fma_f32 v[94:95], v[60:61], v[60:61], v[94:95] op_sel_hi:[0,1,1]
	ds_read_b64 v[16:17], v25 offset:34816
	ds_read_b64 v[18:19], v25 offset:39168
	ds_read_b64 v[20:21], v25 offset:43520
	ds_read_b64 v[22:23], v25 offset:47872
	s_waitcnt lgkmcnt(9)
	v_pk_mul_f32 v[96:97], v[4:5], v[94:95] op_sel:[1,1] op_sel_hi:[0,1] neg_lo:[0,1]
	v_pk_fma_f32 v[4:5], v[4:5], v[94:95], v[96:97] op_sel_hi:[1,0,1]
	v_pk_mul_f32 v[96:97], v[24:25], v[94:95] op_sel:[0,1] op_sel_hi:[0,0] neg_hi:[1,0]
	v_pk_fma_f32 v[94:95], v[60:61], v[94:95], v[96:97] op_sel_hi:[0,1,1]
	ds_read_b64 v[26:27], v25 offset:52224
	ds_read_b64 v[28:29], v25 offset:56576
	ds_read_b64 v[30:31], v25 offset:60928
	ds_read_b64 v[58:59], v25 offset:65280
	s_waitcnt lgkmcnt(12)
	v_pk_mul_f32 v[96:97], v[6:7], v[94:95] op_sel:[1,1] op_sel_hi:[0,1] neg_lo:[0,1]
	v_pk_fma_f32 v[6:7], v[6:7], v[94:95], v[96:97] op_sel_hi:[1,0,1]
	v_pk_mul_f32 v[96:97], v[24:25], v[94:95] op_sel:[0,1] op_sel_hi:[0,0] neg_hi:[1,0]
	v_pk_fma_f32 v[94:95], v[60:61], v[94:95], v[96:97] op_sel_hi:[0,1,1]
	s_waitcnt lgkmcnt(0)
	v_pk_mul_f32 v[96:97], v[8:9], v[94:95] op_sel:[1,1] op_sel_hi:[0,1] neg_lo:[0,1]
	v_pk_fma_f32 v[8:9], v[8:9], v[94:95], v[96:97] op_sel_hi:[1,0,1]
	v_pk_mul_f32 v[96:97], v[24:25], v[94:95] op_sel:[0,1] op_sel_hi:[0,0] neg_hi:[1,0]
	v_pk_fma_f32 v[94:95], v[60:61], v[94:95], v[96:97] op_sel_hi:[0,1,1]
	s_barrier
	v_pk_mul_f32 v[96:97], v[10:11], v[94:95] op_sel:[1,1] op_sel_hi:[0,1] neg_lo:[0,1]
	v_pk_fma_f32 v[10:11], v[10:11], v[94:95], v[96:97] op_sel_hi:[1,0,1]
	v_pk_mul_f32 v[96:97], v[24:25], v[94:95] op_sel:[0,1] op_sel_hi:[0,0] neg_hi:[1,0]
	v_pk_fma_f32 v[94:95], v[60:61], v[94:95], v[96:97] op_sel_hi:[0,1,1]
	s_nop 0
	v_pk_mul_f32 v[96:97], v[12:13], v[94:95] op_sel:[1,1] op_sel_hi:[0,1] neg_lo:[0,1]
	v_pk_fma_f32 v[12:13], v[12:13], v[94:95], v[96:97] op_sel_hi:[1,0,1]
	v_pk_mul_f32 v[96:97], v[24:25], v[94:95] op_sel:[0,1] op_sel_hi:[0,0] neg_hi:[1,0]
	v_pk_fma_f32 v[94:95], v[60:61], v[94:95], v[96:97] op_sel_hi:[0,1,1]
	s_nop 0
	v_pk_mul_f32 v[96:97], v[14:15], v[94:95] op_sel:[1,1] op_sel_hi:[0,1] neg_lo:[0,1]
	v_pk_fma_f32 v[14:15], v[14:15], v[94:95], v[96:97] op_sel_hi:[1,0,1]
	v_pk_mul_f32 v[96:97], v[24:25], v[94:95] op_sel:[0,1] op_sel_hi:[0,0] neg_hi:[1,0]
	v_pk_fma_f32 v[94:95], v[60:61], v[94:95], v[96:97] op_sel_hi:[0,1,1]
	s_nop 0
	v_pk_mul_f32 v[96:97], v[16:17], v[94:95] op_sel:[1,1] op_sel_hi:[0,1] neg_lo:[0,1]
	v_pk_fma_f32 v[16:17], v[16:17], v[94:95], v[96:97] op_sel_hi:[1,0,1]
	v_pk_mul_f32 v[96:97], v[24:25], v[94:95] op_sel:[0,1] op_sel_hi:[0,0] neg_hi:[1,0]
	v_pk_fma_f32 v[94:95], v[60:61], v[94:95], v[96:97] op_sel_hi:[0,1,1]
	s_nop 0
	v_pk_mul_f32 v[96:97], v[18:19], v[94:95] op_sel:[1,1] op_sel_hi:[0,1] neg_lo:[0,1]
	v_pk_fma_f32 v[18:19], v[18:19], v[94:95], v[96:97] op_sel_hi:[1,0,1]
	v_pk_mul_f32 v[96:97], v[24:25], v[94:95] op_sel:[0,1] op_sel_hi:[0,0] neg_hi:[1,0]
	v_pk_fma_f32 v[94:95], v[60:61], v[94:95], v[96:97] op_sel_hi:[0,1,1]
	s_nop 0
	v_pk_mul_f32 v[96:97], v[20:21], v[94:95] op_sel:[1,1] op_sel_hi:[0,1] neg_lo:[0,1]
	v_pk_fma_f32 v[20:21], v[20:21], v[94:95], v[96:97] op_sel_hi:[1,0,1]
	v_pk_mul_f32 v[96:97], v[24:25], v[94:95] op_sel:[0,1] op_sel_hi:[0,0] neg_hi:[1,0]
	v_pk_fma_f32 v[94:95], v[60:61], v[94:95], v[96:97] op_sel_hi:[0,1,1]
	s_nop 0
	v_pk_mul_f32 v[96:97], v[22:23], v[94:95] op_sel:[1,1] op_sel_hi:[0,1] neg_lo:[0,1]
	v_pk_fma_f32 v[22:23], v[22:23], v[94:95], v[96:97] op_sel_hi:[1,0,1]
	v_pk_mul_f32 v[96:97], v[24:25], v[94:95] op_sel:[0,1] op_sel_hi:[0,0] neg_hi:[1,0]
	v_pk_fma_f32 v[94:95], v[60:61], v[94:95], v[96:97] op_sel_hi:[0,1,1]
	s_nop 0
	v_pk_mul_f32 v[96:97], v[26:27], v[94:95] op_sel:[1,1] op_sel_hi:[0,1] neg_lo:[0,1]
	v_pk_fma_f32 v[26:27], v[26:27], v[94:95], v[96:97] op_sel_hi:[1,0,1]
	v_pk_mul_f32 v[96:97], v[24:25], v[94:95] op_sel:[0,1] op_sel_hi:[0,0] neg_hi:[1,0]
	v_pk_fma_f32 v[94:95], v[60:61], v[94:95], v[96:97] op_sel_hi:[0,1,1]
	s_nop 0
	v_pk_mul_f32 v[96:97], v[28:29], v[94:95] op_sel:[1,1] op_sel_hi:[0,1] neg_lo:[0,1]
	v_pk_fma_f32 v[28:29], v[28:29], v[94:95], v[96:97] op_sel_hi:[1,0,1]
	v_pk_mul_f32 v[96:97], v[24:25], v[94:95] op_sel:[0,1] op_sel_hi:[0,0] neg_hi:[1,0]
	v_pk_fma_f32 v[94:95], v[60:61], v[94:95], v[96:97] op_sel_hi:[0,1,1]
	v_pk_mul_f32 v[24:25], v[24:25], v[94:95] op_sel:[0,1] op_sel_hi:[0,0] neg_hi:[1,0]
	v_pk_fma_f32 v[24:25], v[60:61], v[94:95], v[24:25] op_sel_hi:[0,1,1]
	v_pk_mul_f32 v[60:61], v[58:59], v[24:25] op_sel:[1,1] op_sel_hi:[0,1] neg_lo:[0,1]
	v_pk_fma_f32 v[24:25], v[58:59], v[24:25], v[60:61] op_sel_hi:[1,0,1]
	v_pk_add_f32 v[58:59], v[0:1], v[16:17]
	v_pk_add_f32 v[0:1], v[0:1], v[16:17] neg_lo:[0,1] neg_hi:[0,1]
	v_pk_add_f32 v[16:17], v[2:3], v[18:19]
	v_pk_add_f32 v[2:3], v[2:3], v[18:19] neg_lo:[0,1] neg_hi:[0,1]
	v_pk_mul_f32 v[96:97], v[30:31], v[94:95] op_sel:[1,1] op_sel_hi:[0,1] neg_lo:[0,1]
	v_pk_mul_f32 v[18:19], v[2:3], s[18:19]
	v_pk_fma_f32 v[30:31], v[30:31], v[94:95], v[96:97] op_sel_hi:[1,0,1]
	v_pk_fma_f32 v[2:3], v[2:3], s[30:31], v[18:19] op_sel:[0,0,1] op_sel_hi:[1,0,0]
	v_pk_add_f32 v[18:19], v[4:5], v[20:21]
	v_pk_add_f32 v[4:5], v[4:5], v[20:21] neg_lo:[0,1] neg_hi:[0,1]
	s_nop 0
	v_pk_mul_f32 v[20:21], v[4:5], s[10:11]
	s_nop 0
	v_pk_fma_f32 v[4:5], v[4:5], s[14:15], v[20:21] op_sel:[0,0,1] op_sel_hi:[1,0,0]
	v_pk_add_f32 v[20:21], v[6:7], v[22:23]
	v_pk_add_f32 v[6:7], v[6:7], v[22:23] neg_lo:[0,1] neg_hi:[0,1]
	s_nop 0
	v_pk_mul_f32 v[22:23], v[6:7], s[34:35]
	s_nop 0
	v_pk_fma_f32 v[6:7], v[6:7], s[26:27], v[22:23] op_sel:[0,0,1] op_sel_hi:[1,0,0]
	v_pk_add_f32 v[22:23], v[8:9], v[26:27]
	v_pk_add_f32 v[8:9], v[8:9], v[26:27] neg_lo:[0,1] neg_hi:[0,1]
	v_pk_add_f32 v[26:27], v[10:11], v[28:29]
	v_pk_add_f32 v[10:11], v[10:11], v[28:29] neg_lo:[0,1] neg_hi:[0,1]
	s_nop 0
	v_pk_mul_f32 v[28:29], v[10:11], s[34:35]
	s_nop 0
	v_pk_fma_f32 v[10:11], v[10:11], s[26:27], v[28:29] op_sel:[0,0,1] op_sel_hi:[1,0,0] neg_lo:[1,0,0] neg_hi:[1,0,0]
	v_pk_add_f32 v[28:29], v[12:13], v[30:31]
	v_pk_add_f32 v[12:13], v[12:13], v[30:31] neg_lo:[0,1] neg_hi:[0,1]
	s_nop 0
	v_pk_mul_f32 v[30:31], v[12:13], s[10:11]
	s_nop 0
	v_pk_fma_f32 v[12:13], v[12:13], s[14:15], v[30:31] op_sel:[0,0,1] op_sel_hi:[1,0,0] neg_lo:[1,0,0] neg_hi:[1,0,0]
	v_pk_add_f32 v[30:31], v[14:15], v[24:25]
	v_pk_add_f32 v[14:15], v[14:15], v[24:25] neg_lo:[0,1] neg_hi:[0,1]
	s_nop 0
	v_pk_mul_f32 v[24:25], v[14:15], s[18:19]
	s_nop 0
	v_pk_fma_f32 v[14:15], v[14:15], s[30:31], v[24:25] op_sel:[0,0,1] op_sel_hi:[1,0,0] neg_lo:[1,0,0] neg_hi:[1,0,0]
	v_pk_add_f32 v[24:25], v[58:59], v[22:23]
	v_pk_add_f32 v[22:23], v[58:59], v[22:23] neg_lo:[0,1] neg_hi:[0,1]
	v_pk_add_f32 v[58:59], v[16:17], v[26:27]
	v_pk_add_f32 v[16:17], v[16:17], v[26:27] neg_lo:[0,1] neg_hi:[0,1]
	s_nop 0
	v_pk_mul_f32 v[26:27], v[16:17], s[10:11]
	s_nop 0
	v_pk_fma_f32 v[16:17], v[16:17], s[14:15], v[26:27] op_sel:[0,0,1] op_sel_hi:[1,0,0]
	v_pk_add_f32 v[26:27], v[18:19], v[28:29]
	v_pk_add_f32 v[18:19], v[18:19], v[28:29] neg_lo:[0,1] neg_hi:[0,1]
	v_pk_add_f32 v[28:29], v[20:21], v[30:31]
	v_pk_add_f32 v[20:21], v[20:21], v[30:31] neg_lo:[0,1] neg_hi:[0,1]
	s_nop 0
	v_pk_mul_f32 v[30:31], v[20:21], s[10:11]
	s_nop 0
	v_pk_fma_f32 v[20:21], v[20:21], s[14:15], v[30:31] op_sel:[0,0,1] op_sel_hi:[1,0,0] neg_lo:[1,0,0] neg_hi:[1,0,0]
	v_pk_add_f32 v[30:31], v[0:1], v[8:9] op_sel:[0,1] op_sel_hi:[1,0] neg_hi:[0,1]
	v_pk_add_f32 v[0:1], v[0:1], v[8:9] op_sel:[0,1] op_sel_hi:[1,0] neg_lo:[0,1]
	v_pk_add_f32 v[8:9], v[2:3], v[10:11]
	v_pk_add_f32 v[2:3], v[2:3], v[10:11] neg_lo:[0,1] neg_hi:[0,1]
	s_nop 0
	v_pk_mul_f32 v[10:11], v[2:3], s[10:11]
	s_nop 0
	v_pk_fma_f32 v[2:3], v[2:3], s[14:15], v[10:11] op_sel:[0,0,1] op_sel_hi:[1,0,0]
	v_pk_add_f32 v[10:11], v[4:5], v[12:13]
	v_pk_add_f32 v[4:5], v[4:5], v[12:13] neg_lo:[0,1] neg_hi:[0,1]
	v_pk_add_f32 v[12:13], v[6:7], v[14:15]
	v_pk_add_f32 v[6:7], v[6:7], v[14:15] neg_lo:[0,1] neg_hi:[0,1]
	s_nop 0
	v_pk_mul_f32 v[14:15], v[6:7], s[10:11]
	s_nop 0
	v_pk_fma_f32 v[6:7], v[6:7], s[14:15], v[14:15] op_sel:[0,0,1] op_sel_hi:[1,0,0] neg_lo:[1,0,0] neg_hi:[1,0,0]
	v_pk_add_f32 v[14:15], v[24:25], v[26:27]
	v_pk_add_f32 v[24:25], v[24:25], v[26:27] neg_lo:[0,1] neg_hi:[0,1]
	v_pk_add_f32 v[26:27], v[58:59], v[28:29]
	v_pk_add_f32 v[28:29], v[58:59], v[28:29] neg_lo:[0,1] neg_hi:[0,1]
	v_pk_add_f32 v[58:59], v[22:23], v[18:19] op_sel:[0,1] op_sel_hi:[1,0] neg_hi:[0,1]
	v_pk_add_f32 v[18:19], v[22:23], v[18:19] op_sel:[0,1] op_sel_hi:[1,0] neg_lo:[0,1]
	v_pk_add_f32 v[22:23], v[16:17], v[20:21]
	v_pk_add_f32 v[16:17], v[16:17], v[20:21] neg_lo:[0,1] neg_hi:[0,1]
	v_pk_add_f32 v[20:21], v[30:31], v[10:11]
	v_pk_add_f32 v[10:11], v[30:31], v[10:11] neg_lo:[0,1] neg_hi:[0,1]
	v_pk_add_f32 v[30:31], v[8:9], v[12:13]
	v_pk_add_f32 v[8:9], v[8:9], v[12:13] neg_lo:[0,1] neg_hi:[0,1]
	v_pk_add_f32 v[12:13], v[0:1], v[4:5] op_sel:[0,1] op_sel_hi:[1,0] neg_hi:[0,1]
	v_pk_add_f32 v[0:1], v[0:1], v[4:5] op_sel:[0,1] op_sel_hi:[1,0] neg_lo:[0,1]
	v_pk_add_f32 v[4:5], v[2:3], v[6:7]
	v_pk_add_f32 v[2:3], v[2:3], v[6:7] neg_lo:[0,1] neg_hi:[0,1]
	s_nop 0
	v_pk_mul_f32 v[2:3], v[2:3], s[22:23]
	v_pk_add_f32 v[6:7], v[14:15], v[26:27]
	v_pk_add_f32 v[14:15], v[14:15], v[26:27] neg_lo:[0,1] neg_hi:[0,1]
	v_pk_add_f32 v[26:27], v[24:25], v[28:29] op_sel:[0,1] op_sel_hi:[1,0] neg_hi:[0,1]
	v_pk_add_f32 v[24:25], v[24:25], v[28:29] op_sel:[0,1] op_sel_hi:[1,0] neg_lo:[0,1]
	v_pk_add_f32 v[28:29], v[58:59], v[22:23]
	v_pk_add_f32 v[22:23], v[58:59], v[22:23] neg_lo:[0,1] neg_hi:[0,1]
	v_pk_add_f32 v[58:59], v[18:19], v[16:17] op_sel:[0,1] op_sel_hi:[1,0] neg_hi:[0,1]
	v_pk_add_f32 v[16:17], v[18:19], v[16:17] op_sel:[0,1] op_sel_hi:[1,0] neg_lo:[0,1]
	v_pk_add_f32 v[18:19], v[20:21], v[30:31]
	v_pk_add_f32 v[20:21], v[20:21], v[30:31] neg_lo:[0,1] neg_hi:[0,1]
	v_pk_add_f32 v[30:31], v[10:11], v[8:9] op_sel:[0,1] op_sel_hi:[1,0] neg_hi:[0,1]
	v_pk_add_f32 v[8:9], v[10:11], v[8:9] op_sel:[0,1] op_sel_hi:[1,0] neg_lo:[0,1]
	v_pk_add_f32 v[10:11], v[12:13], v[4:5]
	v_pk_add_f32 v[4:5], v[12:13], v[4:5] neg_lo:[0,1] neg_hi:[0,1]
	v_pk_add_f32 v[12:13], v[0:1], v[2:3] op_sel:[0,1] op_sel_hi:[1,0]
	v_pk_add_f32 v[0:1], v[0:1], v[2:3] op_sel:[0,1] op_sel_hi:[1,0] neg_lo:[0,1] neg_hi:[0,1]
	v_lshlrev_b32_e32 v2, 4, v41
	v_and_or_b32 v2, v2, s15, v98
	v_ashrrev_i32_e32 v3, 4, v2
	v_lshlrev_b32_e32 v3, 3, v3
	v_lshlrev_b32_e32 v2, 3, v2
	v_add3_u32 v2, 0, v3, v2
	ds_write_b64 v2, v[6:7]
	ds_write_b64 v2, v[14:15] offset:34816
	ds_write_b64 v2, v[26:27] offset:17408
	ds_write_b64 v2, v[24:25] offset:52224
	ds_write_b64 v2, v[28:29] offset:8704
	ds_write_b64 v2, v[22:23] offset:43520
	ds_write_b64 v2, v[58:59] offset:26112
	ds_write_b64 v2, v[16:17] offset:60928
	ds_write_b64 v2, v[18:19] offset:4352
	ds_write_b64 v2, v[20:21] offset:39168
	ds_write_b64 v2, v[30:31] offset:21760
	ds_write_b64 v2, v[8:9] offset:56576
	ds_write_b64 v2, v[10:11] offset:13056
	ds_write_b64 v2, v[4:5] offset:47872
	ds_write_b64 v2, v[12:13] offset:30464
	ds_write_b64 v2, v[0:1] offset:65280
	s_waitcnt lgkmcnt(0)
	s_barrier
	s_and_saveexec_b64 s[28:29], s[40:41]
	s_cbranch_execz .LBB0_602
	s_add_u32 s4, s38, 0x800000
	s_addc_u32 s5, s39, 0
	v_lshl_add_u64 v[0:1], v[48:49], 1, s[4:5]
	global_load_dwordx4 v[8:11], v[0:1], off offset:16
	global_load_dwordx4 v[12:15], v[0:1], off
	v_mov_b32_e32 v19, 0
	v_mov_b32_e32 v21, 0
	s_and_saveexec_b64 s[8:9], s[42:43]
	s_cbranch_execz .LBB0_678
	v_lshl_add_u64 v[2:3], v[172:173], 1, s[4:5]
	global_load_ushort v2, v[2:3], off offset:-2
	s_waitcnt vmcnt(0)
	v_lshlrev_b32_e32 v21, 16, v2
